# all plain global stores made write-through (sc1) so the seam's L2 writeback has little left to flush; on top of all30
# baseline (speedup 1.0000x reference)
; #define GAS __attribute__((address_space(1)))
; __global__ void __launch_bounds__(NWAVES * 64, 2) hybrid_fwd(const Args A) {
;     ...
;         if (blockIdx.x == 0) { GAS v4u* z = (GAS v4u*)(F.ws + WS_CTL); for (int i = F.tid; i < (int)(CTL_ZERO_BYTES / 16); i += NWAVES * 64) if (i < (int)(WS_PRM / 16) || i >= (int)((CW_SEAM * 4) / 16)) z[i] = (v4u){0u, 0u, 0u, 0u}; }
.LBB0_8:
	v_add_u32_e32 v9, 0xffffe200, v8
	v_cmp_gt_u32_e32 vcc, s12, v9
	s_and_saveexec_b64 s[10:11], vcc
	s_cbranch_execz .LBB0_7
	global_store_dwordx4 v[6:7], v[2:5], off sc1
	s_branch .LBB0_7

; #define GAS __attribute__((address_space(1)))
; #define LAS __attribute__((address_space(3)))
; #define LDS_WAIT() asm volatile("s_waitcnt lgkmcnt(0)" ::: "memory")
; __device__ __forceinline__ unsigned pk2(float lo, float hi) { f32x2_k v = {lo, hi}; bf16x2_k b = __builtin_convertvector(v, bf16x2_k); return __builtin_bit_cast(unsigned, b); }
; __device__ __forceinline__ void p0_finish(const P0Job& j, const f32x4 (&v)[16], LAS float* scr, int lane) {
;     ...
;     for (int i = 0; i < 16; ++i) { const int kk = 4 * i + r; LAS float* d = scr + kk * 65 + 4 * c4; d[0] = v[i][0] * sc; d[1] = v[i][1] * sc; d[2] = v[i][2] * sc; d[3] = v[i][3] * sc; }
;     LDS_WAIT(); asm volatile("" ::: "memory");
;     const int c = lane & 7;
; #pragma unroll
;     for (int hb = 0; hb < 2; ++hb) { const int drow0 = p0_drow(j.kind, n0 + 32 * hb);
;         if (n0 + 32 * hb < j.N && k0 + 8 * c < j.K) {
; #pragma unroll
;             for (int jj = 0; jj < 4; ++jj) { const int n = (lane >> 3) + 8 * jj; const LAS float* sp = scr + (8 * c) * 65 + 32 * hb + n;
;                 v4u o; o.x = pk2(sp[0 * 65], sp[1 * 65]); o.y = pk2(sp[2 * 65], sp[3 * 65]); o.z = pk2(sp[4 * 65], sp[5 * 65]); o.w = pk2(sp[6 * 65], sp[7 * 65]);
;                 GAS v4u* dp = (GAS v4u*)(j.WT + (size_t)(drow0 + n) * j.ldk + k0 + 8 * c); if (j.late) __builtin_nontemporal_store(o, dp); else *dp = o; } } }
.LBB0_129:
	s_waitcnt vmcnt(0)
	ds_write2_b32 v138, v64, v65 offset1:1
	ds_write2_b32 v138, v66, v67 offset0:2 offset1:3
	v_add_u32_e32 v67, 0x820, v138
	v_add_u32_e32 v65, 0x410, v138
	ds_write2_b32 v67, v68, v69 offset1:1
	v_add_u32_e32 v68, 0x828, v138
	ds_write2_b32 v65, v72, v73 offset1:1
	v_add_u32_e32 v66, 0x418, v138
	ds_write2_b32 v68, v70, v71 offset1:1
	v_add_u32_e32 v69, 0xc30, v138
	v_add_u32_e32 v71, 0x1040, v138
	v_add_u32_e32 v72, 0x1048, v138
	ds_write2_b32 v66, v74, v75 offset1:1
	ds_write2_b32 v69, v80, v81 offset1:1
	v_add_u32_e32 v70, 0xc38, v138
	ds_write2_b32 v71, v76, v77 offset1:1
	ds_write2_b32 v72, v78, v79 offset1:1
	v_add_u32_e32 v73, 0x1450, v138
	v_add_u32_e32 v74, 0x1458, v138
	v_add_u32_e32 v75, 0x1860, v138
	v_add_u32_e32 v76, 0x1868, v138
	v_add_u32_e32 v79, 0x2080, v138
	v_add_u32_e32 v80, 0x2088, v138
	ds_write2_b32 v70, v82, v83 offset1:1
	ds_write2_b32 v73, v88, v89 offset1:1
	ds_write2_b32 v74, v90, v91 offset1:1
	ds_write2_b32 v75, v84, v85 offset1:1
	ds_write2_b32 v76, v86, v87 offset1:1
	v_add_u32_e32 v77, 0x1c70, v138
	v_add_u32_e32 v78, 0x1c78, v138
	ds_write2_b32 v79, v92, v93 offset1:1
	ds_write2_b32 v80, v94, v95 offset1:1
	v_add_u32_e32 v81, 0x2490, v138
	v_add_u32_e32 v82, 0x2498, v138
	v_add_u32_e32 v83, 0x28a0, v138
	v_add_u32_e32 v84, 0x28a8, v138
	v_add_u32_e32 v85, 0x2cb0, v138
	v_add_u32_e32 v86, 0x2cb8, v138
	v_add_u32_e32 v87, 0x30c0, v138
	v_add_u32_e32 v88, 0x30c8, v138
	v_add_u32_e32 v89, 0x34d0, v138
	v_add_u32_e32 v90, 0x34d8, v138
	v_add_u32_e32 v91, 0x38e0, v138
	v_add_u32_e32 v92, 0x38e8, v138
	v_add_u32_e32 v93, 0x3cf0, v138
	v_add_u32_e32 v94, 0x3cf8, v138
	ds_write2_b32 v77, v96, v97 offset1:1
	ds_write2_b32 v78, v98, v99 offset1:1
	ds_write2_b32 v81, v104, v105 offset1:1
	ds_write2_b32 v82, v106, v107 offset1:1
	ds_write2_b32 v83, v100, v101 offset1:1
	ds_write2_b32 v84, v102, v103 offset1:1
	ds_write2_b32 v85, v112, v113 offset1:1
	ds_write2_b32 v86, v114, v115 offset1:1
	ds_write2_b32 v87, v108, v109 offset1:1
	ds_write2_b32 v88, v110, v111 offset1:1
	ds_write2_b32 v89, v120, v121 offset1:1
	ds_write2_b32 v90, v122, v123 offset1:1
	ds_write2_b32 v91, v116, v117 offset1:1
	ds_write2_b32 v92, v118, v119 offset1:1
	ds_write2_b32 v93, v124, v125 offset1:1
	ds_write2_b32 v94, v126, v127 offset1:1
	s_waitcnt lgkmcnt(0)
	s_lshl_b32 s57, s53, 7
	v_or_b32_e32 v64, s52, v132
	s_waitcnt lgkmcnt(0)
	s_and_b32 s60, s57, 0xffffff00
	s_ashr_i32 s53, s52, 31
	v_cmp_gt_i32_e32 vcc, s74, v64
	v_add_u32_e32 v64, 0x400, v134
	v_lshlrev_b32_e32 v130, 1, v132
	s_and_saveexec_b64 s[4:5], vcc
	s_cbranch_execz .LBB0_131
	s_and_b32 s61, s56, 64
	s_or_b32 s64, s61, s60
	s_or_b32 s61, s57, s61
	s_bitset1_b32 s61, 7
	s_and_b64 s[62:63], s[54:55], exec
	s_cselect_b32 s61, s64, s61
	ds_read2_b32 v[100:101], v134 offset0:65 offset1:73
	ds_read2_b32 v[102:103], v134 offset1:8
	ds_read2_b32 v[104:105], v134 offset0:130 offset1:138
	ds_read2_b32 v[106:107], v134 offset0:195 offset1:203
	ds_read2_b32 v[108:109], v64 offset0:4 offset1:12
	ds_read2_b32 v[110:111], v64 offset0:69 offset1:77
	ds_read2_b32 v[112:113], v64 offset0:134 offset1:142
	ds_read2_b32 v[114:115], v64 offset0:199 offset1:207
	v_add_u32_e32 v116, s61, v133
	v_ashrrev_i32_e32 v117, 31, v116
	v_lshlrev_b64 v[116:117], 11, v[116:117]
	v_lshl_add_u64 v[116:117], s[50:51], 0, v[116:117]
	s_lshl_b64 s[62:63], s[52:53], 1
	v_lshl_add_u64 v[116:117], v[116:117], 0, s[62:63]
	s_waitcnt lgkmcnt(6)
	v_cvt_pk_bf16_f32 v96, v102, v100
	s_waitcnt lgkmcnt(4)
	v_cvt_pk_bf16_f32 v97, v104, v106
	s_waitcnt lgkmcnt(2)
	v_cvt_pk_bf16_f32 v98, v108, v110
	s_waitcnt lgkmcnt(0)
	v_cvt_pk_bf16_f32 v99, v112, v114
	v_lshl_add_u64 v[116:117], v[116:117], 0, v[130:131]
	v_add_u32_e32 v100, s61, v135
	global_store_dwordx4 v[116:117], v[96:99], off sc1
	s_nop 1
	v_cvt_pk_bf16_f32 v96, v103, v101
	v_ashrrev_i32_e32 v101, 31, v100
	v_lshlrev_b64 v[100:101], 11, v[100:101]
	v_lshl_add_u64 v[100:101], s[50:51], 0, v[100:101]
	v_lshl_add_u64 v[100:101], v[100:101], 0, s[62:63]
	v_cvt_pk_bf16_f32 v97, v105, v107
	v_cvt_pk_bf16_f32 v98, v109, v111
	v_cvt_pk_bf16_f32 v99, v113, v115
	v_lshl_add_u64 v[100:101], v[100:101], 0, v[130:131]
	ds_read2_b32 v[102:103], v134 offset0:81 offset1:89
	ds_read2_b32 v[104:105], v134 offset0:16 offset1:24
	ds_read2_b32 v[106:107], v134 offset0:146 offset1:154
	ds_read2_b32 v[108:109], v134 offset0:211 offset1:219
	ds_read2_b32 v[110:111], v64 offset0:20 offset1:28
	ds_read2_b32 v[112:113], v64 offset0:85 offset1:93
	ds_read2_b32 v[114:115], v64 offset0:150 offset1:158
	ds_read2_b32 v[116:117], v64 offset0:215 offset1:223
	global_store_dwordx4 v[100:101], v[96:99], off sc1
	v_add_u32_e32 v100, s61, v136
	v_ashrrev_i32_e32 v101, 31, v100
	v_lshlrev_b64 v[100:101], 11, v[100:101]
	v_lshl_add_u64 v[100:101], s[50:51], 0, v[100:101]
	v_lshl_add_u64 v[100:101], v[100:101], 0, s[62:63]
	s_waitcnt lgkmcnt(6)
	v_cvt_pk_bf16_f32 v96, v104, v102
	s_waitcnt lgkmcnt(4)
	v_cvt_pk_bf16_f32 v97, v106, v108
	s_waitcnt lgkmcnt(2)
	v_cvt_pk_bf16_f32 v98, v110, v112
	s_waitcnt lgkmcnt(0)
	v_cvt_pk_bf16_f32 v99, v114, v116
	v_lshl_add_u64 v[100:101], v[100:101], 0, v[130:131]
	global_store_dwordx4 v[100:101], v[96:99], off sc1
	v_add_u32_e32 v100, s61, v137
	v_ashrrev_i32_e32 v101, 31, v100
	v_lshlrev_b64 v[100:101], 11, v[100:101]
	v_lshl_add_u64 v[100:101], s[50:51], 0, v[100:101]
	v_lshl_add_u64 v[100:101], v[100:101], 0, s[62:63]
	v_cvt_pk_bf16_f32 v96, v105, v103
	v_cvt_pk_bf16_f32 v97, v107, v109
	v_cvt_pk_bf16_f32 v98, v111, v113
	v_cvt_pk_bf16_f32 v99, v115, v117
	v_lshl_add_u64 v[100:101], v[100:101], 0, v[130:131]
	global_store_dwordx4 v[100:101], v[96:99], off sc1
; #define GAS __attribute__((address_space(1)))
; #define LAS __attribute__((address_space(3)))
; __device__ __forceinline__ unsigned pk2(float lo, float hi) { f32x2_k v = {lo, hi}; bf16x2_k b = __builtin_convertvector(v, bf16x2_k); return __builtin_bit_cast(unsigned, b); }
; __device__ __forceinline__ void p0_finish(const P0Job& j, const f32x4 (&v)[16], LAS float* scr, int lane) {
;     ...
;     for (int hb = 0; hb < 2; ++hb) { const int drow0 = p0_drow(j.kind, n0 + 32 * hb);
;         if (n0 + 32 * hb < j.N && k0 + 8 * c < j.K) {
; #pragma unroll
;             for (int jj = 0; jj < 4; ++jj) { const int n = (lane >> 3) + 8 * jj; const LAS float* sp = scr + (8 * c) * 65 + 32 * hb + n;
;                 v4u o; o.x = pk2(sp[0 * 65], sp[1 * 65]); o.y = pk2(sp[2 * 65], sp[3 * 65]); o.z = pk2(sp[4 * 65], sp[5 * 65]); o.w = pk2(sp[6 * 65], sp[7 * 65]);
;                 GAS v4u* dp = (GAS v4u*)(j.WT + (size_t)(drow0 + n) * j.ldk + k0 + 8 * c); if (j.late) __builtin_nontemporal_store(o, dp); else *dp = o; } } }
.LBB0_131:
	s_or_b64 exec, exec, s[4:5]
	s_or_b32 s56, s56, 32
	s_cmpk_lt_i32 s56, 0xb00
	s_cselect_b64 s[4:5], -1, 0
	s_and_b64 s[62:63], s[4:5], vcc
	s_and_saveexec_b64 s[4:5], s[62:63]
	s_cbranch_execz .LBB0_133
	s_and_b32 s56, s56, 0x60
	s_or_b32 s60, s56, s60
	s_or_b32 s56, s57, s56
	s_bitset1_b32 s56, 7
	s_and_b64 s[54:55], s[54:55], exec
	s_cselect_b32 s54, s60, s56
	ds_read2_b32 v[100:101], v134 offset0:97 offset1:105
	ds_read2_b32 v[102:103], v134 offset0:32 offset1:40
	ds_read2_b32 v[104:105], v134 offset0:162 offset1:170
	ds_read2_b32 v[106:107], v134 offset0:227 offset1:235
	ds_read2_b32 v[108:109], v64 offset0:36 offset1:44
	ds_read2_b32 v[110:111], v64 offset0:101 offset1:109
	ds_read2_b32 v[112:113], v64 offset0:166 offset1:174
	ds_read2_b32 v[114:115], v64 offset0:231 offset1:239
	v_add_u32_e32 v116, s54, v133
	v_ashrrev_i32_e32 v117, 31, v116
	v_lshlrev_b64 v[116:117], 11, v[116:117]
	v_lshl_add_u64 v[116:117], s[50:51], 0, v[116:117]
	s_lshl_b64 s[52:53], s[52:53], 1
	v_lshl_add_u64 v[116:117], v[116:117], 0, s[52:53]
	s_waitcnt lgkmcnt(6)
	v_cvt_pk_bf16_f32 v96, v102, v100
	s_waitcnt lgkmcnt(4)
	v_cvt_pk_bf16_f32 v97, v104, v106
	s_waitcnt lgkmcnt(2)
	v_cvt_pk_bf16_f32 v98, v108, v110
	s_waitcnt lgkmcnt(0)
	v_cvt_pk_bf16_f32 v99, v112, v114
	v_lshl_add_u64 v[116:117], v[116:117], 0, v[130:131]
	v_add_u32_e32 v100, s54, v135
	global_store_dwordx4 v[116:117], v[96:99], off sc1
	s_nop 1
	v_cvt_pk_bf16_f32 v96, v103, v101
	v_ashrrev_i32_e32 v101, 31, v100
	v_lshlrev_b64 v[100:101], 11, v[100:101]
	v_lshl_add_u64 v[100:101], s[50:51], 0, v[100:101]
	v_lshl_add_u64 v[100:101], v[100:101], 0, s[52:53]
	v_cvt_pk_bf16_f32 v97, v105, v107
	v_cvt_pk_bf16_f32 v98, v109, v111
	v_cvt_pk_bf16_f32 v99, v113, v115
	v_lshl_add_u64 v[100:101], v[100:101], 0, v[130:131]
	ds_read2_b32 v[102:103], v134 offset0:113 offset1:121
	ds_read2_b32 v[104:105], v134 offset0:48 offset1:56
	ds_read2_b32 v[106:107], v134 offset0:178 offset1:186
	ds_read2_b32 v[108:109], v134 offset0:243 offset1:251
	ds_read2_b32 v[110:111], v64 offset0:52 offset1:60
	ds_read2_b32 v[112:113], v64 offset0:117 offset1:125
	ds_read2_b32 v[114:115], v64 offset0:182 offset1:190
	ds_read2_b32 v[116:117], v64 offset0:247 offset1:255
	global_store_dwordx4 v[100:101], v[96:99], off sc1
	v_add_u32_e32 v100, s54, v136
	v_ashrrev_i32_e32 v101, 31, v100
	v_lshlrev_b64 v[100:101], 11, v[100:101]
	v_lshl_add_u64 v[100:101], s[50:51], 0, v[100:101]
	v_lshl_add_u64 v[100:101], v[100:101], 0, s[52:53]
	s_waitcnt lgkmcnt(6)
	v_cvt_pk_bf16_f32 v96, v104, v102
	s_waitcnt lgkmcnt(4)
	v_cvt_pk_bf16_f32 v97, v106, v108
	s_waitcnt lgkmcnt(2)
	v_cvt_pk_bf16_f32 v98, v110, v112
	s_waitcnt lgkmcnt(0)
	v_cvt_pk_bf16_f32 v99, v114, v116
	v_lshl_add_u64 v[100:101], v[100:101], 0, v[130:131]
	global_store_dwordx4 v[100:101], v[96:99], off sc1
	v_add_u32_e32 v100, s54, v137
	v_ashrrev_i32_e32 v101, 31, v100
	v_lshlrev_b64 v[100:101], 11, v[100:101]
	v_lshl_add_u64 v[100:101], s[50:51], 0, v[100:101]
	v_lshl_add_u64 v[100:101], v[100:101], 0, s[52:53]
	v_cvt_pk_bf16_f32 v96, v105, v103
	v_cvt_pk_bf16_f32 v97, v107, v109
	v_cvt_pk_bf16_f32 v98, v111, v113
	v_cvt_pk_bf16_f32 v99, v115, v117
	v_lshl_add_u64 v[100:101], v[100:101], 0, v[130:131]
	global_store_dwordx4 v[100:101], v[96:99], off sc1

; #define GAS __attribute__((address_space(1)))
; #define LAS __attribute__((address_space(3)))
; __device__ __forceinline__ unsigned pk2(float lo, float hi) { f32x2_k v = {lo, hi}; bf16x2_k b = __builtin_convertvector(v, bf16x2_k); return __builtin_bit_cast(unsigned, b); }
; __device__ __forceinline__ void p0_finish(const P0Job& j, const f32x4 (&v)[16], LAS float* scr, int lane) {
;     ...
;     for (int hb = 0; hb < 2; ++hb) { const int drow0 = p0_drow(j.kind, n0 + 32 * hb);
;         if (n0 + 32 * hb < j.N && k0 + 8 * c < j.K) {
; #pragma unroll
;             for (int jj = 0; jj < 4; ++jj) { const int n = (lane >> 3) + 8 * jj; const LAS float* sp = scr + (8 * c) * 65 + 32 * hb + n;
;                 v4u o; o.x = pk2(sp[0 * 65], sp[1 * 65]); o.y = pk2(sp[2 * 65], sp[3 * 65]); o.z = pk2(sp[4 * 65], sp[5 * 65]); o.w = pk2(sp[6 * 65], sp[7 * 65]);
;                 GAS v4u* dp = (GAS v4u*)(j.WT + (size_t)(drow0 + n) * j.ldk + k0 + 8 * c); if (j.late) __builtin_nontemporal_store(o, dp); else *dp = o; } } }
.LBB0_145:
	s_lshl_b32 s52, s52, 6
	v_or_b32_e32 v65, s52, v132
	s_ashr_i32 s53, s52, 31
	v_cmp_gt_i32_e64 s[4:5], s74, v65
	s_and_saveexec_b64 s[54:55], s[4:5]
	s_cbranch_execz .LBB0_147
	ds_read2_b32 v[70:71], v134 offset0:65 offset1:73
	ds_read2_b32 v[72:73], v134 offset1:8
	ds_read2_b32 v[74:75], v134 offset0:130 offset1:138
	ds_read2_b32 v[76:77], v134 offset0:195 offset1:203
	ds_read2_b32 v[78:79], v64 offset0:4 offset1:12
	ds_read2_b32 v[80:81], v64 offset0:69 offset1:77
	ds_read2_b32 v[82:83], v64 offset0:134 offset1:142
	ds_read2_b32 v[84:85], v64 offset0:199 offset1:207
	v_add_u32_e32 v86, s59, v133
	v_ashrrev_i32_e32 v87, 31, v86
	v_lshlrev_b64 v[86:87], 11, v[86:87]
	v_lshl_add_u64 v[86:87], s[50:51], 0, v[86:87]
	s_lshl_b64 s[60:61], s[52:53], 1
	v_lshl_add_u64 v[86:87], v[86:87], 0, s[60:61]
	s_waitcnt lgkmcnt(6)
	v_cvt_pk_bf16_f32 v66, v72, v70
	s_waitcnt lgkmcnt(4)
	v_cvt_pk_bf16_f32 v67, v74, v76
	s_waitcnt lgkmcnt(2)
	v_cvt_pk_bf16_f32 v68, v78, v80
	s_waitcnt lgkmcnt(0)
	v_cvt_pk_bf16_f32 v69, v82, v84
	v_lshl_add_u64 v[86:87], v[86:87], 0, v[130:131]
	v_add_u32_e32 v70, s59, v135
	global_store_dwordx4 v[86:87], v[66:69], off sc1
	s_nop 1
	v_cvt_pk_bf16_f32 v66, v73, v71
	v_ashrrev_i32_e32 v71, 31, v70
	v_lshlrev_b64 v[70:71], 11, v[70:71]
	v_lshl_add_u64 v[70:71], s[50:51], 0, v[70:71]
	v_lshl_add_u64 v[70:71], v[70:71], 0, s[60:61]
	v_cvt_pk_bf16_f32 v67, v75, v77
	v_cvt_pk_bf16_f32 v68, v79, v81
	v_cvt_pk_bf16_f32 v69, v83, v85
	v_lshl_add_u64 v[70:71], v[70:71], 0, v[130:131]
	ds_read2_b32 v[72:73], v134 offset0:81 offset1:89
	ds_read2_b32 v[74:75], v134 offset0:16 offset1:24
	ds_read2_b32 v[76:77], v134 offset0:146 offset1:154
	ds_read2_b32 v[78:79], v134 offset0:211 offset1:219
	ds_read2_b32 v[80:81], v64 offset0:20 offset1:28
	ds_read2_b32 v[82:83], v64 offset0:85 offset1:93
	ds_read2_b32 v[84:85], v64 offset0:150 offset1:158
	ds_read2_b32 v[86:87], v64 offset0:215 offset1:223
	global_store_dwordx4 v[70:71], v[66:69], off sc1
	v_add_u32_e32 v70, s59, v136
	v_ashrrev_i32_e32 v71, 31, v70
	v_lshlrev_b64 v[70:71], 11, v[70:71]
	v_lshl_add_u64 v[70:71], s[50:51], 0, v[70:71]
	v_lshl_add_u64 v[70:71], v[70:71], 0, s[60:61]
	s_waitcnt lgkmcnt(6)
	v_cvt_pk_bf16_f32 v66, v74, v72
	s_waitcnt lgkmcnt(4)
	v_cvt_pk_bf16_f32 v67, v76, v78
	s_waitcnt lgkmcnt(2)
	v_cvt_pk_bf16_f32 v68, v80, v82
	s_waitcnt lgkmcnt(0)
	v_cvt_pk_bf16_f32 v69, v84, v86
	v_lshl_add_u64 v[70:71], v[70:71], 0, v[130:131]
	global_store_dwordx4 v[70:71], v[66:69], off sc1
	v_add_u32_e32 v70, s59, v137
	v_ashrrev_i32_e32 v71, 31, v70
	v_lshlrev_b64 v[70:71], 11, v[70:71]
	v_lshl_add_u64 v[70:71], s[50:51], 0, v[70:71]
	v_lshl_add_u64 v[70:71], v[70:71], 0, s[60:61]
	v_cvt_pk_bf16_f32 v66, v75, v73
	v_cvt_pk_bf16_f32 v67, v77, v79
	v_cvt_pk_bf16_f32 v68, v81, v83
	v_cvt_pk_bf16_f32 v69, v85, v87
	v_lshl_add_u64 v[70:71], v[70:71], 0, v[130:131]
	global_store_dwordx4 v[70:71], v[66:69], off sc1

; #define GAS __attribute__((address_space(1)))
; #define LAS __attribute__((address_space(3)))
; __device__ __forceinline__ unsigned pk2(float lo, float hi) { f32x2_k v = {lo, hi}; bf16x2_k b = __builtin_convertvector(v, bf16x2_k); return __builtin_bit_cast(unsigned, b); }
; __device__ __forceinline__ void p0_finish(const P0Job& j, const f32x4 (&v)[16], LAS float* scr, int lane) {
;     ...
;     for (int hb = 0; hb < 2; ++hb) { const int drow0 = p0_drow(j.kind, n0 + 32 * hb);
;         if (n0 + 32 * hb < j.N && k0 + 8 * c < j.K) {
; #pragma unroll
;             for (int jj = 0; jj < 4; ++jj) { const int n = (lane >> 3) + 8 * jj; const LAS float* sp = scr + (8 * c) * 65 + 32 * hb + n;
;                 v4u o; o.x = pk2(sp[0 * 65], sp[1 * 65]); o.y = pk2(sp[2 * 65], sp[3 * 65]); o.z = pk2(sp[4 * 65], sp[5 * 65]); o.w = pk2(sp[6 * 65], sp[7 * 65]);
;                 GAS v4u* dp = (GAS v4u*)(j.WT + (size_t)(drow0 + n) * j.ldk + k0 + 8 * c); if (j.late) __builtin_nontemporal_store(o, dp); else *dp = o; } } }
.LBB0_158:
	s_cmpk_lt_i32 s60, 0xb00
	s_cselect_b64 s[54:55], -1, 0
	s_and_b64 s[54:55], s[54:55], s[4:5]
	s_and_saveexec_b64 s[4:5], s[54:55]
	s_cbranch_execz .LBB0_29
	ds_read2_b32 v[70:71], v134 offset0:97 offset1:105
	ds_read2_b32 v[72:73], v134 offset0:32 offset1:40
	ds_read2_b32 v[74:75], v134 offset0:162 offset1:170
	ds_read2_b32 v[76:77], v134 offset0:227 offset1:235
	ds_read2_b32 v[78:79], v64 offset0:36 offset1:44
	ds_read2_b32 v[80:81], v64 offset0:101 offset1:109
	ds_read2_b32 v[82:83], v64 offset0:166 offset1:174
	ds_read2_b32 v[84:85], v64 offset0:231 offset1:239
	v_add_u32_e32 v86, s59, v133
	v_ashrrev_i32_e32 v87, 31, v86
	v_lshlrev_b64 v[86:87], 11, v[86:87]
	v_lshl_add_u64 v[86:87], s[50:51], 0, v[86:87]
	s_lshl_b64 s[52:53], s[52:53], 1
	v_lshl_add_u64 v[86:87], v[86:87], 0, s[52:53]
	s_waitcnt lgkmcnt(6)
	v_cvt_pk_bf16_f32 v66, v72, v70
	s_waitcnt lgkmcnt(4)
	v_cvt_pk_bf16_f32 v67, v74, v76
	s_waitcnt lgkmcnt(2)
	v_cvt_pk_bf16_f32 v68, v78, v80
	s_waitcnt lgkmcnt(0)
	v_cvt_pk_bf16_f32 v69, v82, v84
	v_lshl_add_u64 v[86:87], v[86:87], 0, v[130:131]
	v_add_u32_e32 v70, s59, v135
	global_store_dwordx4 v[86:87], v[66:69], off sc1
	s_nop 1
	v_cvt_pk_bf16_f32 v66, v73, v71
	v_ashrrev_i32_e32 v71, 31, v70
	v_lshlrev_b64 v[70:71], 11, v[70:71]
	v_lshl_add_u64 v[70:71], s[50:51], 0, v[70:71]
	v_lshl_add_u64 v[70:71], v[70:71], 0, s[52:53]
	v_cvt_pk_bf16_f32 v67, v75, v77
	v_cvt_pk_bf16_f32 v68, v79, v81
	v_cvt_pk_bf16_f32 v69, v83, v85
	v_lshl_add_u64 v[70:71], v[70:71], 0, v[130:131]
	ds_read2_b32 v[72:73], v134 offset0:113 offset1:121
	ds_read2_b32 v[74:75], v134 offset0:48 offset1:56
	ds_read2_b32 v[76:77], v134 offset0:178 offset1:186
	ds_read2_b32 v[78:79], v134 offset0:243 offset1:251
	ds_read2_b32 v[80:81], v64 offset0:52 offset1:60
	ds_read2_b32 v[82:83], v64 offset0:117 offset1:125
	ds_read2_b32 v[84:85], v64 offset0:182 offset1:190
	ds_read2_b32 v[86:87], v64 offset0:247 offset1:255
	global_store_dwordx4 v[70:71], v[66:69], off sc1
	s_waitcnt lgkmcnt(6)
	v_cvt_pk_bf16_f32 v64, v74, v72
	s_waitcnt lgkmcnt(4)
	v_cvt_pk_bf16_f32 v65, v76, v78
	v_add_u32_e32 v68, s59, v136
	v_ashrrev_i32_e32 v69, 31, v68
	v_lshlrev_b64 v[68:69], 11, v[68:69]
	v_lshl_add_u64 v[68:69], s[50:51], 0, v[68:69]
	v_lshl_add_u64 v[68:69], v[68:69], 0, s[52:53]
	s_waitcnt lgkmcnt(2)
	v_cvt_pk_bf16_f32 v66, v80, v82
	s_waitcnt lgkmcnt(0)
	v_cvt_pk_bf16_f32 v67, v84, v86
	v_lshl_add_u64 v[68:69], v[68:69], 0, v[130:131]
	global_store_dwordx4 v[68:69], v[64:67], off sc1
	v_add_u32_e32 v68, s59, v137
	v_ashrrev_i32_e32 v69, 31, v68
	v_lshlrev_b64 v[68:69], 11, v[68:69]
	v_lshl_add_u64 v[68:69], s[50:51], 0, v[68:69]
	v_lshl_add_u64 v[68:69], v[68:69], 0, s[52:53]
	v_cvt_pk_bf16_f32 v64, v75, v73
	v_cvt_pk_bf16_f32 v65, v77, v79
	v_cvt_pk_bf16_f32 v66, v81, v83
	v_cvt_pk_bf16_f32 v67, v85, v87
	v_lshl_add_u64 v[68:69], v[68:69], 0, v[130:131]
	global_store_dwordx4 v[68:69], v[64:67], off sc1
	s_branch .LBB0_29

; #define GAS __attribute__((address_space(1)))
; __device__ __forceinline__ void p0_prologue(Frame& F, const Args& A) {
;     ...
;         GAS v4u* z = (GAS v4u*)(F.ws + WS_WIN + (size_t)SHIFT_COLS * D * 2); const int nz = (PRW - SHIFT_COLS) * D * 2 / 16;
;         for (int i = (F.vcu * NWAVES + F.wave) * 64 + F.lane; i < nz; i += F.G * NWAVES * 64) z[i] = (v4u){0u, 0u, 0u, 0u};
.LBB0_162:
	v_add_u32_e32 v8, s4, v8
	v_cmp_lt_i32_e32 vcc, s3, v8
	global_store_dwordx4 v[6:7], v[0:3], off sc1
	s_or_b64 s[54:55], vcc, s[54:55]
	v_lshl_add_u64 v[6:7], v[6:7], 0, s[52:53]
	s_andn2_b64 exec, exec, s[54:55]
	s_cbranch_execnz .LBB0_162

; __device__ __forceinline__ void p0_prologue(Frame& F, const Args& A) {
;     ...
;         for (int i = gt; i < 1824; i += GT) PRMw[0 + i] = A.in[9][i];
.LBB0_165:
	v_lshl_add_u64 v[6:7], s[48:49], 0, v[0:1]
	global_load_dword v3, v[6:7], off
	v_add_u32_e32 v2, s4, v2
	v_cmp_lt_i32_e32 vcc, s3, v2
	v_lshl_add_u64 v[6:7], s[52:53], 0, v[0:1]
	v_lshl_add_u64 v[0:1], v[0:1], 0, s[54:55]
	s_or_b64 s[56:57], vcc, s[56:57]
	s_waitcnt vmcnt(0)
	global_store_dword v[6:7], v3, off sc1
	s_andn2_b64 exec, exec, s[56:57]
	s_cbranch_execnz .LBB0_165

; __device__ __forceinline__ void p0_prologue(Frame& F, const Args& A) {
;     ...
;         for (int i = gt; i < 512; i += GT) PRMw[2048 + i] = A.in[11][i];
;         for (int i = gt; i < 512; i += GT) PRMw[2560 + i] = A.in[13][i];
;         for (int i = gt; i < 512; i += GT) PRMw[3072 + i] = A.in[16][i];
;         for (int i = gt; i < 512; i += GT) PRMw[3584 + i] = A.in[17][i];
;         for (int i = gt; i < 512; i += GT) PRMw[4096 + i] = A.in[18][i];
;         for (int i = gt; i < 512; i += GT) PRMw[4608 + i] = A.in[19][i];
;         for (int i = gt; i < 512; i += GT) PRMw[5120 + i] = A.in[20][i];
.LBB0_168:
	v_lshl_add_u64 v[8:9], s[46:47], 0, v[2:3]
	global_load_dword v7, v[8:9], off
	v_add_u32_e32 v6, s4, v6
	v_cmp_lt_i32_e32 vcc, s3, v6
	v_lshl_add_u64 v[8:9], s[52:53], 0, v[2:3]
	v_lshl_add_u64 v[2:3], v[2:3], 0, s[50:51]
	s_or_b64 s[54:55], vcc, s[54:55]
	s_waitcnt vmcnt(0)
	global_store_dword v[8:9], v7, off sc1
	s_andn2_b64 exec, exec, s[54:55]
	s_cbranch_execnz .LBB0_168
	s_or_b64 exec, exec, s[54:55]
	s_add_u32 s46, s86, 0x12800
	s_addc_u32 s47, s87, 0
	s_mov_b64 s[52:53], 0
	s_movk_i32 s3, 0x1ff
	v_mov_b64_e32 v[2:3], v[0:1]
	v_mov_b32_e32 v6, v4
.LBB0_170:
	v_lshl_add_u64 v[8:9], s[44:45], 0, v[2:3]
	global_load_dword v7, v[8:9], off
	v_add_u32_e32 v6, s4, v6
	v_cmp_lt_i32_e32 vcc, s3, v6
	v_lshl_add_u64 v[8:9], s[46:47], 0, v[2:3]
	v_lshl_add_u64 v[2:3], v[2:3], 0, s[50:51]
	s_or_b64 s[52:53], vcc, s[52:53]
	s_waitcnt vmcnt(0)
	global_store_dword v[8:9], v7, off sc1
	s_andn2_b64 exec, exec, s[52:53]
	s_cbranch_execnz .LBB0_170
	s_or_b64 exec, exec, s[52:53]
	s_add_u32 s44, s86, 0x13000
	s_addc_u32 s45, s87, 0
	s_mov_b64 s[46:47], 0
	s_movk_i32 s3, 0x1ff
	v_mov_b64_e32 v[2:3], v[0:1]
	v_mov_b32_e32 v6, v4
.LBB0_172:
	v_lshl_add_u64 v[8:9], s[8:9], 0, v[2:3]
	global_load_dword v7, v[8:9], off
	v_add_u32_e32 v6, s4, v6
	v_cmp_lt_i32_e32 vcc, s3, v6
	v_lshl_add_u64 v[8:9], s[44:45], 0, v[2:3]
	v_lshl_add_u64 v[2:3], v[2:3], 0, s[50:51]
	s_or_b64 s[46:47], vcc, s[46:47]
	s_waitcnt vmcnt(0)
	global_store_dword v[8:9], v7, off sc1
	s_andn2_b64 exec, exec, s[46:47]
	s_cbranch_execnz .LBB0_172
	s_or_b64 exec, exec, s[46:47]
	s_add_u32 s8, s86, 0x13800
	s_addc_u32 s9, s87, 0
	s_mov_b64 s[44:45], 0
	s_movk_i32 s3, 0x1ff
	v_mov_b64_e32 v[2:3], v[0:1]
	v_mov_b32_e32 v6, v4
.LBB0_174:
	v_lshl_add_u64 v[8:9], s[10:11], 0, v[2:3]
	global_load_dword v7, v[8:9], off
	v_add_u32_e32 v6, s4, v6
	v_cmp_lt_i32_e32 vcc, s3, v6
	v_lshl_add_u64 v[8:9], s[8:9], 0, v[2:3]
	v_lshl_add_u64 v[2:3], v[2:3], 0, s[50:51]
	s_or_b64 s[44:45], vcc, s[44:45]
	s_waitcnt vmcnt(0)
	global_store_dword v[8:9], v7, off sc1
	s_andn2_b64 exec, exec, s[44:45]
	s_cbranch_execnz .LBB0_174
	s_or_b64 exec, exec, s[44:45]
	s_add_u32 s8, s86, 0x14000
	s_addc_u32 s9, s87, 0
	s_mov_b64 s[10:11], 0
	s_movk_i32 s3, 0x1ff
	v_mov_b64_e32 v[2:3], v[0:1]
	v_mov_b32_e32 v6, v4
.LBB0_176:
	v_lshl_add_u64 v[8:9], s[12:13], 0, v[2:3]
	global_load_dword v7, v[8:9], off
	v_add_u32_e32 v6, s4, v6
	v_cmp_lt_i32_e32 vcc, s3, v6
	v_lshl_add_u64 v[8:9], s[8:9], 0, v[2:3]
	v_lshl_add_u64 v[2:3], v[2:3], 0, s[50:51]
	s_or_b64 s[10:11], vcc, s[10:11]
	s_waitcnt vmcnt(0)
	global_store_dword v[8:9], v7, off sc1
	s_andn2_b64 exec, exec, s[10:11]
	s_cbranch_execnz .LBB0_176
	s_or_b64 exec, exec, s[10:11]
	s_add_u32 s8, s86, 0x14800
	s_addc_u32 s9, s87, 0
	s_mov_b64 s[10:11], 0
	s_movk_i32 s3, 0x1ff
	v_mov_b64_e32 v[2:3], v[0:1]
	v_mov_b32_e32 v6, v4
.LBB0_178:
	v_lshl_add_u64 v[8:9], s[14:15], 0, v[2:3]
	global_load_dword v7, v[8:9], off
	v_add_u32_e32 v6, s4, v6
	v_cmp_lt_i32_e32 vcc, s3, v6
	v_lshl_add_u64 v[8:9], s[8:9], 0, v[2:3]
	v_lshl_add_u64 v[2:3], v[2:3], 0, s[50:51]
	s_or_b64 s[10:11], vcc, s[10:11]
	s_waitcnt vmcnt(0)
	global_store_dword v[8:9], v7, off sc1
	s_andn2_b64 exec, exec, s[10:11]
	s_cbranch_execnz .LBB0_178
	s_or_b64 exec, exec, s[10:11]
	s_add_u32 s8, s86, 0x15000
	s_addc_u32 s9, s87, 0
	s_mov_b64 s[10:11], 0
	s_movk_i32 s3, 0x1ff
	v_mov_b32_e32 v2, v4
.LBB0_180:
	v_lshl_add_u64 v[6:7], s[16:17], 0, v[0:1]
	global_load_dword v3, v[6:7], off
	v_add_u32_e32 v2, s4, v2
	v_cmp_lt_i32_e32 vcc, s3, v2
	v_lshl_add_u64 v[6:7], s[8:9], 0, v[0:1]
	v_lshl_add_u64 v[0:1], v[0:1], 0, s[50:51]
	s_or_b64 s[10:11], vcc, s[10:11]
	s_waitcnt vmcnt(0)
	global_store_dword v[6:7], v3, off sc1
	s_andn2_b64 exec, exec, s[10:11]
	s_cbranch_execnz .LBB0_180

; __device__ __forceinline__ void p0_prologue(Frame& F, const Args& A) {
;     ...
;         for (int i = gt; i < 64; i += GT) PRMw[5632 + i] = A.in[21][i];
;         for (int i = gt; i < 64; i += GT) PRMw[5696 + i] = A.in[22][i];
;         for (int i = gt; i < 64; i += GT) PRMw[5760 + i] = A.in[23][i];
;         for (int i = gt; i < 64; i += GT) PRMw[5824 + i] = A.in[24][i];
.LBB0_183:
	v_lshl_add_u64 v[8:9], s[18:19], 0, v[2:3]
	global_load_dword v7, v[8:9], off
	v_add_u32_e32 v6, s4, v6
	v_cmp_lt_i32_e32 vcc, 63, v6
	v_lshl_add_u64 v[8:9], s[12:13], 0, v[2:3]
	v_lshl_add_u64 v[2:3], v[2:3], 0, s[10:11]
	s_or_b64 s[14:15], vcc, s[14:15]
	s_waitcnt vmcnt(0)
	global_store_dword v[8:9], v7, off sc1
	s_andn2_b64 exec, exec, s[14:15]
	s_cbranch_execnz .LBB0_183
	s_or_b64 exec, exec, s[14:15]
	s_add_u32 s12, s86, 0x15900
	s_addc_u32 s13, s87, 0
	s_mov_b64 s[14:15], 0
	v_mov_b64_e32 v[2:3], v[0:1]
	v_mov_b32_e32 v6, v4
.LBB0_185:
	v_lshl_add_u64 v[8:9], s[20:21], 0, v[2:3]
	global_load_dword v7, v[8:9], off
	v_add_u32_e32 v6, s4, v6
	v_cmp_lt_i32_e32 vcc, 63, v6
	v_lshl_add_u64 v[8:9], s[12:13], 0, v[2:3]
	v_lshl_add_u64 v[2:3], v[2:3], 0, s[10:11]
	s_or_b64 s[14:15], vcc, s[14:15]
	s_waitcnt vmcnt(0)
	global_store_dword v[8:9], v7, off sc1
	s_andn2_b64 exec, exec, s[14:15]
	s_cbranch_execnz .LBB0_185
	s_or_b64 exec, exec, s[14:15]
	s_add_u32 s12, s86, 0x15a00
	s_addc_u32 s13, s87, 0
	s_mov_b64 s[14:15], 0
	v_mov_b64_e32 v[2:3], v[0:1]
	v_mov_b32_e32 v6, v4
.LBB0_187:
	v_lshl_add_u64 v[8:9], s[22:23], 0, v[2:3]
	global_load_dword v7, v[8:9], off
	v_add_u32_e32 v6, s4, v6
	v_cmp_lt_i32_e32 vcc, 63, v6
	v_lshl_add_u64 v[8:9], s[12:13], 0, v[2:3]
	v_lshl_add_u64 v[2:3], v[2:3], 0, s[10:11]
	s_or_b64 s[14:15], vcc, s[14:15]
	s_waitcnt vmcnt(0)
	global_store_dword v[8:9], v7, off sc1
	s_andn2_b64 exec, exec, s[14:15]
	s_cbranch_execnz .LBB0_187
	s_or_b64 exec, exec, s[14:15]
	s_add_u32 s12, s86, 0x15b00
	s_addc_u32 s13, s87, 0
	s_mov_b64 s[14:15], 0
	v_mov_b32_e32 v2, v4
.LBB0_189:
	v_lshl_add_u64 v[6:7], s[24:25], 0, v[0:1]
	global_load_dword v3, v[6:7], off
	v_add_u32_e32 v2, s4, v2
	v_cmp_lt_i32_e32 vcc, 63, v2
	v_lshl_add_u64 v[6:7], s[12:13], 0, v[0:1]
	v_lshl_add_u64 v[0:1], v[0:1], 0, s[10:11]
	s_or_b64 s[14:15], vcc, s[14:15]
	s_waitcnt vmcnt(0)
	global_store_dword v[6:7], v3, off sc1
	s_andn2_b64 exec, exec, s[14:15]
	s_cbranch_execnz .LBB0_189

; __device__ __forceinline__ void p0_prologue(Frame& F, const Args& A) {
;     ...
;         for (int i = gt; i < 128; i += GT) PRMw[5888 + i] = A.in[25][i];
.LBB0_192:
	v_lshl_add_u64 v[6:7], s[26:27], 0, v[0:1]
	global_load_dword v3, v[6:7], off
	v_add_u32_e32 v2, s4, v2
	v_cmp_lt_i32_e32 vcc, s3, v2
	v_lshl_add_u64 v[6:7], s[12:13], 0, v[0:1]
	v_lshl_add_u64 v[0:1], v[0:1], 0, s[10:11]
	s_or_b64 s[14:15], vcc, s[14:15]
	s_waitcnt vmcnt(0)
	global_store_dword v[6:7], v3, off sc1
	s_andn2_b64 exec, exec, s[14:15]
	s_cbranch_execnz .LBB0_192

; __device__ __forceinline__ void p0_prologue(Frame& F, const Args& A) {
;     ...
;         for (int i = gt; i < 1024; i += GT) PRMw[6144 + i] = A.in[2][i];
;         for (int i = gt; i < 1024; i += GT) PRMw[7168 + i] = A.in[6][i];
;         for (int i = gt; i < 1024; i += GT) PRMw[8192 + i] = A.in[7][i];
;         for (int i = gt; i < 1024; i += GT) PRMw[9216 + i] = A.in[26][i];
;         for (int i = gt; i < 1024; i += GT) PRMw[10240 + i] = A.in[27][i];
.LBB0_195:
	v_lshl_add_u64 v[6:7], s[34:35], 0, v[2:3]
	global_load_dword v8, v[6:7], off
	v_add_u32_e32 v5, s4, v5
	v_cmp_lt_i32_e32 vcc, s3, v5
	v_lshl_add_u64 v[6:7], s[12:13], 0, v[2:3]
	v_lshl_add_u64 v[2:3], v[2:3], 0, s[10:11]
	s_or_b64 s[14:15], vcc, s[14:15]
	s_waitcnt vmcnt(0)
	global_store_dword v[6:7], v8, off sc1
	s_andn2_b64 exec, exec, s[14:15]
	s_cbranch_execnz .LBB0_195
	s_or_b64 exec, exec, s[14:15]
	s_add_u32 s12, s86, 0x17000
	s_addc_u32 s13, s87, 0
	s_mov_b64 s[14:15], 0
	s_movk_i32 s3, 0x3ff
	v_mov_b64_e32 v[2:3], v[0:1]
	v_mov_b32_e32 v5, v4
.LBB0_197:
	v_lshl_add_u64 v[6:7], s[40:41], 0, v[2:3]
	global_load_dword v8, v[6:7], off
	v_add_u32_e32 v5, s4, v5
	v_cmp_lt_i32_e32 vcc, s3, v5
	v_lshl_add_u64 v[6:7], s[12:13], 0, v[2:3]
	v_lshl_add_u64 v[2:3], v[2:3], 0, s[10:11]
	s_or_b64 s[14:15], vcc, s[14:15]
	s_waitcnt vmcnt(0)
	global_store_dword v[6:7], v8, off sc1
	s_andn2_b64 exec, exec, s[14:15]
	s_cbranch_execnz .LBB0_197
	s_or_b64 exec, exec, s[14:15]
	s_add_u32 s12, s86, 0x18000
	s_addc_u32 s13, s87, 0
	s_mov_b64 s[14:15], 0
	s_movk_i32 s3, 0x3ff
	v_mov_b64_e32 v[2:3], v[0:1]
	v_mov_b32_e32 v5, v4
.LBB0_199:
	v_lshl_add_u64 v[6:7], s[42:43], 0, v[2:3]
	global_load_dword v8, v[6:7], off
	v_add_u32_e32 v5, s4, v5
	v_cmp_lt_i32_e32 vcc, s3, v5
	v_lshl_add_u64 v[6:7], s[12:13], 0, v[2:3]
	v_lshl_add_u64 v[2:3], v[2:3], 0, s[10:11]
	s_or_b64 s[14:15], vcc, s[14:15]
	s_waitcnt vmcnt(0)
	global_store_dword v[6:7], v8, off sc1
	s_andn2_b64 exec, exec, s[14:15]
	s_cbranch_execnz .LBB0_199
	s_or_b64 exec, exec, s[14:15]
	s_add_u32 s12, s86, 0x19000
	s_addc_u32 s13, s87, 0
	s_mov_b64 s[14:15], 0
	s_movk_i32 s3, 0x3ff
	v_mov_b64_e32 v[2:3], v[0:1]
	v_mov_b32_e32 v5, v4
.LBB0_201:
	v_lshl_add_u64 v[6:7], s[28:29], 0, v[2:3]
	global_load_dword v8, v[6:7], off
	v_add_u32_e32 v5, s4, v5
	v_cmp_lt_i32_e32 vcc, s3, v5
	v_lshl_add_u64 v[6:7], s[12:13], 0, v[2:3]
	v_lshl_add_u64 v[2:3], v[2:3], 0, s[10:11]
	s_or_b64 s[14:15], vcc, s[14:15]
	s_waitcnt vmcnt(0)
	global_store_dword v[6:7], v8, off sc1
	s_andn2_b64 exec, exec, s[14:15]
	s_cbranch_execnz .LBB0_201
	s_or_b64 exec, exec, s[14:15]
	s_add_u32 s12, s86, 0x1a000
	s_addc_u32 s13, s87, 0
	s_mov_b64 s[14:15], 0
	s_movk_i32 s3, 0x3ff
.LBB0_203:
	v_lshl_add_u64 v[2:3], s[30:31], 0, v[0:1]
	global_load_dword v5, v[2:3], off
	v_add_u32_e32 v4, s4, v4
	v_cmp_lt_i32_e32 vcc, s3, v4
	v_lshl_add_u64 v[2:3], s[12:13], 0, v[0:1]
	v_lshl_add_u64 v[0:1], v[0:1], 0, s[10:11]
	s_or_b64 s[14:15], vcc, s[14:15]
	s_waitcnt vmcnt(0)
	global_store_dword v[2:3], v5, off sc1
	s_andn2_b64 exec, exec, s[14:15]
	s_cbranch_execnz .LBB0_203

; __device__ __forceinline__ unsigned pk2(float lo, float hi) { f32x2_k v = {lo, hi}; bf16x2_k b = __builtin_convertvector(v, bf16x2_k); return __builtin_bit_cast(unsigned, b); }
; template <int MODE> __device__ __forceinline__ void norm_rows(Frame& F, const float* xin, const float* y, const float* g1, float coef, float* xo, const float* g2, bf16* xn) {
;     ...
;     for (int m = gw; m < M; m += NGW) {
;         f32x4 v[4];
; #pragma unroll
;         for (int j = 0; j < 4; ++j) v[j] = (MODE == 0) ? __builtin_nontemporal_load((const f32x4*)(xin + (size_t)m * D) + F.lane + 64 * j) : ((const f32x4*)(xin + (size_t)m * D))[F.lane + 64 * j];
;         if (MODE != 0) {
;             f32x4 yy[4]; float s = 0.f;
; #pragma unroll
;             for (int j = 0; j < 4; ++j) { yy[j] = ((const f32x4*)(y + (size_t)m * D))[F.lane + 64 * j]; s += (yy[j].x * yy[j].x + yy[j].y * yy[j].y) + (yy[j].z * yy[j].z + yy[j].w * yy[j].w); }
;             const float rs = coef * __builtin_amdgcn_rsqf(wave_sum(s) * (1.f / D) + NORM_EPS);
; #pragma unroll
;             for (int j = 0; j < 4; ++j) { v[j] = v[j] + yy[j] * gg1[j] * rs; ((f32x4*)(xo + (size_t)m * D))[F.lane + 64 * j] = v[j]; }
;         }
;         if (MODE != 2) {
;             float s = 0.f;
; #pragma unroll
;             for (int j = 0; j < 4; ++j) s += (v[j].x * v[j].x + v[j].y * v[j].y) + (v[j].z * v[j].z + v[j].w * v[j].w);
;             const float rs = __builtin_amdgcn_rsqf(wave_sum(s) * (1.f / D) + NORM_EPS);
;             unsigned long long* o8 = (unsigned long long*)(xn + (size_t)m * D) + F.lane;
; #pragma unroll
;             for (int j = 0; j < 4; ++j) { const f32x4 o = v[j] * gg2[j] * rs; o8[64 * j] = (unsigned long long)pk2(o.x, o.y) | ((unsigned long long)pk2(o.z, o.w) << 32); }
;         }
.LBB0_206:
	global_load_dwordx4 v[22:25], v[18:19], off offset:-3072 nt
	global_load_dwordx4 v[26:29], v[18:19], off offset:-2048 nt
	global_load_dwordx4 v[30:33], v[18:19], off offset:-1024 nt
	global_load_dwordx4 v[34:37], v[18:19], off nt
	s_add_i32 s2, s2, s6
	v_lshl_add_u64 v[18:19], v[18:19], 0, s[8:9]
	s_cmpk_gt_i32 s2, 0x3fff
	s_waitcnt vmcnt(3)
	v_mul_f32_e32 v21, v23, v23
	v_mul_f32_e32 v54, v25, v25
	s_waitcnt vmcnt(2)
	v_mul_f32_e32 v55, v27, v27
	v_mul_f32_e32 v56, v29, v29
	s_waitcnt vmcnt(1)
	v_mul_f32_e32 v57, v31, v31
	v_mul_f32_e32 v58, v33, v33
	v_fmac_f32_e32 v21, v22, v22
	v_fmac_f32_e32 v54, v24, v24
	v_fmac_f32_e32 v55, v26, v26
	v_fmac_f32_e32 v56, v28, v28
	s_waitcnt vmcnt(0)
	v_mul_f32_e32 v59, v35, v35
	v_mul_f32_e32 v60, v37, v37
	v_pk_mul_f32 v[40:41], v[0:1], v[22:23]
	v_fmac_f32_e32 v57, v30, v30
	v_fmac_f32_e32 v58, v32, v32
	v_add_f32_e32 v21, v21, v54
	v_add_f32_e32 v22, v55, v56
	v_fmac_f32_e32 v59, v34, v34
	v_fmac_f32_e32 v60, v36, v36
	v_add_f32_e32 v23, v57, v58
	v_add_f32_e32 v21, v21, v22
	v_pk_mul_f32 v[38:39], v[2:3], v[24:25]
	v_add_f32_e32 v24, v59, v60
	v_add_f32_e32 v21, v21, v23
	v_add_f32_e32 v21, v21, v24
	v_pk_mul_f32 v[42:43], v[6:7], v[28:29]
	v_pk_mul_f32 v[44:45], v[4:5], v[26:27]
	v_add_f32_dpp v21, v21, v21 quad_perm:[1,0,3,2] row_mask:0xf bank_mask:0xf bound_ctrl:1
	v_pk_mul_f32 v[46:47], v[10:11], v[32:33]
	v_pk_mul_f32 v[48:49], v[8:9], v[30:31]
	v_add_f32_dpp v21, v21, v21 quad_perm:[2,3,0,1] row_mask:0xf bank_mask:0xf bound_ctrl:1
	v_pk_mul_f32 v[50:51], v[14:15], v[36:37]
	v_pk_mul_f32 v[52:53], v[12:13], v[34:35]
	v_add_f32_dpp v21, v21, v21 row_half_mirror row_mask:0xf bank_mask:0xf bound_ctrl:1
	s_nop 1
	v_add_f32_dpp v21, v21, v21 row_mirror row_mask:0xf bank_mask:0xf bound_ctrl:1
	v_mov_b32_e32 v22, v21
	s_nop 1
	v_permlane16_swap_b32_e32 v21, v22
	v_add_f32_e32 v21, v21, v22
	v_mov_b32_e32 v22, v21
	s_nop 1
	v_permlane32_swap_b32_e32 v21, v22
	v_add_f32_e32 v21, v21, v22
	v_fmamk_f32 v21, v21, 0x3a800000, v20
	v_rsq_f32_e32 v22, v21
	s_nop 0
	v_pk_mul_f32 v[24:25], v[38:39], v[22:23] op_sel_hi:[1,0]
	v_pk_mul_f32 v[26:27], v[40:41], v[22:23] op_sel_hi:[1,0]
	v_pk_mul_f32 v[28:29], v[42:43], v[22:23] op_sel_hi:[1,0]
	v_pk_mul_f32 v[30:31], v[44:45], v[22:23] op_sel_hi:[1,0]
	v_pk_mul_f32 v[32:33], v[46:47], v[22:23] op_sel_hi:[1,0]
	v_pk_mul_f32 v[34:35], v[48:49], v[22:23] op_sel_hi:[1,0]
	v_pk_mul_f32 v[36:37], v[50:51], v[22:23] op_sel_hi:[1,0]
	v_pk_mul_f32 v[22:23], v[52:53], v[22:23] op_sel_hi:[1,0]
	v_cvt_pk_bf16_f32 v26, v26, v27
	v_cvt_pk_bf16_f32 v27, v24, v25
	v_cvt_pk_bf16_f32 v24, v30, v31
	v_cvt_pk_bf16_f32 v25, v28, v29
	v_cvt_pk_bf16_f32 v28, v34, v35
	v_cvt_pk_bf16_f32 v29, v32, v33
	v_cvt_pk_bf16_f32 v22, v22, v23
	v_cvt_pk_bf16_f32 v23, v36, v37
	global_store_dwordx2 v[16:17], v[26:27], off sc1
	global_store_dwordx2 v[16:17], v[24:25], off offset:512 sc1
	global_store_dwordx2 v[16:17], v[28:29], off offset:1024 sc1
	global_store_dwordx2 v[16:17], v[22:23], off offset:1536 sc1
	v_lshl_add_u64 v[16:17], v[16:17], 0, s[4:5]
	s_cbranch_scc0 .LBB0_206

; __device__ __forceinline__ unsigned cvt_pk_bf16(float lo, float hi) { unsigned r; asm volatile("v_cvt_pk_bf16_f32 %0, %1, %2" : "=v"(r) : "v"(lo), "v"(hi)); return r; }
; __device__ __forceinline__ f32x2p silu_mul2(f32x2p g, f32x2p u) {
;     const f32x2p t = g * (-1.4426950408889634f); f32x2p e; e.x = __builtin_amdgcn_exp2f(t.x); e.y = __builtin_amdgcn_exp2f(t.y);
;     const f32x2p d = e + 1.0f; f32x2p r; r.x = __builtin_amdgcn_rcpf(d.x); r.y = __builtin_amdgcn_rcpf(d.y);
;     return (g * u) * r;
; }
;     __device__ __forceinline__ void operator()(const f32x4 (&acc)[2][2][4][2], const Unit& u, int wr, int wc, int fr, int fq) const {
;         const int row0 = u.pm * BM + wr * 64 + fr, col0 = u.pn * HALF + wc * 32 + 8 * fq;
; #pragma unroll
;         for (int ai = 0; ai < 2; ++ai)
; #pragma unroll
;             for (int m = 0; m < 4; ++m) { bf16_t* rowp = O + (size_t)(row0 + ai * HALF + m * 16) * ldc + col0;
;                 const f32x4 g0 = acc[ai][0][m][0], g1 = acc[ai][0][m][1], u0 = acc[ai][1][m][0], u1 = acc[ai][1][m][1];
;                 const f32x2p a = silu_mul2((f32x2p){g0[0], g0[1]}, (f32x2p){u0[0], u0[1]}), b = silu_mul2((f32x2p){g0[2], g0[3]}, (f32x2p){u0[2], u0[3]});
;                 const f32x2p c = silu_mul2((f32x2p){g1[0], g1[1]}, (f32x2p){u1[0], u1[1]}), d = silu_mul2((f32x2p){g1[2], g1[3]}, (f32x2p){u1[2], u1[3]});
;                 u32x4 w; w.x = cvt_pk_bf16(a.x, a.y); w.y = cvt_pk_bf16(b.x, b.y); w.z = cvt_pk_bf16(c.x, c.y); w.w = cvt_pk_bf16(d.x, d.y);
;                 *(u32x4*)rowp = w; }
.LBB0_272:
	v_pk_mul_f32 v[158:159], v[124:125], s[8:9] op_sel_hi:[1,0]
	v_pk_mul_f32 v[160:161], v[126:127], s[8:9] op_sel_hi:[1,0]
	v_pk_mul_f32 v[122:123], v[126:127], v[122:123]
	v_pk_mul_f32 v[120:121], v[124:125], v[120:121]
	v_pk_mul_f32 v[124:125], v[116:117], s[8:9] op_sel_hi:[1,0]
	v_pk_mul_f32 v[126:127], v[118:119], s[8:9] op_sel_hi:[1,0]
	v_exp_f32_e32 v158, v158
	v_exp_f32_e32 v159, v159
	v_exp_f32_e32 v160, v160
	v_exp_f32_e32 v161, v161
	v_exp_f32_e32 v124, v124
	v_exp_f32_e32 v125, v125
	v_exp_f32_e32 v126, v126
	v_exp_f32_e32 v127, v127
	v_pk_add_f32 v[158:159], v[158:159], 1.0 op_sel_hi:[1,0]
	v_pk_add_f32 v[160:161], v[160:161], 1.0 op_sel_hi:[1,0]
	v_pk_add_f32 v[124:125], v[124:125], 1.0 op_sel_hi:[1,0]
	v_pk_add_f32 v[126:127], v[126:127], 1.0 op_sel_hi:[1,0]
	v_readlane_b32 s22, v254, 15
	v_rcp_f32_e32 v158, v158
	v_rcp_f32_e32 v159, v159
	v_rcp_f32_e32 v160, v160
	v_rcp_f32_e32 v161, v161
	v_rcp_f32_e32 v124, v124
	v_rcp_f32_e32 v125, v125
	v_rcp_f32_e32 v126, v126
	v_rcp_f32_e32 v127, v127
	v_lshl_add_u32 v146, s43, 7, v150
	v_readlane_b32 s23, v254, 16
	v_lshl_add_u32 v154, s20, 8, v148
	v_ashrrev_i32_e32 v147, 31, v146
	v_mov_b64_e32 v[144:145], s[22:23]
	v_mad_i64_i32 v[156:157], s[22:23], v154, s42, v[144:145]
	v_lshlrev_b64 v[146:147], 1, v[146:147]
	v_pk_mul_f32 v[114:115], v[118:119], v[114:115]
	v_pk_mul_f32 v[112:113], v[116:117], v[112:113]
	v_lshl_add_u64 v[156:157], v[156:157], 0, v[146:147]
	v_pk_mul_f32 v[120:121], v[158:159], v[120:121]
	v_pk_mul_f32 v[122:123], v[160:161], v[122:123]
	v_pk_mul_f32 v[116:117], v[124:125], v[112:113]
	v_pk_mul_f32 v[118:119], v[126:127], v[114:115]
	v_cvt_pk_bf16_f32 v112, v120, v121
	v_cvt_pk_bf16_f32 v113, v122, v123
	v_cvt_pk_bf16_f32 v114, v116, v117
	v_pk_mul_f32 v[116:117], v[110:111], s[8:9] op_sel_hi:[1,0]
	v_cvt_pk_bf16_f32 v115, v118, v119
	global_store_dwordx4 v[156:157], v[112:115], off sc1
	v_pk_mul_f32 v[106:107], v[110:111], v[106:107]
	v_pk_mul_f32 v[104:105], v[108:109], v[104:105]
	v_pk_mul_f32 v[114:115], v[108:109], s[8:9] op_sel_hi:[1,0]
	v_pk_mul_f32 v[108:109], v[100:101], s[8:9] op_sel_hi:[1,0]
	v_pk_mul_f32 v[110:111], v[102:103], s[8:9] op_sel_hi:[1,0]
	v_exp_f32_e32 v114, v114
	v_exp_f32_e32 v115, v115
	v_exp_f32_e32 v116, v116
	v_exp_f32_e32 v117, v117
	v_exp_f32_e32 v108, v108
	v_exp_f32_e32 v109, v109
	v_exp_f32_e32 v110, v110
	v_exp_f32_e32 v111, v111
	v_pk_add_f32 v[114:115], v[114:115], 1.0 op_sel_hi:[1,0]
	v_pk_add_f32 v[116:117], v[116:117], 1.0 op_sel_hi:[1,0]
	v_pk_add_f32 v[108:109], v[108:109], 1.0 op_sel_hi:[1,0]
	v_pk_add_f32 v[110:111], v[110:111], 1.0 op_sel_hi:[1,0]
	v_rcp_f32_e32 v114, v114
	v_rcp_f32_e32 v115, v115
	v_rcp_f32_e32 v116, v116
	v_rcp_f32_e32 v117, v117
	v_rcp_f32_e32 v108, v108
	v_rcp_f32_e32 v109, v109
	v_rcp_f32_e32 v110, v110
	v_rcp_f32_e32 v111, v111
	v_or_b32_e32 v112, 16, v154
	v_mad_i64_i32 v[112:113], s[22:23], v112, s42, v[144:145]
	v_pk_mul_f32 v[98:99], v[102:103], v[98:99]
	v_pk_mul_f32 v[96:97], v[100:101], v[96:97]
	v_lshl_add_u64 v[112:113], v[112:113], 0, v[146:147]
	v_pk_mul_f32 v[104:105], v[114:115], v[104:105]
	v_pk_mul_f32 v[106:107], v[116:117], v[106:107]
	v_pk_mul_f32 v[100:101], v[108:109], v[96:97]
	v_pk_mul_f32 v[102:103], v[110:111], v[98:99]
	v_cvt_pk_bf16_f32 v96, v104, v105
	v_cvt_pk_bf16_f32 v97, v106, v107
	v_cvt_pk_bf16_f32 v98, v100, v101
	v_pk_mul_f32 v[100:101], v[94:95], s[8:9] op_sel_hi:[1,0]
	v_cvt_pk_bf16_f32 v99, v102, v103
	global_store_dwordx4 v[112:113], v[96:99], off sc1
	v_pk_mul_f32 v[90:91], v[94:95], v[90:91]
	v_pk_mul_f32 v[88:89], v[92:93], v[88:89]
	v_pk_mul_f32 v[98:99], v[92:93], s[8:9] op_sel_hi:[1,0]
	v_pk_mul_f32 v[92:93], v[84:85], s[8:9] op_sel_hi:[1,0]
	v_pk_mul_f32 v[94:95], v[86:87], s[8:9] op_sel_hi:[1,0]
	v_exp_f32_e32 v98, v98
	v_exp_f32_e32 v99, v99
	v_exp_f32_e32 v100, v100
	v_exp_f32_e32 v101, v101
	v_exp_f32_e32 v92, v92
	v_exp_f32_e32 v93, v93
	v_exp_f32_e32 v94, v94
	v_exp_f32_e32 v95, v95
	v_pk_add_f32 v[98:99], v[98:99], 1.0 op_sel_hi:[1,0]
	v_pk_add_f32 v[100:101], v[100:101], 1.0 op_sel_hi:[1,0]
	v_pk_add_f32 v[92:93], v[92:93], 1.0 op_sel_hi:[1,0]
	v_pk_add_f32 v[94:95], v[94:95], 1.0 op_sel_hi:[1,0]
	v_rcp_f32_e32 v98, v98
	v_rcp_f32_e32 v99, v99
	v_rcp_f32_e32 v100, v100
	v_rcp_f32_e32 v101, v101
	v_rcp_f32_e32 v92, v92
	v_rcp_f32_e32 v93, v93
	v_rcp_f32_e32 v94, v94
	v_rcp_f32_e32 v95, v95
	v_or_b32_e32 v96, 32, v154
	v_mad_i64_i32 v[96:97], s[22:23], v96, s42, v[144:145]
	v_pk_mul_f32 v[82:83], v[86:87], v[82:83]
	v_pk_mul_f32 v[80:81], v[84:85], v[80:81]
	v_lshl_add_u64 v[96:97], v[96:97], 0, v[146:147]
	v_pk_mul_f32 v[88:89], v[98:99], v[88:89]
	v_pk_mul_f32 v[90:91], v[100:101], v[90:91]
	v_pk_mul_f32 v[84:85], v[92:93], v[80:81]
	v_pk_mul_f32 v[86:87], v[94:95], v[82:83]
	v_cvt_pk_bf16_f32 v80, v88, v89
	v_cvt_pk_bf16_f32 v81, v90, v91
	v_cvt_pk_bf16_f32 v82, v84, v85
	v_pk_mul_f32 v[84:85], v[78:79], s[8:9] op_sel_hi:[1,0]
	v_cvt_pk_bf16_f32 v83, v86, v87
	global_store_dwordx4 v[96:97], v[80:83], off sc1
	v_pk_mul_f32 v[74:75], v[78:79], v[74:75]
	v_pk_mul_f32 v[72:73], v[76:77], v[72:73]
	v_pk_mul_f32 v[82:83], v[76:77], s[8:9] op_sel_hi:[1,0]
	v_pk_mul_f32 v[76:77], v[68:69], s[8:9] op_sel_hi:[1,0]
	v_pk_mul_f32 v[78:79], v[70:71], s[8:9] op_sel_hi:[1,0]
	v_exp_f32_e32 v82, v82
	v_exp_f32_e32 v83, v83
	v_exp_f32_e32 v84, v84
	v_exp_f32_e32 v85, v85
	v_exp_f32_e32 v76, v76
	v_exp_f32_e32 v77, v77
	v_exp_f32_e32 v78, v78
	v_exp_f32_e32 v79, v79
	v_pk_add_f32 v[82:83], v[82:83], 1.0 op_sel_hi:[1,0]
	v_pk_add_f32 v[84:85], v[84:85], 1.0 op_sel_hi:[1,0]
	v_pk_add_f32 v[76:77], v[76:77], 1.0 op_sel_hi:[1,0]
; __device__ __forceinline__ unsigned cvt_pk_bf16(float lo, float hi) { unsigned r; asm volatile("v_cvt_pk_bf16_f32 %0, %1, %2" : "=v"(r) : "v"(lo), "v"(hi)); return r; }
; __device__ __forceinline__ f32x2p silu_mul2(f32x2p g, f32x2p u) {
;     const f32x2p t = g * (-1.4426950408889634f); f32x2p e; e.x = __builtin_amdgcn_exp2f(t.x); e.y = __builtin_amdgcn_exp2f(t.y);
;     const f32x2p d = e + 1.0f; f32x2p r; r.x = __builtin_amdgcn_rcpf(d.x); r.y = __builtin_amdgcn_rcpf(d.y);
;     return (g * u) * r;
; }
;     __device__ __forceinline__ void operator()(const f32x4 (&acc)[2][2][4][2], const Unit& u, int wr, int wc, int fr, int fq) const {
;         const int row0 = u.pm * BM + wr * 64 + fr, col0 = u.pn * HALF + wc * 32 + 8 * fq;
; #pragma unroll
;         for (int ai = 0; ai < 2; ++ai)
; #pragma unroll
;             for (int m = 0; m < 4; ++m) { bf16_t* rowp = O + (size_t)(row0 + ai * HALF + m * 16) * ldc + col0;
;                 const f32x4 g0 = acc[ai][0][m][0], g1 = acc[ai][0][m][1], u0 = acc[ai][1][m][0], u1 = acc[ai][1][m][1];
;                 const f32x2p a = silu_mul2((f32x2p){g0[0], g0[1]}, (f32x2p){u0[0], u0[1]}), b = silu_mul2((f32x2p){g0[2], g0[3]}, (f32x2p){u0[2], u0[3]});
;                 const f32x2p c = silu_mul2((f32x2p){g1[0], g1[1]}, (f32x2p){u1[0], u1[1]}), d = silu_mul2((f32x2p){g1[2], g1[3]}, (f32x2p){u1[2], u1[3]});
;                 u32x4 w; w.x = cvt_pk_bf16(a.x, a.y); w.y = cvt_pk_bf16(b.x, b.y); w.z = cvt_pk_bf16(c.x, c.y); w.w = cvt_pk_bf16(d.x, d.y);
;                 *(u32x4*)rowp = w; }
	v_pk_add_f32 v[78:79], v[78:79], 1.0 op_sel_hi:[1,0]
	v_rcp_f32_e32 v82, v82
	v_rcp_f32_e32 v83, v83
	v_rcp_f32_e32 v84, v84
	v_rcp_f32_e32 v85, v85
	v_rcp_f32_e32 v76, v76
	v_rcp_f32_e32 v77, v77
	v_rcp_f32_e32 v78, v78
	v_rcp_f32_e32 v79, v79
	v_or_b32_e32 v80, 48, v154
	v_mad_i64_i32 v[80:81], s[22:23], v80, s42, v[144:145]
	v_pk_mul_f32 v[66:67], v[70:71], v[66:67]
	v_pk_mul_f32 v[64:65], v[68:69], v[64:65]
	v_lshl_add_u64 v[80:81], v[80:81], 0, v[146:147]
	v_pk_mul_f32 v[72:73], v[82:83], v[72:73]
	v_pk_mul_f32 v[74:75], v[84:85], v[74:75]
	v_pk_mul_f32 v[68:69], v[76:77], v[64:65]
	v_pk_mul_f32 v[70:71], v[78:79], v[66:67]
	v_cvt_pk_bf16_f32 v64, v72, v73
	v_cvt_pk_bf16_f32 v65, v74, v75
	v_cvt_pk_bf16_f32 v66, v68, v69
	v_pk_mul_f32 v[68:69], v[62:63], s[8:9] op_sel_hi:[1,0]
	v_cvt_pk_bf16_f32 v67, v70, v71
	global_store_dwordx4 v[80:81], v[64:67], off sc1
	v_pk_mul_f32 v[58:59], v[62:63], v[58:59]
	v_pk_mul_f32 v[56:57], v[60:61], v[56:57]
	v_pk_mul_f32 v[66:67], v[60:61], s[8:9] op_sel_hi:[1,0]
	v_pk_mul_f32 v[60:61], v[52:53], s[8:9] op_sel_hi:[1,0]
	v_pk_mul_f32 v[62:63], v[54:55], s[8:9] op_sel_hi:[1,0]
	v_exp_f32_e32 v66, v66
	v_exp_f32_e32 v67, v67
	v_exp_f32_e32 v68, v68
	v_exp_f32_e32 v69, v69
	v_exp_f32_e32 v60, v60
	v_exp_f32_e32 v61, v61
	v_exp_f32_e32 v62, v62
	v_exp_f32_e32 v63, v63
	v_pk_add_f32 v[66:67], v[66:67], 1.0 op_sel_hi:[1,0]
	v_pk_add_f32 v[68:69], v[68:69], 1.0 op_sel_hi:[1,0]
	v_pk_add_f32 v[60:61], v[60:61], 1.0 op_sel_hi:[1,0]
	v_pk_add_f32 v[62:63], v[62:63], 1.0 op_sel_hi:[1,0]
	v_rcp_f32_e32 v66, v66
	v_rcp_f32_e32 v67, v67
	v_rcp_f32_e32 v68, v68
	v_rcp_f32_e32 v69, v69
	v_rcp_f32_e32 v60, v60
	v_rcp_f32_e32 v61, v61
	v_rcp_f32_e32 v62, v62
	v_rcp_f32_e32 v63, v63
	v_add_u32_e32 v64, 0x80, v154
	v_mad_i64_i32 v[64:65], s[22:23], v64, s42, v[144:145]
	v_pk_mul_f32 v[50:51], v[54:55], v[50:51]
	v_pk_mul_f32 v[48:49], v[52:53], v[48:49]
	v_lshl_add_u64 v[64:65], v[64:65], 0, v[146:147]
	v_pk_mul_f32 v[56:57], v[66:67], v[56:57]
	v_pk_mul_f32 v[58:59], v[68:69], v[58:59]
	v_pk_mul_f32 v[52:53], v[60:61], v[48:49]
	v_pk_mul_f32 v[54:55], v[62:63], v[50:51]
	v_cvt_pk_bf16_f32 v48, v56, v57
	v_cvt_pk_bf16_f32 v49, v58, v59
	v_cvt_pk_bf16_f32 v50, v52, v53
	v_pk_mul_f32 v[52:53], v[46:47], s[8:9] op_sel_hi:[1,0]
	v_cvt_pk_bf16_f32 v51, v54, v55
	global_store_dwordx4 v[64:65], v[48:51], off sc1
	v_pk_mul_f32 v[42:43], v[46:47], v[42:43]
	v_pk_mul_f32 v[40:41], v[44:45], v[40:41]
	v_pk_mul_f32 v[50:51], v[44:45], s[8:9] op_sel_hi:[1,0]
	v_pk_mul_f32 v[44:45], v[36:37], s[8:9] op_sel_hi:[1,0]
	v_pk_mul_f32 v[46:47], v[38:39], s[8:9] op_sel_hi:[1,0]
	v_exp_f32_e32 v50, v50
	v_exp_f32_e32 v51, v51
	v_exp_f32_e32 v52, v52
	v_exp_f32_e32 v53, v53
	v_exp_f32_e32 v44, v44
	v_exp_f32_e32 v45, v45
	v_exp_f32_e32 v46, v46
	v_exp_f32_e32 v47, v47
	v_pk_add_f32 v[50:51], v[50:51], 1.0 op_sel_hi:[1,0]
	v_pk_add_f32 v[52:53], v[52:53], 1.0 op_sel_hi:[1,0]
	v_pk_add_f32 v[44:45], v[44:45], 1.0 op_sel_hi:[1,0]
	v_pk_add_f32 v[46:47], v[46:47], 1.0 op_sel_hi:[1,0]
	v_rcp_f32_e32 v50, v50
	v_rcp_f32_e32 v51, v51
	v_rcp_f32_e32 v52, v52
	v_rcp_f32_e32 v53, v53
	v_rcp_f32_e32 v44, v44
	v_rcp_f32_e32 v45, v45
	v_rcp_f32_e32 v46, v46
	v_rcp_f32_e32 v47, v47
	v_add_u32_e32 v48, 0x90, v154
	v_mad_i64_i32 v[48:49], s[22:23], v48, s42, v[144:145]
	v_pk_mul_f32 v[34:35], v[38:39], v[34:35]
	v_pk_mul_f32 v[32:33], v[36:37], v[32:33]
	v_lshl_add_u64 v[48:49], v[48:49], 0, v[146:147]
	v_pk_mul_f32 v[40:41], v[50:51], v[40:41]
	v_pk_mul_f32 v[42:43], v[52:53], v[42:43]
	v_pk_mul_f32 v[36:37], v[44:45], v[32:33]
	v_pk_mul_f32 v[38:39], v[46:47], v[34:35]
	v_cvt_pk_bf16_f32 v32, v40, v41
	v_cvt_pk_bf16_f32 v33, v42, v43
	v_cvt_pk_bf16_f32 v34, v36, v37
	v_pk_mul_f32 v[36:37], v[30:31], s[8:9] op_sel_hi:[1,0]
	v_cvt_pk_bf16_f32 v35, v38, v39
	global_store_dwordx4 v[48:49], v[32:35], off sc1
	v_pk_mul_f32 v[26:27], v[30:31], v[26:27]
	v_pk_mul_f32 v[24:25], v[28:29], v[24:25]
	v_pk_mul_f32 v[34:35], v[28:29], s[8:9] op_sel_hi:[1,0]
	v_pk_mul_f32 v[28:29], v[20:21], s[8:9] op_sel_hi:[1,0]
	v_pk_mul_f32 v[30:31], v[22:23], s[8:9] op_sel_hi:[1,0]
	v_exp_f32_e32 v34, v34
	v_exp_f32_e32 v35, v35
	v_exp_f32_e32 v36, v36
	v_exp_f32_e32 v37, v37
	v_exp_f32_e32 v28, v28
	v_exp_f32_e32 v29, v29
	v_exp_f32_e32 v30, v30
	v_exp_f32_e32 v31, v31
	v_pk_add_f32 v[34:35], v[34:35], 1.0 op_sel_hi:[1,0]
	v_pk_add_f32 v[36:37], v[36:37], 1.0 op_sel_hi:[1,0]
	v_pk_add_f32 v[28:29], v[28:29], 1.0 op_sel_hi:[1,0]
	v_pk_add_f32 v[30:31], v[30:31], 1.0 op_sel_hi:[1,0]
	v_rcp_f32_e32 v34, v34
	v_rcp_f32_e32 v35, v35
	v_rcp_f32_e32 v36, v36
	v_rcp_f32_e32 v37, v37
	v_rcp_f32_e32 v28, v28
	v_rcp_f32_e32 v29, v29
	v_rcp_f32_e32 v30, v30
	v_rcp_f32_e32 v31, v31
	v_add_u32_e32 v32, 0xa0, v154
	v_mad_i64_i32 v[32:33], s[22:23], v32, s42, v[144:145]
	v_pk_mul_f32 v[18:19], v[22:23], v[18:19]
	v_pk_mul_f32 v[16:17], v[20:21], v[16:17]
	v_lshl_add_u64 v[32:33], v[32:33], 0, v[146:147]
	v_pk_mul_f32 v[24:25], v[34:35], v[24:25]
	v_pk_mul_f32 v[26:27], v[36:37], v[26:27]
	v_pk_mul_f32 v[20:21], v[28:29], v[16:17]
	v_pk_mul_f32 v[22:23], v[30:31], v[18:19]
	v_cvt_pk_bf16_f32 v16, v24, v25
	v_cvt_pk_bf16_f32 v17, v26, v27
	v_cvt_pk_bf16_f32 v18, v20, v21
	v_pk_mul_f32 v[20:21], v[14:15], s[8:9] op_sel_hi:[1,0]
	v_cvt_pk_bf16_f32 v19, v22, v23
	global_store_dwordx4 v[32:33], v[16:19], off sc1
	v_pk_mul_f32 v[10:11], v[14:15], v[10:11]
	v_pk_mul_f32 v[8:9], v[12:13], v[8:9]
	v_pk_mul_f32 v[18:19], v[12:13], s[8:9] op_sel_hi:[1,0]
	v_pk_mul_f32 v[12:13], v[4:5], s[8:9] op_sel_hi:[1,0]
	v_pk_mul_f32 v[14:15], v[6:7], s[8:9] op_sel_hi:[1,0]
	v_exp_f32_e32 v18, v18
	v_exp_f32_e32 v19, v19
	v_exp_f32_e32 v20, v20
	v_exp_f32_e32 v21, v21
	v_exp_f32_e32 v12, v12
	v_exp_f32_e32 v13, v13
	v_exp_f32_e32 v14, v14
	v_exp_f32_e32 v15, v15
	v_pk_add_f32 v[18:19], v[18:19], 1.0 op_sel_hi:[1,0]
	v_pk_add_f32 v[20:21], v[20:21], 1.0 op_sel_hi:[1,0]
	v_pk_add_f32 v[12:13], v[12:13], 1.0 op_sel_hi:[1,0]
	v_pk_add_f32 v[14:15], v[14:15], 1.0 op_sel_hi:[1,0]
	v_rcp_f32_e32 v18, v18
	v_rcp_f32_e32 v19, v19
	v_rcp_f32_e32 v20, v20
	v_rcp_f32_e32 v21, v21
	v_rcp_f32_e32 v12, v12
	v_rcp_f32_e32 v13, v13
	v_rcp_f32_e32 v14, v14
	v_rcp_f32_e32 v15, v15
	v_add_u32_e32 v16, 0xb0, v154
	v_mad_i64_i32 v[16:17], s[22:23], v16, s42, v[144:145]
	v_lshl_add_u64 v[16:17], v[16:17], 0, v[146:147]
	v_pk_mul_f32 v[2:3], v[6:7], v[2:3]
	v_pk_mul_f32 v[0:1], v[4:5], v[0:1]
	s_andn2_b64 vcc, exec, s[4:5]
	s_mov_b64 s[4:5], -1
	v_pk_mul_f32 v[8:9], v[18:19], v[8:9]
	v_pk_mul_f32 v[10:11], v[20:21], v[10:11]
	v_pk_mul_f32 v[4:5], v[12:13], v[0:1]
	v_pk_mul_f32 v[6:7], v[14:15], v[2:3]
	v_cvt_pk_bf16_f32 v0, v8, v9
	v_cvt_pk_bf16_f32 v1, v10, v11
	v_cvt_pk_bf16_f32 v2, v4, v5
	s_nop 0
	v_cvt_pk_bf16_f32 v3, v6, v7
	global_store_dwordx4 v[16:17], v[0:3], off sc1
	s_cbranch_vccnz .LBB0_265
	s_andn2_b64 vcc, exec, s[0:1]
	s_cbranch_vccnz .LBB0_264
	s_barrier
	s_branch .LBB0_264

; #define GAS __attribute__((address_space(1)))
; #define LAS __attribute__((address_space(3)))
; __device__ __forceinline__ unsigned pk2(float lo, float hi) { f32x2_k v = {lo, hi}; bf16x2_k b = __builtin_convertvector(v, bf16x2_k); return __builtin_bit_cast(unsigned, b); }
; __device__ __forceinline__ void p0_finish(const P0Job& j, const f32x4 (&v)[16], LAS float* scr, int lane) {
;     ...
;     for (int hb = 0; hb < 2; ++hb) { const int drow0 = p0_drow(j.kind, n0 + 32 * hb);
;         if (n0 + 32 * hb < j.N && k0 + 8 * c < j.K) {
; #pragma unroll
;             for (int jj = 0; jj < 4; ++jj) { const int n = (lane >> 3) + 8 * jj; const LAS float* sp = scr + (8 * c) * 65 + 32 * hb + n;
;                 v4u o; o.x = pk2(sp[0 * 65], sp[1 * 65]); o.y = pk2(sp[2 * 65], sp[3 * 65]); o.z = pk2(sp[4 * 65], sp[5 * 65]); o.w = pk2(sp[6 * 65], sp[7 * 65]);
;                 GAS v4u* dp = (GAS v4u*)(j.WT + (size_t)(drow0 + n) * j.ldk + k0 + 8 * c); if (j.late) __builtin_nontemporal_store(o, dp); else *dp = o; } } }
.LBB0_436:
	s_ashr_i32 s45, s44, 31
	v_or_b32_e32 v64, s44, v128
	s_cmp_lt_i32 s46, s69
	s_cselect_b64 s[48:49], -1, 0
	v_cmp_gt_i32_e64 s[8:9], s68, v64
	s_and_b64 s[58:59], s[48:49], s[8:9]
	v_add_u32_e32 v64, 0x400, v135
	s_and_saveexec_b64 s[48:49], s[58:59]
	s_cbranch_execz .LBB0_438
	v_add_u32_e32 v95, s56, v134
	ds_read2_b32 v[100:101], v135 offset0:65 offset1:73
	ds_read2_b32 v[102:103], v135 offset1:8
	ds_read2_b32 v[104:105], v135 offset0:130 offset1:138
	ds_read2_b32 v[106:107], v135 offset0:195 offset1:203
	ds_read2_b32 v[108:109], v64 offset0:4 offset1:12
	ds_read2_b32 v[110:111], v64 offset0:69 offset1:77
	ds_read2_b32 v[112:113], v64 offset0:134 offset1:142
	ds_read2_b32 v[114:115], v64 offset0:199 offset1:207
	v_mad_u64_u32 v[116:117], s[58:59], v95, s68, 0
	s_waitcnt lgkmcnt(6)
	v_cvt_pk_bf16_f32 v96, v102, v100
	v_ashrrev_i32_e32 v102, 31, v95
	v_mov_b32_e32 v100, v117
	v_mad_u64_u32 v[118:119], s[58:59], v102, s68, v[100:101]
	v_mov_b32_e32 v117, v118
	v_lshl_add_u64 v[116:117], v[116:117], 1, s[2:3]
	s_lshl_b64 s[58:59], s[44:45], 1
	v_lshl_add_u64 v[116:117], v[116:117], 0, s[58:59]
	v_lshlrev_b32_e32 v130, 1, v128
	s_waitcnt lgkmcnt(4)
	v_cvt_pk_bf16_f32 v97, v104, v106
	s_waitcnt lgkmcnt(2)
	v_cvt_pk_bf16_f32 v98, v108, v110
	s_waitcnt lgkmcnt(0)
	v_cvt_pk_bf16_f32 v99, v112, v114
	v_lshl_add_u64 v[116:117], v[116:117], 0, v[130:131]
	v_add_u32_e32 v95, s56, v136
	global_store_dwordx4 v[116:117], v[96:99], off sc1
	s_nop 1
	v_cvt_pk_bf16_f32 v96, v103, v101
	v_mad_u64_u32 v[100:101], s[72:73], v95, s68, 0
	v_ashrrev_i32_e32 v103, 31, v95
	v_mov_b32_e32 v102, v101
	v_mad_u64_u32 v[102:103], s[72:73], v103, s68, v[102:103]
	v_mov_b32_e32 v101, v102
	v_lshl_add_u64 v[100:101], v[100:101], 1, s[2:3]
	v_lshl_add_u64 v[100:101], v[100:101], 0, s[58:59]
	v_cvt_pk_bf16_f32 v97, v105, v107
	v_cvt_pk_bf16_f32 v98, v109, v111
	v_cvt_pk_bf16_f32 v99, v113, v115
	v_lshl_add_u64 v[100:101], v[100:101], 0, v[130:131]
	v_add_u32_e32 v95, s56, v137
	ds_read2_b32 v[102:103], v135 offset0:81 offset1:89
	ds_read2_b32 v[104:105], v135 offset0:16 offset1:24
	ds_read2_b32 v[106:107], v135 offset0:146 offset1:154
	ds_read2_b32 v[108:109], v135 offset0:211 offset1:219
	ds_read2_b32 v[110:111], v64 offset0:20 offset1:28
	ds_read2_b32 v[112:113], v64 offset0:85 offset1:93
	ds_read2_b32 v[114:115], v64 offset0:150 offset1:158
	ds_read2_b32 v[116:117], v64 offset0:215 offset1:223
	global_store_dwordx4 v[100:101], v[96:99], off sc1
	v_mad_u64_u32 v[100:101], s[72:73], v95, s68, 0
	s_waitcnt lgkmcnt(6)
	v_cvt_pk_bf16_f32 v96, v104, v102
	v_ashrrev_i32_e32 v104, 31, v95
	v_mov_b32_e32 v102, v101
	v_mad_u64_u32 v[118:119], s[72:73], v104, s68, v[102:103]
	v_mov_b32_e32 v101, v118
	v_lshl_add_u64 v[100:101], v[100:101], 1, s[2:3]
	v_lshl_add_u64 v[100:101], v[100:101], 0, s[58:59]
	s_waitcnt lgkmcnt(4)
	v_cvt_pk_bf16_f32 v97, v106, v108
	s_waitcnt lgkmcnt(2)
	v_cvt_pk_bf16_f32 v98, v110, v112
	s_waitcnt lgkmcnt(0)
	v_cvt_pk_bf16_f32 v99, v114, v116
	v_lshl_add_u64 v[100:101], v[100:101], 0, v[130:131]
	v_add_u32_e32 v95, s56, v138
	global_store_dwordx4 v[100:101], v[96:99], off sc1
	v_mad_u64_u32 v[100:101], s[56:57], v95, s68, 0
	s_nop 0
	v_cvt_pk_bf16_f32 v96, v105, v103
	v_ashrrev_i32_e32 v103, 31, v95
	v_mov_b32_e32 v102, v101
	v_mad_u64_u32 v[102:103], s[56:57], v103, s68, v[102:103]
	v_mov_b32_e32 v101, v102
	v_lshl_add_u64 v[100:101], v[100:101], 1, s[2:3]
	v_readlane_b32 s72, v254, 11
	v_lshl_add_u64 v[100:101], v[100:101], 0, s[58:59]
	v_readlane_b32 s73, v254, 12
	v_cvt_pk_bf16_f32 v97, v107, v109
	v_cvt_pk_bf16_f32 v98, v111, v113
	v_cvt_pk_bf16_f32 v99, v115, v117
	v_lshl_add_u64 v[100:101], v[100:101], 0, v[130:131]
	global_store_dwordx4 v[100:101], v[96:99], off sc1

; #define GAS __attribute__((address_space(1)))
; #define LAS __attribute__((address_space(3)))
; __device__ __forceinline__ unsigned pk2(float lo, float hi) { f32x2_k v = {lo, hi}; bf16x2_k b = __builtin_convertvector(v, bf16x2_k); return __builtin_bit_cast(unsigned, b); }
; __device__ __forceinline__ void p0_finish(const P0Job& j, const f32x4 (&v)[16], LAS float* scr, int lane) {
;     ...
;     for (int hb = 0; hb < 2; ++hb) { const int drow0 = p0_drow(j.kind, n0 + 32 * hb);
;         if (n0 + 32 * hb < j.N && k0 + 8 * c < j.K) {
; #pragma unroll
;             for (int jj = 0; jj < 4; ++jj) { const int n = (lane >> 3) + 8 * jj; const LAS float* sp = scr + (8 * c) * 65 + 32 * hb + n;
;                 v4u o; o.x = pk2(sp[0 * 65], sp[1 * 65]); o.y = pk2(sp[2 * 65], sp[3 * 65]); o.z = pk2(sp[4 * 65], sp[5 * 65]); o.w = pk2(sp[6 * 65], sp[7 * 65]);
;                 GAS v4u* dp = (GAS v4u*)(j.WT + (size_t)(drow0 + n) * j.ldk + k0 + 8 * c); if (j.late) __builtin_nontemporal_store(o, dp); else *dp = o; } } }
.LBB0_447:
	s_cmp_lt_i32 s47, s69
	s_cselect_b64 s[46:47], -1, 0
	s_and_b64 s[46:47], s[46:47], s[8:9]
	s_and_saveexec_b64 s[8:9], s[46:47]
	s_cbranch_execz .LBB0_449
	v_add_u32_e32 v95, s56, v134
	ds_read2_b32 v[100:101], v135 offset0:97 offset1:105
	ds_read2_b32 v[102:103], v135 offset0:32 offset1:40
	ds_read2_b32 v[104:105], v135 offset0:162 offset1:170
	ds_read2_b32 v[106:107], v135 offset0:227 offset1:235
	ds_read2_b32 v[108:109], v64 offset0:36 offset1:44
	ds_read2_b32 v[110:111], v64 offset0:101 offset1:109
	ds_read2_b32 v[112:113], v64 offset0:166 offset1:174
	ds_read2_b32 v[114:115], v64 offset0:231 offset1:239
	v_mad_u64_u32 v[116:117], s[46:47], v95, s68, 0
	s_waitcnt lgkmcnt(6)
	v_cvt_pk_bf16_f32 v96, v102, v100
	v_ashrrev_i32_e32 v102, 31, v95
	v_mov_b32_e32 v100, v117
	v_mad_u64_u32 v[118:119], s[46:47], v102, s68, v[100:101]
	v_mov_b32_e32 v117, v118
	v_lshl_add_u64 v[116:117], v[116:117], 1, s[2:3]
	s_lshl_b64 s[44:45], s[44:45], 1
	v_lshl_add_u64 v[116:117], v[116:117], 0, s[44:45]
	v_lshlrev_b32_e32 v130, 1, v128
	s_waitcnt lgkmcnt(4)
	v_cvt_pk_bf16_f32 v97, v104, v106
	s_waitcnt lgkmcnt(2)
	v_cvt_pk_bf16_f32 v98, v108, v110
	s_waitcnt lgkmcnt(0)
	v_cvt_pk_bf16_f32 v99, v112, v114
	v_lshl_add_u64 v[116:117], v[116:117], 0, v[130:131]
	v_add_u32_e32 v95, s56, v136
	global_store_dwordx4 v[116:117], v[96:99], off sc1
	s_nop 1
	v_cvt_pk_bf16_f32 v96, v103, v101
	v_mad_u64_u32 v[100:101], s[46:47], v95, s68, 0
	v_ashrrev_i32_e32 v103, 31, v95
	v_mov_b32_e32 v102, v101
	v_mad_u64_u32 v[102:103], s[46:47], v103, s68, v[102:103]
	v_mov_b32_e32 v101, v102
	v_lshl_add_u64 v[100:101], v[100:101], 1, s[2:3]
	v_lshl_add_u64 v[100:101], v[100:101], 0, s[44:45]
	v_cvt_pk_bf16_f32 v97, v105, v107
	v_cvt_pk_bf16_f32 v98, v109, v111
	v_cvt_pk_bf16_f32 v99, v113, v115
	v_lshl_add_u64 v[100:101], v[100:101], 0, v[130:131]
	v_add_u32_e32 v95, s56, v137
	ds_read2_b32 v[102:103], v135 offset0:113 offset1:121
	ds_read2_b32 v[104:105], v135 offset0:48 offset1:56
	ds_read2_b32 v[106:107], v135 offset0:178 offset1:186
	ds_read2_b32 v[108:109], v135 offset0:243 offset1:251
	ds_read2_b32 v[110:111], v64 offset0:52 offset1:60
	ds_read2_b32 v[112:113], v64 offset0:117 offset1:125
	ds_read2_b32 v[114:115], v64 offset0:182 offset1:190
	ds_read2_b32 v[116:117], v64 offset0:247 offset1:255
	global_store_dwordx4 v[100:101], v[96:99], off sc1
	v_mad_u64_u32 v[100:101], s[46:47], v95, s68, 0
	s_waitcnt lgkmcnt(6)
	v_cvt_pk_bf16_f32 v96, v104, v102
	v_ashrrev_i32_e32 v104, 31, v95
	v_mov_b32_e32 v102, v101
	v_mad_u64_u32 v[118:119], s[46:47], v104, s68, v[102:103]
	v_mov_b32_e32 v101, v118
	v_lshl_add_u64 v[100:101], v[100:101], 1, s[2:3]
	v_lshl_add_u64 v[100:101], v[100:101], 0, s[44:45]
	s_waitcnt lgkmcnt(4)
	v_cvt_pk_bf16_f32 v97, v106, v108
	s_waitcnt lgkmcnt(2)
	v_cvt_pk_bf16_f32 v98, v110, v112
	s_waitcnt lgkmcnt(0)
	v_cvt_pk_bf16_f32 v99, v114, v116
	v_lshl_add_u64 v[100:101], v[100:101], 0, v[130:131]
	v_add_u32_e32 v95, s56, v138
	global_store_dwordx4 v[100:101], v[96:99], off sc1
	v_mad_u64_u32 v[100:101], s[46:47], v95, s68, 0
	s_nop 0
	v_cvt_pk_bf16_f32 v96, v105, v103
	v_ashrrev_i32_e32 v103, 31, v95
	v_mov_b32_e32 v102, v101
	v_mad_u64_u32 v[102:103], s[46:47], v103, s68, v[102:103]
	v_mov_b32_e32 v101, v102
	v_lshl_add_u64 v[100:101], v[100:101], 1, s[2:3]
	v_lshl_add_u64 v[100:101], v[100:101], 0, s[44:45]
	v_cvt_pk_bf16_f32 v97, v107, v109
	v_cvt_pk_bf16_f32 v98, v111, v113
	v_cvt_pk_bf16_f32 v99, v115, v117
	v_lshl_add_u64 v[100:101], v[100:101], 0, v[130:131]
	global_store_dwordx4 v[100:101], v[96:99], off sc1

; #define GAS __attribute__((address_space(1)))
; #define LAS __attribute__((address_space(3)))
; __device__ __forceinline__ unsigned pk2(float lo, float hi) { f32x2_k v = {lo, hi}; bf16x2_k b = __builtin_convertvector(v, bf16x2_k); return __builtin_bit_cast(unsigned, b); }
; __device__ __forceinline__ void p0_finish(const P0Job& j, const f32x4 (&v)[16], LAS float* scr, int lane) {
;     ...
;     for (int hb = 0; hb < 2; ++hb) { const int drow0 = p0_drow(j.kind, n0 + 32 * hb);
;         if (n0 + 32 * hb < j.N && k0 + 8 * c < j.K) {
; #pragma unroll
;             for (int jj = 0; jj < 4; ++jj) { const int n = (lane >> 3) + 8 * jj; const LAS float* sp = scr + (8 * c) * 65 + 32 * hb + n;
;                 v4u o; o.x = pk2(sp[0 * 65], sp[1 * 65]); o.y = pk2(sp[2 * 65], sp[3 * 65]); o.z = pk2(sp[4 * 65], sp[5 * 65]); o.w = pk2(sp[6 * 65], sp[7 * 65]);
;                 GAS v4u* dp = (GAS v4u*)(j.WT + (size_t)(drow0 + n) * j.ldk + k0 + 8 * c); if (j.late) __builtin_nontemporal_store(o, dp); else *dp = o; } } }
.LBB0_465:
	s_lshl_b32 s2, s44, 6
	s_ashr_i32 s3, s2, 31
	v_or_b32_e32 v65, s2, v128
	s_cmp_lt_i32 s46, s66
	s_cselect_b64 s[44:45], -1, 0
	v_cmp_gt_i32_e64 s[8:9], s65, v65
	s_and_b64 s[50:51], s[44:45], s[8:9]
	s_and_saveexec_b64 s[44:45], s[50:51]
	s_cbranch_execz .LBB0_467
	ds_read2_b32 v[70:71], v135 offset0:65 offset1:73
	ds_read2_b32 v[72:73], v135 offset1:8
	ds_read2_b32 v[74:75], v135 offset0:130 offset1:138
	ds_read2_b32 v[76:77], v135 offset0:195 offset1:203
	ds_read2_b32 v[78:79], v64 offset0:4 offset1:12
	ds_read2_b32 v[80:81], v64 offset0:69 offset1:77
	ds_read2_b32 v[82:83], v64 offset0:134 offset1:142
	ds_read2_b32 v[84:85], v64 offset0:199 offset1:207
	v_add_u32_e32 v65, s49, v134
	v_mad_i64_i32 v[86:87], s[50:51], v65, s65, 0
	v_lshl_add_u64 v[86:87], v[86:87], 1, s[0:1]
	s_lshl_b64 s[50:51], s[2:3], 1
	v_lshl_add_u64 v[86:87], v[86:87], 0, s[50:51]
	v_lshlrev_b32_e32 v130, 1, v128
	s_waitcnt lgkmcnt(6)
	v_cvt_pk_bf16_f32 v66, v72, v70
	s_waitcnt lgkmcnt(4)
	v_cvt_pk_bf16_f32 v67, v74, v76
	s_waitcnt lgkmcnt(2)
	v_cvt_pk_bf16_f32 v68, v78, v80
	s_waitcnt lgkmcnt(0)
	v_cvt_pk_bf16_f32 v69, v82, v84
	v_lshl_add_u64 v[86:87], v[86:87], 0, v[130:131]
	v_add_u32_e32 v65, s49, v136
	global_store_dwordx4 v[86:87], v[66:69], off sc1
	s_nop 1
	v_cvt_pk_bf16_f32 v66, v73, v71
	v_mad_i64_i32 v[70:71], s[52:53], v65, s65, 0
	v_lshl_add_u64 v[70:71], v[70:71], 1, s[0:1]
	v_cvt_pk_bf16_f32 v67, v75, v77
	v_cvt_pk_bf16_f32 v68, v79, v81
	v_cvt_pk_bf16_f32 v69, v83, v85
	v_lshl_add_u64 v[70:71], v[70:71], 0, s[50:51]
	ds_read2_b32 v[72:73], v135 offset0:81 offset1:89
	ds_read2_b32 v[74:75], v135 offset0:16 offset1:24
	ds_read2_b32 v[76:77], v135 offset0:146 offset1:154
	ds_read2_b32 v[78:79], v135 offset0:211 offset1:219
	ds_read2_b32 v[80:81], v64 offset0:20 offset1:28
	ds_read2_b32 v[82:83], v64 offset0:85 offset1:93
	ds_read2_b32 v[84:85], v64 offset0:150 offset1:158
	ds_read2_b32 v[86:87], v64 offset0:215 offset1:223
	v_lshl_add_u64 v[70:71], v[70:71], 0, v[130:131]
	v_add_u32_e32 v65, s49, v137
	global_store_dwordx4 v[70:71], v[66:69], off sc1
	v_mad_i64_i32 v[70:71], s[52:53], v65, s65, 0
	v_lshl_add_u64 v[70:71], v[70:71], 1, s[0:1]
	v_lshl_add_u64 v[70:71], v[70:71], 0, s[50:51]
	s_waitcnt lgkmcnt(6)
	v_cvt_pk_bf16_f32 v66, v74, v72
	s_waitcnt lgkmcnt(4)
	v_cvt_pk_bf16_f32 v67, v76, v78
	s_waitcnt lgkmcnt(2)
	v_cvt_pk_bf16_f32 v68, v80, v82
	s_waitcnt lgkmcnt(0)
	v_cvt_pk_bf16_f32 v69, v84, v86
	v_lshl_add_u64 v[70:71], v[70:71], 0, v[130:131]
	v_add_u32_e32 v65, s49, v138
	global_store_dwordx4 v[70:71], v[66:69], off sc1
	v_mad_i64_i32 v[70:71], s[52:53], v65, s65, 0
	v_lshl_add_u64 v[70:71], v[70:71], 1, s[0:1]
	v_lshl_add_u64 v[70:71], v[70:71], 0, s[50:51]
	v_cvt_pk_bf16_f32 v66, v75, v73
	v_cvt_pk_bf16_f32 v67, v77, v79
	v_cvt_pk_bf16_f32 v68, v81, v83
	v_cvt_pk_bf16_f32 v69, v85, v87
	v_lshl_add_u64 v[70:71], v[70:71], 0, v[130:131]
	global_store_dwordx4 v[70:71], v[66:69], off sc1

; #define GAS __attribute__((address_space(1)))
; #define LAS __attribute__((address_space(3)))
; __device__ __forceinline__ unsigned pk2(float lo, float hi) { f32x2_k v = {lo, hi}; bf16x2_k b = __builtin_convertvector(v, bf16x2_k); return __builtin_bit_cast(unsigned, b); }
; __device__ __forceinline__ void p0_finish(const P0Job& j, const f32x4 (&v)[16], LAS float* scr, int lane) {
;     ...
;     for (int hb = 0; hb < 2; ++hb) { const int drow0 = p0_drow(j.kind, n0 + 32 * hb);
;         if (n0 + 32 * hb < j.N && k0 + 8 * c < j.K) {
; #pragma unroll
;             for (int jj = 0; jj < 4; ++jj) { const int n = (lane >> 3) + 8 * jj; const LAS float* sp = scr + (8 * c) * 65 + 32 * hb + n;
;                 v4u o; o.x = pk2(sp[0 * 65], sp[1 * 65]); o.y = pk2(sp[2 * 65], sp[3 * 65]); o.z = pk2(sp[4 * 65], sp[5 * 65]); o.w = pk2(sp[6 * 65], sp[7 * 65]);
;                 GAS v4u* dp = (GAS v4u*)(j.WT + (size_t)(drow0 + n) * j.ldk + k0 + 8 * c); if (j.late) __builtin_nontemporal_store(o, dp); else *dp = o; } } }
.LBB0_478:
	s_cmp_lt_i32 s50, s66
	s_cselect_b64 s[44:45], -1, 0
	s_and_b64 s[44:45], s[44:45], s[8:9]
	s_and_saveexec_b64 s[8:9], s[44:45]
	s_cbranch_execz .LBB0_279
	ds_read2_b32 v[70:71], v135 offset0:97 offset1:105
	ds_read2_b32 v[72:73], v135 offset0:32 offset1:40
	ds_read2_b32 v[74:75], v135 offset0:162 offset1:170
	ds_read2_b32 v[76:77], v135 offset0:227 offset1:235
	ds_read2_b32 v[78:79], v64 offset0:36 offset1:44
	ds_read2_b32 v[80:81], v64 offset0:101 offset1:109
	ds_read2_b32 v[82:83], v64 offset0:166 offset1:174
	ds_read2_b32 v[84:85], v64 offset0:231 offset1:239
	v_add_u32_e32 v65, s49, v134
	v_mad_i64_i32 v[86:87], s[44:45], v65, s65, 0
	v_lshl_add_u64 v[86:87], v[86:87], 1, s[0:1]
	s_lshl_b64 s[2:3], s[2:3], 1
	v_lshl_add_u64 v[86:87], v[86:87], 0, s[2:3]
	v_lshlrev_b32_e32 v130, 1, v128
	s_waitcnt lgkmcnt(6)
	v_cvt_pk_bf16_f32 v66, v72, v70
	s_waitcnt lgkmcnt(4)
	v_cvt_pk_bf16_f32 v67, v74, v76
	s_waitcnt lgkmcnt(2)
	v_cvt_pk_bf16_f32 v68, v78, v80
	s_waitcnt lgkmcnt(0)
	v_cvt_pk_bf16_f32 v69, v82, v84
	v_lshl_add_u64 v[86:87], v[86:87], 0, v[130:131]
	v_add_u32_e32 v65, s49, v136
	global_store_dwordx4 v[86:87], v[66:69], off sc1
	s_nop 1
	v_cvt_pk_bf16_f32 v66, v73, v71
	v_mad_i64_i32 v[70:71], s[44:45], v65, s65, 0
	v_lshl_add_u64 v[70:71], v[70:71], 1, s[0:1]
	v_lshl_add_u64 v[70:71], v[70:71], 0, s[2:3]
	v_cvt_pk_bf16_f32 v67, v75, v77
	v_cvt_pk_bf16_f32 v68, v79, v81
	v_cvt_pk_bf16_f32 v69, v83, v85
	v_lshl_add_u64 v[70:71], v[70:71], 0, v[130:131]
	ds_read2_b32 v[72:73], v135 offset0:113 offset1:121
	ds_read2_b32 v[74:75], v135 offset0:48 offset1:56
	ds_read2_b32 v[76:77], v135 offset0:178 offset1:186
	ds_read2_b32 v[78:79], v135 offset0:243 offset1:251
	ds_read2_b32 v[80:81], v64 offset0:52 offset1:60
	ds_read2_b32 v[82:83], v64 offset0:117 offset1:125
	ds_read2_b32 v[84:85], v64 offset0:182 offset1:190
	ds_read2_b32 v[86:87], v64 offset0:247 offset1:255
	global_store_dwordx4 v[70:71], v[66:69], off sc1
	s_waitcnt lgkmcnt(6)
	v_cvt_pk_bf16_f32 v64, v74, v72
	s_waitcnt lgkmcnt(4)
	v_cvt_pk_bf16_f32 v65, v76, v78
	v_add_u32_e32 v68, s49, v137
	v_mad_i64_i32 v[68:69], s[44:45], v68, s65, 0
	v_lshl_add_u64 v[68:69], v[68:69], 1, s[0:1]
	v_lshl_add_u64 v[68:69], v[68:69], 0, s[2:3]
	s_waitcnt lgkmcnt(2)
	v_cvt_pk_bf16_f32 v66, v80, v82
	s_waitcnt lgkmcnt(0)
	v_cvt_pk_bf16_f32 v67, v84, v86
	v_lshl_add_u64 v[68:69], v[68:69], 0, v[130:131]
	global_store_dwordx4 v[68:69], v[64:67], off sc1
	v_add_u32_e32 v68, s49, v138
	v_mad_i64_i32 v[68:69], s[44:45], v68, s65, 0
	v_lshl_add_u64 v[68:69], v[68:69], 1, s[0:1]
	v_lshl_add_u64 v[68:69], v[68:69], 0, s[2:3]
	v_cvt_pk_bf16_f32 v64, v75, v73
	v_cvt_pk_bf16_f32 v65, v77, v79
	v_cvt_pk_bf16_f32 v66, v81, v83
	v_cvt_pk_bf16_f32 v67, v85, v87
	v_lshl_add_u64 v[68:69], v[68:69], 0, v[130:131]
	global_store_dwordx4 v[68:69], v[64:67], off sc1
	s_branch .LBB0_279

; #define GAS __attribute__((address_space(1)))
; #define LAS __attribute__((address_space(3)))
; __device__ __forceinline__ unsigned pk2(float lo, float hi) { f32x2_k v = {lo, hi}; bf16x2_k b = __builtin_convertvector(v, bf16x2_k); return __builtin_bit_cast(unsigned, b); }
; __device__ __forceinline__ void p0_finish(const P0Job& j, const f32x4 (&v)[16], LAS float* scr, int lane) {
;     ...
;     for (int hb = 0; hb < 2; ++hb) { const int drow0 = p0_drow(j.kind, n0 + 32 * hb);
;         if (n0 + 32 * hb < j.N && k0 + 8 * c < j.K) {
; #pragma unroll
;             for (int jj = 0; jj < 4; ++jj) { const int n = (lane >> 3) + 8 * jj; const LAS float* sp = scr + (8 * c) * 65 + 32 * hb + n;
;                 v4u o; o.x = pk2(sp[0 * 65], sp[1 * 65]); o.y = pk2(sp[2 * 65], sp[3 * 65]); o.z = pk2(sp[4 * 65], sp[5 * 65]); o.w = pk2(sp[6 * 65], sp[7 * 65]);
;                 GAS v4u* dp = (GAS v4u*)(j.WT + (size_t)(drow0 + n) * j.ldk + k0 + 8 * c); if (j.late) __builtin_nontemporal_store(o, dp); else *dp = o; } } }
.LBB0_642:
	s_ashr_i32 s45, s44, 31
	v_or_b32_e32 v64, s44, v128
	s_cmp_lt_i32 s46, s68
	s_cselect_b64 s[48:49], -1, 0
	v_cmp_gt_i32_e64 s[8:9], s67, v64
	s_and_b64 s[58:59], s[48:49], s[8:9]
	v_add_u32_e32 v64, 0x400, v135
	v_lshlrev_b32_e32 v130, 1, v128
	s_and_saveexec_b64 s[48:49], s[58:59]
	s_cbranch_execz .LBB0_644
	v_add_u32_e32 v95, s56, v134
	ds_read2_b32 v[100:101], v135 offset0:65 offset1:73
	ds_read2_b32 v[102:103], v135 offset1:8
	ds_read2_b32 v[104:105], v135 offset0:130 offset1:138
	ds_read2_b32 v[106:107], v135 offset0:195 offset1:203
	ds_read2_b32 v[108:109], v64 offset0:4 offset1:12
	ds_read2_b32 v[110:111], v64 offset0:69 offset1:77
	ds_read2_b32 v[112:113], v64 offset0:134 offset1:142
	ds_read2_b32 v[114:115], v64 offset0:199 offset1:207
	v_mad_u64_u32 v[116:117], s[58:59], v95, s67, 0
	s_waitcnt lgkmcnt(6)
	v_cvt_pk_bf16_f32 v96, v102, v100
	v_ashrrev_i32_e32 v102, 31, v95
	v_mov_b32_e32 v100, v117
	v_mad_u64_u32 v[118:119], s[58:59], v102, s67, v[100:101]
	v_mov_b32_e32 v117, v118
	v_lshl_add_u64 v[116:117], v[116:117], 1, s[2:3]
	s_lshl_b64 s[58:59], s[44:45], 1
	v_lshl_add_u64 v[116:117], v[116:117], 0, s[58:59]
	s_waitcnt lgkmcnt(4)
	v_cvt_pk_bf16_f32 v97, v104, v106
	s_waitcnt lgkmcnt(2)
	v_cvt_pk_bf16_f32 v98, v108, v110
	s_waitcnt lgkmcnt(0)
	v_cvt_pk_bf16_f32 v99, v112, v114
	v_lshl_add_u64 v[116:117], v[116:117], 0, v[130:131]
	v_add_u32_e32 v95, s56, v136
	global_store_dwordx4 v[116:117], v[96:99], off sc1
	s_nop 1
	v_cvt_pk_bf16_f32 v96, v103, v101
	v_mad_u64_u32 v[100:101], s[72:73], v95, s67, 0
	v_ashrrev_i32_e32 v103, 31, v95
	v_mov_b32_e32 v102, v101
	v_mad_u64_u32 v[102:103], s[72:73], v103, s67, v[102:103]
	v_mov_b32_e32 v101, v102
	v_lshl_add_u64 v[100:101], v[100:101], 1, s[2:3]
	v_lshl_add_u64 v[100:101], v[100:101], 0, s[58:59]
	v_cvt_pk_bf16_f32 v97, v105, v107
	v_cvt_pk_bf16_f32 v98, v109, v111
	v_cvt_pk_bf16_f32 v99, v113, v115
	v_lshl_add_u64 v[100:101], v[100:101], 0, v[130:131]
	v_add_u32_e32 v95, s56, v137
	ds_read2_b32 v[102:103], v135 offset0:81 offset1:89
	ds_read2_b32 v[104:105], v135 offset0:16 offset1:24
	ds_read2_b32 v[106:107], v135 offset0:146 offset1:154
	ds_read2_b32 v[108:109], v135 offset0:211 offset1:219
	ds_read2_b32 v[110:111], v64 offset0:20 offset1:28
	ds_read2_b32 v[112:113], v64 offset0:85 offset1:93
	ds_read2_b32 v[114:115], v64 offset0:150 offset1:158
	ds_read2_b32 v[116:117], v64 offset0:215 offset1:223
	global_store_dwordx4 v[100:101], v[96:99], off sc1
	v_mad_u64_u32 v[100:101], s[72:73], v95, s67, 0
	s_waitcnt lgkmcnt(6)
	v_cvt_pk_bf16_f32 v96, v104, v102
	v_ashrrev_i32_e32 v104, 31, v95
	v_mov_b32_e32 v102, v101
	v_mad_u64_u32 v[118:119], s[72:73], v104, s67, v[102:103]
	v_mov_b32_e32 v101, v118
	v_lshl_add_u64 v[100:101], v[100:101], 1, s[2:3]
	v_lshl_add_u64 v[100:101], v[100:101], 0, s[58:59]
	s_waitcnt lgkmcnt(4)
	v_cvt_pk_bf16_f32 v97, v106, v108
	s_waitcnt lgkmcnt(2)
	v_cvt_pk_bf16_f32 v98, v110, v112
	s_waitcnt lgkmcnt(0)
	v_cvt_pk_bf16_f32 v99, v114, v116
	v_lshl_add_u64 v[100:101], v[100:101], 0, v[130:131]
	v_add_u32_e32 v95, s56, v138
	global_store_dwordx4 v[100:101], v[96:99], off sc1
	v_mad_u64_u32 v[100:101], s[56:57], v95, s67, 0
	s_nop 0
	v_cvt_pk_bf16_f32 v96, v105, v103
	v_ashrrev_i32_e32 v103, 31, v95
	v_mov_b32_e32 v102, v101
	v_mad_u64_u32 v[102:103], s[56:57], v103, s67, v[102:103]
	v_mov_b32_e32 v101, v102
	v_lshl_add_u64 v[100:101], v[100:101], 1, s[2:3]
	v_readlane_b32 s72, v254, 11
	v_lshl_add_u64 v[100:101], v[100:101], 0, s[58:59]
	v_readlane_b32 s73, v254, 12
	v_cvt_pk_bf16_f32 v97, v107, v109
	v_cvt_pk_bf16_f32 v98, v111, v113
	v_cvt_pk_bf16_f32 v99, v115, v117
	v_lshl_add_u64 v[100:101], v[100:101], 0, v[130:131]
	global_store_dwordx4 v[100:101], v[96:99], off sc1

; #define GAS __attribute__((address_space(1)))
; #define LAS __attribute__((address_space(3)))
; __device__ __forceinline__ unsigned pk2(float lo, float hi) { f32x2_k v = {lo, hi}; bf16x2_k b = __builtin_convertvector(v, bf16x2_k); return __builtin_bit_cast(unsigned, b); }
; __device__ __forceinline__ void p0_finish(const P0Job& j, const f32x4 (&v)[16], LAS float* scr, int lane) {
;     ...
;     for (int hb = 0; hb < 2; ++hb) { const int drow0 = p0_drow(j.kind, n0 + 32 * hb);
;         if (n0 + 32 * hb < j.N && k0 + 8 * c < j.K) {
; #pragma unroll
;             for (int jj = 0; jj < 4; ++jj) { const int n = (lane >> 3) + 8 * jj; const LAS float* sp = scr + (8 * c) * 65 + 32 * hb + n;
;                 v4u o; o.x = pk2(sp[0 * 65], sp[1 * 65]); o.y = pk2(sp[2 * 65], sp[3 * 65]); o.z = pk2(sp[4 * 65], sp[5 * 65]); o.w = pk2(sp[6 * 65], sp[7 * 65]);
;                 GAS v4u* dp = (GAS v4u*)(j.WT + (size_t)(drow0 + n) * j.ldk + k0 + 8 * c); if (j.late) __builtin_nontemporal_store(o, dp); else *dp = o; } } }
.LBB0_653:
	s_cmp_lt_i32 s47, s68
	s_cselect_b64 s[46:47], -1, 0
	s_and_b64 s[46:47], s[46:47], s[8:9]
	s_and_saveexec_b64 s[8:9], s[46:47]
	s_cbranch_execz .LBB0_655
	v_add_u32_e32 v95, s56, v134
	ds_read2_b32 v[100:101], v135 offset0:97 offset1:105
	ds_read2_b32 v[102:103], v135 offset0:32 offset1:40
	ds_read2_b32 v[104:105], v135 offset0:162 offset1:170
	ds_read2_b32 v[106:107], v135 offset0:227 offset1:235
	ds_read2_b32 v[108:109], v64 offset0:36 offset1:44
	ds_read2_b32 v[110:111], v64 offset0:101 offset1:109
	ds_read2_b32 v[112:113], v64 offset0:166 offset1:174
	ds_read2_b32 v[114:115], v64 offset0:231 offset1:239
	v_mad_u64_u32 v[116:117], s[46:47], v95, s67, 0
	s_waitcnt lgkmcnt(6)
	v_cvt_pk_bf16_f32 v96, v102, v100
	v_ashrrev_i32_e32 v102, 31, v95
	v_mov_b32_e32 v100, v117
	v_mad_u64_u32 v[118:119], s[46:47], v102, s67, v[100:101]
	v_mov_b32_e32 v117, v118
	v_lshl_add_u64 v[116:117], v[116:117], 1, s[2:3]
	s_lshl_b64 s[44:45], s[44:45], 1
	v_lshl_add_u64 v[116:117], v[116:117], 0, s[44:45]
	s_waitcnt lgkmcnt(4)
	v_cvt_pk_bf16_f32 v97, v104, v106
	s_waitcnt lgkmcnt(2)
	v_cvt_pk_bf16_f32 v98, v108, v110
	s_waitcnt lgkmcnt(0)
	v_cvt_pk_bf16_f32 v99, v112, v114
	v_lshl_add_u64 v[116:117], v[116:117], 0, v[130:131]
	v_add_u32_e32 v95, s56, v136
	global_store_dwordx4 v[116:117], v[96:99], off sc1
	s_nop 1
	v_cvt_pk_bf16_f32 v96, v103, v101
	v_mad_u64_u32 v[100:101], s[46:47], v95, s67, 0
	v_ashrrev_i32_e32 v103, 31, v95
	v_mov_b32_e32 v102, v101
	v_mad_u64_u32 v[102:103], s[46:47], v103, s67, v[102:103]
	v_mov_b32_e32 v101, v102
	v_lshl_add_u64 v[100:101], v[100:101], 1, s[2:3]
	v_lshl_add_u64 v[100:101], v[100:101], 0, s[44:45]
	v_cvt_pk_bf16_f32 v97, v105, v107
	v_cvt_pk_bf16_f32 v98, v109, v111
	v_cvt_pk_bf16_f32 v99, v113, v115
	v_lshl_add_u64 v[100:101], v[100:101], 0, v[130:131]
	v_add_u32_e32 v95, s56, v137
	ds_read2_b32 v[102:103], v135 offset0:113 offset1:121
	ds_read2_b32 v[104:105], v135 offset0:48 offset1:56
	ds_read2_b32 v[106:107], v135 offset0:178 offset1:186
	ds_read2_b32 v[108:109], v135 offset0:243 offset1:251
	ds_read2_b32 v[110:111], v64 offset0:52 offset1:60
	ds_read2_b32 v[112:113], v64 offset0:117 offset1:125
	ds_read2_b32 v[114:115], v64 offset0:182 offset1:190
	ds_read2_b32 v[116:117], v64 offset0:247 offset1:255
	global_store_dwordx4 v[100:101], v[96:99], off sc1
	v_mad_u64_u32 v[100:101], s[46:47], v95, s67, 0
	s_waitcnt lgkmcnt(6)
	v_cvt_pk_bf16_f32 v96, v104, v102
	v_ashrrev_i32_e32 v104, 31, v95
	v_mov_b32_e32 v102, v101
	v_mad_u64_u32 v[118:119], s[46:47], v104, s67, v[102:103]
	v_mov_b32_e32 v101, v118
	v_lshl_add_u64 v[100:101], v[100:101], 1, s[2:3]
	v_lshl_add_u64 v[100:101], v[100:101], 0, s[44:45]
	s_waitcnt lgkmcnt(4)
	v_cvt_pk_bf16_f32 v97, v106, v108
	s_waitcnt lgkmcnt(2)
	v_cvt_pk_bf16_f32 v98, v110, v112
	s_waitcnt lgkmcnt(0)
	v_cvt_pk_bf16_f32 v99, v114, v116
	v_lshl_add_u64 v[100:101], v[100:101], 0, v[130:131]
	v_add_u32_e32 v95, s56, v138
	global_store_dwordx4 v[100:101], v[96:99], off sc1
	v_mad_u64_u32 v[100:101], s[46:47], v95, s67, 0
	s_nop 0
	v_cvt_pk_bf16_f32 v96, v105, v103
	v_ashrrev_i32_e32 v103, 31, v95
	v_mov_b32_e32 v102, v101
	v_mad_u64_u32 v[102:103], s[46:47], v103, s67, v[102:103]
	v_mov_b32_e32 v101, v102
	v_lshl_add_u64 v[100:101], v[100:101], 1, s[2:3]
	v_lshl_add_u64 v[100:101], v[100:101], 0, s[44:45]
	v_cvt_pk_bf16_f32 v97, v107, v109
	v_cvt_pk_bf16_f32 v98, v111, v113
	v_cvt_pk_bf16_f32 v99, v115, v117
	v_lshl_add_u64 v[100:101], v[100:101], 0, v[130:131]
	global_store_dwordx4 v[100:101], v[96:99], off sc1

; #define GAS __attribute__((address_space(1)))
; #define LAS __attribute__((address_space(3)))
; __device__ __forceinline__ unsigned pk2(float lo, float hi) { f32x2_k v = {lo, hi}; bf16x2_k b = __builtin_convertvector(v, bf16x2_k); return __builtin_bit_cast(unsigned, b); }
; __device__ __forceinline__ void p0_finish(const P0Job& j, const f32x4 (&v)[16], LAS float* scr, int lane) {
;     ...
;     for (int hb = 0; hb < 2; ++hb) { const int drow0 = p0_drow(j.kind, n0 + 32 * hb);
;         if (n0 + 32 * hb < j.N && k0 + 8 * c < j.K) {
; #pragma unroll
;             for (int jj = 0; jj < 4; ++jj) { const int n = (lane >> 3) + 8 * jj; const LAS float* sp = scr + (8 * c) * 65 + 32 * hb + n;
;                 v4u o; o.x = pk2(sp[0 * 65], sp[1 * 65]); o.y = pk2(sp[2 * 65], sp[3 * 65]); o.z = pk2(sp[4 * 65], sp[5 * 65]); o.w = pk2(sp[6 * 65], sp[7 * 65]);
;                 GAS v4u* dp = (GAS v4u*)(j.WT + (size_t)(drow0 + n) * j.ldk + k0 + 8 * c); if (j.late) __builtin_nontemporal_store(o, dp); else *dp = o; } } }
.LBB0_671:
	s_lshl_b32 s2, s44, 6
	s_ashr_i32 s3, s2, 31
	v_or_b32_e32 v65, s2, v128
	s_cmp_lt_i32 s46, s64
	s_cselect_b64 s[44:45], -1, 0
	v_cmp_gt_i32_e64 s[8:9], s63, v65
	s_and_b64 s[50:51], s[44:45], s[8:9]
	s_and_saveexec_b64 s[44:45], s[50:51]
	s_cbranch_execz .LBB0_673
	ds_read2_b32 v[70:71], v135 offset0:65 offset1:73
	ds_read2_b32 v[72:73], v135 offset1:8
	ds_read2_b32 v[74:75], v135 offset0:130 offset1:138
	ds_read2_b32 v[76:77], v135 offset0:195 offset1:203
	ds_read2_b32 v[78:79], v64 offset0:4 offset1:12
	ds_read2_b32 v[80:81], v64 offset0:69 offset1:77
	ds_read2_b32 v[82:83], v64 offset0:134 offset1:142
	ds_read2_b32 v[84:85], v64 offset0:199 offset1:207
	v_add_u32_e32 v65, s49, v134
	v_mad_i64_i32 v[86:87], s[50:51], v65, s63, 0
	v_lshl_add_u64 v[86:87], v[86:87], 1, s[0:1]
	s_lshl_b64 s[50:51], s[2:3], 1
	v_lshl_add_u64 v[86:87], v[86:87], 0, s[50:51]
	s_waitcnt lgkmcnt(6)
	v_cvt_pk_bf16_f32 v66, v72, v70
	s_waitcnt lgkmcnt(4)
	v_cvt_pk_bf16_f32 v67, v74, v76
	s_waitcnt lgkmcnt(2)
	v_cvt_pk_bf16_f32 v68, v78, v80
	s_waitcnt lgkmcnt(0)
	v_cvt_pk_bf16_f32 v69, v82, v84
	v_lshl_add_u64 v[86:87], v[86:87], 0, v[130:131]
	v_add_u32_e32 v65, s49, v136
	global_store_dwordx4 v[86:87], v[66:69], off sc1
	s_nop 1
	v_cvt_pk_bf16_f32 v66, v73, v71
	v_mad_i64_i32 v[70:71], s[52:53], v65, s63, 0
	v_lshl_add_u64 v[70:71], v[70:71], 1, s[0:1]
	v_cvt_pk_bf16_f32 v67, v75, v77
	v_cvt_pk_bf16_f32 v68, v79, v81
	v_cvt_pk_bf16_f32 v69, v83, v85
	v_lshl_add_u64 v[70:71], v[70:71], 0, s[50:51]
	ds_read2_b32 v[72:73], v135 offset0:81 offset1:89
	ds_read2_b32 v[74:75], v135 offset0:16 offset1:24
	ds_read2_b32 v[76:77], v135 offset0:146 offset1:154
	ds_read2_b32 v[78:79], v135 offset0:211 offset1:219
	ds_read2_b32 v[80:81], v64 offset0:20 offset1:28
	ds_read2_b32 v[82:83], v64 offset0:85 offset1:93
	ds_read2_b32 v[84:85], v64 offset0:150 offset1:158
	ds_read2_b32 v[86:87], v64 offset0:215 offset1:223
	v_lshl_add_u64 v[70:71], v[70:71], 0, v[130:131]
	v_add_u32_e32 v65, s49, v137
	global_store_dwordx4 v[70:71], v[66:69], off sc1
	v_mad_i64_i32 v[70:71], s[52:53], v65, s63, 0
	v_lshl_add_u64 v[70:71], v[70:71], 1, s[0:1]
	v_lshl_add_u64 v[70:71], v[70:71], 0, s[50:51]
	s_waitcnt lgkmcnt(6)
	v_cvt_pk_bf16_f32 v66, v74, v72
	s_waitcnt lgkmcnt(4)
	v_cvt_pk_bf16_f32 v67, v76, v78
	s_waitcnt lgkmcnt(2)
	v_cvt_pk_bf16_f32 v68, v80, v82
	s_waitcnt lgkmcnt(0)
	v_cvt_pk_bf16_f32 v69, v84, v86
	v_lshl_add_u64 v[70:71], v[70:71], 0, v[130:131]
	v_add_u32_e32 v65, s49, v138
	global_store_dwordx4 v[70:71], v[66:69], off sc1
	v_mad_i64_i32 v[70:71], s[52:53], v65, s63, 0
	v_lshl_add_u64 v[70:71], v[70:71], 1, s[0:1]
	v_lshl_add_u64 v[70:71], v[70:71], 0, s[50:51]
	v_cvt_pk_bf16_f32 v66, v75, v73
	v_cvt_pk_bf16_f32 v67, v77, v79
	v_cvt_pk_bf16_f32 v68, v81, v83
	v_cvt_pk_bf16_f32 v69, v85, v87
	v_lshl_add_u64 v[70:71], v[70:71], 0, v[130:131]
	global_store_dwordx4 v[70:71], v[66:69], off sc1

; #define GAS __attribute__((address_space(1)))
; #define LAS __attribute__((address_space(3)))
; __device__ __forceinline__ unsigned pk2(float lo, float hi) { f32x2_k v = {lo, hi}; bf16x2_k b = __builtin_convertvector(v, bf16x2_k); return __builtin_bit_cast(unsigned, b); }
; __device__ __forceinline__ void p0_finish(const P0Job& j, const f32x4 (&v)[16], LAS float* scr, int lane) {
;     ...
;     for (int hb = 0; hb < 2; ++hb) { const int drow0 = p0_drow(j.kind, n0 + 32 * hb);
;         if (n0 + 32 * hb < j.N && k0 + 8 * c < j.K) {
; #pragma unroll
;             for (int jj = 0; jj < 4; ++jj) { const int n = (lane >> 3) + 8 * jj; const LAS float* sp = scr + (8 * c) * 65 + 32 * hb + n;
;                 v4u o; o.x = pk2(sp[0 * 65], sp[1 * 65]); o.y = pk2(sp[2 * 65], sp[3 * 65]); o.z = pk2(sp[4 * 65], sp[5 * 65]); o.w = pk2(sp[6 * 65], sp[7 * 65]);
;                 GAS v4u* dp = (GAS v4u*)(j.WT + (size_t)(drow0 + n) * j.ldk + k0 + 8 * c); if (j.late) __builtin_nontemporal_store(o, dp); else *dp = o; } } }
.LBB0_684:
	s_cmp_lt_i32 s50, s64
	s_cselect_b64 s[44:45], -1, 0
	s_and_b64 s[44:45], s[44:45], s[8:9]
	s_and_saveexec_b64 s[8:9], s[44:45]
	s_cbranch_execz .LBB0_484
	ds_read2_b32 v[70:71], v135 offset0:97 offset1:105
	ds_read2_b32 v[72:73], v135 offset0:32 offset1:40
	ds_read2_b32 v[74:75], v135 offset0:162 offset1:170
	ds_read2_b32 v[76:77], v135 offset0:227 offset1:235
	ds_read2_b32 v[78:79], v64 offset0:36 offset1:44
	ds_read2_b32 v[80:81], v64 offset0:101 offset1:109
	ds_read2_b32 v[82:83], v64 offset0:166 offset1:174
	ds_read2_b32 v[84:85], v64 offset0:231 offset1:239
	v_add_u32_e32 v65, s49, v134
	v_mad_i64_i32 v[86:87], s[44:45], v65, s63, 0
	v_lshl_add_u64 v[86:87], v[86:87], 1, s[0:1]
	s_lshl_b64 s[2:3], s[2:3], 1
	v_lshl_add_u64 v[86:87], v[86:87], 0, s[2:3]
	s_waitcnt lgkmcnt(6)
	v_cvt_pk_bf16_f32 v66, v72, v70
	s_waitcnt lgkmcnt(4)
	v_cvt_pk_bf16_f32 v67, v74, v76
	s_waitcnt lgkmcnt(2)
	v_cvt_pk_bf16_f32 v68, v78, v80
	s_waitcnt lgkmcnt(0)
	v_cvt_pk_bf16_f32 v69, v82, v84
	v_lshl_add_u64 v[86:87], v[86:87], 0, v[130:131]
	v_add_u32_e32 v65, s49, v136
	global_store_dwordx4 v[86:87], v[66:69], off sc1
	s_nop 1
	v_cvt_pk_bf16_f32 v66, v73, v71
	v_mad_i64_i32 v[70:71], s[44:45], v65, s63, 0
	v_lshl_add_u64 v[70:71], v[70:71], 1, s[0:1]
	v_lshl_add_u64 v[70:71], v[70:71], 0, s[2:3]
	v_cvt_pk_bf16_f32 v67, v75, v77
	v_cvt_pk_bf16_f32 v68, v79, v81
	v_cvt_pk_bf16_f32 v69, v83, v85
	v_lshl_add_u64 v[70:71], v[70:71], 0, v[130:131]
	ds_read2_b32 v[72:73], v135 offset0:113 offset1:121
	ds_read2_b32 v[74:75], v135 offset0:48 offset1:56
	ds_read2_b32 v[76:77], v135 offset0:178 offset1:186
	ds_read2_b32 v[78:79], v135 offset0:243 offset1:251
	ds_read2_b32 v[80:81], v64 offset0:52 offset1:60
	ds_read2_b32 v[82:83], v64 offset0:117 offset1:125
	ds_read2_b32 v[84:85], v64 offset0:182 offset1:190
	ds_read2_b32 v[86:87], v64 offset0:247 offset1:255
	global_store_dwordx4 v[70:71], v[66:69], off sc1
	s_waitcnt lgkmcnt(6)
	v_cvt_pk_bf16_f32 v64, v74, v72
	s_waitcnt lgkmcnt(4)
	v_cvt_pk_bf16_f32 v65, v76, v78
	v_add_u32_e32 v68, s49, v137
	v_mad_i64_i32 v[68:69], s[44:45], v68, s63, 0
	v_lshl_add_u64 v[68:69], v[68:69], 1, s[0:1]
	v_lshl_add_u64 v[68:69], v[68:69], 0, s[2:3]
	s_waitcnt lgkmcnt(2)
	v_cvt_pk_bf16_f32 v66, v80, v82
	s_waitcnt lgkmcnt(0)
	v_cvt_pk_bf16_f32 v67, v84, v86
	v_lshl_add_u64 v[68:69], v[68:69], 0, v[130:131]
	global_store_dwordx4 v[68:69], v[64:67], off sc1
	v_add_u32_e32 v68, s49, v138
	v_mad_i64_i32 v[68:69], s[44:45], v68, s63, 0
	v_lshl_add_u64 v[68:69], v[68:69], 1, s[0:1]
	v_lshl_add_u64 v[68:69], v[68:69], 0, s[2:3]
	v_cvt_pk_bf16_f32 v64, v75, v73
	v_cvt_pk_bf16_f32 v65, v77, v79
	v_cvt_pk_bf16_f32 v66, v81, v83
	v_cvt_pk_bf16_f32 v67, v85, v87
	v_lshl_add_u64 v[68:69], v[68:69], 0, v[130:131]
	global_store_dwordx4 v[68:69], v[64:67], off sc1
	s_branch .LBB0_484

; __device__ __forceinline__ u32x4 pack_bf8(f32x4 a, f32x4 b) { u32x4 w; w.x = cvt_pk_bf16(a[0], a[1]); w.y = cvt_pk_bf16(a[2], a[3]); w.z = cvt_pk_bf16(b[0], b[1]); w.w = cvt_pk_bf16(b[2], b[3]); return w; }
;     __device__ __forceinline__ void fused(f32x4 (&acc)[2][2][4][2], const Unit& u, int wr, int wc, int fr, int fq, PG8_LAS unsigned char* lds, int wid, int lane) const {
;     ...
;         f32x4 gv[2][2];
; #pragma unroll
;         for (int bj = 0; bj < 2; ++bj)
; #pragma unroll
;             for (int n = 0; n < 2; ++n) gv[bj][n] = *(const f32x4*)(g2 + col0 + bj * HALF + n * 4);
; #pragma unroll
;         for (int ai = 0; ai < 2; ++ai)
; #pragma unroll
;             for (int m = 0; m < 4; ++m) { const int r = ai * HALF + wr * 64 + m * 16 + fr; const float rs = S[r]; const size_t off = (size_t)(u.pm * BM + r) * ldc + col0;
; #pragma unroll
;                 for (int bj = 0; bj < 2; ++bj) { const f32x4 x0 = acc[ai][bj][m][0], x1 = acc[ai][bj][m][1];
;                     __builtin_nontemporal_store(pack_bf8(x0, x1), (u32x4*)(out + off + bj * HALF));
;                     *(u32x4*)(xn + off + bj * HALF) = pack_bf8(x0 * gv[bj][0] * rs, x1 * gv[bj][1] * rs); }
;                 asm volatile("" ::: "memory"); }
.LBB0_819:
	s_or_b64 exec, exec, s[0:1]
	v_lshl_add_u64 v[128:129], v[212:213], 2, s[86:87]
	s_mov_b32 s2, 0x17000
	v_add_co_u32_e32 v130, vcc, s2, v128
	s_waitcnt lgkmcnt(0)
	s_barrier
	s_mov_b64 s[0:1], 0x17000
	v_addc_co_u32_e32 v131, vcc, 0, v129, vcc
	global_load_dwordx4 v[140:143], v[130:131], off
	v_lshl_add_u64 v[128:129], v[128:129], 0, s[0:1]
	global_load_dwordx4 v[136:139], v[128:129], off offset:16
	s_waitcnt lgkmcnt(0)
	global_load_dwordx4 v[132:135], v[128:129], off offset:512
	s_nop 0
	global_load_dwordx4 v[128:131], v[128:129], off offset:528
	ds_read_b32 v162, v211 offset:8192
	v_add_u32_e32 v160, 16, v216
	v_ashrrev_i32_e32 v217, 31, v216
	v_ashrrev_i32_e32 v161, 31, v160
	v_lshlrev_b64 v[156:157], 10, v[216:217]
	v_lshl_add_u64 v[164:165], v[156:157], 0, v[212:213]
	v_lshlrev_b64 v[160:161], 10, v[160:161]
	v_cvt_pk_bf16_f32 v156, v124, v125
	v_cvt_pk_bf16_f32 v157, v126, v127
	v_cvt_pk_bf16_f32 v158, v120, v121
	v_cvt_pk_bf16_f32 v159, v122, v123
	v_lshlrev_b64 v[164:165], 1, v[164:165]
	v_lshl_add_u64 v[160:161], v[160:161], 0, v[212:213]
	v_lshl_add_u64 v[166:167], s[84:85], 0, v[164:165]
	v_lshl_add_u64 v[164:165], s[80:81], 0, v[164:165]
	v_lshlrev_b64 v[160:161], 1, v[160:161]
	global_store_dwordx4 v[166:167], v[156:159], off nt
	v_add_u32_e32 v154, 32, v216
	v_ashrrev_i32_e32 v155, 31, v154
	v_lshl_add_u64 v[156:157], s[84:85], 0, v[160:161]
	v_lshl_add_u64 v[158:159], s[80:81], 0, v[160:161]
	v_add_u32_e32 v152, 48, v216
	v_ashrrev_i32_e32 v153, 31, v152
	s_waitcnt vmcnt(3)
	v_pk_mul_f32 v[122:123], v[122:123], v[138:139]
	v_pk_mul_f32 v[120:121], v[120:121], v[136:137]
	v_pk_mul_f32 v[126:127], v[126:127], v[142:143]
	v_pk_mul_f32 v[124:125], v[124:125], v[140:141]
	s_waitcnt lgkmcnt(0)
	v_pk_mul_f32 v[186:187], v[122:123], v[162:163] op_sel_hi:[1,0]
	v_pk_mul_f32 v[122:123], v[120:121], v[162:163] op_sel_hi:[1,0]
	s_waitcnt vmcnt(2)
	v_pk_mul_f32 v[160:161], v[106:107], v[134:135]
	v_pk_mul_f32 v[168:169], v[104:105], v[132:133]
	s_waitcnt vmcnt(1)
	v_pk_mul_f32 v[170:171], v[118:119], v[130:131]
	v_pk_mul_f32 v[172:173], v[116:117], v[128:129]
	v_pk_mul_f32 v[126:127], v[126:127], v[162:163] op_sel_hi:[1,0]
	v_pk_mul_f32 v[124:125], v[124:125], v[162:163] op_sel_hi:[1,0]
	v_pk_mul_f32 v[160:161], v[160:161], v[162:163] op_sel_hi:[1,0]
	v_cvt_pk_bf16_f32 v120, v124, v125
	v_cvt_pk_bf16_f32 v121, v126, v127
	v_cvt_pk_bf16_f32 v122, v122, v123
	v_cvt_pk_bf16_f32 v123, v186, v187
	global_store_dwordx4 v[164:165], v[120:123], off sc1
	v_cvt_pk_bf16_f32 v104, v104, v105
	v_cvt_pk_bf16_f32 v105, v106, v107
	v_cvt_pk_bf16_f32 v106, v116, v117
	v_cvt_pk_bf16_f32 v107, v118, v119
	v_pk_mul_f32 v[168:169], v[168:169], v[162:163] op_sel_hi:[1,0]
	v_pk_mul_f32 v[170:171], v[170:171], v[162:163] op_sel_hi:[1,0]
	v_pk_mul_f32 v[162:163], v[172:173], v[162:163] op_sel_hi:[1,0]
	global_store_dwordx4 v[166:167], v[104:107], off offset:256 nt
	v_pk_mul_f32 v[174:175], v[110:111], v[142:143]
	v_pk_mul_f32 v[176:177], v[108:109], v[140:141]
	v_cvt_pk_bf16_f32 v104, v168, v169
	v_cvt_pk_bf16_f32 v105, v160, v161
	v_cvt_pk_bf16_f32 v106, v162, v163
	v_cvt_pk_bf16_f32 v107, v170, v171
	global_store_dwordx4 v[164:165], v[104:107], off offset:256 sc1
	ds_read_b32 v116, v211 offset:8256
	v_pk_mul_f32 v[178:179], v[114:115], v[138:139]
	v_cvt_pk_bf16_f32 v104, v108, v109
	v_cvt_pk_bf16_f32 v105, v110, v111
	v_cvt_pk_bf16_f32 v106, v112, v113
	v_cvt_pk_bf16_f32 v107, v114, v115
	v_pk_mul_f32 v[180:181], v[112:113], v[136:137]
	global_store_dwordx4 v[156:157], v[104:107], off nt
	v_pk_mul_f32 v[182:183], v[102:103], v[134:135]
	v_pk_mul_f32 v[184:185], v[100:101], v[132:133]
	s_waitcnt lgkmcnt(0)
	v_pk_mul_f32 v[106:107], v[174:175], v[116:117] op_sel_hi:[1,0]
	v_pk_mul_f32 v[104:105], v[176:177], v[116:117] op_sel_hi:[1,0]
	v_pk_mul_f32 v[108:109], v[178:179], v[116:117] op_sel_hi:[1,0]
	v_pk_mul_f32 v[110:111], v[180:181], v[116:117] op_sel_hi:[1,0]
	v_cvt_pk_bf16_f32 v104, v104, v105
	v_cvt_pk_bf16_f32 v105, v106, v107
	v_pk_mul_f32 v[112:113], v[182:183], v[116:117] op_sel_hi:[1,0]
	v_cvt_pk_bf16_f32 v106, v110, v111
	v_cvt_pk_bf16_f32 v107, v108, v109
	global_store_dwordx4 v[158:159], v[104:107], off sc1
	v_cvt_pk_bf16_f32 v100, v100, v101
	v_cvt_pk_bf16_f32 v101, v102, v103
	v_cvt_pk_bf16_f32 v102, v96, v97
	v_cvt_pk_bf16_f32 v103, v98, v99
	v_pk_mul_f32 v[98:99], v[98:99], v[130:131]
	v_pk_mul_f32 v[96:97], v[96:97], v[128:129]
	global_store_dwordx4 v[156:157], v[100:103], off offset:256 nt
	s_nop 1
	v_pk_mul_f32 v[102:103], v[98:99], v[116:117] op_sel_hi:[1,0]
	v_pk_mul_f32 v[98:99], v[96:97], v[116:117] op_sel_hi:[1,0]
	v_pk_mul_f32 v[100:101], v[184:185], v[116:117] op_sel_hi:[1,0]
	s_nop 0
	v_cvt_pk_bf16_f32 v96, v100, v101
	v_cvt_pk_bf16_f32 v97, v112, v113
	v_cvt_pk_bf16_f32 v98, v98, v99
	v_cvt_pk_bf16_f32 v99, v102, v103
	global_store_dwordx4 v[158:159], v[96:99], off offset:256 sc1
	ds_read_b32 v100, v211 offset:8320
	s_nop 0
	v_lshlrev_b64 v[96:97], 10, v[154:155]
	v_lshl_add_u64 v[102:103], v[96:97], 0, v[212:213]
	v_lshlrev_b64 v[102:103], 1, v[102:103]
	v_cvt_pk_bf16_f32 v96, v92, v93
	v_cvt_pk_bf16_f32 v97, v94, v95
	v_cvt_pk_bf16_f32 v98, v88, v89
	v_cvt_pk_bf16_f32 v99, v90, v91
	v_lshl_add_u64 v[104:105], s[84:85], 0, v[102:103]
	v_pk_mul_f32 v[92:93], v[92:93], v[140:141]
	v_pk_mul_f32 v[90:91], v[90:91], v[138:139]
	v_pk_mul_f32 v[88:89], v[88:89], v[136:137]
	global_store_dwordx4 v[104:105], v[96:99], off nt
	v_pk_mul_f32 v[94:95], v[94:95], v[142:143]
	s_waitcnt lgkmcnt(0)
; __device__ __forceinline__ u32x4 pack_bf8(f32x4 a, f32x4 b) { u32x4 w; w.x = cvt_pk_bf16(a[0], a[1]); w.y = cvt_pk_bf16(a[2], a[3]); w.z = cvt_pk_bf16(b[0], b[1]); w.w = cvt_pk_bf16(b[2], b[3]); return w; }
;     __device__ __forceinline__ void fused(f32x4 (&acc)[2][2][4][2], const Unit& u, int wr, int wc, int fr, int fq, PG8_LAS unsigned char* lds, int wid, int lane) const {
;     ...
;         for (int ai = 0; ai < 2; ++ai)
; #pragma unroll
;             for (int m = 0; m < 4; ++m) { const int r = ai * HALF + wr * 64 + m * 16 + fr; const float rs = S[r]; const size_t off = (size_t)(u.pm * BM + r) * ldc + col0;
; #pragma unroll
;                 for (int bj = 0; bj < 2; ++bj) { const f32x4 x0 = acc[ai][bj][m][0], x1 = acc[ai][bj][m][1];
;                     __builtin_nontemporal_store(pack_bf8(x0, x1), (u32x4*)(out + off + bj * HALF));
;                     *(u32x4*)(xn + off + bj * HALF) = pack_bf8(x0 * gv[bj][0] * rs, x1 * gv[bj][1] * rs); }
;                 asm volatile("" ::: "memory"); }
	v_pk_mul_f32 v[92:93], v[92:93], v[100:101] op_sel_hi:[1,0]
	v_pk_mul_f32 v[96:97], v[90:91], v[100:101] op_sel_hi:[1,0]
	v_pk_mul_f32 v[90:91], v[88:89], v[100:101] op_sel_hi:[1,0]
	v_pk_mul_f32 v[94:95], v[94:95], v[100:101] op_sel_hi:[1,0]
	v_cvt_pk_bf16_f32 v88, v92, v93
	v_lshl_add_u64 v[92:93], s[80:81], 0, v[102:103]
	v_cvt_pk_bf16_f32 v89, v94, v95
	v_cvt_pk_bf16_f32 v90, v90, v91
	v_cvt_pk_bf16_f32 v91, v96, v97
	global_store_dwordx4 v[92:93], v[88:91], off sc1
	s_nop 1
	v_cvt_pk_bf16_f32 v88, v84, v85
	v_cvt_pk_bf16_f32 v89, v86, v87
	v_cvt_pk_bf16_f32 v90, v80, v81
	v_cvt_pk_bf16_f32 v91, v82, v83
	v_pk_mul_f32 v[82:83], v[82:83], v[130:131]
	v_pk_mul_f32 v[80:81], v[80:81], v[128:129]
	global_store_dwordx4 v[104:105], v[88:91], off offset:256 nt
	v_pk_mul_f32 v[86:87], v[86:87], v[134:135]
	v_pk_mul_f32 v[84:85], v[84:85], v[132:133]
	v_pk_mul_f32 v[88:89], v[82:83], v[100:101] op_sel_hi:[1,0]
	v_pk_mul_f32 v[82:83], v[80:81], v[100:101] op_sel_hi:[1,0]
	v_pk_mul_f32 v[86:87], v[86:87], v[100:101] op_sel_hi:[1,0]
	v_pk_mul_f32 v[84:85], v[84:85], v[100:101] op_sel_hi:[1,0]
	s_nop 0
	v_cvt_pk_bf16_f32 v80, v84, v85
	v_cvt_pk_bf16_f32 v81, v86, v87
	v_cvt_pk_bf16_f32 v82, v82, v83
	v_cvt_pk_bf16_f32 v83, v88, v89
	global_store_dwordx4 v[92:93], v[80:83], off offset:256 sc1
	ds_read_b32 v84, v211 offset:8384
	s_nop 0
	v_lshlrev_b64 v[80:81], 10, v[152:153]
	v_lshl_add_u64 v[86:87], v[80:81], 0, v[212:213]
	v_lshlrev_b64 v[86:87], 1, v[86:87]
	v_cvt_pk_bf16_f32 v80, v76, v77
	v_cvt_pk_bf16_f32 v81, v78, v79
	v_cvt_pk_bf16_f32 v82, v72, v73
	v_cvt_pk_bf16_f32 v83, v74, v75
	v_lshl_add_u64 v[88:89], s[84:85], 0, v[86:87]
	v_pk_mul_f32 v[76:77], v[76:77], v[140:141]
	v_pk_mul_f32 v[74:75], v[74:75], v[138:139]
	v_pk_mul_f32 v[72:73], v[72:73], v[136:137]
	global_store_dwordx4 v[88:89], v[80:83], off nt
	v_pk_mul_f32 v[78:79], v[78:79], v[142:143]
	s_waitcnt lgkmcnt(0)
	v_pk_mul_f32 v[76:77], v[76:77], v[84:85] op_sel_hi:[1,0]
	v_pk_mul_f32 v[80:81], v[74:75], v[84:85] op_sel_hi:[1,0]
	v_pk_mul_f32 v[74:75], v[72:73], v[84:85] op_sel_hi:[1,0]
	v_pk_mul_f32 v[78:79], v[78:79], v[84:85] op_sel_hi:[1,0]
	v_cvt_pk_bf16_f32 v72, v76, v77
	v_lshl_add_u64 v[76:77], s[80:81], 0, v[86:87]
	v_cvt_pk_bf16_f32 v73, v78, v79
	v_cvt_pk_bf16_f32 v74, v74, v75
	v_cvt_pk_bf16_f32 v75, v80, v81
	global_store_dwordx4 v[76:77], v[72:75], off sc1
	s_nop 1
	v_cvt_pk_bf16_f32 v72, v68, v69
	v_cvt_pk_bf16_f32 v73, v70, v71
	v_cvt_pk_bf16_f32 v74, v64, v65
	v_cvt_pk_bf16_f32 v75, v66, v67
	v_pk_mul_f32 v[66:67], v[66:67], v[130:131]
	v_pk_mul_f32 v[64:65], v[64:65], v[128:129]
	global_store_dwordx4 v[88:89], v[72:75], off offset:256 nt
	v_pk_mul_f32 v[70:71], v[70:71], v[134:135]
	v_pk_mul_f32 v[68:69], v[68:69], v[132:133]
	v_pk_mul_f32 v[72:73], v[66:67], v[84:85] op_sel_hi:[1,0]
	v_pk_mul_f32 v[66:67], v[64:65], v[84:85] op_sel_hi:[1,0]
	v_pk_mul_f32 v[70:71], v[70:71], v[84:85] op_sel_hi:[1,0]
	v_pk_mul_f32 v[68:69], v[68:69], v[84:85] op_sel_hi:[1,0]
	s_nop 0
	v_cvt_pk_bf16_f32 v64, v68, v69
	v_cvt_pk_bf16_f32 v65, v70, v71
	v_cvt_pk_bf16_f32 v66, v66, v67
	v_cvt_pk_bf16_f32 v67, v72, v73
	global_store_dwordx4 v[76:77], v[64:67], off offset:256 sc1
	ds_read_b32 v68, v211 offset:8704
	v_lshl_add_u64 v[70:71], v[150:151], 0, v[212:213]
	v_lshlrev_b64 v[70:71], 1, v[70:71]
	v_cvt_pk_bf16_f32 v64, v60, v61
	v_cvt_pk_bf16_f32 v65, v62, v63
	v_cvt_pk_bf16_f32 v66, v56, v57
	v_cvt_pk_bf16_f32 v67, v58, v59
	v_lshl_add_u64 v[72:73], s[84:85], 0, v[70:71]
	v_pk_mul_f32 v[60:61], v[60:61], v[140:141]
	v_pk_mul_f32 v[58:59], v[58:59], v[138:139]
	v_pk_mul_f32 v[56:57], v[56:57], v[136:137]
	global_store_dwordx4 v[72:73], v[64:67], off nt
	v_pk_mul_f32 v[62:63], v[62:63], v[142:143]
	s_waitcnt lgkmcnt(0)
	v_pk_mul_f32 v[60:61], v[60:61], v[68:69] op_sel_hi:[1,0]
	v_pk_mul_f32 v[64:65], v[58:59], v[68:69] op_sel_hi:[1,0]
	v_pk_mul_f32 v[58:59], v[56:57], v[68:69] op_sel_hi:[1,0]
	v_pk_mul_f32 v[62:63], v[62:63], v[68:69] op_sel_hi:[1,0]
	v_cvt_pk_bf16_f32 v56, v60, v61
	v_lshl_add_u64 v[60:61], s[80:81], 0, v[70:71]
	v_cvt_pk_bf16_f32 v57, v62, v63
	v_cvt_pk_bf16_f32 v58, v58, v59
	v_cvt_pk_bf16_f32 v59, v64, v65
	global_store_dwordx4 v[60:61], v[56:59], off sc1
	s_nop 1
	v_cvt_pk_bf16_f32 v56, v52, v53
	v_cvt_pk_bf16_f32 v57, v54, v55
	v_cvt_pk_bf16_f32 v58, v48, v49
	v_cvt_pk_bf16_f32 v59, v50, v51
	v_pk_mul_f32 v[50:51], v[50:51], v[130:131]
	v_pk_mul_f32 v[48:49], v[48:49], v[128:129]
	global_store_dwordx4 v[72:73], v[56:59], off offset:256 nt
	v_pk_mul_f32 v[54:55], v[54:55], v[134:135]
	v_pk_mul_f32 v[52:53], v[52:53], v[132:133]
	v_pk_mul_f32 v[56:57], v[50:51], v[68:69] op_sel_hi:[1,0]
	v_pk_mul_f32 v[50:51], v[48:49], v[68:69] op_sel_hi:[1,0]
	v_pk_mul_f32 v[54:55], v[54:55], v[68:69] op_sel_hi:[1,0]
	v_pk_mul_f32 v[52:53], v[52:53], v[68:69] op_sel_hi:[1,0]
	s_nop 0
	v_cvt_pk_bf16_f32 v48, v52, v53
	v_cvt_pk_bf16_f32 v49, v54, v55
	v_cvt_pk_bf16_f32 v50, v50, v51
	v_cvt_pk_bf16_f32 v51, v56, v57
	global_store_dwordx4 v[60:61], v[48:51], off offset:256 sc1
	ds_read_b32 v52, v211 offset:8768
	v_lshl_add_u64 v[54:55], v[148:149], 0, v[212:213]
	v_lshlrev_b64 v[54:55], 1, v[54:55]
	v_cvt_pk_bf16_f32 v48, v44, v45
	v_cvt_pk_bf16_f32 v49, v46, v47
	v_cvt_pk_bf16_f32 v50, v40, v41
	v_cvt_pk_bf16_f32 v51, v42, v43
	v_lshl_add_u64 v[56:57], s[84:85], 0, v[54:55]
	v_pk_mul_f32 v[44:45], v[44:45], v[140:141]
	v_pk_mul_f32 v[42:43], v[42:43], v[138:139]
	v_pk_mul_f32 v[40:41], v[40:41], v[136:137]
	global_store_dwordx4 v[56:57], v[48:51], off nt
	v_pk_mul_f32 v[46:47], v[46:47], v[142:143]
	s_waitcnt lgkmcnt(0)
; __device__ __forceinline__ u32x4 pack_bf8(f32x4 a, f32x4 b) { u32x4 w; w.x = cvt_pk_bf16(a[0], a[1]); w.y = cvt_pk_bf16(a[2], a[3]); w.z = cvt_pk_bf16(b[0], b[1]); w.w = cvt_pk_bf16(b[2], b[3]); return w; }
;     __device__ __forceinline__ void fused(f32x4 (&acc)[2][2][4][2], const Unit& u, int wr, int wc, int fr, int fq, PG8_LAS unsigned char* lds, int wid, int lane) const {
;     ...
;         for (int ai = 0; ai < 2; ++ai)
; #pragma unroll
;             for (int m = 0; m < 4; ++m) { const int r = ai * HALF + wr * 64 + m * 16 + fr; const float rs = S[r]; const size_t off = (size_t)(u.pm * BM + r) * ldc + col0;
; #pragma unroll
;                 for (int bj = 0; bj < 2; ++bj) { const f32x4 x0 = acc[ai][bj][m][0], x1 = acc[ai][bj][m][1];
;                     __builtin_nontemporal_store(pack_bf8(x0, x1), (u32x4*)(out + off + bj * HALF));
;                     *(u32x4*)(xn + off + bj * HALF) = pack_bf8(x0 * gv[bj][0] * rs, x1 * gv[bj][1] * rs); }
;                 asm volatile("" ::: "memory"); }
	v_pk_mul_f32 v[44:45], v[44:45], v[52:53] op_sel_hi:[1,0]
	v_pk_mul_f32 v[48:49], v[42:43], v[52:53] op_sel_hi:[1,0]
	v_pk_mul_f32 v[42:43], v[40:41], v[52:53] op_sel_hi:[1,0]
	v_pk_mul_f32 v[46:47], v[46:47], v[52:53] op_sel_hi:[1,0]
	v_cvt_pk_bf16_f32 v40, v44, v45
	v_lshl_add_u64 v[44:45], s[80:81], 0, v[54:55]
	v_cvt_pk_bf16_f32 v41, v46, v47
	v_cvt_pk_bf16_f32 v42, v42, v43
	v_cvt_pk_bf16_f32 v43, v48, v49
	global_store_dwordx4 v[44:45], v[40:43], off sc1
	s_nop 1
	v_cvt_pk_bf16_f32 v40, v36, v37
	v_cvt_pk_bf16_f32 v41, v38, v39
	v_cvt_pk_bf16_f32 v42, v32, v33
	v_cvt_pk_bf16_f32 v43, v34, v35
	v_pk_mul_f32 v[34:35], v[34:35], v[130:131]
	v_pk_mul_f32 v[32:33], v[32:33], v[128:129]
	global_store_dwordx4 v[56:57], v[40:43], off offset:256 nt
	v_pk_mul_f32 v[38:39], v[38:39], v[134:135]
	v_pk_mul_f32 v[36:37], v[36:37], v[132:133]
	v_pk_mul_f32 v[40:41], v[34:35], v[52:53] op_sel_hi:[1,0]
	v_pk_mul_f32 v[34:35], v[32:33], v[52:53] op_sel_hi:[1,0]
	v_pk_mul_f32 v[38:39], v[38:39], v[52:53] op_sel_hi:[1,0]
	v_pk_mul_f32 v[36:37], v[36:37], v[52:53] op_sel_hi:[1,0]
	s_nop 0
	v_cvt_pk_bf16_f32 v32, v36, v37
	v_cvt_pk_bf16_f32 v33, v38, v39
	v_cvt_pk_bf16_f32 v34, v34, v35
	v_cvt_pk_bf16_f32 v35, v40, v41
	global_store_dwordx4 v[44:45], v[32:35], off offset:256 sc1
	ds_read_b32 v36, v211 offset:8832
	v_lshl_add_u64 v[38:39], v[146:147], 0, v[212:213]
	v_lshlrev_b64 v[38:39], 1, v[38:39]
	v_cvt_pk_bf16_f32 v32, v28, v29
	v_cvt_pk_bf16_f32 v33, v30, v31
	v_cvt_pk_bf16_f32 v34, v24, v25
	v_cvt_pk_bf16_f32 v35, v26, v27
	v_lshl_add_u64 v[40:41], s[84:85], 0, v[38:39]
	v_pk_mul_f32 v[28:29], v[28:29], v[140:141]
	v_pk_mul_f32 v[26:27], v[26:27], v[138:139]
	v_pk_mul_f32 v[24:25], v[24:25], v[136:137]
	global_store_dwordx4 v[40:41], v[32:35], off nt
	v_pk_mul_f32 v[30:31], v[30:31], v[142:143]
	s_waitcnt lgkmcnt(0)
	v_pk_mul_f32 v[28:29], v[28:29], v[36:37] op_sel_hi:[1,0]
	v_pk_mul_f32 v[32:33], v[26:27], v[36:37] op_sel_hi:[1,0]
	v_pk_mul_f32 v[26:27], v[24:25], v[36:37] op_sel_hi:[1,0]
	v_pk_mul_f32 v[30:31], v[30:31], v[36:37] op_sel_hi:[1,0]
	v_cvt_pk_bf16_f32 v24, v28, v29
	v_lshl_add_u64 v[28:29], s[80:81], 0, v[38:39]
	v_cvt_pk_bf16_f32 v25, v30, v31
	v_cvt_pk_bf16_f32 v26, v26, v27
	v_cvt_pk_bf16_f32 v27, v32, v33
	global_store_dwordx4 v[28:29], v[24:27], off sc1
	s_nop 1
	v_cvt_pk_bf16_f32 v24, v20, v21
	v_cvt_pk_bf16_f32 v25, v22, v23
	v_cvt_pk_bf16_f32 v26, v16, v17
	v_cvt_pk_bf16_f32 v27, v18, v19
	v_pk_mul_f32 v[18:19], v[18:19], v[130:131]
	v_pk_mul_f32 v[16:17], v[16:17], v[128:129]
	global_store_dwordx4 v[40:41], v[24:27], off offset:256 nt
	v_pk_mul_f32 v[22:23], v[22:23], v[134:135]
	v_pk_mul_f32 v[20:21], v[20:21], v[132:133]
	v_pk_mul_f32 v[24:25], v[18:19], v[36:37] op_sel_hi:[1,0]
	v_pk_mul_f32 v[18:19], v[16:17], v[36:37] op_sel_hi:[1,0]
	v_pk_mul_f32 v[22:23], v[22:23], v[36:37] op_sel_hi:[1,0]
	v_pk_mul_f32 v[20:21], v[20:21], v[36:37] op_sel_hi:[1,0]
	s_nop 0
	v_cvt_pk_bf16_f32 v16, v20, v21
	v_cvt_pk_bf16_f32 v17, v22, v23
	v_cvt_pk_bf16_f32 v18, v18, v19
	v_cvt_pk_bf16_f32 v19, v24, v25
	global_store_dwordx4 v[28:29], v[16:19], off offset:256 sc1
	ds_read_b32 v20, v211 offset:8896
	v_lshl_add_u64 v[22:23], v[144:145], 0, v[212:213]
	v_lshlrev_b64 v[22:23], 1, v[22:23]
	v_cvt_pk_bf16_f32 v16, v12, v13
	v_cvt_pk_bf16_f32 v17, v14, v15
	v_cvt_pk_bf16_f32 v18, v8, v9
	v_cvt_pk_bf16_f32 v19, v10, v11
	v_lshl_add_u64 v[24:25], s[84:85], 0, v[22:23]
	v_pk_mul_f32 v[12:13], v[12:13], v[140:141]
	v_pk_mul_f32 v[10:11], v[10:11], v[138:139]
	v_pk_mul_f32 v[8:9], v[8:9], v[136:137]
	global_store_dwordx4 v[24:25], v[16:19], off nt
	v_pk_mul_f32 v[14:15], v[14:15], v[142:143]
	s_waitcnt lgkmcnt(0)
	v_pk_mul_f32 v[12:13], v[12:13], v[20:21] op_sel_hi:[1,0]
	v_pk_mul_f32 v[16:17], v[10:11], v[20:21] op_sel_hi:[1,0]
	v_pk_mul_f32 v[10:11], v[8:9], v[20:21] op_sel_hi:[1,0]
	v_pk_mul_f32 v[14:15], v[14:15], v[20:21] op_sel_hi:[1,0]
	v_cvt_pk_bf16_f32 v8, v12, v13
	v_lshl_add_u64 v[12:13], s[80:81], 0, v[22:23]
	v_cvt_pk_bf16_f32 v9, v14, v15
	v_cvt_pk_bf16_f32 v10, v10, v11
	v_cvt_pk_bf16_f32 v11, v16, v17
	global_store_dwordx4 v[12:13], v[8:11], off sc1
	s_nop 1
	v_cvt_pk_bf16_f32 v8, v4, v5
	v_cvt_pk_bf16_f32 v9, v6, v7
	v_cvt_pk_bf16_f32 v10, v0, v1
	v_cvt_pk_bf16_f32 v11, v2, v3
	v_pk_mul_f32 v[2:3], v[2:3], v[130:131]
	v_pk_mul_f32 v[0:1], v[0:1], v[128:129]
	global_store_dwordx4 v[24:25], v[8:11], off offset:256 nt
	v_pk_mul_f32 v[6:7], v[6:7], v[134:135]
	v_pk_mul_f32 v[4:5], v[4:5], v[132:133]
	v_pk_mul_f32 v[8:9], v[2:3], v[20:21] op_sel_hi:[1,0]
	v_pk_mul_f32 v[2:3], v[0:1], v[20:21] op_sel_hi:[1,0]
	v_pk_mul_f32 v[6:7], v[6:7], v[20:21] op_sel_hi:[1,0]
	v_pk_mul_f32 v[4:5], v[4:5], v[20:21] op_sel_hi:[1,0]
	s_nop 0
	v_cvt_pk_bf16_f32 v0, v4, v5
	v_cvt_pk_bf16_f32 v1, v6, v7
	v_cvt_pk_bf16_f32 v2, v2, v3
	v_cvt_pk_bf16_f32 v3, v8, v9
	global_store_dwordx4 v[12:13], v[0:3], off offset:256 sc1

; __device__ __forceinline__ unsigned cvt_pk_bf16(float lo, float hi) { unsigned r; asm volatile("v_cvt_pk_bf16_f32 %0, %1, %2" : "=v"(r) : "v"(lo), "v"(hi)); return r; }
;     __device__ __forceinline__ void operator()(const f32x4 (&acc)[2][2][4][2], const Unit& u, int wr, int wc, int fr, int fq) const {
;         const int row0 = u.pm * BM + wr * 64 + fr; const bool first = u.pn < 8;
;         bf16_t* base = first ? O0 : O1; const int ldc = first ? ld0 : ld1; const int col0 = (first ? u.pn : u.pn - 8) * BM + wc * 32 + 8 * fq;
; #pragma unroll
;         for (int ai = 0; ai < 2; ++ai)
; #pragma unroll
;             for (int m = 0; m < 4; ++m) { bf16_t* rowp = base + (size_t)(row0 + ai * HALF + m * 16) * ldc + col0;
; #pragma unroll
;                 for (int bj = 0; bj < 2; ++bj) { const f32x4 v0 = acc[ai][bj][m][0], v1 = acc[ai][bj][m][1];
;                     u32x4 w; w.x = cvt_pk_bf16(v0[0], v0[1]); w.y = cvt_pk_bf16(v0[2], v0[3]); w.z = cvt_pk_bf16(v1[0], v1[1]); w.w = cvt_pk_bf16(v1[2], v1[3]);
;                     *(u32x4*)(rowp + bj * HALF) = w; } }
.LBB0_885:
	s_lshl_b32 s13, s42, 8
	v_lshl_add_u32 v154, s16, 8, v146
	s_add_i32 s16, s13, 0xfffff800
	s_cmp_lt_i32 s42, 8
	v_readlane_b32 s20, v254, 15
	v_readlane_b32 s21, v254, 16
	s_cselect_b32 s13, s13, s16
	s_cselect_b32 s9, s21, s35
	s_cselect_b32 s20, s20, s34
	v_add_u32_e32 v152, s13, v148
	v_mov_b32_e32 v144, s20
	v_mov_b32_e32 v145, s9
	s_cselect_b32 s9, s41, 0x600
	v_ashrrev_i32_e32 v153, 31, v152
	v_lshl_add_u64 v[144:145], v[152:153], 1, v[144:145]
	v_mad_i64_i32 v[152:153], s[20:21], s9, v154, 0
	v_lshl_add_u64 v[152:153], v[152:153], 1, v[144:145]
	v_cvt_pk_bf16_f32 v124, v124, v125
	v_cvt_pk_bf16_f32 v125, v126, v127
	v_cvt_pk_bf16_f32 v126, v120, v121
	v_cvt_pk_bf16_f32 v127, v122, v123
	global_store_dwordx4 v[152:153], v[124:127], off sc1
	v_cvt_pk_bf16_f32 v112, v112, v113
	v_cvt_pk_bf16_f32 v113, v114, v115
	v_cvt_pk_bf16_f32 v114, v104, v105
	v_or_b32_e32 v104, 16, v154
	v_mad_i64_i32 v[104:105], s[20:21], s9, v104, 0
	v_cvt_pk_bf16_f32 v115, v106, v107
	global_store_dwordx4 v[152:153], v[112:115], off offset:256 sc1
	s_andn2_b64 vcc, exec, s[4:5]
	s_mov_b64 s[4:5], -1
	v_lshl_add_u64 v[112:113], v[104:105], 1, v[144:145]
	v_cvt_pk_bf16_f32 v104, v116, v117
	v_cvt_pk_bf16_f32 v105, v118, v119
	v_cvt_pk_bf16_f32 v106, v108, v109
	v_cvt_pk_bf16_f32 v107, v110, v111
	global_store_dwordx4 v[112:113], v[104:107], off sc1
	v_cvt_pk_bf16_f32 v96, v96, v97
	v_cvt_pk_bf16_f32 v97, v98, v99
	v_cvt_pk_bf16_f32 v98, v88, v89
	v_or_b32_e32 v88, 32, v154
	v_mad_i64_i32 v[88:89], s[20:21], s9, v88, 0
	v_cvt_pk_bf16_f32 v99, v90, v91
	global_store_dwordx4 v[112:113], v[96:99], off offset:256 sc1
	s_nop 1
	v_lshl_add_u64 v[96:97], v[88:89], 1, v[144:145]
	v_cvt_pk_bf16_f32 v88, v100, v101
	v_cvt_pk_bf16_f32 v89, v102, v103
	v_cvt_pk_bf16_f32 v90, v92, v93
	v_cvt_pk_bf16_f32 v91, v94, v95
	global_store_dwordx4 v[96:97], v[88:91], off sc1
	v_cvt_pk_bf16_f32 v80, v80, v81
	v_cvt_pk_bf16_f32 v81, v82, v83
	v_cvt_pk_bf16_f32 v82, v72, v73
	v_or_b32_e32 v72, 48, v154
	v_mad_i64_i32 v[72:73], s[20:21], s9, v72, 0
	v_cvt_pk_bf16_f32 v83, v74, v75
	global_store_dwordx4 v[96:97], v[80:83], off offset:256 sc1
	s_nop 1
	v_lshl_add_u64 v[80:81], v[72:73], 1, v[144:145]
	v_cvt_pk_bf16_f32 v72, v84, v85
	v_cvt_pk_bf16_f32 v73, v86, v87
	v_cvt_pk_bf16_f32 v74, v76, v77
	v_cvt_pk_bf16_f32 v75, v78, v79
	global_store_dwordx4 v[80:81], v[72:75], off sc1
	v_cvt_pk_bf16_f32 v68, v68, v69
	v_cvt_pk_bf16_f32 v69, v70, v71
	v_cvt_pk_bf16_f32 v70, v64, v65
	v_add_u32_e32 v64, 0x80, v154
	v_mad_i64_i32 v[64:65], s[20:21], s9, v64, 0
	v_lshl_add_u64 v[64:65], v[64:65], 1, v[144:145]
	v_cvt_pk_bf16_f32 v71, v66, v67
	global_store_dwordx4 v[80:81], v[68:71], off offset:256 sc1
	v_cvt_pk_bf16_f32 v60, v60, v61
	v_cvt_pk_bf16_f32 v61, v62, v63
	v_cvt_pk_bf16_f32 v62, v56, v57
	v_cvt_pk_bf16_f32 v63, v58, v59
	global_store_dwordx4 v[64:65], v[60:63], off sc1
	v_cvt_pk_bf16_f32 v48, v48, v49
	v_cvt_pk_bf16_f32 v49, v50, v51
	v_cvt_pk_bf16_f32 v50, v40, v41
	v_add_u32_e32 v40, 0x90, v154
	v_mad_i64_i32 v[40:41], s[20:21], s9, v40, 0
	v_cvt_pk_bf16_f32 v51, v42, v43
	global_store_dwordx4 v[64:65], v[48:51], off offset:256 sc1
	s_nop 1
	v_lshl_add_u64 v[48:49], v[40:41], 1, v[144:145]
	v_cvt_pk_bf16_f32 v40, v52, v53
	v_cvt_pk_bf16_f32 v41, v54, v55
	v_cvt_pk_bf16_f32 v42, v44, v45
	v_cvt_pk_bf16_f32 v43, v46, v47
	global_store_dwordx4 v[48:49], v[40:43], off sc1
	v_cvt_pk_bf16_f32 v32, v32, v33
	v_cvt_pk_bf16_f32 v33, v34, v35
	v_cvt_pk_bf16_f32 v34, v24, v25
	v_add_u32_e32 v24, 0xa0, v154
	v_mad_i64_i32 v[24:25], s[20:21], s9, v24, 0
	v_cvt_pk_bf16_f32 v35, v26, v27
	global_store_dwordx4 v[48:49], v[32:35], off offset:256 sc1
	s_nop 1
	v_lshl_add_u64 v[32:33], v[24:25], 1, v[144:145]
	v_cvt_pk_bf16_f32 v24, v36, v37
	v_cvt_pk_bf16_f32 v25, v38, v39
	v_cvt_pk_bf16_f32 v26, v28, v29
	v_cvt_pk_bf16_f32 v27, v30, v31
	global_store_dwordx4 v[32:33], v[24:27], off sc1
	v_cvt_pk_bf16_f32 v16, v16, v17
	v_cvt_pk_bf16_f32 v17, v18, v19
	v_cvt_pk_bf16_f32 v18, v8, v9
	v_add_u32_e32 v8, 0xb0, v154
	v_mad_i64_i32 v[8:9], s[20:21], s9, v8, 0
	v_cvt_pk_bf16_f32 v19, v10, v11
	global_store_dwordx4 v[32:33], v[16:19], off offset:256 sc1
	s_nop 1
	v_lshl_add_u64 v[16:17], v[8:9], 1, v[144:145]
	v_cvt_pk_bf16_f32 v8, v20, v21
	v_cvt_pk_bf16_f32 v9, v22, v23
	v_cvt_pk_bf16_f32 v10, v12, v13
	v_cvt_pk_bf16_f32 v11, v14, v15
	global_store_dwordx4 v[16:17], v[8:11], off sc1
	v_cvt_pk_bf16_f32 v4, v4, v5
	v_cvt_pk_bf16_f32 v5, v6, v7
	v_cvt_pk_bf16_f32 v6, v0, v1
	v_cvt_pk_bf16_f32 v7, v2, v3
	global_store_dwordx4 v[16:17], v[4:7], off offset:256 sc1
	s_cbranch_vccnz .LBB0_878
	s_andn2_b64 vcc, exec, s[0:1]
	s_cbranch_vccnz .LBB0_877
	s_barrier
	s_branch .LBB0_877

; #define GAS __attribute__((address_space(1)))
; #define LAS __attribute__((address_space(3)))
; __device__ __forceinline__ unsigned pk2(float lo, float hi) { f32x2_k v = {lo, hi}; bf16x2_k b = __builtin_convertvector(v, bf16x2_k); return __builtin_bit_cast(unsigned, b); }
; __device__ __forceinline__ void p0_finish(const P0Job& j, const f32x4 (&v)[16], LAS float* scr, int lane) {
;     ...
;     for (int hb = 0; hb < 2; ++hb) { const int drow0 = p0_drow(j.kind, n0 + 32 * hb);
;         if (n0 + 32 * hb < j.N && k0 + 8 * c < j.K) {
; #pragma unroll
;             for (int jj = 0; jj < 4; ++jj) { const int n = (lane >> 3) + 8 * jj; const LAS float* sp = scr + (8 * c) * 65 + 32 * hb + n;
;                 v4u o; o.x = pk2(sp[0 * 65], sp[1 * 65]); o.y = pk2(sp[2 * 65], sp[3 * 65]); o.z = pk2(sp[4 * 65], sp[5 * 65]); o.w = pk2(sp[6 * 65], sp[7 * 65]);
;                 GAS v4u* dp = (GAS v4u*)(j.WT + (size_t)(drow0 + n) * j.ldk + k0 + 8 * c); if (j.late) __builtin_nontemporal_store(o, dp); else *dp = o; } } }
.LBB0_1067:
	s_ashr_i32 s49, s48, 31
	v_or_b32_e32 v64, s48, v128
	s_cmp_lt_i32 s50, s75
	s_cselect_b64 s[52:53], -1, 0
	v_cmp_gt_i32_e64 s[8:9], s73, v64
	s_and_b64 s[62:63], s[52:53], s[8:9]
	v_add_u32_e32 v64, 0x400, v135
	s_and_saveexec_b64 s[52:53], s[62:63]
	s_cbranch_execz .LBB0_1069
	v_add_u32_e32 v95, s60, v134
	ds_read2_b32 v[100:101], v135 offset0:65 offset1:73
	ds_read2_b32 v[102:103], v135 offset1:8
	ds_read2_b32 v[104:105], v135 offset0:130 offset1:138
	ds_read2_b32 v[106:107], v135 offset0:195 offset1:203
	ds_read2_b32 v[108:109], v64 offset0:4 offset1:12
	ds_read2_b32 v[110:111], v64 offset0:69 offset1:77
	ds_read2_b32 v[112:113], v64 offset0:134 offset1:142
	ds_read2_b32 v[114:115], v64 offset0:199 offset1:207
	v_mad_u64_u32 v[116:117], s[62:63], v95, s73, 0
	s_waitcnt lgkmcnt(6)
	v_cvt_pk_bf16_f32 v96, v102, v100
	v_ashrrev_i32_e32 v102, 31, v95
	v_mov_b32_e32 v100, v117
	v_mad_u64_u32 v[118:119], s[62:63], v102, s73, v[100:101]
	v_mov_b32_e32 v117, v118
	v_lshl_add_u64 v[116:117], v[116:117], 1, s[2:3]
	s_lshl_b64 s[62:63], s[48:49], 1
	v_lshl_add_u64 v[116:117], v[116:117], 0, s[62:63]
	v_lshlrev_b32_e32 v130, 1, v128
	s_waitcnt lgkmcnt(4)
	v_cvt_pk_bf16_f32 v97, v104, v106
	s_waitcnt lgkmcnt(2)
	v_cvt_pk_bf16_f32 v98, v108, v110
	s_waitcnt lgkmcnt(0)
	v_cvt_pk_bf16_f32 v99, v112, v114
	v_lshl_add_u64 v[116:117], v[116:117], 0, v[130:131]
	v_add_u32_e32 v95, s60, v136
	global_store_dwordx4 v[116:117], v[96:99], off sc1
	s_nop 1
	v_cvt_pk_bf16_f32 v96, v103, v101
	v_mad_u64_u32 v[100:101], s[76:77], v95, s73, 0
	v_ashrrev_i32_e32 v103, 31, v95
	v_mov_b32_e32 v102, v101
	v_mad_u64_u32 v[102:103], s[76:77], v103, s73, v[102:103]
	v_mov_b32_e32 v101, v102
	v_lshl_add_u64 v[100:101], v[100:101], 1, s[2:3]
	v_lshl_add_u64 v[100:101], v[100:101], 0, s[62:63]
	v_cvt_pk_bf16_f32 v97, v105, v107
	v_cvt_pk_bf16_f32 v98, v109, v111
	v_cvt_pk_bf16_f32 v99, v113, v115
	v_lshl_add_u64 v[100:101], v[100:101], 0, v[130:131]
	v_add_u32_e32 v95, s60, v137
	ds_read2_b32 v[102:103], v135 offset0:81 offset1:89
	ds_read2_b32 v[104:105], v135 offset0:16 offset1:24
	ds_read2_b32 v[106:107], v135 offset0:146 offset1:154
	ds_read2_b32 v[108:109], v135 offset0:211 offset1:219
	ds_read2_b32 v[110:111], v64 offset0:20 offset1:28
	ds_read2_b32 v[112:113], v64 offset0:85 offset1:93
	ds_read2_b32 v[114:115], v64 offset0:150 offset1:158
	ds_read2_b32 v[116:117], v64 offset0:215 offset1:223
	global_store_dwordx4 v[100:101], v[96:99], off sc1
	v_mad_u64_u32 v[100:101], s[76:77], v95, s73, 0
	s_waitcnt lgkmcnt(6)
	v_cvt_pk_bf16_f32 v96, v104, v102
	v_ashrrev_i32_e32 v104, 31, v95
	v_mov_b32_e32 v102, v101
	v_mad_u64_u32 v[118:119], s[76:77], v104, s73, v[102:103]
	v_mov_b32_e32 v101, v118
	v_lshl_add_u64 v[100:101], v[100:101], 1, s[2:3]
	v_readlane_b32 s76, v254, 11
	v_lshl_add_u64 v[100:101], v[100:101], 0, s[62:63]
	s_waitcnt lgkmcnt(4)
	v_cvt_pk_bf16_f32 v97, v106, v108
	s_waitcnt lgkmcnt(2)
	v_cvt_pk_bf16_f32 v98, v110, v112
	s_waitcnt lgkmcnt(0)
	v_cvt_pk_bf16_f32 v99, v114, v116
	v_readlane_b32 s77, v254, 12
	v_lshl_add_u64 v[100:101], v[100:101], 0, v[130:131]
	v_add_u32_e32 v95, s60, v138
	s_load_dword s77, s[76:77], 0x110
	global_store_dwordx4 v[100:101], v[96:99], off sc1
	v_mad_u64_u32 v[100:101], s[60:61], v95, s73, 0
	s_nop 0
	v_cvt_pk_bf16_f32 v96, v105, v103
	v_ashrrev_i32_e32 v103, 31, v95
	v_mov_b32_e32 v102, v101
	v_mad_u64_u32 v[102:103], s[60:61], v103, s73, v[102:103]
	v_mov_b32_e32 v101, v102
	v_lshl_add_u64 v[100:101], v[100:101], 1, s[2:3]
	v_lshl_add_u64 v[100:101], v[100:101], 0, s[62:63]
	v_cvt_pk_bf16_f32 v97, v107, v109
	v_cvt_pk_bf16_f32 v98, v111, v113
	v_cvt_pk_bf16_f32 v99, v115, v117
	v_lshl_add_u64 v[100:101], v[100:101], 0, v[130:131]
	global_store_dwordx4 v[100:101], v[96:99], off sc1

; #define GAS __attribute__((address_space(1)))
; #define LAS __attribute__((address_space(3)))
; __device__ __forceinline__ unsigned pk2(float lo, float hi) { f32x2_k v = {lo, hi}; bf16x2_k b = __builtin_convertvector(v, bf16x2_k); return __builtin_bit_cast(unsigned, b); }
; __device__ __forceinline__ void p0_finish(const P0Job& j, const f32x4 (&v)[16], LAS float* scr, int lane) {
;     ...
;     for (int hb = 0; hb < 2; ++hb) { const int drow0 = p0_drow(j.kind, n0 + 32 * hb);
;         if (n0 + 32 * hb < j.N && k0 + 8 * c < j.K) {
; #pragma unroll
;             for (int jj = 0; jj < 4; ++jj) { const int n = (lane >> 3) + 8 * jj; const LAS float* sp = scr + (8 * c) * 65 + 32 * hb + n;
;                 v4u o; o.x = pk2(sp[0 * 65], sp[1 * 65]); o.y = pk2(sp[2 * 65], sp[3 * 65]); o.z = pk2(sp[4 * 65], sp[5 * 65]); o.w = pk2(sp[6 * 65], sp[7 * 65]);
;                 GAS v4u* dp = (GAS v4u*)(j.WT + (size_t)(drow0 + n) * j.ldk + k0 + 8 * c); if (j.late) __builtin_nontemporal_store(o, dp); else *dp = o; } } }
.LBB0_1078:
	s_cmp_lt_i32 s51, s75
	s_cselect_b64 s[50:51], -1, 0
	s_and_b64 s[50:51], s[50:51], s[8:9]
	s_and_saveexec_b64 s[8:9], s[50:51]
	s_cbranch_execz .LBB0_1080
	v_add_u32_e32 v95, s60, v134
	ds_read2_b32 v[100:101], v135 offset0:97 offset1:105
	ds_read2_b32 v[102:103], v135 offset0:32 offset1:40
	ds_read2_b32 v[104:105], v135 offset0:162 offset1:170
	ds_read2_b32 v[106:107], v135 offset0:227 offset1:235
	ds_read2_b32 v[108:109], v64 offset0:36 offset1:44
	ds_read2_b32 v[110:111], v64 offset0:101 offset1:109
	ds_read2_b32 v[112:113], v64 offset0:166 offset1:174
	ds_read2_b32 v[114:115], v64 offset0:231 offset1:239
	v_mad_u64_u32 v[116:117], s[50:51], v95, s73, 0
	s_waitcnt lgkmcnt(0)
	v_cvt_pk_bf16_f32 v96, v102, v100
	v_ashrrev_i32_e32 v102, 31, v95
	v_mov_b32_e32 v100, v117
	v_mad_u64_u32 v[118:119], s[50:51], v102, s73, v[100:101]
	v_mov_b32_e32 v117, v118
	v_lshl_add_u64 v[116:117], v[116:117], 1, s[2:3]
	s_lshl_b64 s[48:49], s[48:49], 1
	v_lshl_add_u64 v[116:117], v[116:117], 0, s[48:49]
	v_lshlrev_b32_e32 v130, 1, v128
	v_cvt_pk_bf16_f32 v97, v104, v106
	v_cvt_pk_bf16_f32 v98, v108, v110
	v_cvt_pk_bf16_f32 v99, v112, v114
	v_lshl_add_u64 v[116:117], v[116:117], 0, v[130:131]
	v_add_u32_e32 v95, s60, v136
	global_store_dwordx4 v[116:117], v[96:99], off sc1
	s_nop 1
	v_cvt_pk_bf16_f32 v96, v103, v101
	v_mad_u64_u32 v[100:101], s[50:51], v95, s73, 0
	v_ashrrev_i32_e32 v103, 31, v95
	v_mov_b32_e32 v102, v101
	v_mad_u64_u32 v[102:103], s[50:51], v103, s73, v[102:103]
	v_mov_b32_e32 v101, v102
	v_lshl_add_u64 v[100:101], v[100:101], 1, s[2:3]
	v_lshl_add_u64 v[100:101], v[100:101], 0, s[48:49]
	v_cvt_pk_bf16_f32 v97, v105, v107
	v_cvt_pk_bf16_f32 v98, v109, v111
	v_cvt_pk_bf16_f32 v99, v113, v115
	v_lshl_add_u64 v[100:101], v[100:101], 0, v[130:131]
	v_add_u32_e32 v95, s60, v137
	ds_read2_b32 v[102:103], v135 offset0:113 offset1:121
	ds_read2_b32 v[104:105], v135 offset0:48 offset1:56
	ds_read2_b32 v[106:107], v135 offset0:178 offset1:186
	ds_read2_b32 v[108:109], v135 offset0:243 offset1:251
	ds_read2_b32 v[110:111], v64 offset0:52 offset1:60
	ds_read2_b32 v[112:113], v64 offset0:117 offset1:125
	ds_read2_b32 v[114:115], v64 offset0:182 offset1:190
	ds_read2_b32 v[116:117], v64 offset0:247 offset1:255
	global_store_dwordx4 v[100:101], v[96:99], off sc1
	v_mad_u64_u32 v[100:101], s[50:51], v95, s73, 0
	s_waitcnt lgkmcnt(6)
	v_cvt_pk_bf16_f32 v96, v104, v102
	v_ashrrev_i32_e32 v104, 31, v95
	v_mov_b32_e32 v102, v101
	v_mad_u64_u32 v[118:119], s[50:51], v104, s73, v[102:103]
	v_mov_b32_e32 v101, v118
	v_lshl_add_u64 v[100:101], v[100:101], 1, s[2:3]
	v_lshl_add_u64 v[100:101], v[100:101], 0, s[48:49]
	s_waitcnt lgkmcnt(4)
	v_cvt_pk_bf16_f32 v97, v106, v108
	s_waitcnt lgkmcnt(2)
	v_cvt_pk_bf16_f32 v98, v110, v112
	s_waitcnt lgkmcnt(0)
	v_cvt_pk_bf16_f32 v99, v114, v116
	v_lshl_add_u64 v[100:101], v[100:101], 0, v[130:131]
	v_add_u32_e32 v95, s60, v138
	global_store_dwordx4 v[100:101], v[96:99], off sc1
	v_mad_u64_u32 v[100:101], s[50:51], v95, s73, 0
	s_nop 0
	v_cvt_pk_bf16_f32 v96, v105, v103
	v_ashrrev_i32_e32 v103, 31, v95
	v_mov_b32_e32 v102, v101
	v_mad_u64_u32 v[102:103], s[50:51], v103, s73, v[102:103]
	v_mov_b32_e32 v101, v102
	v_lshl_add_u64 v[100:101], v[100:101], 1, s[2:3]
	v_lshl_add_u64 v[100:101], v[100:101], 0, s[48:49]
	v_cvt_pk_bf16_f32 v97, v107, v109
	v_cvt_pk_bf16_f32 v98, v111, v113
	v_cvt_pk_bf16_f32 v99, v115, v117
	v_lshl_add_u64 v[100:101], v[100:101], 0, v[130:131]
	global_store_dwordx4 v[100:101], v[96:99], off sc1

; #define GAS __attribute__((address_space(1)))
; #define LAS __attribute__((address_space(3)))
; __device__ __forceinline__ unsigned pk2(float lo, float hi) { f32x2_k v = {lo, hi}; bf16x2_k b = __builtin_convertvector(v, bf16x2_k); return __builtin_bit_cast(unsigned, b); }
; __device__ __forceinline__ void p0_finish(const P0Job& j, const f32x4 (&v)[16], LAS float* scr, int lane) {
;     ...
;     for (int hb = 0; hb < 2; ++hb) { const int drow0 = p0_drow(j.kind, n0 + 32 * hb);
;         if (n0 + 32 * hb < j.N && k0 + 8 * c < j.K) {
; #pragma unroll
;             for (int jj = 0; jj < 4; ++jj) { const int n = (lane >> 3) + 8 * jj; const LAS float* sp = scr + (8 * c) * 65 + 32 * hb + n;
;                 v4u o; o.x = pk2(sp[0 * 65], sp[1 * 65]); o.y = pk2(sp[2 * 65], sp[3 * 65]); o.z = pk2(sp[4 * 65], sp[5 * 65]); o.w = pk2(sp[6 * 65], sp[7 * 65]);
;                 GAS v4u* dp = (GAS v4u*)(j.WT + (size_t)(drow0 + n) * j.ldk + k0 + 8 * c); if (j.late) __builtin_nontemporal_store(o, dp); else *dp = o; } } }
.LBB0_1096:
	s_lshl_b32 s2, s48, 6
	s_ashr_i32 s3, s2, 31
	v_or_b32_e32 v65, s2, v128
	s_cmp_lt_i32 s50, s71
	s_cselect_b64 s[48:49], -1, 0
	v_cmp_gt_i32_e64 s[8:9], s72, v65
	s_and_b64 s[54:55], s[48:49], s[8:9]
	s_and_saveexec_b64 s[48:49], s[54:55]
	s_cbranch_execz .LBB0_1098
	ds_read2_b32 v[70:71], v135 offset0:65 offset1:73
	ds_read2_b32 v[72:73], v135 offset1:8
	ds_read2_b32 v[74:75], v135 offset0:130 offset1:138
	ds_read2_b32 v[76:77], v135 offset0:195 offset1:203
	ds_read2_b32 v[78:79], v64 offset0:4 offset1:12
	ds_read2_b32 v[80:81], v64 offset0:69 offset1:77
	ds_read2_b32 v[82:83], v64 offset0:134 offset1:142
	ds_read2_b32 v[84:85], v64 offset0:199 offset1:207
	v_add_u32_e32 v65, s53, v134
	v_mad_i64_i32 v[86:87], s[54:55], v65, s72, 0
	v_lshl_add_u64 v[86:87], v[86:87], 1, s[0:1]
	s_lshl_b64 s[54:55], s[2:3], 1
	v_lshl_add_u64 v[86:87], v[86:87], 0, s[54:55]
	v_lshlrev_b32_e32 v130, 1, v128
	s_waitcnt lgkmcnt(0)
	v_cvt_pk_bf16_f32 v66, v72, v70
	v_cvt_pk_bf16_f32 v67, v74, v76
	v_cvt_pk_bf16_f32 v68, v78, v80
	v_cvt_pk_bf16_f32 v69, v82, v84
	v_lshl_add_u64 v[86:87], v[86:87], 0, v[130:131]
	v_add_u32_e32 v65, s53, v136
	global_store_dwordx4 v[86:87], v[66:69], off sc1
	s_nop 1
	v_cvt_pk_bf16_f32 v66, v73, v71
	v_mad_i64_i32 v[70:71], s[56:57], v65, s72, 0
	v_lshl_add_u64 v[70:71], v[70:71], 1, s[0:1]
	v_cvt_pk_bf16_f32 v67, v75, v77
	v_cvt_pk_bf16_f32 v68, v79, v81
	v_cvt_pk_bf16_f32 v69, v83, v85
	v_lshl_add_u64 v[70:71], v[70:71], 0, s[54:55]
	ds_read2_b32 v[72:73], v135 offset0:81 offset1:89
	ds_read2_b32 v[74:75], v135 offset0:16 offset1:24
	ds_read2_b32 v[76:77], v135 offset0:146 offset1:154
	ds_read2_b32 v[78:79], v135 offset0:211 offset1:219
	ds_read2_b32 v[80:81], v64 offset0:20 offset1:28
	ds_read2_b32 v[82:83], v64 offset0:85 offset1:93
	ds_read2_b32 v[84:85], v64 offset0:150 offset1:158
	ds_read2_b32 v[86:87], v64 offset0:215 offset1:223
	v_lshl_add_u64 v[70:71], v[70:71], 0, v[130:131]
	v_add_u32_e32 v65, s53, v137
	global_store_dwordx4 v[70:71], v[66:69], off sc1
	v_mad_i64_i32 v[70:71], s[56:57], v65, s72, 0
	v_lshl_add_u64 v[70:71], v[70:71], 1, s[0:1]
	v_lshl_add_u64 v[70:71], v[70:71], 0, s[54:55]
	s_waitcnt lgkmcnt(6)
	v_cvt_pk_bf16_f32 v66, v74, v72
	s_waitcnt lgkmcnt(4)
	v_cvt_pk_bf16_f32 v67, v76, v78
	s_waitcnt lgkmcnt(2)
	v_cvt_pk_bf16_f32 v68, v80, v82
	s_waitcnt lgkmcnt(0)
	v_cvt_pk_bf16_f32 v69, v84, v86
	v_lshl_add_u64 v[70:71], v[70:71], 0, v[130:131]
	v_add_u32_e32 v65, s53, v138
	global_store_dwordx4 v[70:71], v[66:69], off sc1
	v_mad_i64_i32 v[70:71], s[56:57], v65, s72, 0
	v_lshl_add_u64 v[70:71], v[70:71], 1, s[0:1]
	v_lshl_add_u64 v[70:71], v[70:71], 0, s[54:55]
	v_cvt_pk_bf16_f32 v66, v75, v73
	v_cvt_pk_bf16_f32 v67, v77, v79
	v_cvt_pk_bf16_f32 v68, v81, v83
	v_cvt_pk_bf16_f32 v69, v85, v87
	v_lshl_add_u64 v[70:71], v[70:71], 0, v[130:131]
	global_store_dwordx4 v[70:71], v[66:69], off sc1

; #define GAS __attribute__((address_space(1)))
; #define LAS __attribute__((address_space(3)))
; __device__ __forceinline__ unsigned pk2(float lo, float hi) { f32x2_k v = {lo, hi}; bf16x2_k b = __builtin_convertvector(v, bf16x2_k); return __builtin_bit_cast(unsigned, b); }
; __device__ __forceinline__ void p0_finish(const P0Job& j, const f32x4 (&v)[16], LAS float* scr, int lane) {
;     ...
;     for (int hb = 0; hb < 2; ++hb) { const int drow0 = p0_drow(j.kind, n0 + 32 * hb);
;         if (n0 + 32 * hb < j.N && k0 + 8 * c < j.K) {
; #pragma unroll
;             for (int jj = 0; jj < 4; ++jj) { const int n = (lane >> 3) + 8 * jj; const LAS float* sp = scr + (8 * c) * 65 + 32 * hb + n;
;                 v4u o; o.x = pk2(sp[0 * 65], sp[1 * 65]); o.y = pk2(sp[2 * 65], sp[3 * 65]); o.z = pk2(sp[4 * 65], sp[5 * 65]); o.w = pk2(sp[6 * 65], sp[7 * 65]);
;                 GAS v4u* dp = (GAS v4u*)(j.WT + (size_t)(drow0 + n) * j.ldk + k0 + 8 * c); if (j.late) __builtin_nontemporal_store(o, dp); else *dp = o; } } }
.LBB0_1109:
	s_cmp_lt_i32 s54, s71
	s_cselect_b64 s[48:49], -1, 0
	s_and_b64 s[48:49], s[48:49], s[8:9]
	s_and_saveexec_b64 s[8:9], s[48:49]
	s_cbranch_execz .LBB0_892
	ds_read2_b32 v[70:71], v135 offset0:97 offset1:105
	ds_read2_b32 v[72:73], v135 offset0:32 offset1:40
	ds_read2_b32 v[74:75], v135 offset0:162 offset1:170
	ds_read2_b32 v[76:77], v135 offset0:227 offset1:235
	ds_read2_b32 v[78:79], v64 offset0:36 offset1:44
	ds_read2_b32 v[80:81], v64 offset0:101 offset1:109
	ds_read2_b32 v[82:83], v64 offset0:166 offset1:174
	ds_read2_b32 v[84:85], v64 offset0:231 offset1:239
	v_add_u32_e32 v65, s53, v134
	v_mad_i64_i32 v[86:87], s[48:49], v65, s72, 0
	v_lshl_add_u64 v[86:87], v[86:87], 1, s[0:1]
	s_lshl_b64 s[2:3], s[2:3], 1
	v_lshl_add_u64 v[86:87], v[86:87], 0, s[2:3]
	v_lshlrev_b32_e32 v130, 1, v128
	s_waitcnt lgkmcnt(0)
	v_cvt_pk_bf16_f32 v66, v72, v70
	v_cvt_pk_bf16_f32 v67, v74, v76
	v_cvt_pk_bf16_f32 v68, v78, v80
	v_cvt_pk_bf16_f32 v69, v82, v84
	v_lshl_add_u64 v[86:87], v[86:87], 0, v[130:131]
	v_add_u32_e32 v65, s53, v136
	global_store_dwordx4 v[86:87], v[66:69], off sc1
	s_nop 1
	v_cvt_pk_bf16_f32 v66, v73, v71
	v_mad_i64_i32 v[70:71], s[48:49], v65, s72, 0
	v_lshl_add_u64 v[70:71], v[70:71], 1, s[0:1]
	v_lshl_add_u64 v[70:71], v[70:71], 0, s[2:3]
	v_cvt_pk_bf16_f32 v67, v75, v77
	v_cvt_pk_bf16_f32 v68, v79, v81
	v_cvt_pk_bf16_f32 v69, v83, v85
	v_lshl_add_u64 v[70:71], v[70:71], 0, v[130:131]
	ds_read2_b32 v[72:73], v135 offset0:113 offset1:121
	ds_read2_b32 v[74:75], v135 offset0:48 offset1:56
	ds_read2_b32 v[76:77], v135 offset0:178 offset1:186
	ds_read2_b32 v[78:79], v135 offset0:243 offset1:251
	ds_read2_b32 v[80:81], v64 offset0:52 offset1:60
	ds_read2_b32 v[82:83], v64 offset0:117 offset1:125
	ds_read2_b32 v[84:85], v64 offset0:182 offset1:190
	ds_read2_b32 v[86:87], v64 offset0:247 offset1:255
	global_store_dwordx4 v[70:71], v[66:69], off sc1
	s_waitcnt lgkmcnt(6)
	v_cvt_pk_bf16_f32 v64, v74, v72
	s_waitcnt lgkmcnt(4)
	v_cvt_pk_bf16_f32 v65, v76, v78
	v_add_u32_e32 v68, s53, v137
	v_mad_i64_i32 v[68:69], s[48:49], v68, s72, 0
	v_lshl_add_u64 v[68:69], v[68:69], 1, s[0:1]
	v_lshl_add_u64 v[68:69], v[68:69], 0, s[2:3]
	s_waitcnt lgkmcnt(2)
	v_cvt_pk_bf16_f32 v66, v80, v82
	s_waitcnt lgkmcnt(0)
	v_cvt_pk_bf16_f32 v67, v84, v86
	v_lshl_add_u64 v[68:69], v[68:69], 0, v[130:131]
	global_store_dwordx4 v[68:69], v[64:67], off sc1
	v_add_u32_e32 v68, s53, v138
	v_mad_i64_i32 v[68:69], s[48:49], v68, s72, 0
	v_lshl_add_u64 v[68:69], v[68:69], 1, s[0:1]
	v_lshl_add_u64 v[68:69], v[68:69], 0, s[2:3]
	v_cvt_pk_bf16_f32 v64, v75, v73
	v_cvt_pk_bf16_f32 v65, v77, v79
	v_cvt_pk_bf16_f32 v66, v81, v83
	v_cvt_pk_bf16_f32 v67, v85, v87
	v_lshl_add_u64 v[68:69], v[68:69], 0, v[130:131]
	global_store_dwordx4 v[68:69], v[64:67], off sc1
	s_branch .LBB0_892

; #define GAS __attribute__((address_space(1)))
; #define LAS __attribute__((address_space(3)))
; __device__ __forceinline__ unsigned pk2(float lo, float hi) { f32x2_k v = {lo, hi}; bf16x2_k b = __builtin_convertvector(v, bf16x2_k); return __builtin_bit_cast(unsigned, b); }
; __device__ __forceinline__ void p0_finish(const P0Job& j, const f32x4 (&v)[16], LAS float* scr, int lane) {
;     ...
;     for (int hb = 0; hb < 2; ++hb) { const int drow0 = p0_drow(j.kind, n0 + 32 * hb);
;         if (n0 + 32 * hb < j.N && k0 + 8 * c < j.K) {
; #pragma unroll
;             for (int jj = 0; jj < 4; ++jj) { const int n = (lane >> 3) + 8 * jj; const LAS float* sp = scr + (8 * c) * 65 + 32 * hb + n;
;                 v4u o; o.x = pk2(sp[0 * 65], sp[1 * 65]); o.y = pk2(sp[2 * 65], sp[3 * 65]); o.z = pk2(sp[4 * 65], sp[5 * 65]); o.w = pk2(sp[6 * 65], sp[7 * 65]);
;                 GAS v4u* dp = (GAS v4u*)(j.WT + (size_t)(drow0 + n) * j.ldk + k0 + 8 * c); if (j.late) __builtin_nontemporal_store(o, dp); else *dp = o; } } }
.LBB0_1293:
	s_ashr_i32 s49, s48, 31
	v_or_b32_e32 v64, s48, v128
	s_cmp_lt_i32 s50, s72
	s_cselect_b64 s[52:53], -1, 0
	v_cmp_gt_i32_e64 s[8:9], s69, v64
	s_and_b64 s[62:63], s[52:53], s[8:9]
	v_add_u32_e32 v64, 0x400, v135
	v_lshlrev_b32_e32 v130, 1, v128
	s_and_saveexec_b64 s[52:53], s[62:63]
	s_cbranch_execz .LBB0_1295
	v_add_u32_e32 v95, s60, v134
	ds_read2_b32 v[100:101], v135 offset0:65 offset1:73
	ds_read2_b32 v[102:103], v135 offset1:8
	ds_read2_b32 v[104:105], v135 offset0:130 offset1:138
	ds_read2_b32 v[106:107], v135 offset0:195 offset1:203
	ds_read2_b32 v[108:109], v64 offset0:4 offset1:12
	ds_read2_b32 v[110:111], v64 offset0:69 offset1:77
	ds_read2_b32 v[112:113], v64 offset0:134 offset1:142
	ds_read2_b32 v[114:115], v64 offset0:199 offset1:207
	v_mad_u64_u32 v[116:117], s[62:63], v95, s69, 0
	s_waitcnt lgkmcnt(6)
	v_cvt_pk_bf16_f32 v96, v102, v100
	v_ashrrev_i32_e32 v102, 31, v95
	v_mov_b32_e32 v100, v117
	v_mad_u64_u32 v[118:119], s[62:63], v102, s69, v[100:101]
	v_mov_b32_e32 v117, v118
	v_lshl_add_u64 v[116:117], v[116:117], 1, s[2:3]
	s_lshl_b64 s[62:63], s[48:49], 1
	v_lshl_add_u64 v[116:117], v[116:117], 0, s[62:63]
	s_waitcnt lgkmcnt(4)
	v_cvt_pk_bf16_f32 v97, v104, v106
	s_waitcnt lgkmcnt(2)
	v_cvt_pk_bf16_f32 v98, v108, v110
	s_waitcnt lgkmcnt(0)
	v_cvt_pk_bf16_f32 v99, v112, v114
	v_lshl_add_u64 v[116:117], v[116:117], 0, v[130:131]
	v_add_u32_e32 v95, s60, v136
	global_store_dwordx4 v[116:117], v[96:99], off sc1
	s_nop 1
	v_cvt_pk_bf16_f32 v96, v103, v101
	v_mad_u64_u32 v[100:101], s[74:75], v95, s69, 0
	v_ashrrev_i32_e32 v103, 31, v95
	v_mov_b32_e32 v102, v101
	v_mad_u64_u32 v[102:103], s[74:75], v103, s69, v[102:103]
	v_mov_b32_e32 v101, v102
	v_lshl_add_u64 v[100:101], v[100:101], 1, s[2:3]
	v_lshl_add_u64 v[100:101], v[100:101], 0, s[62:63]
	v_cvt_pk_bf16_f32 v97, v105, v107
	v_cvt_pk_bf16_f32 v98, v109, v111
	v_cvt_pk_bf16_f32 v99, v113, v115
	v_lshl_add_u64 v[100:101], v[100:101], 0, v[130:131]
	v_add_u32_e32 v95, s60, v137
	ds_read2_b32 v[102:103], v135 offset0:81 offset1:89
	ds_read2_b32 v[104:105], v135 offset0:16 offset1:24
	ds_read2_b32 v[106:107], v135 offset0:146 offset1:154
	ds_read2_b32 v[108:109], v135 offset0:211 offset1:219
	ds_read2_b32 v[110:111], v64 offset0:20 offset1:28
	ds_read2_b32 v[112:113], v64 offset0:85 offset1:93
	ds_read2_b32 v[114:115], v64 offset0:150 offset1:158
	ds_read2_b32 v[116:117], v64 offset0:215 offset1:223
	global_store_dwordx4 v[100:101], v[96:99], off sc1
	v_mad_u64_u32 v[100:101], s[74:75], v95, s69, 0
	s_waitcnt lgkmcnt(6)
	v_cvt_pk_bf16_f32 v96, v104, v102
	v_ashrrev_i32_e32 v104, 31, v95
	v_mov_b32_e32 v102, v101
	v_mad_u64_u32 v[118:119], s[74:75], v104, s69, v[102:103]
	v_mov_b32_e32 v101, v118
	v_lshl_add_u64 v[100:101], v[100:101], 1, s[2:3]
	v_lshl_add_u64 v[100:101], v[100:101], 0, s[62:63]
	s_waitcnt lgkmcnt(4)
	v_cvt_pk_bf16_f32 v97, v106, v108
	s_waitcnt lgkmcnt(2)
	v_cvt_pk_bf16_f32 v98, v110, v112
	s_waitcnt lgkmcnt(0)
	v_cvt_pk_bf16_f32 v99, v114, v116
	v_lshl_add_u64 v[100:101], v[100:101], 0, v[130:131]
	v_add_u32_e32 v95, s60, v138
	global_store_dwordx4 v[100:101], v[96:99], off sc1
	v_mad_u64_u32 v[100:101], s[60:61], v95, s69, 0
	s_nop 0
	v_cvt_pk_bf16_f32 v96, v105, v103
	v_ashrrev_i32_e32 v103, 31, v95
	v_mov_b32_e32 v102, v101
	v_mad_u64_u32 v[102:103], s[60:61], v103, s69, v[102:103]
	v_mov_b32_e32 v101, v102
	v_lshl_add_u64 v[100:101], v[100:101], 1, s[2:3]
	v_lshl_add_u64 v[100:101], v[100:101], 0, s[62:63]
	v_cvt_pk_bf16_f32 v97, v107, v109
	v_cvt_pk_bf16_f32 v98, v111, v113
	v_cvt_pk_bf16_f32 v99, v115, v117
	v_lshl_add_u64 v[100:101], v[100:101], 0, v[130:131]
	global_store_dwordx4 v[100:101], v[96:99], off sc1

; #define GAS __attribute__((address_space(1)))
; #define LAS __attribute__((address_space(3)))
; __device__ __forceinline__ unsigned pk2(float lo, float hi) { f32x2_k v = {lo, hi}; bf16x2_k b = __builtin_convertvector(v, bf16x2_k); return __builtin_bit_cast(unsigned, b); }
; __device__ __forceinline__ void p0_finish(const P0Job& j, const f32x4 (&v)[16], LAS float* scr, int lane) {
;     ...
;     for (int hb = 0; hb < 2; ++hb) { const int drow0 = p0_drow(j.kind, n0 + 32 * hb);
;         if (n0 + 32 * hb < j.N && k0 + 8 * c < j.K) {
; #pragma unroll
;             for (int jj = 0; jj < 4; ++jj) { const int n = (lane >> 3) + 8 * jj; const LAS float* sp = scr + (8 * c) * 65 + 32 * hb + n;
;                 v4u o; o.x = pk2(sp[0 * 65], sp[1 * 65]); o.y = pk2(sp[2 * 65], sp[3 * 65]); o.z = pk2(sp[4 * 65], sp[5 * 65]); o.w = pk2(sp[6 * 65], sp[7 * 65]);
;                 GAS v4u* dp = (GAS v4u*)(j.WT + (size_t)(drow0 + n) * j.ldk + k0 + 8 * c); if (j.late) __builtin_nontemporal_store(o, dp); else *dp = o; } } }
.LBB0_1304:
	s_cmp_lt_i32 s51, s72
	s_cselect_b64 s[50:51], -1, 0
	s_and_b64 s[50:51], s[50:51], s[8:9]
	s_and_saveexec_b64 s[8:9], s[50:51]
	s_cbranch_execz .LBB0_1306
	v_add_u32_e32 v95, s60, v134
	ds_read2_b32 v[100:101], v135 offset0:97 offset1:105
	ds_read2_b32 v[102:103], v135 offset0:32 offset1:40
	ds_read2_b32 v[104:105], v135 offset0:162 offset1:170
	ds_read2_b32 v[106:107], v135 offset0:227 offset1:235
	ds_read2_b32 v[108:109], v64 offset0:36 offset1:44
	ds_read2_b32 v[110:111], v64 offset0:101 offset1:109
	ds_read2_b32 v[112:113], v64 offset0:166 offset1:174
	ds_read2_b32 v[114:115], v64 offset0:231 offset1:239
	v_mad_u64_u32 v[116:117], s[50:51], v95, s69, 0
	s_waitcnt lgkmcnt(6)
	v_cvt_pk_bf16_f32 v96, v102, v100
	v_ashrrev_i32_e32 v102, 31, v95
	v_mov_b32_e32 v100, v117
	v_mad_u64_u32 v[118:119], s[50:51], v102, s69, v[100:101]
	v_mov_b32_e32 v117, v118
	v_lshl_add_u64 v[116:117], v[116:117], 1, s[2:3]
	s_lshl_b64 s[48:49], s[48:49], 1
	v_lshl_add_u64 v[116:117], v[116:117], 0, s[48:49]
	s_waitcnt lgkmcnt(4)
	v_cvt_pk_bf16_f32 v97, v104, v106
	s_waitcnt lgkmcnt(2)
	v_cvt_pk_bf16_f32 v98, v108, v110
	s_waitcnt lgkmcnt(0)
	v_cvt_pk_bf16_f32 v99, v112, v114
	v_lshl_add_u64 v[116:117], v[116:117], 0, v[130:131]
	v_add_u32_e32 v95, s60, v136
	global_store_dwordx4 v[116:117], v[96:99], off sc1
	s_nop 1
	v_cvt_pk_bf16_f32 v96, v103, v101
	v_mad_u64_u32 v[100:101], s[50:51], v95, s69, 0
	v_ashrrev_i32_e32 v103, 31, v95
	v_mov_b32_e32 v102, v101
	v_mad_u64_u32 v[102:103], s[50:51], v103, s69, v[102:103]
	v_mov_b32_e32 v101, v102
	v_lshl_add_u64 v[100:101], v[100:101], 1, s[2:3]
	v_lshl_add_u64 v[100:101], v[100:101], 0, s[48:49]
	v_cvt_pk_bf16_f32 v97, v105, v107
	v_cvt_pk_bf16_f32 v98, v109, v111
	v_cvt_pk_bf16_f32 v99, v113, v115
	v_lshl_add_u64 v[100:101], v[100:101], 0, v[130:131]
	v_add_u32_e32 v95, s60, v137
	ds_read2_b32 v[102:103], v135 offset0:113 offset1:121
	ds_read2_b32 v[104:105], v135 offset0:48 offset1:56
	ds_read2_b32 v[106:107], v135 offset0:178 offset1:186
	ds_read2_b32 v[108:109], v135 offset0:243 offset1:251
	ds_read2_b32 v[110:111], v64 offset0:52 offset1:60
	ds_read2_b32 v[112:113], v64 offset0:117 offset1:125
	ds_read2_b32 v[114:115], v64 offset0:182 offset1:190
	ds_read2_b32 v[116:117], v64 offset0:247 offset1:255
	global_store_dwordx4 v[100:101], v[96:99], off sc1
	v_mad_u64_u32 v[100:101], s[50:51], v95, s69, 0
	s_waitcnt lgkmcnt(6)
	v_cvt_pk_bf16_f32 v96, v104, v102
	v_ashrrev_i32_e32 v104, 31, v95
	v_mov_b32_e32 v102, v101
	v_mad_u64_u32 v[118:119], s[50:51], v104, s69, v[102:103]
	v_mov_b32_e32 v101, v118
	v_lshl_add_u64 v[100:101], v[100:101], 1, s[2:3]
	v_lshl_add_u64 v[100:101], v[100:101], 0, s[48:49]
	s_waitcnt lgkmcnt(4)
	v_cvt_pk_bf16_f32 v97, v106, v108
	s_waitcnt lgkmcnt(2)
	v_cvt_pk_bf16_f32 v98, v110, v112
	s_waitcnt lgkmcnt(0)
	v_cvt_pk_bf16_f32 v99, v114, v116
	v_lshl_add_u64 v[100:101], v[100:101], 0, v[130:131]
	v_add_u32_e32 v95, s60, v138
	global_store_dwordx4 v[100:101], v[96:99], off sc1
	v_mad_u64_u32 v[100:101], s[50:51], v95, s69, 0
	s_nop 0
	v_cvt_pk_bf16_f32 v96, v105, v103
	v_ashrrev_i32_e32 v103, 31, v95
	v_mov_b32_e32 v102, v101
	v_mad_u64_u32 v[102:103], s[50:51], v103, s69, v[102:103]
	v_mov_b32_e32 v101, v102
	v_lshl_add_u64 v[100:101], v[100:101], 1, s[2:3]
	v_lshl_add_u64 v[100:101], v[100:101], 0, s[48:49]
	v_cvt_pk_bf16_f32 v97, v107, v109
	v_cvt_pk_bf16_f32 v98, v111, v113
	v_cvt_pk_bf16_f32 v99, v115, v117
	v_lshl_add_u64 v[100:101], v[100:101], 0, v[130:131]
	global_store_dwordx4 v[100:101], v[96:99], off sc1

; #define GAS __attribute__((address_space(1)))
; #define LAS __attribute__((address_space(3)))
; __device__ __forceinline__ unsigned pk2(float lo, float hi) { f32x2_k v = {lo, hi}; bf16x2_k b = __builtin_convertvector(v, bf16x2_k); return __builtin_bit_cast(unsigned, b); }
; __device__ __forceinline__ void p0_finish(const P0Job& j, const f32x4 (&v)[16], LAS float* scr, int lane) {
;     ...
;     for (int hb = 0; hb < 2; ++hb) { const int drow0 = p0_drow(j.kind, n0 + 32 * hb);
;         if (n0 + 32 * hb < j.N && k0 + 8 * c < j.K) {
; #pragma unroll
;             for (int jj = 0; jj < 4; ++jj) { const int n = (lane >> 3) + 8 * jj; const LAS float* sp = scr + (8 * c) * 65 + 32 * hb + n;
;                 v4u o; o.x = pk2(sp[0 * 65], sp[1 * 65]); o.y = pk2(sp[2 * 65], sp[3 * 65]); o.z = pk2(sp[4 * 65], sp[5 * 65]); o.w = pk2(sp[6 * 65], sp[7 * 65]);
;                 GAS v4u* dp = (GAS v4u*)(j.WT + (size_t)(drow0 + n) * j.ldk + k0 + 8 * c); if (j.late) __builtin_nontemporal_store(o, dp); else *dp = o; } } }
.LBB0_1322:
	s_lshl_b32 s2, s48, 6
	s_ashr_i32 s3, s2, 31
	v_or_b32_e32 v65, s2, v128
	s_cmp_lt_i32 s50, s68
	s_cselect_b64 s[48:49], -1, 0
	v_cmp_gt_i32_e64 s[8:9], s67, v65
	s_and_b64 s[54:55], s[48:49], s[8:9]
	s_and_saveexec_b64 s[48:49], s[54:55]
	s_cbranch_execz .LBB0_1324
	ds_read2_b32 v[70:71], v135 offset0:65 offset1:73
	ds_read2_b32 v[72:73], v135 offset1:8
	ds_read2_b32 v[74:75], v135 offset0:130 offset1:138
	ds_read2_b32 v[76:77], v135 offset0:195 offset1:203
	ds_read2_b32 v[78:79], v64 offset0:4 offset1:12
	ds_read2_b32 v[80:81], v64 offset0:69 offset1:77
	ds_read2_b32 v[82:83], v64 offset0:134 offset1:142
	ds_read2_b32 v[84:85], v64 offset0:199 offset1:207
	v_add_u32_e32 v65, s53, v134
	v_mad_i64_i32 v[86:87], s[54:55], v65, s67, 0
	v_lshl_add_u64 v[86:87], v[86:87], 1, s[0:1]
	s_lshl_b64 s[54:55], s[2:3], 1
	v_lshl_add_u64 v[86:87], v[86:87], 0, s[54:55]
	s_waitcnt lgkmcnt(6)
	v_cvt_pk_bf16_f32 v66, v72, v70
	s_waitcnt lgkmcnt(4)
	v_cvt_pk_bf16_f32 v67, v74, v76
	s_waitcnt lgkmcnt(2)
	v_cvt_pk_bf16_f32 v68, v78, v80
	s_waitcnt lgkmcnt(0)
	v_cvt_pk_bf16_f32 v69, v82, v84
	v_lshl_add_u64 v[86:87], v[86:87], 0, v[130:131]
	v_add_u32_e32 v65, s53, v136
	global_store_dwordx4 v[86:87], v[66:69], off sc1
	s_nop 1
	v_cvt_pk_bf16_f32 v66, v73, v71
	v_mad_i64_i32 v[70:71], s[56:57], v65, s67, 0
	v_lshl_add_u64 v[70:71], v[70:71], 1, s[0:1]
	v_cvt_pk_bf16_f32 v67, v75, v77
	v_cvt_pk_bf16_f32 v68, v79, v81
	v_cvt_pk_bf16_f32 v69, v83, v85
	v_lshl_add_u64 v[70:71], v[70:71], 0, s[54:55]
	ds_read2_b32 v[72:73], v135 offset0:81 offset1:89
	ds_read2_b32 v[74:75], v135 offset0:16 offset1:24
	ds_read2_b32 v[76:77], v135 offset0:146 offset1:154
	ds_read2_b32 v[78:79], v135 offset0:211 offset1:219
	ds_read2_b32 v[80:81], v64 offset0:20 offset1:28
	ds_read2_b32 v[82:83], v64 offset0:85 offset1:93
	ds_read2_b32 v[84:85], v64 offset0:150 offset1:158
	ds_read2_b32 v[86:87], v64 offset0:215 offset1:223
	v_lshl_add_u64 v[70:71], v[70:71], 0, v[130:131]
	v_add_u32_e32 v65, s53, v137
	global_store_dwordx4 v[70:71], v[66:69], off sc1
	v_mad_i64_i32 v[70:71], s[56:57], v65, s67, 0
	v_lshl_add_u64 v[70:71], v[70:71], 1, s[0:1]
	v_lshl_add_u64 v[70:71], v[70:71], 0, s[54:55]
	s_waitcnt lgkmcnt(6)
	v_cvt_pk_bf16_f32 v66, v74, v72
	s_waitcnt lgkmcnt(4)
	v_cvt_pk_bf16_f32 v67, v76, v78
	s_waitcnt lgkmcnt(2)
	v_cvt_pk_bf16_f32 v68, v80, v82
	s_waitcnt lgkmcnt(0)
	v_cvt_pk_bf16_f32 v69, v84, v86
	v_lshl_add_u64 v[70:71], v[70:71], 0, v[130:131]
	v_add_u32_e32 v65, s53, v138
	global_store_dwordx4 v[70:71], v[66:69], off sc1
	v_mad_i64_i32 v[70:71], s[56:57], v65, s67, 0
	v_lshl_add_u64 v[70:71], v[70:71], 1, s[0:1]
	v_lshl_add_u64 v[70:71], v[70:71], 0, s[54:55]
	v_cvt_pk_bf16_f32 v66, v75, v73
	v_cvt_pk_bf16_f32 v67, v77, v79
	v_cvt_pk_bf16_f32 v68, v81, v83
	v_cvt_pk_bf16_f32 v69, v85, v87
	v_lshl_add_u64 v[70:71], v[70:71], 0, v[130:131]
	global_store_dwordx4 v[70:71], v[66:69], off sc1

; #define GAS __attribute__((address_space(1)))
; #define LAS __attribute__((address_space(3)))
; __device__ __forceinline__ unsigned pk2(float lo, float hi) { f32x2_k v = {lo, hi}; bf16x2_k b = __builtin_convertvector(v, bf16x2_k); return __builtin_bit_cast(unsigned, b); }
; __device__ __forceinline__ void p0_finish(const P0Job& j, const f32x4 (&v)[16], LAS float* scr, int lane) {
;     ...
;     for (int hb = 0; hb < 2; ++hb) { const int drow0 = p0_drow(j.kind, n0 + 32 * hb);
;         if (n0 + 32 * hb < j.N && k0 + 8 * c < j.K) {
; #pragma unroll
;             for (int jj = 0; jj < 4; ++jj) { const int n = (lane >> 3) + 8 * jj; const LAS float* sp = scr + (8 * c) * 65 + 32 * hb + n;
;                 v4u o; o.x = pk2(sp[0 * 65], sp[1 * 65]); o.y = pk2(sp[2 * 65], sp[3 * 65]); o.z = pk2(sp[4 * 65], sp[5 * 65]); o.w = pk2(sp[6 * 65], sp[7 * 65]);
;                 GAS v4u* dp = (GAS v4u*)(j.WT + (size_t)(drow0 + n) * j.ldk + k0 + 8 * c); if (j.late) __builtin_nontemporal_store(o, dp); else *dp = o; } } }
.LBB0_1335:
	s_cmp_lt_i32 s54, s68
	s_cselect_b64 s[48:49], -1, 0
	s_and_b64 s[48:49], s[48:49], s[8:9]
	s_and_saveexec_b64 s[8:9], s[48:49]
	s_cbranch_execz .LBB0_1115
	ds_read2_b32 v[70:71], v135 offset0:97 offset1:105
	ds_read2_b32 v[72:73], v135 offset0:32 offset1:40
	ds_read2_b32 v[74:75], v135 offset0:162 offset1:170
	ds_read2_b32 v[76:77], v135 offset0:227 offset1:235
	ds_read2_b32 v[78:79], v64 offset0:36 offset1:44
	ds_read2_b32 v[80:81], v64 offset0:101 offset1:109
	ds_read2_b32 v[82:83], v64 offset0:166 offset1:174
	ds_read2_b32 v[84:85], v64 offset0:231 offset1:239
	v_add_u32_e32 v65, s53, v134
	v_mad_i64_i32 v[86:87], s[48:49], v65, s67, 0
	v_lshl_add_u64 v[86:87], v[86:87], 1, s[0:1]
	s_lshl_b64 s[2:3], s[2:3], 1
	v_lshl_add_u64 v[86:87], v[86:87], 0, s[2:3]
	s_waitcnt lgkmcnt(6)
	v_cvt_pk_bf16_f32 v66, v72, v70
	s_waitcnt lgkmcnt(4)
	v_cvt_pk_bf16_f32 v67, v74, v76
	s_waitcnt lgkmcnt(2)
	v_cvt_pk_bf16_f32 v68, v78, v80
	s_waitcnt lgkmcnt(0)
	v_cvt_pk_bf16_f32 v69, v82, v84
	v_lshl_add_u64 v[86:87], v[86:87], 0, v[130:131]
	v_add_u32_e32 v65, s53, v136
	global_store_dwordx4 v[86:87], v[66:69], off sc1
	s_nop 1
	v_cvt_pk_bf16_f32 v66, v73, v71
	v_mad_i64_i32 v[70:71], s[48:49], v65, s67, 0
	v_lshl_add_u64 v[70:71], v[70:71], 1, s[0:1]
	v_lshl_add_u64 v[70:71], v[70:71], 0, s[2:3]
	v_cvt_pk_bf16_f32 v67, v75, v77
	v_cvt_pk_bf16_f32 v68, v79, v81
	v_cvt_pk_bf16_f32 v69, v83, v85
	v_lshl_add_u64 v[70:71], v[70:71], 0, v[130:131]
	ds_read2_b32 v[72:73], v135 offset0:113 offset1:121
	ds_read2_b32 v[74:75], v135 offset0:48 offset1:56
	ds_read2_b32 v[76:77], v135 offset0:178 offset1:186
	ds_read2_b32 v[78:79], v135 offset0:243 offset1:251
	ds_read2_b32 v[80:81], v64 offset0:52 offset1:60
	ds_read2_b32 v[82:83], v64 offset0:117 offset1:125
	ds_read2_b32 v[84:85], v64 offset0:182 offset1:190
	ds_read2_b32 v[86:87], v64 offset0:247 offset1:255
	global_store_dwordx4 v[70:71], v[66:69], off sc1
	s_waitcnt lgkmcnt(6)
	v_cvt_pk_bf16_f32 v64, v74, v72
	s_waitcnt lgkmcnt(4)
	v_cvt_pk_bf16_f32 v65, v76, v78
	v_add_u32_e32 v68, s53, v137
	v_mad_i64_i32 v[68:69], s[48:49], v68, s67, 0
	v_lshl_add_u64 v[68:69], v[68:69], 1, s[0:1]
	v_lshl_add_u64 v[68:69], v[68:69], 0, s[2:3]
	s_waitcnt lgkmcnt(2)
	v_cvt_pk_bf16_f32 v66, v80, v82
	s_waitcnt lgkmcnt(0)
	v_cvt_pk_bf16_f32 v67, v84, v86
	v_lshl_add_u64 v[68:69], v[68:69], 0, v[130:131]
	global_store_dwordx4 v[68:69], v[64:67], off sc1
	v_add_u32_e32 v68, s53, v138
	v_mad_i64_i32 v[68:69], s[48:49], v68, s67, 0
	v_lshl_add_u64 v[68:69], v[68:69], 1, s[0:1]
	v_lshl_add_u64 v[68:69], v[68:69], 0, s[2:3]
	v_cvt_pk_bf16_f32 v64, v75, v73
	v_cvt_pk_bf16_f32 v65, v77, v79
	v_cvt_pk_bf16_f32 v66, v81, v83
	v_cvt_pk_bf16_f32 v67, v85, v87
	v_lshl_add_u64 v[68:69], v[68:69], 0, v[130:131]
	global_store_dwordx4 v[68:69], v[64:67], off sc1
	s_branch .LBB0_1115

; #define LAS __attribute__((address_space(3)))
; __device__ __forceinline__ void st4_lds(LAS unsigned char* p, f32x4 v) { v2u w; w.x = pk2(v[0], v[1]); w.y = pk2(v[2], v[3]); *(LAS v2u*)p = w; }
; __device__ __forceinline__ void st4_g(bf16* p, f32x4 v) { v2u w; w.x = pk2(v[0], v[1]); w.y = pk2(v[2], v[3]); *(GAS v2u*)p = w; }
; __device__ __forceinline__ f32x4 ld4_lds(const LAS unsigned char* p) { const v2u w = *(const LAS v2u*)p; return (f32x4){bflo(w.x), bfhi(w.x), bflo(w.y), bfhi(w.y)}; }
; #define LBAR() asm volatile("s_waitcnt lgkmcnt(0)\n\ts_barrier" ::: "memory")
; __device__ __forceinline__ void rwkv_chunk_group(Frame& F, int bc, unsigned long long& tsub) {
;     ...
; #pragma unroll
;     for (int q = 0; q < 2; ++q) { const int tw = 2 * w + q, p0 = 16 * (tw >> 2), q0 = 16 * (tw & 3); const int o = (p0 + fr) * LD + (q0 + 4 * fq) * 2;
;         const f32x4 ap = mm_tile(L + L_TT, LD, q0, L + L_ATT, LD, p0, 2, Z4, fr, fq);
;         const f32x4 w1 = mm_tile(L + L_NAK, LD, q0, L + L_VT, LD, p0, 2, Z4, fr, fq);
;         st4_lds(L + L_APT + o, ap); st4_lds(L + L_W1T + o, w1); }
;     LBAR();
;     {
;         bf16* RPp = (bf16*)(F.ws + WS_RP) + (size_t)item * 4096; bf16* PTp = (bf16*)(F.ws + WS_PT) + (size_t)item * 4096;
; #pragma unroll
;         for (int q = 0; q < 2; ++q) { const int tw = 2 * w + q, p0 = 16 * (tw >> 2), q0 = 16 * (tw & 3); const int p = p0 + fr; const int o = p * LD + (q0 + 4 * fq) * 2;
;             const f32x4 u0 = mm_tile(L + L_TT, LD, q0, L + L_W1T, LD, p0, 2, Z4, fr, fq);
;             const f32x4 rp = mm_tile(L + L_APT, LD, q0, L + L_NRB, LD, p0, 2, ld4_lds(L + L_RT + o), fr, fq);
;             f32x4 pt = mm_tile(L + L_APT, LD, q0, L + L_BH, LD, p0, 2, Z4, fr, fq);
;             const float wc = *(const LAS float*)(L + L_WC + p * 4);
; #pragma unroll
;             for (int v = 0; v < 4; ++v) if (p == q0 + 4 * fq + v) pt[v] += wc;
;             st4_lds(L + L_U0T + o, u0);
;             st4_g(RPp + p * 64 + q0 + 4 * fq, rp); st4_g(PTp + ((p0 >> 4) * 2 + (q0 >> 5)) * 512 + fr * 32 + (q0 & 16) + 4 * fq, pt); }
;     }
.LBB0_1411:
	v_add_u32_e32 v130, v108, v110
	v_add_u32_e32 v131, v108, v128
	v_add_u32_e32 v133, v109, v110
	v_add_u32_e32 v148, v109, v128
	s_lshl_b64 s[64:65], s[72:73], 1
	s_mov_b32 s77, s95
	s_mov_b32 s93, s95
	ds_read_b128 v[174:177], v130
	ds_read_b128 v[80:83], v107 offset:36864
	ds_read_b128 v[88:91], v133
	ds_read_b128 v[190:193], v107 offset:46080
	ds_read_b128 v[182:185], v131
	ds_read_b128 v[96:99], v148
	ds_read_b128 v[178:181], v130 offset:64
	ds_read_b128 v[84:87], v107 offset:36928
	ds_read_b128 v[92:95], v133 offset:64
	ds_read_b128 v[194:197], v107 offset:46144
	ds_read_b128 v[186:189], v131 offset:64
	ds_read_b128 v[100:103], v148 offset:64
	s_waitcnt lgkmcnt(10)
	v_mfma_f32_16x16x32_bf16 v[36:39], v[174:177], v[80:83], 0
	s_waitcnt lgkmcnt(8)
	v_mfma_f32_16x16x32_bf16 v[40:43], v[88:91], v[190:193], 0
	s_waitcnt lgkmcnt(7)
	v_mfma_f32_16x16x32_bf16 v[44:47], v[182:185], v[80:83], 0
	s_waitcnt lgkmcnt(6)
	v_mfma_f32_16x16x32_bf16 v[224:227], v[96:99], v[190:193], 0
	s_waitcnt lgkmcnt(4)
	v_mfma_f32_16x16x32_bf16 v[36:39], v[178:181], v[84:87], v[36:39]
	s_waitcnt lgkmcnt(2)
	v_mfma_f32_16x16x32_bf16 v[40:43], v[92:95], v[194:197], v[40:43]
	s_waitcnt lgkmcnt(1)
	v_mfma_f32_16x16x32_bf16 v[44:47], v[186:189], v[84:87], v[44:47]
	s_waitcnt lgkmcnt(0)
	v_mfma_f32_16x16x32_bf16 v[224:227], v[100:103], v[194:197], v[224:227]
	ds_read_b128 v[228:231], v144
	ds_read_b128 v[232:235], v144 offset:64
	ds_read_b64 v[250:251], v78 offset:27648
	ds_read_b64 v[164:165], v79 offset:27648
	ds_read_b32 v173, v145
	s_nop 7
	v_cvt_pk_bf16_f32 v36, v36, v37
	v_cvt_pk_bf16_f32 v37, v38, v39
	v_cvt_pk_bf16_f32 v38, v40, v41
	v_cvt_pk_bf16_f32 v39, v42, v43
	ds_write2st64_b64 v142, v[36:37], v[38:39] offset1:18
	v_cvt_pk_bf16_f32 v44, v44, v45
	v_cvt_pk_bf16_f32 v45, v46, v47
	v_cvt_pk_bf16_f32 v46, v224, v225
	v_cvt_pk_bf16_f32 v47, v226, v227
	ds_write2st64_b64 v143, v[44:45], v[46:47] offset1:18
	ds_read_b128 v[80:83], v107 offset:55296
	ds_read_b128 v[84:87], v107 offset:55360
	s_waitcnt lgkmcnt(0)
	s_barrier
	ds_read_b128 v[88:91], v107 offset:9216
	ds_read_b128 v[96:99], v76
	ds_read_b128 v[236:239], v77
	ds_read_b128 v[92:95], v107 offset:9280
	ds_read_b128 v[100:103], v76 offset:64
	ds_read_b128 v[242:245], v77 offset:64
	v_lshlrev_b32_e32 v40, 16, v250
	v_and_b32_e32 v41, 0xffff0000, v250
	v_lshlrev_b32_e32 v42, 16, v251
	v_and_b32_e32 v43, 0xffff0000, v251
	v_lshlrev_b32_e32 v246, 16, v164
	v_and_b32_e32 v247, 0xffff0000, v164
	v_lshlrev_b32_e32 v248, 16, v165
	v_and_b32_e32 v249, 0xffff0000, v165
	s_waitcnt lgkmcnt(5)
	v_mfma_f32_16x16x32_bf16 v[36:39], v[174:177], v[88:91], 0
	s_waitcnt lgkmcnt(4)
	v_mfma_f32_16x16x32_bf16 v[40:43], v[96:99], v[228:231], v[40:43]
	v_mfma_f32_16x16x32_bf16 v[44:47], v[96:99], v[80:83], 0
	v_mfma_f32_16x16x32_bf16 v[224:227], v[182:185], v[88:91], 0
	s_waitcnt lgkmcnt(3)
	v_mfma_f32_16x16x32_bf16 v[246:249], v[236:239], v[228:231], v[246:249]
	v_mfma_f32_16x16x32_bf16 v[198:201], v[236:239], v[80:83], 0
	s_waitcnt lgkmcnt(2)
	v_mfma_f32_16x16x32_bf16 v[36:39], v[178:181], v[92:95], v[36:39]
	s_waitcnt lgkmcnt(1)
	v_mfma_f32_16x16x32_bf16 v[40:43], v[100:103], v[232:235], v[40:43]
	v_mfma_f32_16x16x32_bf16 v[44:47], v[100:103], v[84:87], v[44:47]
	v_mfma_f32_16x16x32_bf16 v[224:227], v[186:189], v[92:95], v[224:227]
	s_waitcnt lgkmcnt(0)
	v_mfma_f32_16x16x32_bf16 v[246:249], v[242:245], v[232:235], v[246:249]
	v_mfma_f32_16x16x32_bf16 v[198:201], v[242:245], v[84:87], v[198:201]
	v_lshl_add_u64 v[148:149], v[66:67], 0, s[64:65]
	v_lshl_add_u64 v[150:151], v[74:75], 0, s[64:65]
	v_lshl_add_u64 v[160:161], v[68:69], 0, s[64:65]
	v_lshl_add_u64 v[166:167], v[70:71], 0, s[64:65]
	s_nop 4
	v_cvt_pk_bf16_f32 v36, v36, v37
	v_cvt_pk_bf16_f32 v37, v38, v39
	ds_write_b64 v78, v[36:37] offset:18432
	v_cvt_pk_bf16_f32 v224, v224, v225
	v_cvt_pk_bf16_f32 v225, v226, v227
	ds_write_b64 v79, v[224:225] offset:18432
	ds_read_b128 v[80:83], v146
	ds_read_b128 v[84:87], v146 offset:64
	ds_read_b128 v[96:99], v76 offset:46080
	ds_read_b128 v[174:177], v76 offset:64512
	ds_read_b128 v[182:185], v76 offset:55296
	ds_read_b128 v[100:103], v76 offset:46144
	ds_read_b128 v[178:181], v76 offset:64576
	ds_read_b128 v[186:189], v76 offset:55360
	v_add_f32_e32 v168, v173, v44
	v_cndmask_b32_e64 v44, v44, v168, s[18:19]
	v_add_f32_e32 v168, v173, v45
	v_cndmask_b32_e64 v45, v45, v168, s[20:21]
	v_add_f32_e32 v168, v173, v46
	v_cndmask_b32_e64 v46, v46, v168, s[22:23]
	v_add_f32_e32 v168, v173, v47
	v_cndmask_b32_e64 v47, v47, v168, s[24:25]
	v_add_f32_e32 v168, v173, v198
	v_cndmask_b32_e64 v198, v198, v168, s[26:27]
	v_add_f32_e32 v168, v173, v199
	v_cndmask_b32_e64 v199, v199, v168, s[28:29]
	v_add_f32_e32 v168, v173, v200
	v_cndmask_b32_e64 v200, v200, v168, s[30:31]
	v_add_f32_e32 v168, v173, v201
	v_cndmask_b32_e64 v201, v201, v168, s[34:35]
	v_cvt_pk_bf16_f32 v40, v40, v41
	v_cvt_pk_bf16_f32 v41, v42, v43
	v_lshl_add_u64 v[168:169], v[148:149], 0, s[76:77]
	global_store_dwordx2 v[168:169], v[40:41], off sc1
	v_cvt_pk_bf16_f32 v44, v44, v45
	v_cvt_pk_bf16_f32 v45, v46, v47
	global_store_dwordx2 v[150:151], v[44:45], off sc1
	v_cvt_pk_bf16_f32 v246, v246, v247
	v_cvt_pk_bf16_f32 v247, v248, v249
	v_lshl_add_u64 v[168:169], v[148:149], 0, s[92:93]
	global_store_dwordx2 v[168:169], v[246:247], off sc1
	v_cvt_pk_bf16_f32 v198, v198, v199
	v_cvt_pk_bf16_f32 v199, v200, v201
	global_store_dwordx2 v[150:151], v[198:199], off offset:32 sc1
	s_waitcnt lgkmcnt(0)
	s_barrier
; __device__ __forceinline__ void st4_g(bf16* p, f32x4 v) { v2u w; w.x = pk2(v[0], v[1]); w.y = pk2(v[2], v[3]); *(GAS v2u*)p = w; }
; #define LBAR() asm volatile("s_waitcnt lgkmcnt(0)\n\ts_barrier" ::: "memory")
; __device__ __forceinline__ void rwkv_chunk_group(Frame& F, int bc, unsigned long long& tsub) {
;     ...
;     {
;         const int gc = h * 64 + ch;
;         const float mur = mu[gc], muk = mu[512 + gc], muv = mu[1024 + gc];
;         const float w0 = (PRM + 2048)[gc], a0 = (PRM + 2560)[gc], k_k = (PRM + 3072)[gc], k_a = (PRM + 3584)[gc], r_k = (PRM + 4096)[gc];
;     ...
;     {
;         bf16* Y0p = (bf16*)(F.ws + WS_Y0) + (size_t)item * 4096; bf16* QCp = (bf16*)(F.ws + WS_QC) + (size_t)item * 4096;
; #pragma unroll
;         for (int q = 0; q < 2; ++q) { const int tw = 2 * w + q, p0 = 16 * (tw >> 2), q0 = 16 * (tw & 3); const int p = p0 + fr;
;             f32x4 y0 = mm_tile(L + L_VT, LD, q0, L + L_NRK, LD, p0, 2, Z4, fr, fq);
;             y0 = mm_tile(L + L_U0T, LD, q0, L + L_NRB, LD, p0, 2, y0, fr, fq);
;             f32x4 qc = mm_tile(L + L_KH, LD, q0, L + L_VT, LD, p0, 2, Z4, fr, fq);
;             qc = mm_tile(L + L_BH, LD, q0, L + L_U0T, LD, p0, 2, qc, fr, fq);
;             st4_g(Y0p + p * 64 + q0 + 4 * fq, y0); st4_g(QCp + p * 64 + q0 + 4 * fq, qc); }
;     }
;     LBAR();
	ds_read_b128 v[88:91], v107 offset:18432
	ds_read_b128 v[236:239], v76 offset:18432
	ds_read_b128 v[92:95], v107 offset:18496
	ds_read_b128 v[242:245], v76 offset:18496
	ds_read_b128 v[246:249], v77 offset:46080
	ds_read_b128 v[198:201], v77 offset:46144
	v_mfma_f32_16x16x32_bf16 v[36:39], v[96:99], v[80:83], 0
	v_mfma_f32_16x16x32_bf16 v[36:39], v[100:103], v[84:87], v[36:39]
	v_mfma_f32_16x16x32_bf16 v[40:43], v[174:177], v[190:193], 0
	v_mfma_f32_16x16x32_bf16 v[40:43], v[178:181], v[194:197], v[40:43]
	ds_read_b128 v[174:177], v77 offset:64512
	ds_read_b128 v[178:181], v77 offset:64576
	s_waitcnt lgkmcnt(7)
	v_mfma_f32_16x16x32_bf16 v[40:43], v[182:185], v[88:91], v[40:43]
	s_waitcnt lgkmcnt(5)
	v_mfma_f32_16x16x32_bf16 v[40:43], v[186:189], v[92:95], v[40:43]
	ds_read_b128 v[182:185], v77 offset:55296
	ds_read_b128 v[186:189], v77 offset:55360
	v_mfma_f32_16x16x32_bf16 v[36:39], v[236:239], v[228:231], v[36:39]
	s_waitcnt lgkmcnt(6)
	v_mfma_f32_16x16x32_bf16 v[36:39], v[242:245], v[232:235], v[36:39]
	ds_read_b128 v[236:239], v77 offset:18432
	ds_read_b128 v[242:245], v77 offset:18496
	s_waitcnt lgkmcnt(7)
	v_mfma_f32_16x16x32_bf16 v[44:47], v[246:249], v[80:83], 0
	s_waitcnt lgkmcnt(6)
	v_mfma_f32_16x16x32_bf16 v[44:47], v[198:201], v[84:87], v[44:47]
	s_waitcnt lgkmcnt(5)
	v_mfma_f32_16x16x32_bf16 v[224:227], v[174:177], v[190:193], 0
	s_waitcnt lgkmcnt(4)
	v_mfma_f32_16x16x32_bf16 v[224:227], v[178:181], v[194:197], v[224:227]
	s_waitcnt lgkmcnt(3)
	v_mfma_f32_16x16x32_bf16 v[224:227], v[182:185], v[88:91], v[224:227]
	s_waitcnt lgkmcnt(2)
	v_mfma_f32_16x16x32_bf16 v[224:227], v[186:189], v[92:95], v[224:227]
	s_waitcnt lgkmcnt(1)
	v_mfma_f32_16x16x32_bf16 v[44:47], v[236:239], v[228:231], v[44:47]
	s_waitcnt lgkmcnt(0)
	v_mfma_f32_16x16x32_bf16 v[44:47], v[242:245], v[232:235], v[44:47]
	v_cvt_pk_bf16_f32 v36, v36, v37
	v_cvt_pk_bf16_f32 v37, v38, v39
	v_lshl_add_u64 v[168:169], v[160:161], 0, s[76:77]
	global_store_dwordx2 v[168:169], v[36:37], off sc1
	v_cvt_pk_bf16_f32 v40, v40, v41
	v_cvt_pk_bf16_f32 v41, v42, v43
	v_lshl_add_u64 v[168:169], v[166:167], 0, s[76:77]
	global_store_dwordx2 v[168:169], v[40:41], off sc1
	s_nop 7
	v_cvt_pk_bf16_f32 v224, v224, v225
	v_cvt_pk_bf16_f32 v225, v226, v227
	v_lshl_add_u64 v[168:169], v[166:167], 0, s[92:93]
	global_store_dwordx2 v[168:169], v[224:225], off sc1
	v_cvt_pk_bf16_f32 v44, v44, v45
	v_cvt_pk_bf16_f32 v45, v46, v47
	v_lshl_add_u64 v[168:169], v[160:161], 0, s[92:93]
	global_store_dwordx2 v[168:169], v[44:45], off sc1
	s_waitcnt lgkmcnt(0)
	s_barrier
	s_cmp_lg_u32 s12, 8
	s_cbranch_scc0 .LBB0_1392
.LBB0_1412:
	s_waitcnt vmcnt(8)
	v_perm_b32 v160, v203, v202, s5
	v_perm_b32 v161, v216, v215, s5
	v_perm_b32 v166, v204, v203, s5
	v_perm_b32 v167, v217, v216, s5
	v_perm_b32 v168, v206, v205, s5
	v_perm_b32 v169, v219, v218, s5
	v_perm_b32 v170, v212, v207, s5
	v_perm_b32 v171, v221, v220, s5
	v_perm_b32 v165, v214, v213, s5
	v_perm_b32 v172, v223, v222, s5
	v_readlane_b32 s98, v254, 2
	v_readlane_b32 s100, v254, 20
	v_readlane_b32 s101, v254, 21
	s_add_i32 s98, s98, s12
	s_lshl_b32 s98, s98, 6
	s_and_b32 s98, s98, 0x1c0
	v_add_lshl_u32 v238, v208, s98, 2
	v_mov_b32_e32 v239, 0
	s_nop 0
	v_lshl_add_u64 v[232:233], s[100:101], 0, v[238:239]
	s_mov_b64 s[100:101], 0x2000
	v_lshl_add_u64 v[234:235], v[232:233], 0, s[100:101]
	s_mov_b64 s[100:101], 0x3800
	v_lshl_add_u64 v[236:237], v[232:233], 0, s[100:101]
	global_load_dword v224, v[232:233], off
	global_load_dword v225, v[232:233], off offset:2048
	global_load_dword v226, v[234:235], off offset:-4096
	global_load_dword v227, v[234:235], off
	global_load_dword v228, v[234:235], off offset:2048
	global_load_dword v229, v[236:237], off offset:-2048
	global_load_dword v230, v[236:237], off
	global_load_dword v231, v[236:237], off offset:2048
	s_waitcnt lgkmcnt(0)
	s_barrier
	v_xor_b32_e32 v102, 64, v137
	v_xor_b32_e32 v103, 64, v139
	ds_read_b128 v[36:39], v137
	ds_read_b128 v[76:79], v139
	ds_read_b128 v[98:101], v102
	ds_read_b128 v[174:177], v103
	ds_read_b128 v[40:43], v137 offset:8192
	ds_read_b128 v[80:83], v139 offset:8192
	ds_read_b128 v[178:181], v102 offset:8192
	ds_read_b128 v[182:185], v103 offset:8192
	ds_read_b128 v[44:47], v138
	ds_read_b128 v[84:87], v140
	ds_read_b128 v[186:189], v138 offset:4096
	ds_read_b128 v[232:235], v140 offset:4096
	ds_read_b128 v[236:239], v138 offset:8192
	ds_read_b128 v[240:243], v140 offset:8192
	ds_read_b128 v[244:247], v138 offset:12288
	s_waitcnt lgkmcnt(14)
	v_mfma_f32_16x16x32_bf16 v[36:39], v[0:3], v[36:39], 0
	ds_read_b128 v[248:251], v140 offset:12288

; #define LAS __attribute__((address_space(3)))
; __device__ __forceinline__ void rwkv_chunk_group(Frame& F, int bc, unsigned long long& tsub) {
;     ...
;         for (int q = 0; q < 2; ++q) { const int n0 = 16 * ((2 * w + q) & 3); aw[q] = Z4; aa[q] = Z4; ag[q] = Z4;
;             const LAS unsigned char* wp = L + L_LWA + (n0 + fr) * 128 + fq * 16; const LAS unsigned char* gp = L + L_LG + (n0 + fr) * 64 + fq * 16;
; #pragma unroll
;             for (int k = 0; k < 2; ++k) { aw[q] = __builtin_amdgcn_mfma_f32_16x16x32_bf16(xw[k], *(const LAS bf16x8*)(wp + k * 64), aw[q], 0, 0, 0); aa[q] = __builtin_amdgcn_mfma_f32_16x16x32_bf16(xa[k], *(const LAS bf16x8*)(wp + 8192 + k * 64), aa[q], 0, 0, 0); }
; #pragma unroll
;             for (int k = 0; k < 5; ++k) ag[q] = __builtin_amdgcn_mfma_f32_16x16x32_bf16(xg[k], *(const LAS bf16x8*)(gp + k * 4096), ag[q], 0, 0, 0);
	s_mov_b32 s68, s12
	s_waitcnt lgkmcnt(14)
	v_mfma_f32_16x16x32_bf16 v[76:79], v[0:3], v[76:79], 0
	ds_read_b128 v[88:91], v138 offset:16384
	v_readlane_b32 s12, v254, 2
	s_add_i32 s14, s68, s12
	s_waitcnt lgkmcnt(14)
	v_mfma_f32_16x16x32_bf16 v[36:39], v[4:7], v[98:101], v[36:39]
	ds_read_b128 v[98:101], v140 offset:16384
	s_lshl_b32 s14, s14, 6
	s_waitcnt lgkmcnt(14)
	v_mfma_f32_16x16x32_bf16 v[76:79], v[4:7], v[174:177], v[76:79]
	s_and_b32 s14, s14, 0x1c0
	s_waitcnt lgkmcnt(13)
	v_mfma_f32_16x16x32_bf16 v[40:43], v[8:11], v[40:43], 0
	s_add_i32 s66, s11, s14
	s_waitcnt lgkmcnt(12)
	v_mfma_f32_16x16x32_bf16 v[80:83], v[8:11], v[80:83], 0

; #define LAS __attribute__((address_space(3)))
; __device__ __forceinline__ void rwkv_chunk_group(Frame& F, int bc, unsigned long long& tsub) {
;     ...
;         for (int q = 0; q < 2; ++q) { const int n0 = 16 * ((2 * w + q) & 3); aw[q] = Z4; aa[q] = Z4; ag[q] = Z4;
;             const LAS unsigned char* wp = L + L_LWA + (n0 + fr) * 128 + fq * 16; const LAS unsigned char* gp = L + L_LG + (n0 + fr) * 64 + fq * 16;
; #pragma unroll
;             for (int k = 0; k < 2; ++k) { aw[q] = __builtin_amdgcn_mfma_f32_16x16x32_bf16(xw[k], *(const LAS bf16x8*)(wp + k * 64), aw[q], 0, 0, 0); aa[q] = __builtin_amdgcn_mfma_f32_16x16x32_bf16(xa[k], *(const LAS bf16x8*)(wp + 8192 + k * 64), aa[q], 0, 0, 0); }
; #pragma unroll
;             for (int k = 0; k < 5; ++k) ag[q] = __builtin_amdgcn_mfma_f32_16x16x32_bf16(xg[k], *(const LAS bf16x8*)(gp + k * 4096), ag[q], 0, 0, 0);
	s_waitcnt lgkmcnt(11)
	v_mfma_f32_16x16x32_bf16 v[40:43], v[12:15], v[178:181], v[40:43]

; #define LAS __attribute__((address_space(3)))
; __device__ __forceinline__ void rwkv_chunk_group(Frame& F, int bc, unsigned long long& tsub) {
;     ...
;         for (int q = 0; q < 2; ++q) { const int n0 = 16 * ((2 * w + q) & 3); aw[q] = Z4; aa[q] = Z4; ag[q] = Z4;
;             const LAS unsigned char* wp = L + L_LWA + (n0 + fr) * 128 + fq * 16; const LAS unsigned char* gp = L + L_LG + (n0 + fr) * 64 + fq * 16;
; #pragma unroll
;             for (int k = 0; k < 2; ++k) { aw[q] = __builtin_amdgcn_mfma_f32_16x16x32_bf16(xw[k], *(const LAS bf16x8*)(wp + k * 64), aw[q], 0, 0, 0); aa[q] = __builtin_amdgcn_mfma_f32_16x16x32_bf16(xa[k], *(const LAS bf16x8*)(wp + 8192 + k * 64), aa[q], 0, 0, 0); }
; #pragma unroll
;             for (int k = 0; k < 5; ++k) ag[q] = __builtin_amdgcn_mfma_f32_16x16x32_bf16(xg[k], *(const LAS bf16x8*)(gp + k * 4096), ag[q], 0, 0, 0);
	s_waitcnt lgkmcnt(10)
	v_mfma_f32_16x16x32_bf16 v[80:83], v[12:15], v[182:185], v[80:83]
	s_mov_b32 s64, s12
	s_waitcnt lgkmcnt(9)
	v_mfma_f32_16x16x32_bf16 v[44:47], v[16:19], v[44:47], 0
	s_add_i32 s12, s68, 1
	s_waitcnt lgkmcnt(8)
	v_mfma_f32_16x16x32_bf16 v[84:87], v[16:19], v[84:87], 0
	s_add_i32 s13, s12, s64
	s_waitcnt lgkmcnt(7)
	v_mfma_f32_16x16x32_bf16 v[44:47], v[20:23], v[186:189], v[44:47]

; #define LAS __attribute__((address_space(3)))
; __device__ __forceinline__ void rwkv_chunk_group(Frame& F, int bc, unsigned long long& tsub) {
;     ...
;         for (int q = 0; q < 2; ++q) { const int n0 = 16 * ((2 * w + q) & 3); aw[q] = Z4; aa[q] = Z4; ag[q] = Z4;
;             const LAS unsigned char* wp = L + L_LWA + (n0 + fr) * 128 + fq * 16; const LAS unsigned char* gp = L + L_LG + (n0 + fr) * 64 + fq * 16;
; #pragma unroll
;             for (int k = 0; k < 2; ++k) { aw[q] = __builtin_amdgcn_mfma_f32_16x16x32_bf16(xw[k], *(const LAS bf16x8*)(wp + k * 64), aw[q], 0, 0, 0); aa[q] = __builtin_amdgcn_mfma_f32_16x16x32_bf16(xa[k], *(const LAS bf16x8*)(wp + 8192 + k * 64), aa[q], 0, 0, 0); }
; #pragma unroll
;             for (int k = 0; k < 5; ++k) ag[q] = __builtin_amdgcn_mfma_f32_16x16x32_bf16(xg[k], *(const LAS bf16x8*)(gp + k * 4096), ag[q], 0, 0, 0);
	s_waitcnt lgkmcnt(6)
	v_mfma_f32_16x16x32_bf16 v[84:87], v[20:23], v[232:235], v[84:87]

; #define LAS __attribute__((address_space(3)))
; __device__ __forceinline__ void rwkv_chunk_group(Frame& F, int bc, unsigned long long& tsub) {
;     ...
;         for (int q = 0; q < 2; ++q) { const int n0 = 16 * ((2 * w + q) & 3); aw[q] = Z4; aa[q] = Z4; ag[q] = Z4;
;             const LAS unsigned char* wp = L + L_LWA + (n0 + fr) * 128 + fq * 16; const LAS unsigned char* gp = L + L_LG + (n0 + fr) * 64 + fq * 16;
; #pragma unroll
;             for (int k = 0; k < 2; ++k) { aw[q] = __builtin_amdgcn_mfma_f32_16x16x32_bf16(xw[k], *(const LAS bf16x8*)(wp + k * 64), aw[q], 0, 0, 0); aa[q] = __builtin_amdgcn_mfma_f32_16x16x32_bf16(xa[k], *(const LAS bf16x8*)(wp + 8192 + k * 64), aa[q], 0, 0, 0); }
; #pragma unroll
;             for (int k = 0; k < 5; ++k) ag[q] = __builtin_amdgcn_mfma_f32_16x16x32_bf16(xg[k], *(const LAS bf16x8*)(gp + k * 4096), ag[q], 0, 0, 0);
	s_waitcnt lgkmcnt(5)
	v_mfma_f32_16x16x32_bf16 v[44:47], v[24:27], v[236:239], v[44:47]

; #define LAS __attribute__((address_space(3)))
; __device__ __forceinline__ void rwkv_chunk_group(Frame& F, int bc, unsigned long long& tsub) {
;     ...
;         for (int q = 0; q < 2; ++q) { const int n0 = 16 * ((2 * w + q) & 3); aw[q] = Z4; aa[q] = Z4; ag[q] = Z4;
;             const LAS unsigned char* wp = L + L_LWA + (n0 + fr) * 128 + fq * 16; const LAS unsigned char* gp = L + L_LG + (n0 + fr) * 64 + fq * 16;
; #pragma unroll
;             for (int k = 0; k < 2; ++k) { aw[q] = __builtin_amdgcn_mfma_f32_16x16x32_bf16(xw[k], *(const LAS bf16x8*)(wp + k * 64), aw[q], 0, 0, 0); aa[q] = __builtin_amdgcn_mfma_f32_16x16x32_bf16(xa[k], *(const LAS bf16x8*)(wp + 8192 + k * 64), aa[q], 0, 0, 0); }
; #pragma unroll
;             for (int k = 0; k < 5; ++k) ag[q] = __builtin_amdgcn_mfma_f32_16x16x32_bf16(xg[k], *(const LAS bf16x8*)(gp + k * 4096), ag[q], 0, 0, 0);
	s_waitcnt lgkmcnt(4)
	v_mfma_f32_16x16x32_bf16 v[84:87], v[24:27], v[240:243], v[84:87]

; #define LAS __attribute__((address_space(3)))
; __device__ __forceinline__ void rwkv_chunk_group(Frame& F, int bc, unsigned long long& tsub) {
;     ...
;         for (int q = 0; q < 2; ++q) { const int n0 = 16 * ((2 * w + q) & 3); aw[q] = Z4; aa[q] = Z4; ag[q] = Z4;
;             const LAS unsigned char* wp = L + L_LWA + (n0 + fr) * 128 + fq * 16; const LAS unsigned char* gp = L + L_LG + (n0 + fr) * 64 + fq * 16;
; #pragma unroll
;             for (int k = 0; k < 2; ++k) { aw[q] = __builtin_amdgcn_mfma_f32_16x16x32_bf16(xw[k], *(const LAS bf16x8*)(wp + k * 64), aw[q], 0, 0, 0); aa[q] = __builtin_amdgcn_mfma_f32_16x16x32_bf16(xa[k], *(const LAS bf16x8*)(wp + 8192 + k * 64), aa[q], 0, 0, 0); }
; #pragma unroll
;             for (int k = 0; k < 5; ++k) ag[q] = __builtin_amdgcn_mfma_f32_16x16x32_bf16(xg[k], *(const LAS bf16x8*)(gp + k * 4096), ag[q], 0, 0, 0);
	s_waitcnt lgkmcnt(3)
	v_mfma_f32_16x16x32_bf16 v[44:47], v[28:31], v[244:247], v[44:47]
	v_lshlrev_b32_e32 v197, 16, v162
	s_waitcnt lgkmcnt(2)
	v_mfma_f32_16x16x32_bf16 v[84:87], v[28:31], v[248:251], v[84:87]
	v_and_b32_e32 v199, 0xffff0000, v172
	s_waitcnt lgkmcnt(1)
	v_mfma_f32_16x16x32_bf16 v[44:47], v[32:35], v[88:91], v[44:47]
	s_ashr_i32 s67, s66, 31
	s_waitcnt lgkmcnt(0)
	v_mfma_f32_16x16x32_bf16 v[84:87], v[32:35], v[98:101], v[84:87]
	s_and_b32 s13, s13, 7
	s_nop 7
	s_nop 7


; #define LAS __attribute__((address_space(3)))
; __device__ __forceinline__ void rwkv_chunk_group(Frame& F, int bc, unsigned long long& tsub) {
;     ...
;         for (int q = 0; q < 2; ++q) { const int tw = 2 * w + q, m0 = 16 * (tw >> 2), n0 = 16 * (tw & 3);
; #pragma unroll
;             for (int v = 0; v < 4; ++v) { const int t = m0 + 4 * fq + v, cc = n0 + fr;
;                 *(LAS float*)(L + L_WL + (t * 65 + cc) * 4) = aw[q][v]; *(LAS float*)(L + L_AL + (t * 65 + cc) * 4) = aa[q][v]; *(LAS float*)(L + L_GL + (t * 65 + cc) * 4) = ag[q][v]; } }
	ds_write_b32 v111, v36

; #define LAS __attribute__((address_space(3)))
; __device__ __forceinline__ void rwkv_chunk_group(Frame& F, int bc, unsigned long long& tsub) {
;     ...
;         for (int q = 0; q < 2; ++q) { const int tw = 2 * w + q, m0 = 16 * (tw >> 2), n0 = 16 * (tw & 3);
; #pragma unroll
;             for (int v = 0; v < 4; ++v) { const int t = m0 + 4 * fq + v, cc = n0 + fr;
;                 *(LAS float*)(L + L_WL + (t * 65 + cc) * 4) = aw[q][v]; *(LAS float*)(L + L_AL + (t * 65 + cc) * 4) = aa[q][v]; *(LAS float*)(L + L_GL + (t * 65 + cc) * 4) = ag[q][v]; } }
	ds_write_b32 v111, v40 offset:16640

; #define LAS __attribute__((address_space(3)))
; __device__ __forceinline__ void rwkv_chunk_group(Frame& F, int bc, unsigned long long& tsub) {
;     ...
;         for (int q = 0; q < 2; ++q) { const int tw = 2 * w + q, m0 = 16 * (tw >> 2), n0 = 16 * (tw & 3);
; #pragma unroll
;             for (int v = 0; v < 4; ++v) { const int t = m0 + 4 * fq + v, cc = n0 + fr;
;                 *(LAS float*)(L + L_WL + (t * 65 + cc) * 4) = aw[q][v]; *(LAS float*)(L + L_AL + (t * 65 + cc) * 4) = aa[q][v]; *(LAS float*)(L + L_GL + (t * 65 + cc) * 4) = ag[q][v]; } }
	ds_write_b32 v111, v44 offset:33280

; #define LAS __attribute__((address_space(3)))
; __device__ __forceinline__ void rwkv_chunk_group(Frame& F, int bc, unsigned long long& tsub) {
;     ...
;         for (int q = 0; q < 2; ++q) { const int tw = 2 * w + q, m0 = 16 * (tw >> 2), n0 = 16 * (tw & 3);
; #pragma unroll
;             for (int v = 0; v < 4; ++v) { const int t = m0 + 4 * fq + v, cc = n0 + fr;
;                 *(LAS float*)(L + L_WL + (t * 65 + cc) * 4) = aw[q][v]; *(LAS float*)(L + L_AL + (t * 65 + cc) * 4) = aa[q][v]; *(LAS float*)(L + L_GL + (t * 65 + cc) * 4) = ag[q][v]; } }
	ds_write_b32 v112, v37

; #define LAS __attribute__((address_space(3)))
; __device__ __forceinline__ void rwkv_chunk_group(Frame& F, int bc, unsigned long long& tsub) {
;     ...
;         for (int q = 0; q < 2; ++q) { const int tw = 2 * w + q, m0 = 16 * (tw >> 2), n0 = 16 * (tw & 3);
; #pragma unroll
;             for (int v = 0; v < 4; ++v) { const int t = m0 + 4 * fq + v, cc = n0 + fr;
;                 *(LAS float*)(L + L_WL + (t * 65 + cc) * 4) = aw[q][v]; *(LAS float*)(L + L_AL + (t * 65 + cc) * 4) = aa[q][v]; *(LAS float*)(L + L_GL + (t * 65 + cc) * 4) = ag[q][v]; } }
	ds_write_b32 v112, v41 offset:16640

; #define LAS __attribute__((address_space(3)))
; __device__ __forceinline__ void rwkv_chunk_group(Frame& F, int bc, unsigned long long& tsub) {
;     ...
;         for (int q = 0; q < 2; ++q) { const int tw = 2 * w + q, m0 = 16 * (tw >> 2), n0 = 16 * (tw & 3);
; #pragma unroll
;             for (int v = 0; v < 4; ++v) { const int t = m0 + 4 * fq + v, cc = n0 + fr;
;                 *(LAS float*)(L + L_WL + (t * 65 + cc) * 4) = aw[q][v]; *(LAS float*)(L + L_AL + (t * 65 + cc) * 4) = aa[q][v]; *(LAS float*)(L + L_GL + (t * 65 + cc) * 4) = ag[q][v]; } }
	ds_write_b32 v112, v45 offset:33280

; #define LAS __attribute__((address_space(3)))
; __device__ __forceinline__ void rwkv_chunk_group(Frame& F, int bc, unsigned long long& tsub) {
;     ...
;         for (int q = 0; q < 2; ++q) { const int tw = 2 * w + q, m0 = 16 * (tw >> 2), n0 = 16 * (tw & 3);
; #pragma unroll
;             for (int v = 0; v < 4; ++v) { const int t = m0 + 4 * fq + v, cc = n0 + fr;
;                 *(LAS float*)(L + L_WL + (t * 65 + cc) * 4) = aw[q][v]; *(LAS float*)(L + L_AL + (t * 65 + cc) * 4) = aa[q][v]; *(LAS float*)(L + L_GL + (t * 65 + cc) * 4) = ag[q][v]; } }
	ds_write_b32 v113, v38

; #define LAS __attribute__((address_space(3)))
; __device__ __forceinline__ void rwkv_chunk_group(Frame& F, int bc, unsigned long long& tsub) {
;     ...
;         for (int q = 0; q < 2; ++q) { const int tw = 2 * w + q, m0 = 16 * (tw >> 2), n0 = 16 * (tw & 3);
; #pragma unroll
;             for (int v = 0; v < 4; ++v) { const int t = m0 + 4 * fq + v, cc = n0 + fr;
;                 *(LAS float*)(L + L_WL + (t * 65 + cc) * 4) = aw[q][v]; *(LAS float*)(L + L_AL + (t * 65 + cc) * 4) = aa[q][v]; *(LAS float*)(L + L_GL + (t * 65 + cc) * 4) = ag[q][v]; } }
	ds_write_b32 v113, v42 offset:16640

; #define LAS __attribute__((address_space(3)))
; __device__ __forceinline__ void rwkv_chunk_group(Frame& F, int bc, unsigned long long& tsub) {
;     ...
;         for (int q = 0; q < 2; ++q) { const int tw = 2 * w + q, m0 = 16 * (tw >> 2), n0 = 16 * (tw & 3);
; #pragma unroll
;             for (int v = 0; v < 4; ++v) { const int t = m0 + 4 * fq + v, cc = n0 + fr;
;                 *(LAS float*)(L + L_WL + (t * 65 + cc) * 4) = aw[q][v]; *(LAS float*)(L + L_AL + (t * 65 + cc) * 4) = aa[q][v]; *(LAS float*)(L + L_GL + (t * 65 + cc) * 4) = ag[q][v]; } }
	ds_write_b32 v113, v46 offset:33280

; #define LAS __attribute__((address_space(3)))
; __device__ __forceinline__ void rwkv_chunk_group(Frame& F, int bc, unsigned long long& tsub) {
;     ...
;         for (int q = 0; q < 2; ++q) { const int tw = 2 * w + q, m0 = 16 * (tw >> 2), n0 = 16 * (tw & 3);
; #pragma unroll
;             for (int v = 0; v < 4; ++v) { const int t = m0 + 4 * fq + v, cc = n0 + fr;
;                 *(LAS float*)(L + L_WL + (t * 65 + cc) * 4) = aw[q][v]; *(LAS float*)(L + L_AL + (t * 65 + cc) * 4) = aa[q][v]; *(LAS float*)(L + L_GL + (t * 65 + cc) * 4) = ag[q][v]; } }
	ds_write_b32 v114, v39

; #define LAS __attribute__((address_space(3)))
; __device__ __forceinline__ void rwkv_chunk_group(Frame& F, int bc, unsigned long long& tsub) {
;     ...
;         for (int q = 0; q < 2; ++q) { const int tw = 2 * w + q, m0 = 16 * (tw >> 2), n0 = 16 * (tw & 3);
; #pragma unroll
;             for (int v = 0; v < 4; ++v) { const int t = m0 + 4 * fq + v, cc = n0 + fr;
;                 *(LAS float*)(L + L_WL + (t * 65 + cc) * 4) = aw[q][v]; *(LAS float*)(L + L_AL + (t * 65 + cc) * 4) = aa[q][v]; *(LAS float*)(L + L_GL + (t * 65 + cc) * 4) = ag[q][v]; } }
	ds_write_b32 v114, v43 offset:16640

; #define LAS __attribute__((address_space(3)))
; __device__ __forceinline__ void rwkv_chunk_group(Frame& F, int bc, unsigned long long& tsub) {
;     ...
;         for (int q = 0; q < 2; ++q) { const int tw = 2 * w + q, m0 = 16 * (tw >> 2), n0 = 16 * (tw & 3);
; #pragma unroll
;             for (int v = 0; v < 4; ++v) { const int t = m0 + 4 * fq + v, cc = n0 + fr;
;                 *(LAS float*)(L + L_WL + (t * 65 + cc) * 4) = aw[q][v]; *(LAS float*)(L + L_AL + (t * 65 + cc) * 4) = aa[q][v]; *(LAS float*)(L + L_GL + (t * 65 + cc) * 4) = ag[q][v]; } }
	ds_write_b32 v114, v47 offset:33280

; #define LAS __attribute__((address_space(3)))
; __device__ __forceinline__ void rwkv_chunk_group(Frame& F, int bc, unsigned long long& tsub) {
;     ...
;         for (int q = 0; q < 2; ++q) { const int tw = 2 * w + q, m0 = 16 * (tw >> 2), n0 = 16 * (tw & 3);
; #pragma unroll
;             for (int v = 0; v < 4; ++v) { const int t = m0 + 4 * fq + v, cc = n0 + fr;
;                 *(LAS float*)(L + L_WL + (t * 65 + cc) * 4) = aw[q][v]; *(LAS float*)(L + L_AL + (t * 65 + cc) * 4) = aa[q][v]; *(LAS float*)(L + L_GL + (t * 65 + cc) * 4) = ag[q][v]; } }
	ds_write_b32 v115, v76

; #define LAS __attribute__((address_space(3)))
; __device__ __forceinline__ void rwkv_chunk_group(Frame& F, int bc, unsigned long long& tsub) {
;     ...
;         for (int q = 0; q < 2; ++q) { const int tw = 2 * w + q, m0 = 16 * (tw >> 2), n0 = 16 * (tw & 3);
; #pragma unroll
;             for (int v = 0; v < 4; ++v) { const int t = m0 + 4 * fq + v, cc = n0 + fr;
;                 *(LAS float*)(L + L_WL + (t * 65 + cc) * 4) = aw[q][v]; *(LAS float*)(L + L_AL + (t * 65 + cc) * 4) = aa[q][v]; *(LAS float*)(L + L_GL + (t * 65 + cc) * 4) = ag[q][v]; } }
	ds_write_b32 v115, v80 offset:16640

; #define LAS __attribute__((address_space(3)))
; __device__ __forceinline__ void rwkv_chunk_group(Frame& F, int bc, unsigned long long& tsub) {
;     ...
;         for (int q = 0; q < 2; ++q) { const int tw = 2 * w + q, m0 = 16 * (tw >> 2), n0 = 16 * (tw & 3);
; #pragma unroll
;             for (int v = 0; v < 4; ++v) { const int t = m0 + 4 * fq + v, cc = n0 + fr;
;                 *(LAS float*)(L + L_WL + (t * 65 + cc) * 4) = aw[q][v]; *(LAS float*)(L + L_AL + (t * 65 + cc) * 4) = aa[q][v]; *(LAS float*)(L + L_GL + (t * 65 + cc) * 4) = ag[q][v]; } }
	ds_write_b32 v115, v84 offset:33280

; #define LAS __attribute__((address_space(3)))
; __device__ __forceinline__ void rwkv_chunk_group(Frame& F, int bc, unsigned long long& tsub) {
;     ...
;         for (int q = 0; q < 2; ++q) { const int tw = 2 * w + q, m0 = 16 * (tw >> 2), n0 = 16 * (tw & 3);
; #pragma unroll
;             for (int v = 0; v < 4; ++v) { const int t = m0 + 4 * fq + v, cc = n0 + fr;
;                 *(LAS float*)(L + L_WL + (t * 65 + cc) * 4) = aw[q][v]; *(LAS float*)(L + L_AL + (t * 65 + cc) * 4) = aa[q][v]; *(LAS float*)(L + L_GL + (t * 65 + cc) * 4) = ag[q][v]; } }
	ds_write_b32 v116, v77

; #define LAS __attribute__((address_space(3)))
; __device__ __forceinline__ void rwkv_chunk_group(Frame& F, int bc, unsigned long long& tsub) {
;     ...
;         for (int q = 0; q < 2; ++q) { const int tw = 2 * w + q, m0 = 16 * (tw >> 2), n0 = 16 * (tw & 3);
; #pragma unroll
;             for (int v = 0; v < 4; ++v) { const int t = m0 + 4 * fq + v, cc = n0 + fr;
;                 *(LAS float*)(L + L_WL + (t * 65 + cc) * 4) = aw[q][v]; *(LAS float*)(L + L_AL + (t * 65 + cc) * 4) = aa[q][v]; *(LAS float*)(L + L_GL + (t * 65 + cc) * 4) = ag[q][v]; } }
	ds_write_b32 v116, v81 offset:16640

; #define LAS __attribute__((address_space(3)))
; __device__ __forceinline__ void rwkv_chunk_group(Frame& F, int bc, unsigned long long& tsub) {
;     ...
;         for (int q = 0; q < 2; ++q) { const int tw = 2 * w + q, m0 = 16 * (tw >> 2), n0 = 16 * (tw & 3);
; #pragma unroll
;             for (int v = 0; v < 4; ++v) { const int t = m0 + 4 * fq + v, cc = n0 + fr;
;                 *(LAS float*)(L + L_WL + (t * 65 + cc) * 4) = aw[q][v]; *(LAS float*)(L + L_AL + (t * 65 + cc) * 4) = aa[q][v]; *(LAS float*)(L + L_GL + (t * 65 + cc) * 4) = ag[q][v]; } }
	ds_write_b32 v116, v85 offset:33280

; #define LAS __attribute__((address_space(3)))
; __device__ __forceinline__ void rwkv_chunk_group(Frame& F, int bc, unsigned long long& tsub) {
;     ...
;         for (int q = 0; q < 2; ++q) { const int tw = 2 * w + q, m0 = 16 * (tw >> 2), n0 = 16 * (tw & 3);
; #pragma unroll
;             for (int v = 0; v < 4; ++v) { const int t = m0 + 4 * fq + v, cc = n0 + fr;
;                 *(LAS float*)(L + L_WL + (t * 65 + cc) * 4) = aw[q][v]; *(LAS float*)(L + L_AL + (t * 65 + cc) * 4) = aa[q][v]; *(LAS float*)(L + L_GL + (t * 65 + cc) * 4) = ag[q][v]; } }
	ds_write_b32 v117, v78

; #define LAS __attribute__((address_space(3)))
; __device__ __forceinline__ void rwkv_chunk_group(Frame& F, int bc, unsigned long long& tsub) {
;     ...
;         for (int q = 0; q < 2; ++q) { const int tw = 2 * w + q, m0 = 16 * (tw >> 2), n0 = 16 * (tw & 3);
; #pragma unroll
;             for (int v = 0; v < 4; ++v) { const int t = m0 + 4 * fq + v, cc = n0 + fr;
;                 *(LAS float*)(L + L_WL + (t * 65 + cc) * 4) = aw[q][v]; *(LAS float*)(L + L_AL + (t * 65 + cc) * 4) = aa[q][v]; *(LAS float*)(L + L_GL + (t * 65 + cc) * 4) = ag[q][v]; } }
	ds_write_b32 v117, v82 offset:16640

; #define LAS __attribute__((address_space(3)))
; __device__ __forceinline__ void rwkv_chunk_group(Frame& F, int bc, unsigned long long& tsub) {
;     ...
;         for (int q = 0; q < 2; ++q) { const int tw = 2 * w + q, m0 = 16 * (tw >> 2), n0 = 16 * (tw & 3);
; #pragma unroll
;             for (int v = 0; v < 4; ++v) { const int t = m0 + 4 * fq + v, cc = n0 + fr;
;                 *(LAS float*)(L + L_WL + (t * 65 + cc) * 4) = aw[q][v]; *(LAS float*)(L + L_AL + (t * 65 + cc) * 4) = aa[q][v]; *(LAS float*)(L + L_GL + (t * 65 + cc) * 4) = ag[q][v]; } }
	ds_write_b32 v117, v86 offset:33280

; #define LAS __attribute__((address_space(3)))
; __device__ __forceinline__ void rwkv_chunk_group(Frame& F, int bc, unsigned long long& tsub) {
;     ...
;         for (int q = 0; q < 2; ++q) { const int tw = 2 * w + q, m0 = 16 * (tw >> 2), n0 = 16 * (tw & 3);
; #pragma unroll
;             for (int v = 0; v < 4; ++v) { const int t = m0 + 4 * fq + v, cc = n0 + fr;
;                 *(LAS float*)(L + L_WL + (t * 65 + cc) * 4) = aw[q][v]; *(LAS float*)(L + L_AL + (t * 65 + cc) * 4) = aa[q][v]; *(LAS float*)(L + L_GL + (t * 65 + cc) * 4) = ag[q][v]; } }
	ds_write_b32 v118, v79

; #define LAS __attribute__((address_space(3)))
; __device__ __forceinline__ void rwkv_chunk_group(Frame& F, int bc, unsigned long long& tsub) {
;     ...
;         for (int q = 0; q < 2; ++q) { const int tw = 2 * w + q, m0 = 16 * (tw >> 2), n0 = 16 * (tw & 3);
; #pragma unroll
;             for (int v = 0; v < 4; ++v) { const int t = m0 + 4 * fq + v, cc = n0 + fr;
;                 *(LAS float*)(L + L_WL + (t * 65 + cc) * 4) = aw[q][v]; *(LAS float*)(L + L_AL + (t * 65 + cc) * 4) = aa[q][v]; *(LAS float*)(L + L_GL + (t * 65 + cc) * 4) = ag[q][v]; } }
	ds_write_b32 v118, v83 offset:16640

; #define LAS __attribute__((address_space(3)))
; __device__ __forceinline__ void rwkv_chunk_group(Frame& F, int bc, unsigned long long& tsub) {
;     ...
;         for (int q = 0; q < 2; ++q) { const int tw = 2 * w + q, m0 = 16 * (tw >> 2), n0 = 16 * (tw & 3);
; #pragma unroll
;             for (int v = 0; v < 4; ++v) { const int t = m0 + 4 * fq + v, cc = n0 + fr;
;                 *(LAS float*)(L + L_WL + (t * 65 + cc) * 4) = aw[q][v]; *(LAS float*)(L + L_AL + (t * 65 + cc) * 4) = aa[q][v]; *(LAS float*)(L + L_GL + (t * 65 + cc) * 4) = ag[q][v]; } }
	ds_write_b32 v118, v87 offset:33280


; #define LBAR() asm volatile("s_waitcnt lgkmcnt(0)\n\ts_barrier" ::: "memory")
; __device__ __forceinline__ void rwkv_chunk_group(Frame& F, int bc, unsigned long long& tsub) {
;     ...
;         LBAR();
	s_waitcnt lgkmcnt(0)
	s_barrier


; __device__ __forceinline__ void rwkv_chunk_group(Frame& F, int bc, unsigned long long& tsub) {
;     ...
;         const float mur = mu[gc], muk = mu[512 + gc], muv = mu[1024 + gc];
;         const float w0 = (PRM + 2048)[gc], a0 = (PRM + 2560)[gc], k_k = (PRM + 3072)[gc], k_a = (PRM + 3584)[gc], r_k = (PRM + 4096)[gc];
	s_waitcnt vmcnt(0)
	v_mov_b32_e32 v95, v224
	v_mov_b32_e32 v42, v225


; __device__ __forceinline__ void rwkv_chunk_group(Frame& F, int bc, unsigned long long& tsub) {
;     ...
;         const float mur = mu[gc], muk = mu[512 + gc], muv = mu[1024 + gc];
;         const float w0 = (PRM + 2048)[gc], a0 = (PRM + 2560)[gc], k_k = (PRM + 3072)[gc], k_a = (PRM + 3584)[gc], r_k = (PRM + 4096)[gc];
	s_nop 0


; __device__ __forceinline__ void rwkv_chunk_group(Frame& F, int bc, unsigned long long& tsub) {
;     ...
;         const float mur = mu[gc], muk = mu[512 + gc], muv = mu[1024 + gc];
;         const float w0 = (PRM + 2048)[gc], a0 = (PRM + 2560)[gc], k_k = (PRM + 3072)[gc], k_a = (PRM + 3584)[gc], r_k = (PRM + 4096)[gc];
	v_mov_b32_e32 v52, v226


; __device__ __forceinline__ void rwkv_chunk_group(Frame& F, int bc, unsigned long long& tsub) {
;     ...
;         const float mur = mu[gc], muk = mu[512 + gc], muv = mu[1024 + gc];
;         const float w0 = (PRM + 2048)[gc], a0 = (PRM + 2560)[gc], k_k = (PRM + 3072)[gc], k_a = (PRM + 3584)[gc], r_k = (PRM + 4096)[gc];
	v_mov_b32_e32 v45, v227


; __device__ __forceinline__ void rwkv_chunk_group(Frame& F, int bc, unsigned long long& tsub) {
;     ...
;         float pr = bf2f(raw[0][0]), pk = bf2f(raw[0][1]), pv = bf2f(raw[0][2]);
;         bf16* VBp = (bf16*)(F.ws + WS_VB) + (size_t)item * 4096; bf16* Gp = (bf16*)(F.ws + WS_G) + (size_t)item * 4096;
;         float run = 0.f; float kkv[8], icv[8], sq[8], bq[8];
; #pragma unroll
;         for (int tt = 0; tt < 8; ++tt) { const int t = tb + tt;
;             const float cr = bf2f(raw[tt + 1][0]), ck = bf2f(raw[tt + 1][1]), cv = bf2f(raw[tt + 1][2]);
;             const float r = cr + (pr - cr) * mur, k = ck + (pk - ck) * muk, v = cv + (pv - cv) * muv; pr = cr; pk = ck; pv = cv;
	v_lshlrev_b32_e32 v82, 16, v155
	v_and_b32_e32 v77, 0xffff0000, v167

; __device__ __forceinline__ void rwkv_chunk_group(Frame& F, int bc, unsigned long long& tsub) {
;     ...
;         const float mur = mu[gc], muk = mu[512 + gc], muv = mu[1024 + gc];
;         const float w0 = (PRM + 2048)[gc], a0 = (PRM + 2560)[gc], k_k = (PRM + 3072)[gc], k_a = (PRM + 3584)[gc], r_k = (PRM + 4096)[gc];
	v_mov_b32_e32 v43, v228


; __device__ __forceinline__ void rwkv_chunk_group(Frame& F, int bc, unsigned long long& tsub) {
;     ...
;         float pr = bf2f(raw[0][0]), pk = bf2f(raw[0][1]), pv = bf2f(raw[0][2]);
;         bf16* VBp = (bf16*)(F.ws + WS_VB) + (size_t)item * 4096; bf16* Gp = (bf16*)(F.ws + WS_G) + (size_t)item * 4096;
;         float run = 0.f; float kkv[8], icv[8], sq[8], bq[8];
; #pragma unroll
;         for (int tt = 0; tt < 8; ++tt) { const int t = tb + tt;
;             const float cr = bf2f(raw[tt + 1][0]), ck = bf2f(raw[tt + 1][1]), cv = bf2f(raw[tt + 1][2]);
;             const float r = cr + (pr - cr) * mur, k = ck + (pk - ck) * muk, v = cv + (pv - cv) * muv; pr = cr; pk = ck; pv = cv;
	v_lshlrev_b32_e32 v76, 16, v167
	v_and_b32_e32 v79, 0xffff0000, v166


; __device__ __forceinline__ void rwkv_chunk_group(Frame& F, int bc, unsigned long long& tsub) {
;     ...
;         const float mur = mu[gc], muk = mu[512 + gc], muv = mu[1024 + gc];
;         const float w0 = (PRM + 2048)[gc], a0 = (PRM + 2560)[gc], k_k = (PRM + 3072)[gc], k_a = (PRM + 3584)[gc], r_k = (PRM + 4096)[gc];
;         float rr[8], kp[8], vv[8], aa[8], bb[8], ld[8], vbv[8], ggv[8];
;         float pr = bf2f(raw[0][0]), pk = bf2f(raw[0][1]), pv = bf2f(raw[0][2]);
;         bf16* VBp = (bf16*)(F.ws + WS_VB) + (size_t)item * 4096; bf16* Gp = (bf16*)(F.ws + WS_G) + (size_t)item * 4096;
;         float run = 0.f; float kkv[8], icv[8], sq[8], bq[8];
; #pragma unroll
;         for (int tt = 0; tt < 8; ++tt) { const int t = tb + tt;
;             const float cr = bf2f(raw[tt + 1][0]), ck = bf2f(raw[tt + 1][1]), cv = bf2f(raw[tt + 1][2]);
;             const float r = cr + (pr - cr) * mur, k = ck + (pk - ck) * muk, v = cv + (pv - cv) * muv; pr = cr; pk = ck; pv = cv;
	v_mov_b32_e32 v44, v229
	v_lshlrev_b32_e32 v78, 16, v166

; __device__ __forceinline__ void rwkv_chunk_group(Frame& F, int bc, unsigned long long& tsub) {
;     ...
;         const float mur = mu[gc], muk = mu[512 + gc], muv = mu[1024 + gc];
;         const float w0 = (PRM + 2048)[gc], a0 = (PRM + 2560)[gc], k_k = (PRM + 3072)[gc], k_a = (PRM + 3584)[gc], r_k = (PRM + 4096)[gc];
	v_mov_b32_e32 v46, v230


; __device__ __forceinline__ void rwkv_chunk_group(Frame& F, int bc, unsigned long long& tsub) {
;     ...
;             const float cr = bf2f(raw[tt + 1][0]), ck = bf2f(raw[tt + 1][1]), cv = bf2f(raw[tt + 1][2]);
;             const float r = cr + (pr - cr) * mur, k = ck + (pk - ck) * muk, v = cv + (pv - cv) * muv; pr = cr; pk = ck; pv = cv;
	v_lshlrev_b32_e32 v86, 16, v157
	v_and_b32_e32 v91, 0xffff0000, v168

; __device__ __forceinline__ void rwkv_chunk_group(Frame& F, int bc, unsigned long long& tsub) {
;     ...
;             const float cr = bf2f(raw[tt + 1][0]), ck = bf2f(raw[tt + 1][1]), cv = bf2f(raw[tt + 1][2]);
;             const float r = cr + (pr - cr) * mur, k = ck + (pk - ck) * muk, v = cv + (pv - cv) * muv; pr = cr; pk = ck; pv = cv;
	v_mov_b32_e32 v103, v231
	v_lshlrev_b32_e32 v36, 16, v153
	v_lshlrev_b32_e32 v37, 16, v154
	v_sub_f32_e32 v36, v36, v37


; #define LAS __attribute__((address_space(3)))
; __device__ __forceinline__ void rwkv_chunk_group(Frame& F, int bc, unsigned long long& tsub) {
;     ...
;             const float r = cr + (pr - cr) * mur, k = ck + (pk - ck) * muk, v = cv + (pv - cv) * muv; pr = cr; pk = ck; pv = cv;
;             const float wl = *(const LAS float*)(L + L_WL + (t * 65 + ch) * 4), al = *(const LAS float*)(L + L_AL + (t * 65 + ch) * 4), gl = *(const LAS float*)(L + L_GL + (t * 65 + ch) * 4);
	ds_read_b32 v38, v119 offset:16640
	ds_read_b32 v47, v119 offset:33280
	ds_read_b32 v177, v120 offset:33280
	ds_read_b32 v185, v122 offset:33280
	ds_read_b32 v191, v125 offset:16640
	v_lshlrev_b32_e32 v90, 16, v168
	v_and_b32_e32 v85, 0xffff0000, v169
	ds_read_b32 v182, v121 offset:33280
	ds_read_b32 v96, v124 offset:16640
	ds_read_b32 v189, v123 offset:33280
	ds_read_b32 v193, v124 offset:33280
	ds_read_b32 v194, v125 offset:33280
	s_waitcnt vmcnt(7)
	v_fma_f32 v173, v36, v95, v37

; __device__ __forceinline__ void rwkv_chunk_group(Frame& F, int bc, unsigned long long& tsub) {
;     ...
;             const float z = -(w0 + wl); const float sp = fmaxf(z, 0.f) + __logf(1.f + __expf(-fabsf(z)));
	ds_read_b32 v36, v119
	s_waitcnt vmcnt(4) lgkmcnt(0)
	v_add_f32_e32 v36, v45, v36
	v_max_f32_e64 v39, -v36, 0
	v_mul_f32_e64 v36, |v36|, s1
	v_exp_f32_e32 v36, v36
	s_nop 0
	v_add_f32_e32 v36, 1.0, v36

; __device__ __forceinline__ void rwkv_chunk_group(Frame& F, int bc, unsigned long long& tsub) {
;     ...
;             const float z = -(w0 + wl); const float sp = fmaxf(z, 0.f) + __logf(1.f + __expf(-fabsf(z)));
	s_nop 1


; __device__ __forceinline__ void rwkv_chunk_group(Frame& F, int bc, unsigned long long& tsub) {
;     ...
;             const float z = -(w0 + wl); const float sp = fmaxf(z, 0.f) + __logf(1.f + __expf(-fabsf(z)));
	v_log_f32_e32 v36, v36
	s_nop 0
	v_mul_f32_e32 v40, 0x3f317217, v36
	v_fma_f32 v40, v36, s9, -v40
	v_fmac_f32_e32 v40, 0x3377d1cf, v36
	v_fmac_f32_e32 v40, 0x3f317217, v36

; __device__ __forceinline__ void rwkv_chunk_group(Frame& F, int bc, unsigned long long& tsub) {
;     ...
;             const float z = -(w0 + wl); const float sp = fmaxf(z, 0.f) + __logf(1.f + __expf(-fabsf(z)));
	s_nop 1
	v_mov_b32_e32 v36, v40


; __device__ __forceinline__ void rwkv_chunk_group(Frame& F, int bc, unsigned long long& tsub) {
;     ...
;             const float z = -(w0 + wl); const float sp = fmaxf(z, 0.f) + __logf(1.f + __expf(-fabsf(z)));
	v_add_f32_e32 v36, v39, v36

; __device__ __forceinline__ float sigmoidf_(float x) { return __builtin_amdgcn_rcpf(1.0f + __expf(-x)); }
; __device__ __forceinline__ void rwkv_chunk_group(Frame& F, int bc, unsigned long long& tsub) {
;     ...
;             const float lgd = -__expf(-sp - 0.5f);
;             const float ic = sigmoidf_(a0 + al);
	ds_read_b32 v39, v120
	v_sub_f32_e32 v36, -0.5, v36
	v_mul_f32_e32 v36, 0x3fb8aa3b, v36
	v_exp_f32_e32 v102, v36
	s_waitcnt vmcnt(3)
	v_add_f32_e32 v36, v43, v38
	v_mul_f32_e32 v36, 0xbfb8aa3b, v36

; #define LAS __attribute__((address_space(3)))
; __device__ __forceinline__ float sigmoidf_(float x) { return __builtin_amdgcn_rcpf(1.0f + __expf(-x)); }
; __device__ __forceinline__ void rwkv_chunk_group(Frame& F, int bc, unsigned long long& tsub) {
;     ...
;             const float r = cr + (pr - cr) * mur, k = ck + (pk - ck) * muk, v = cv + (pv - cv) * muv; pr = cr; pk = ck; pv = cv;
;             const float wl = *(const LAS float*)(L + L_WL + (t * 65 + ch) * 4), al = *(const LAS float*)(L + L_AL + (t * 65 + ch) * 4), gl = *(const LAS float*)(L + L_GL + (t * 65 + ch) * 4);
;             const float z = -(w0 + wl); const float sp = fmaxf(z, 0.f) + __logf(1.f + __expf(-fabsf(z)));
;             const float lgd = -__expf(-sp - 0.5f);
;             const float ic = sigmoidf_(a0 + al);
	v_exp_f32_e32 v36, v36
	ds_read_b32 v40, v120 offset:16640
	s_waitcnt lgkmcnt(1)
	v_add_f32_e32 v39, v45, v39
	v_max_f32_e64 v41, -v39, 0
	v_mul_f32_e64 v39, |v39|, s1
	v_exp_f32_e32 v39, v39
	v_add_f32_e32 v36, 1.0, v36
	v_rcp_f32_e32 v38, v36
	v_sub_f32_e32 v36, v37, v82
	v_fma_f32 v174, v36, v95, v82
	v_and_b32_e32 v37, 0xffff0000, v161
	v_lshlrev_b32_e32 v36, 16, v161
	v_add_f32_e32 v39, 1.0, v39
	v_pk_add_f32 v[36:37], v[36:37], v[76:77] neg_lo:[0,1] neg_hi:[0,1]

; __device__ __forceinline__ void rwkv_chunk_group(Frame& F, int bc, unsigned long long& tsub) {
;     ...
;             const float r = cr + (pr - cr) * mur, k = ck + (pk - ck) * muk, v = cv + (pv - cv) * muv; pr = cr; pk = ck; pv = cv;
	v_pk_fma_f32 v[36:37], v[36:37], v[52:53], v[76:77] op_sel_hi:[1,0,1]
	s_nop 0


; __device__ __forceinline__ void rwkv_chunk_group(Frame& F, int bc, unsigned long long& tsub) {
;     ...
;             const float z = -(w0 + wl); const float sp = fmaxf(z, 0.f) + __logf(1.f + __expf(-fabsf(z)));
	v_log_f32_e32 v39, v39
	s_nop 0
	v_mul_f32_e32 v76, 0x3f317217, v39
	v_fma_f32 v76, v39, s9, -v76
	v_fmac_f32_e32 v76, 0x3377d1cf, v39
	v_fmac_f32_e32 v76, 0x3f317217, v39

; __device__ __forceinline__ void rwkv_chunk_group(Frame& F, int bc, unsigned long long& tsub) {
;     ...
;             const float z = -(w0 + wl); const float sp = fmaxf(z, 0.f) + __logf(1.f + __expf(-fabsf(z)));
	s_nop 1
	v_mov_b32_e32 v39, v76


; __device__ __forceinline__ float sigmoidf_(float x) { return __builtin_amdgcn_rcpf(1.0f + __expf(-x)); }
; __device__ __forceinline__ void rwkv_chunk_group(Frame& F, int bc, unsigned long long& tsub) {
;     ...
;             const float z = -(w0 + wl); const float sp = fmaxf(z, 0.f) + __logf(1.f + __expf(-fabsf(z)));
;             const float lgd = -__expf(-sp - 0.5f);
;             const float ic = sigmoidf_(a0 + al);
;             const float kv = k * k_k; const float kq = k * (1.f + (ic - 1.f) * k_a);
;             kkv[tt] = kv; icv[tt] = ic; sq[tt] = kv * kv; bq[tt] = r * kq * r_k;
;             rr[tt] = r; kp[tt] = kq; vv[tt] = v; run += lgd; ld[tt] = run; ggv[tt] = gl;
	v_add_f32_e32 v39, v41, v39
	v_sub_f32_e32 v39, -0.5, v39
	v_mul_f32_e32 v39, 0x3fb8aa3b, v39
	v_exp_f32_e32 v76, v39
	s_waitcnt lgkmcnt(0)
	v_add_f32_e32 v39, v43, v40
	v_mul_f32_e32 v39, 0xbfb8aa3b, v39
	v_exp_f32_e32 v39, v39
	v_and_b32_e32 v41, 0xffff0000, v160
	v_lshlrev_b32_e32 v40, 16, v160
	v_pk_add_f32 v[40:41], v[40:41], v[78:79] neg_lo:[0,1] neg_hi:[0,1]
	v_add_f32_e32 v39, 1.0, v39
	v_rcp_f32_e32 v39, v39
	v_pk_fma_f32 v[80:81], v[40:41], v[42:43], v[78:79] op_sel_hi:[1,0,1]
	v_sub_f32_e64 v176, -v102, v76
	v_lshlrev_b32_e32 v76, 16, v156
	v_pk_add_f32 v[40:41], v[38:39], -1.0 op_sel_hi:[1,0]
	s_waitcnt vmcnt(1)
	v_pk_fma_f32 v[40:41], v[46:47], v[40:41], 1.0 op_sel_hi:[0,1,0]
	v_pk_mul_f32 v[40:41], v[80:81], v[40:41]
	s_nop 0
	v_mul_f32_e32 v78, v173, v40
	s_waitcnt vmcnt(0)
	v_mul_f32_e32 v101, v103, v78
	v_mul_f32_e32 v78, v174, v41
	v_mul_f32_e32 v100, v103, v78
	v_sub_f32_e32 v78, v82, v76
	v_fma_f32 v175, v78, v95, v76

; #define LAS __attribute__((address_space(3)))
; __device__ __forceinline__ void rwkv_chunk_group(Frame& F, int bc, unsigned long long& tsub) {
;     ...
;             const float wl = *(const LAS float*)(L + L_WL + (t * 65 + ch) * 4), al = *(const LAS float*)(L + L_AL + (t * 65 + ch) * 4), gl = *(const LAS float*)(L + L_GL + (t * 65 + ch) * 4);
	ds_read_b32 v78, v121

; #define LAS __attribute__((address_space(3)))
; __device__ __forceinline__ float sigmoidf_(float x) { return __builtin_amdgcn_rcpf(1.0f + __expf(-x)); }
; __device__ __forceinline__ void rwkv_chunk_group(Frame& F, int bc, unsigned long long& tsub) {
;     ...
;             const float r = cr + (pr - cr) * mur, k = ck + (pk - ck) * muk, v = cv + (pv - cv) * muv; pr = cr; pk = ck; pv = cv;
;             const float wl = *(const LAS float*)(L + L_WL + (t * 65 + ch) * 4), al = *(const LAS float*)(L + L_AL + (t * 65 + ch) * 4), gl = *(const LAS float*)(L + L_GL + (t * 65 + ch) * 4);
;             const float z = -(w0 + wl); const float sp = fmaxf(z, 0.f) + __logf(1.f + __expf(-fabsf(z)));
;             const float lgd = -__expf(-sp - 0.5f);
;             const float ic = sigmoidf_(a0 + al);
	ds_read_b32 v82, v121 offset:16640
	v_sub_f32_e32 v76, v76, v86
	v_fma_f32 v178, v76, v95, v86
	s_waitcnt lgkmcnt(1)
	v_add_f32_e32 v78, v45, v78
	v_max_f32_e64 v83, -v78, 0
	v_mul_f32_e64 v78, |v78|, s1
	v_exp_f32_e32 v78, v78
	s_waitcnt lgkmcnt(0)
	v_add_f32_e32 v82, v43, v82
	v_mul_f32_e32 v82, 0xbfb8aa3b, v82
	v_exp_f32_e32 v82, v82
	v_add_f32_e32 v78, 1.0, v78

; __device__ __forceinline__ float sigmoidf_(float x) { return __builtin_amdgcn_rcpf(1.0f + __expf(-x)); }
; __device__ __forceinline__ void rwkv_chunk_group(Frame& F, int bc, unsigned long long& tsub) {
;     ...
;             const float ic = sigmoidf_(a0 + al);
	v_add_f32_e32 v82, 1.0, v82
	s_nop 0


; __device__ __forceinline__ float sigmoidf_(float x) { return __builtin_amdgcn_rcpf(1.0f + __expf(-x)); }
; __device__ __forceinline__ void rwkv_chunk_group(Frame& F, int bc, unsigned long long& tsub) {
;     ...
;             const float z = -(w0 + wl); const float sp = fmaxf(z, 0.f) + __logf(1.f + __expf(-fabsf(z)));
;             const float lgd = -__expf(-sp - 0.5f);
;             const float ic = sigmoidf_(a0 + al);
	v_log_f32_e32 v78, v78
	v_rcp_f32_e32 v82, v82
	v_mul_f32_e32 v84, 0x3f317217, v78
	v_fma_f32 v84, v78, s9, -v84
	v_fmac_f32_e32 v84, 0x3377d1cf, v78
	v_fmac_f32_e32 v84, 0x3f317217, v78

; __device__ __forceinline__ void rwkv_chunk_group(Frame& F, int bc, unsigned long long& tsub) {
;     ...
;             const float z = -(w0 + wl); const float sp = fmaxf(z, 0.f) + __logf(1.f + __expf(-fabsf(z)));
	s_nop 1
	v_mov_b32_e32 v78, v84


; __device__ __forceinline__ void rwkv_chunk_group(Frame& F, int bc, unsigned long long& tsub) {
;     ...
;             const float z = -(w0 + wl); const float sp = fmaxf(z, 0.f) + __logf(1.f + __expf(-fabsf(z)));
;             const float lgd = -__expf(-sp - 0.5f);
	v_add_f32_e32 v78, v83, v78
	v_sub_f32_e32 v78, -0.5, v78
	v_mul_f32_e32 v78, 0x3fb8aa3b, v78
	v_exp_f32_e32 v78, v78

; #define LAS __attribute__((address_space(3)))
; __device__ __forceinline__ float sigmoidf_(float x) { return __builtin_amdgcn_rcpf(1.0f + __expf(-x)); }
; __device__ __forceinline__ void rwkv_chunk_group(Frame& F, int bc, unsigned long long& tsub) {
;     ...
;             const float wl = *(const LAS float*)(L + L_WL + (t * 65 + ch) * 4), al = *(const LAS float*)(L + L_AL + (t * 65 + ch) * 4), gl = *(const LAS float*)(L + L_GL + (t * 65 + ch) * 4);
;             const float z = -(w0 + wl); const float sp = fmaxf(z, 0.f) + __logf(1.f + __expf(-fabsf(z)));
;             const float lgd = -__expf(-sp - 0.5f);
;             const float ic = sigmoidf_(a0 + al);
;             const float kv = k * k_k; const float kq = k * (1.f + (ic - 1.f) * k_a);
;             kkv[tt] = kv; icv[tt] = ic; sq[tt] = kv * kv; bq[tt] = r * kq * r_k;
;             rr[tt] = r; kp[tt] = kq; vv[tt] = v; run += lgd; ld[tt] = run; ggv[tt] = gl;
	ds_read_b32 v83, v122 offset:16640
	v_lshlrev_b32_e32 v84, 16, v169
	v_sub_f32_e32 v179, v176, v78

; #define LAS __attribute__((address_space(3)))
; __device__ __forceinline__ void rwkv_chunk_group(Frame& F, int bc, unsigned long long& tsub) {
;     ...
;             const float r = cr + (pr - cr) * mur, k = ck + (pk - ck) * muk, v = cv + (pv - cv) * muv; pr = cr; pk = ck; pv = cv;
;             const float wl = *(const LAS float*)(L + L_WL + (t * 65 + ch) * 4), al = *(const LAS float*)(L + L_AL + (t * 65 + ch) * 4), gl = *(const LAS float*)(L + L_GL + (t * 65 + ch) * 4);
;             const float z = -(w0 + wl); const float sp = fmaxf(z, 0.f) + __logf(1.f + __expf(-fabsf(z)));
	ds_read_b32 v78, v122
	v_pk_mov_b32 v[76:77], v[76:77], v[84:85] op_sel:[1,0]
	s_waitcnt lgkmcnt(0)
	v_add_f32_e32 v78, v45, v78
	v_max_f32_e64 v87, -v78, 0
	v_mul_f32_e64 v78, |v78|, s1
	v_exp_f32_e32 v78, v78
	v_pk_add_f32 v[76:77], v[76:77], v[84:85] neg_lo:[0,1] neg_hi:[0,1]
	v_add_f32_e32 v78, 1.0, v78

; __device__ __forceinline__ void rwkv_chunk_group(Frame& F, int bc, unsigned long long& tsub) {
;     ...
;             const float r = cr + (pr - cr) * mur, k = ck + (pk - ck) * muk, v = cv + (pv - cv) * muv; pr = cr; pk = ck; pv = cv;
	v_pk_fma_f32 v[76:77], v[76:77], v[52:53], v[84:85] op_sel_hi:[1,0,1]
	s_nop 0


; __device__ __forceinline__ void rwkv_chunk_group(Frame& F, int bc, unsigned long long& tsub) {
;     ...
;             const float z = -(w0 + wl); const float sp = fmaxf(z, 0.f) + __logf(1.f + __expf(-fabsf(z)));
	v_log_f32_e32 v78, v78
	s_nop 0
	v_mul_f32_e32 v88, 0x3f317217, v78
	v_fma_f32 v88, v78, s9, -v88
	v_fmac_f32_e32 v88, 0x3377d1cf, v78
	v_fmac_f32_e32 v88, 0x3f317217, v78

; __device__ __forceinline__ void rwkv_chunk_group(Frame& F, int bc, unsigned long long& tsub) {
;     ...
;             const float z = -(w0 + wl); const float sp = fmaxf(z, 0.f) + __logf(1.f + __expf(-fabsf(z)));
	s_nop 1
	v_mov_b32_e32 v78, v88


; __device__ __forceinline__ float sigmoidf_(float x) { return __builtin_amdgcn_rcpf(1.0f + __expf(-x)); }
; __device__ __forceinline__ void rwkv_chunk_group(Frame& F, int bc, unsigned long long& tsub) {
;     ...
;             const float z = -(w0 + wl); const float sp = fmaxf(z, 0.f) + __logf(1.f + __expf(-fabsf(z)));
;             const float lgd = -__expf(-sp - 0.5f);
;             const float ic = sigmoidf_(a0 + al);
;             const float kv = k * k_k; const float kq = k * (1.f + (ic - 1.f) * k_a);
;             kkv[tt] = kv; icv[tt] = ic; sq[tt] = kv * kv; bq[tt] = r * kq * r_k;
;             rr[tt] = r; kp[tt] = kq; vv[tt] = v; run += lgd; ld[tt] = run; ggv[tt] = gl;
	v_add_f32_e32 v78, v87, v78
	v_sub_f32_e32 v78, -0.5, v78
	v_mul_f32_e32 v78, 0x3fb8aa3b, v78
	v_exp_f32_e32 v87, v78
	v_add_f32_e32 v78, v43, v83
	v_mul_f32_e32 v78, 0xbfb8aa3b, v78
	v_exp_f32_e32 v78, v78
	v_sub_f32_e32 v181, v179, v87
	v_lshlrev_b32_e32 v87, 16, v158
	v_sub_f32_e32 v86, v86, v87
	v_add_f32_e32 v78, 1.0, v78
	v_rcp_f32_e32 v83, v78
	v_pk_mov_b32 v[78:79], v[78:79], v[90:91] op_sel:[1,0]
	v_fma_f32 v180, v86, v95, v87
	v_pk_add_f32 v[78:79], v[78:79], v[90:91] neg_lo:[0,1] neg_hi:[0,1]

; __device__ __forceinline__ void rwkv_chunk_group(Frame& F, int bc, unsigned long long& tsub) {
;     ...
;             const float kv = k * k_k; const float kq = k * (1.f + (ic - 1.f) * k_a);
;             kkv[tt] = kv; icv[tt] = ic; sq[tt] = kv * kv; bq[tt] = r * kq * r_k;
;             rr[tt] = r; kp[tt] = kq; vv[tt] = v; run += lgd; ld[tt] = run; ggv[tt] = gl;
	v_pk_fma_f32 v[88:89], v[78:79], v[42:43], v[90:91] op_sel_hi:[1,0,1]
	v_pk_add_f32 v[78:79], v[82:83], -1.0 op_sel_hi:[1,0]
	ds_read_b32 v86, v123
	v_pk_fma_f32 v[78:79], v[46:47], v[78:79], 1.0 op_sel_hi:[0,1,0]
	v_pk_mul_f32 v[78:79], v[88:89], v[78:79]
	s_nop 0
	v_mul_f32_e32 v92, v175, v78
	v_mul_f32_e32 v187, v103, v92
	v_mul_f32_e32 v92, v178, v79
	v_mul_f32_e32 v186, v103, v92

; #define LAS __attribute__((address_space(3)))
; __device__ __forceinline__ void rwkv_chunk_group(Frame& F, int bc, unsigned long long& tsub) {
;     ...
;             const float wl = *(const LAS float*)(L + L_WL + (t * 65 + ch) * 4), al = *(const LAS float*)(L + L_AL + (t * 65 + ch) * 4), gl = *(const LAS float*)(L + L_GL + (t * 65 + ch) * 4);
;             const float z = -(w0 + wl); const float sp = fmaxf(z, 0.f) + __logf(1.f + __expf(-fabsf(z)));
	ds_read_b32 v92, v123 offset:16640
	s_waitcnt lgkmcnt(1)
	v_add_f32_e32 v86, v45, v86
	v_max_f32_e64 v93, -v86, 0
	v_mul_f32_e64 v86, |v86|, s1
	v_exp_f32_e32 v86, v86
	s_nop 0
	v_add_f32_e32 v86, 1.0, v86

; __device__ __forceinline__ void rwkv_chunk_group(Frame& F, int bc, unsigned long long& tsub) {
;     ...
;             const float z = -(w0 + wl); const float sp = fmaxf(z, 0.f) + __logf(1.f + __expf(-fabsf(z)));
	s_nop 1


; __device__ __forceinline__ void rwkv_chunk_group(Frame& F, int bc, unsigned long long& tsub) {
;     ...
;             const float z = -(w0 + wl); const float sp = fmaxf(z, 0.f) + __logf(1.f + __expf(-fabsf(z)));
	v_log_f32_e32 v86, v86
	s_nop 0
	v_mul_f32_e32 v94, 0x3f317217, v86
	v_fma_f32 v94, v86, s9, -v94
	v_fmac_f32_e32 v94, 0x3377d1cf, v86
	v_fmac_f32_e32 v94, 0x3f317217, v86

; __device__ __forceinline__ void rwkv_chunk_group(Frame& F, int bc, unsigned long long& tsub) {
;     ...
;             const float z = -(w0 + wl); const float sp = fmaxf(z, 0.f) + __logf(1.f + __expf(-fabsf(z)));
	s_nop 1
	v_mov_b32_e32 v86, v94


; __device__ __forceinline__ void rwkv_chunk_group(Frame& F, int bc, unsigned long long& tsub) {
;     ...
;             const float r = cr + (pr - cr) * mur, k = ck + (pk - ck) * muk, v = cv + (pv - cv) * muv; pr = cr; pk = ck; pv = cv;
	v_lshlrev_b32_e32 v94, 16, v159
	v_sub_f32_e32 v87, v87, v94
	v_fma_f32 v183, v87, v95, v94

; #define LAS __attribute__((address_space(3)))
; __device__ __forceinline__ float sigmoidf_(float x) { return __builtin_amdgcn_rcpf(1.0f + __expf(-x)); }
; __device__ __forceinline__ void rwkv_chunk_group(Frame& F, int bc, unsigned long long& tsub) {
;     ...
;             const float wl = *(const LAS float*)(L + L_WL + (t * 65 + ch) * 4), al = *(const LAS float*)(L + L_AL + (t * 65 + ch) * 4), gl = *(const LAS float*)(L + L_GL + (t * 65 + ch) * 4);
;             const float z = -(w0 + wl); const float sp = fmaxf(z, 0.f) + __logf(1.f + __expf(-fabsf(z)));
;             const float lgd = -__expf(-sp - 0.5f);
;             const float ic = sigmoidf_(a0 + al);
	ds_read_b32 v87, v124
	v_add_f32_e32 v86, v93, v86
	v_sub_f32_e32 v86, -0.5, v86
	v_mul_f32_e32 v86, 0x3fb8aa3b, v86
	v_exp_f32_e32 v93, v86
	s_waitcnt lgkmcnt(0)
	v_add_f32_e32 v87, v45, v87
	v_max_f32_e64 v97, -v87, 0
	v_mul_f32_e64 v87, |v87|, s1
	v_exp_f32_e32 v87, v87
	v_add_f32_e32 v86, v43, v92
	v_mul_f32_e32 v86, 0xbfb8aa3b, v86
	v_exp_f32_e32 v86, v86
	v_add_f32_e32 v87, 1.0, v87

; __device__ __forceinline__ void rwkv_chunk_group(Frame& F, int bc, unsigned long long& tsub) {
;     ...
;             rr[tt] = r; kp[tt] = kq; vv[tt] = v; run += lgd; ld[tt] = run; ggv[tt] = gl;
	v_sub_f32_e32 v184, v181, v93
	v_add_f32_e32 v86, 1.0, v86


; __device__ __forceinline__ float sigmoidf_(float x) { return __builtin_amdgcn_rcpf(1.0f + __expf(-x)); }
; __device__ __forceinline__ void rwkv_chunk_group(Frame& F, int bc, unsigned long long& tsub) {
;     ...
;             const float z = -(w0 + wl); const float sp = fmaxf(z, 0.f) + __logf(1.f + __expf(-fabsf(z)));
;             const float lgd = -__expf(-sp - 0.5f);
;             const float ic = sigmoidf_(a0 + al);
	v_log_f32_e32 v87, v87
	v_rcp_f32_e32 v86, v86
	v_sub_f32_e32 v94, v94, v197
	v_and_b32_e32 v93, 0xffff0000, v171
	v_mul_f32_e32 v98, 0x3f317217, v87
	v_fma_f32 v98, v87, s9, -v98
	v_fmac_f32_e32 v98, 0x3377d1cf, v87
	v_fmac_f32_e32 v98, 0x3f317217, v87

; #define LAS __attribute__((address_space(3)))
; __device__ __forceinline__ void rwkv_chunk_group(Frame& F, int bc, unsigned long long& tsub) {
;     ...
;             const float cr = bf2f(raw[tt + 1][0]), ck = bf2f(raw[tt + 1][1]), cv = bf2f(raw[tt + 1][2]);
;             const float r = cr + (pr - cr) * mur, k = ck + (pk - ck) * muk, v = cv + (pv - cv) * muv; pr = cr; pk = ck; pv = cv;
;             const float wl = *(const LAS float*)(L + L_WL + (t * 65 + ch) * 4), al = *(const LAS float*)(L + L_AL + (t * 65 + ch) * 4), gl = *(const LAS float*)(L + L_GL + (t * 65 + ch) * 4);
;             const float z = -(w0 + wl); const float sp = fmaxf(z, 0.f) + __logf(1.f + __expf(-fabsf(z)));
	v_lshlrev_b32_e32 v92, 16, v171
	v_pk_mov_b32 v[84:85], v[84:85], v[92:93] op_sel:[1,0]
	v_mov_b32_e32 v87, v98


; #define LAS __attribute__((address_space(3)))
; __device__ __forceinline__ float sigmoidf_(float x) { return __builtin_amdgcn_rcpf(1.0f + __expf(-x)); }
; __device__ __forceinline__ void rwkv_chunk_group(Frame& F, int bc, unsigned long long& tsub) {
;     ...
;             const float r = cr + (pr - cr) * mur, k = ck + (pk - ck) * muk, v = cv + (pv - cv) * muv; pr = cr; pk = ck; pv = cv;
;             const float wl = *(const LAS float*)(L + L_WL + (t * 65 + ch) * 4), al = *(const LAS float*)(L + L_AL + (t * 65 + ch) * 4), gl = *(const LAS float*)(L + L_GL + (t * 65 + ch) * 4);
;             const float z = -(w0 + wl); const float sp = fmaxf(z, 0.f) + __logf(1.f + __expf(-fabsf(z)));
;             const float lgd = -__expf(-sp - 0.5f);
;             const float ic = sigmoidf_(a0 + al);
;             const float kv = k * k_k; const float kq = k * (1.f + (ic - 1.f) * k_a);
;             kkv[tt] = kv; icv[tt] = ic; sq[tt] = kv * kv; bq[tt] = r * kq * r_k;
;             rr[tt] = r; kp[tt] = kq; vv[tt] = v; run += lgd; ld[tt] = run; ggv[tt] = gl;
	v_add_f32_e32 v87, v97, v87
	v_sub_f32_e32 v87, -0.5, v87
	v_mul_f32_e32 v87, 0x3fb8aa3b, v87
	v_exp_f32_e32 v188, v87
	v_add_f32_e32 v87, v43, v96
	v_mul_f32_e32 v87, 0xbfb8aa3b, v87
	v_exp_f32_e32 v87, v87
	v_and_b32_e32 v97, 0xffff0000, v170
	v_lshlrev_b32_e32 v96, 16, v170
	v_pk_mov_b32 v[90:91], v[90:91], v[96:97] op_sel:[1,0]
	v_add_f32_e32 v87, 1.0, v87
	v_rcp_f32_e32 v87, v87
	v_pk_add_f32 v[90:91], v[90:91], v[96:97] neg_lo:[0,1] neg_hi:[0,1]
	v_pk_add_f32 v[84:85], v[84:85], v[92:93] neg_lo:[0,1] neg_hi:[0,1]
	v_pk_fma_f32 v[98:99], v[90:91], v[42:43], v[96:97] op_sel_hi:[1,0,1]
	v_pk_add_f32 v[90:91], v[86:87], -1.0 op_sel_hi:[1,0]
	v_pk_fma_f32 v[84:85], v[84:85], v[52:53], v[92:93] op_sel_hi:[1,0,1]
	v_pk_fma_f32 v[90:91], v[46:47], v[90:91], 1.0 op_sel_hi:[0,1,0]
	v_pk_mul_f32 v[90:91], v[98:99], v[90:91]
	s_nop 0
	v_mul_f32_e32 v190, v180, v90
	v_mul_f32_e32 v196, v103, v190
	v_mul_f32_e32 v190, v183, v91
	v_mul_f32_e32 v195, v103, v190
	v_sub_f32_e32 v190, v184, v188
	v_fma_f32 v188, v94, v95, v197

; #define LAS __attribute__((address_space(3)))
; __device__ __forceinline__ float sigmoidf_(float x) { return __builtin_amdgcn_rcpf(1.0f + __expf(-x)); }
; __device__ __forceinline__ void rwkv_chunk_group(Frame& F, int bc, unsigned long long& tsub) {
;     ...
;             const float wl = *(const LAS float*)(L + L_WL + (t * 65 + ch) * 4), al = *(const LAS float*)(L + L_AL + (t * 65 + ch) * 4), gl = *(const LAS float*)(L + L_GL + (t * 65 + ch) * 4);
;             const float z = -(w0 + wl); const float sp = fmaxf(z, 0.f) + __logf(1.f + __expf(-fabsf(z)));
;             const float lgd = -__expf(-sp - 0.5f);
;             const float ic = sigmoidf_(a0 + al);
;             const float kv = k * k_k; const float kq = k * (1.f + (ic - 1.f) * k_a);
;             kkv[tt] = kv; icv[tt] = ic; sq[tt] = kv * kv; bq[tt] = r * kq * r_k;
;             rr[tt] = r; kp[tt] = kq; vv[tt] = v; run += lgd; ld[tt] = run; ggv[tt] = gl;
;         }
;         wave_sum8(sq); wave_sum8(bq);
	ds_read_b32 v94, v125
	v_permlane32_swap_b32_e32 v101, v196
	v_permlane32_swap_b32_e32 v100, v195
	s_waitcnt lgkmcnt(0)
	v_add_f32_e32 v94, v45, v94
	v_max_f32_e64 v192, -v94, 0
	v_mul_f32_e64 v94, |v94|, s1
	v_exp_f32_e32 v94, v94
	v_add_f32_e32 v201, v101, v196
	v_add_f32_e32 v195, v100, v195
	v_add_f32_e32 v94, 1.0, v94

; __device__ __forceinline__ void rwkv_chunk_group(Frame& F, int bc, unsigned long long& tsub) {
;     ...
;             const float z = -(w0 + wl); const float sp = fmaxf(z, 0.f) + __logf(1.f + __expf(-fabsf(z)));
	s_nop 1


; __device__ __forceinline__ void rwkv_chunk_group(Frame& F, int bc, unsigned long long& tsub) {
;     ...
;             const float z = -(w0 + wl); const float sp = fmaxf(z, 0.f) + __logf(1.f + __expf(-fabsf(z)));
	v_log_f32_e32 v94, v94
	s_nop 0
	v_mul_f32_e32 v198, 0x3f317217, v94
	v_fma_f32 v198, v94, s9, -v198
	v_fmac_f32_e32 v198, 0x3377d1cf, v94
	v_fmac_f32_e32 v198, 0x3f317217, v94

; __device__ __forceinline__ void rwkv_chunk_group(Frame& F, int bc, unsigned long long& tsub) {
;     ...
;             const float z = -(w0 + wl); const float sp = fmaxf(z, 0.f) + __logf(1.f + __expf(-fabsf(z)));
	s_nop 1
	v_mov_b32_e32 v94, v198


; #define LAS __attribute__((address_space(3)))
; __device__ __forceinline__ void rwkv_chunk_group(Frame& F, int bc, unsigned long long& tsub) {
;     ...
;             const float r = cr + (pr - cr) * mur, k = ck + (pk - ck) * muk, v = cv + (pv - cv) * muv; pr = cr; pk = ck; pv = cv;
;             const float wl = *(const LAS float*)(L + L_WL + (t * 65 + ch) * 4), al = *(const LAS float*)(L + L_AL + (t * 65 + ch) * 4), gl = *(const LAS float*)(L + L_GL + (t * 65 + ch) * 4);
;             const float z = -(w0 + wl); const float sp = fmaxf(z, 0.f) + __logf(1.f + __expf(-fabsf(z)));
;             const float lgd = -__expf(-sp - 0.5f);
	v_lshlrev_b32_e32 v198, 16, v172
	v_pk_mov_b32 v[92:93], v[92:93], v[198:199] op_sel:[1,0]
	v_add_f32_e32 v94, v192, v94
	v_pk_add_f32 v[92:93], v[92:93], v[198:199] neg_lo:[0,1] neg_hi:[0,1]
	v_sub_f32_e32 v94, -0.5, v94
	v_pk_fma_f32 v[92:93], v[92:93], v[52:53], v[198:199] op_sel_hi:[1,0,1]

; #define LAS __attribute__((address_space(3)))
; __device__ __forceinline__ void rwkv_chunk_group(Frame& F, int bc, unsigned long long& tsub) {
;     ...
;             const float wl = *(const LAS float*)(L + L_WL + (t * 65 + ch) * 4), al = *(const LAS float*)(L + L_AL + (t * 65 + ch) * 4), gl = *(const LAS float*)(L + L_GL + (t * 65 + ch) * 4);
;             const float z = -(w0 + wl); const float sp = fmaxf(z, 0.f) + __logf(1.f + __expf(-fabsf(z)));
;             const float lgd = -__expf(-sp - 0.5f);
	ds_read_b32 v52, v126
	v_mul_f32_e32 v94, 0x3fb8aa3b, v94
	v_exp_f32_e32 v192, v94
	v_add_f32_e32 v94, v43, v191
	v_lshlrev_b32_e32 v191, 16, v163
	v_sub_f32_e32 v197, v197, v191
	v_fmac_f32_e32 v191, v197, v95


; #define LAS __attribute__((address_space(3)))
; __device__ __forceinline__ float sigmoidf_(float x) { return __builtin_amdgcn_rcpf(1.0f + __expf(-x)); }
; __device__ __forceinline__ void rwkv_chunk_group(Frame& F, int bc, unsigned long long& tsub) {
;     ...
;             const float wl = *(const LAS float*)(L + L_WL + (t * 65 + ch) * 4), al = *(const LAS float*)(L + L_AL + (t * 65 + ch) * 4), gl = *(const LAS float*)(L + L_GL + (t * 65 + ch) * 4);
;             const float z = -(w0 + wl); const float sp = fmaxf(z, 0.f) + __logf(1.f + __expf(-fabsf(z)));
;             const float lgd = -__expf(-sp - 0.5f);
;             const float ic = sigmoidf_(a0 + al);
	ds_read_b32 v95, v126 offset:16640
	ds_read_b32 v200, v126 offset:33280
	s_waitcnt lgkmcnt(2)
	v_add_f32_e32 v45, v45, v52
	v_max_f32_e64 v52, -v45, 0
	v_mul_f32_e64 v45, |v45|, s1
	v_exp_f32_e32 v45, v45
	s_waitcnt lgkmcnt(1)
	v_add_f32_e32 v43, v43, v95
	v_mul_f32_e32 v94, 0xbfb8aa3b, v94
	v_mul_f32_e32 v43, 0xbfb8aa3b, v43
	v_add_f32_e32 v45, 1.0, v45

; __device__ __forceinline__ float sigmoidf_(float x) { return __builtin_amdgcn_rcpf(1.0f + __expf(-x)); }
; __device__ __forceinline__ void rwkv_chunk_group(Frame& F, int bc, unsigned long long& tsub) {
;     ...
;             const float z = -(w0 + wl); const float sp = fmaxf(z, 0.f) + __logf(1.f + __expf(-fabsf(z)));
;             const float lgd = -__expf(-sp - 0.5f);
;             const float ic = sigmoidf_(a0 + al);
	v_exp_f32_e32 v94, v94
	v_exp_f32_e32 v43, v43


; __device__ __forceinline__ float sigmoidf_(float x) { return __builtin_amdgcn_rcpf(1.0f + __expf(-x)); }
; __device__ __forceinline__ void rwkv_chunk_group(Frame& F, int bc, unsigned long long& tsub) {
;     ...
;             const float z = -(w0 + wl); const float sp = fmaxf(z, 0.f) + __logf(1.f + __expf(-fabsf(z)));
;             const float lgd = -__expf(-sp - 0.5f);
;             const float ic = sigmoidf_(a0 + al);
	v_log_f32_e32 v45, v45
	v_add_f32_e32 v94, 1.0, v94
	v_add_f32_e32 v43, 1.0, v43
	v_rcp_f32_e32 v94, v94
	v_mul_f32_e32 v197, 0x3f317217, v45
	v_fma_f32 v197, v45, s9, -v197
	v_fmac_f32_e32 v197, 0x3377d1cf, v45
	v_fmac_f32_e32 v197, 0x3f317217, v45

; __device__ __forceinline__ float sigmoidf_(float x) { return __builtin_amdgcn_rcpf(1.0f + __expf(-x)); }
; __device__ __forceinline__ void rwkv_chunk_group(Frame& F, int bc, unsigned long long& tsub) {
;     ...
;             const float z = -(w0 + wl); const float sp = fmaxf(z, 0.f) + __logf(1.f + __expf(-fabsf(z)));
;             const float lgd = -__expf(-sp - 0.5f);
;             const float ic = sigmoidf_(a0 + al);
	v_rcp_f32_e32 v95, v43
	v_sub_f32_e32 v192, v190, v192
	v_mov_b32_e32 v45, v197


; #define GAS __attribute__((address_space(1)))
; #define LAS __attribute__((address_space(3)))
; __device__ __forceinline__ unsigned pk2(float lo, float hi) { f32x2_k v = {lo, hi}; bf16x2_k b = __builtin_convertvector(v, bf16x2_k); return __builtin_bit_cast(unsigned, b); }
; __device__ __forceinline__ void rwkv_chunk_group(Frame& F, int bc, unsigned long long& tsub) {
;     ...
;         wave_sum8(sq); wave_sum8(bq);
; #pragma unroll
;         for (int tt = 0; tt < 8; ++tt) { const float kn = kkv[tt] * __builtin_amdgcn_rsqf(fmaxf(sq[tt], 1e-24f));
;             aa[tt] = -kn; bb[tt] = kn * icv[tt]; vbv[tt] = bq[tt] * vv[tt]; }
;         *(LAS float*)(L + L_GT + (w * 64 + ch) * 4) = run;
;         *(GAS v4u*)(VBp + ch * 64 + tb) = (v4u){pk2(vbv[0], vbv[1]), pk2(vbv[2], vbv[3]), pk2(vbv[4], vbv[5]), pk2(vbv[6], vbv[7])};
;         *(GAS v4u*)(Gp + ch * 64 + tb) = (v4u){pk2(ggv[0], ggv[1]), pk2(ggv[2], ggv[3]), pk2(ggv[4], ggv[5]), pk2(ggv[6], ggv[7])};
;         if (hh + 1 < RW_H) {
;             const bool has = (c * CH + tb > 0);
; #pragma unroll
;             for (int tt = 0; tt < 9; ++tt) { const size_t off = (size_t)(row0 + tb + tt - 1) * PRW + hnext * 64 + ch;
;                 if (tt > 0 || has) { raw[tt][0] = P[off]; raw[tt][1] = P[off + 512]; raw[tt][2] = P[off + 1024]; } }
	v_add_f32_e32 v45, v52, v45
	v_sub_f32_e32 v45, -0.5, v45
	v_mul_f32_e32 v45, 0x3fb8aa3b, v45
	v_exp_f32_e32 v45, v45
	s_nop 0
	v_pk_mul_f32 v[100:101], v[80:81], v[44:45] op_sel_hi:[1,0]
	v_pk_mul_f32 v[80:81], v[98:99], v[44:45] op_sel_hi:[1,0]
	v_pk_mul_f32 v[196:197], v[100:101], v[100:101]
	v_pk_mul_f32 v[98:99], v[80:81], v[80:81]
	v_sub_f32_e32 v52, v192, v45
	s_nop 0
	v_permlane32_swap_b32_e32 v196, v98
	v_permlane32_swap_b32_e32 v197, v99
	v_add_f32_e32 v196, v196, v98
	v_add_f32_e32 v197, v197, v99
	v_lshlrev_b32_e32 v98, 16, v165
	v_and_b32_e32 v99, 0xffff0000, v165
	v_pk_mov_b32 v[96:97], v[96:97], v[98:99] op_sel:[1,0]
	v_pk_mul_f32 v[88:89], v[88:89], v[44:45] op_sel_hi:[1,0]
	v_pk_add_f32 v[96:97], v[96:97], v[98:99] neg_lo:[0,1] neg_hi:[0,1]
	v_pk_mul_f32 v[198:199], v[88:89], v[88:89]
	v_pk_fma_f32 v[42:43], v[96:97], v[42:43], v[98:99] op_sel_hi:[1,0,1]
	v_pk_add_f32 v[98:99], v[94:95], -1.0 op_sel_hi:[1,0]
	v_pk_mul_f32 v[44:45], v[42:43], v[44:45] op_sel_hi:[1,0]
	v_pk_fma_f32 v[98:99], v[46:47], v[98:99], 1.0 op_sel_hi:[0,1,0]
	v_pk_mul_f32 v[42:43], v[42:43], v[98:99]
	v_pk_mul_f32 v[96:97], v[44:45], v[44:45]
	v_mul_f32_e32 v46, v188, v42
	v_mul_f32_e32 v46, v103, v46
	s_nop 1
	v_permlane32_swap_b32_e32 v187, v46
	v_add_f32_e32 v46, v187, v46
	v_mul_f32_e32 v98, v191, v43
	s_nop 0
	v_permlane16_swap_b32_e32 v201, v46
	v_mul_f32_e32 v98, v103, v98
	v_add_f32_e32 v46, v201, v46
	s_nop 0
	v_permlane32_swap_b32_e32 v186, v98
	v_add_f32_dpp v46, v46, v46 quad_perm:[1,0,3,2] row_mask:0xf bank_mask:0xf bound_ctrl:1
	v_add_f32_e32 v98, v186, v98
	s_nop 1
	v_permlane16_swap_b32_e32 v195, v98
	v_add_f32_dpp v46, v46, v46 quad_perm:[2,3,0,1] row_mask:0xf bank_mask:0xf bound_ctrl:1
	v_add_f32_e32 v98, v195, v98
	v_permlane32_swap_b32_e32 v198, v96
	v_add_f32_dpp v46, v46, v46 row_half_mirror row_mask:0xf bank_mask:0xf bound_ctrl:1
	v_permlane32_swap_b32_e32 v199, v97
	s_nop 0
	v_add_f32_dpp v46, v46, v46 row_mirror row_mask:0xf bank_mask:0xf bound_ctrl:1
	v_add_f32_dpp v98, v98, v98 quad_perm:[1,0,3,2] row_mask:0xf bank_mask:0xf bound_ctrl:1
	v_readlane_b32 s14, v46, 0
	v_readlane_b32 s64, v46, 16
	v_readlane_b32 s72, v46, 32
	v_readlane_b32 s96, v46, 48
	v_add_f32_e32 v46, v198, v96
	v_add_f32_e32 v96, v199, v97
	v_add_f32_dpp v98, v98, v98 quad_perm:[2,3,0,1] row_mask:0xf bank_mask:0xf bound_ctrl:1
	v_permlane16_swap_b32_e32 v196, v46
	v_permlane16_swap_b32_e32 v197, v96
	v_add_f32_dpp v98, v98, v98 row_half_mirror row_mask:0xf bank_mask:0xf bound_ctrl:1
	v_add_f32_e32 v46, v196, v46
	v_add_f32_e32 v96, v197, v96
	v_add_f32_dpp v98, v98, v98 row_mirror row_mask:0xf bank_mask:0xf bound_ctrl:1
	v_add_f32_dpp v46, v46, v46 quad_perm:[1,0,3,2] row_mask:0xf bank_mask:0xf bound_ctrl:1
	v_add_f32_dpp v96, v96, v96 quad_perm:[1,0,3,2] row_mask:0xf bank_mask:0xf bound_ctrl:1
	v_readlane_b32 s73, v98, 32
	v_add_f32_dpp v46, v46, v46 quad_perm:[2,3,0,1] row_mask:0xf bank_mask:0xf bound_ctrl:1
	v_add_f32_dpp v96, v96, v96 quad_perm:[2,3,0,1] row_mask:0xf bank_mask:0xf bound_ctrl:1
	v_readlane_b32 s15, v98, 0
	v_readlane_b32 s65, v98, 16
	v_readlane_b32 s97, v98, 48
	v_add_f32_dpp v46, v46, v46 row_half_mirror row_mask:0xf bank_mask:0xf bound_ctrl:1
	v_add_f32_dpp v96, v96, v96 row_half_mirror row_mask:0xf bank_mask:0xf bound_ctrl:1
	v_pk_mul_f32 v[196:197], v[84:85], s[72:73]
	s_lshl_b64 s[72:73], s[66:67], 13
	v_pk_mul_f32 v[98:99], v[36:37], s[14:15]
	v_pk_mul_f32 v[186:187], v[76:77], s[64:65]
	v_add_f32_dpp v46, v46, v46 row_mirror row_mask:0xf bank_mask:0xf bound_ctrl:1
	v_add_f32_dpp v96, v96, v96 row_mirror row_mask:0xf bank_mask:0xf bound_ctrl:1
	v_pk_mul_f32 v[198:199], v[92:93], s[96:97]
	v_readlane_b32 s15, v254, 39
	s_cmp_eq_u32 s68, 7
	v_readlane_b32 s93, v46, 0
	v_readlane_b32 s71, v46, 16
	v_readlane_b32 s69, v46, 32
	v_readlane_b32 s64, v46, 48
	v_readlane_b32 s14, v96, 0
	v_readlane_b32 s77, v96, 16
	v_readlane_b32 s70, v96, 32
	v_readlane_b32 s65, v96, 48
	v_add_u32_e32 v46, s15, v105
	v_cvt_pk_bf16_f32 v96, v98, v99
	v_cvt_pk_bf16_f32 v97, v186, v187
	v_cvt_pk_bf16_f32 v98, v196, v197
	v_cvt_pk_bf16_f32 v99, v198, v199
	v_lshl_add_u64 v[186:187], v[62:63], 0, s[72:73]
	s_cselect_b64 s[96:97], -1, 0
	ds_write_b32 v46, v52
	global_store_dwordx4 v[186:187], v[96:99], off sc1
	s_and_b64 vcc, exec, s[96:97]
	s_nop 0
	v_cvt_pk_bf16_f32 v96, v47, v177
	v_cvt_pk_bf16_f32 v97, v182, v185
	v_cvt_pk_bf16_f32 v98, v189, v193
	s_waitcnt lgkmcnt(1)
	v_cvt_pk_bf16_f32 v99, v194, v200
	v_lshl_add_u64 v[46:47], v[64:65], 0, s[72:73]
	global_store_dwordx4 v[46:47], v[96:99], off sc1
	s_cbranch_vccnz .LBB0_1416
	v_readlane_b32 s72, v254, 60
	s_lshl_b32 s94, s13, 7
	v_readlane_b32 s73, v254, 61
	v_lshl_add_u64 v[46:47], v[56:57], 0, s[94:95]
	s_andn2_b64 vcc, exec, s[72:73]
	s_cbranch_vccnz .LBB0_1415
	v_readlane_b32 s72, v254, 62
	v_readlane_b32 s73, v254, 63
	s_nop 1
	v_lshl_add_u64 v[96:97], v[46:47], 0, s[72:73]
	global_load_ushort v153, v[96:97], off
	global_load_ushort v202, v[96:97], off offset:1024
	global_load_ushort v215, v[96:97], off offset:2048

; #define GAS __attribute__((address_space(1)))
; #define LAS __attribute__((address_space(3)))
; __device__ __forceinline__ void st4_lds(LAS unsigned char* p, f32x4 v) { v2u w; w.x = pk2(v[0], v[1]); w.y = pk2(v[2], v[3]); *(LAS v2u*)p = w; }
; __device__ __forceinline__ void st4_g(bf16* p, f32x4 v) { v2u w; w.x = pk2(v[0], v[1]); w.y = pk2(v[2], v[3]); *(GAS v2u*)p = w; }
; __device__ __forceinline__ void scan_load(const bf16* PT, const bf16* QC, int c, ScanOps& o, int w, int fr, int fq) {
; #pragma unroll
;     for (int q = 0; q < 2; ++q) { const int tw = 2 * w + q, p0 = 16 * (tw >> 2), q0 = 16 * (tw & 3);
;         o.pf[q][0] = *(const GAS bf16x8*)(PT + (size_t)c * 4096 + ((q0 >> 4) * 2) * 512 + fr * 32 + fq * 8); o.pf[q][1] = *(const GAS bf16x8*)(PT + (size_t)c * 4096 + ((q0 >> 4) * 2 + 1) * 512 + fr * 32 + fq * 8);
;         o.qi[q] = *(const GAS v2u*)(QC + (size_t)c * 4096 + (p0 + fr) * 64 + q0 + 4 * fq); }
; __device__ __forceinline__ void scan_step(LAS unsigned char* L, bf16* S, int c, const ScanOps& o, f32x4 (&acc)[2], int w, int fr, int fq) {
; #pragma unroll
;     for (int q = 0; q < 2; ++q) { const int tw = 2 * w + q, p0 = 16 * (tw >> 2), q0 = 16 * (tw & 3);
;         st4_g(S + (size_t)c * 4096 + (p0 + fr) * 64 + q0 + 4 * fq, acc[q]);
;         st4_lds(L + (c & 1) * ARR + (p0 + fr) * LD + (q0 + 4 * fq) * 2, acc[q]); }
.LBB0_1531:
	s_add_i32 s25, s26, 4
	v_mov_b32_e32 v67, v57
	s_add_u32 s28, s14, s19
	s_nop 2
	v_cvt_pk_bf16_f32 v118, v48, v49
	v_cvt_pk_bf16_f32 v119, v50, v51
	s_waitcnt vmcnt(18)
	v_lshlrev_b32_e32 v48, 16, v68
	v_and_b32_e32 v49, 0xffff0000, v68
	v_lshlrev_b32_e32 v50, 16, v69
	v_and_b32_e32 v51, 0xffff0000, v69
	v_lshl_add_u64 v[68:69], s[4:5], 0, v[66:67]
	s_addc_u32 s29, s12, 0
	v_cvt_pk_bf16_f32 v116, v52, v53
	v_cvt_pk_bf16_f32 v117, v54, v55
	v_add_u32_e32 v128, v80, v81
	v_add_co_u32_e32 v120, vcc, s22, v64
	v_lshl_add_u64 v[68:69], v[58:59], 1, v[68:69]
	s_add_u32 s4, s14, s20
	v_addc_co_u32_e32 v121, vcc, 0, v65, vcc


; __device__ __forceinline__ void st4_lds(LAS unsigned char* p, f32x4 v) { v2u w; w.x = pk2(v[0], v[1]); w.y = pk2(v[2], v[3]); *(LAS v2u*)p = w; }
; __device__ __forceinline__ void scan_step(LAS unsigned char* L, bf16* S, int c, const ScanOps& o, f32x4 (&acc)[2], int w, int fr, int fq) {
;     ...
;         st4_lds(L + (c & 1) * ARR + (p0 + fr) * LD + (q0 + 4 * fq) * 2, acc[q]); }
	ds_write_b64 v128, v[116:117]
	ds_write_b64 v82, v[118:119]
	v_lshl_add_u64 v[72:73], v[68:69], 0, s[6:7]
	v_lshl_add_u64 v[68:69], v[68:69], 0, s[8:9]
	s_addc_u32 s5, s12, 0
	s_add_i32 s0, s26, 8


; #define GAS __attribute__((address_space(1)))
; __device__ __forceinline__ void st4_lds(LAS unsigned char* p, f32x4 v) { v2u w; w.x = pk2(v[0], v[1]); w.y = pk2(v[2], v[3]); *(LAS v2u*)p = w; }
; __device__ __forceinline__ void st4_g(bf16* p, f32x4 v) { v2u w; w.x = pk2(v[0], v[1]); w.y = pk2(v[2], v[3]); *(GAS v2u*)p = w; }
; #define LBAR() asm volatile("s_waitcnt lgkmcnt(0)\n\ts_barrier" ::: "memory")
; __device__ __forceinline__ void scan_load(const bf16* PT, const bf16* QC, int c, ScanOps& o, int w, int fr, int fq) {
; #pragma unroll
;     for (int q = 0; q < 2; ++q) { const int tw = 2 * w + q, p0 = 16 * (tw >> 2), q0 = 16 * (tw & 3);
;         o.pf[q][0] = *(const GAS bf16x8*)(PT + (size_t)c * 4096 + ((q0 >> 4) * 2) * 512 + fr * 32 + fq * 8); o.pf[q][1] = *(const GAS bf16x8*)(PT + (size_t)c * 4096 + ((q0 >> 4) * 2 + 1) * 512 + fr * 32 + fq * 8);
;         o.qi[q] = *(const GAS v2u*)(QC + (size_t)c * 4096 + (p0 + fr) * 64 + q0 + 4 * fq); }
; __device__ __forceinline__ void scan_step(LAS unsigned char* L, bf16* S, int c, const ScanOps& o, f32x4 (&acc)[2], int w, int fr, int fq) {
;     ...
;         st4_g(S + (size_t)c * 4096 + (p0 + fr) * 64 + q0 + 4 * fq, acc[q]);
;         st4_lds(L + (c & 1) * ARR + (p0 + fr) * LD + (q0 + 4 * fq) * 2, acc[q]); }
;     LBAR();
	v_add_co_u32_e32 v122, vcc, s23, v64
	v_lshl_add_u64 v[70:71], s[28:29], 0, v[56:57]
	global_load_dwordx2 v[124:125], v[72:73], off
	global_load_dwordx2 v[126:127], v[68:69], off
	v_lshl_add_u64 v[68:69], s[4:5], 0, v[56:57]
	s_cmp_lt_u32 s25, 60
	v_addc_co_u32_e32 v123, vcc, 0, v65, vcc
	v_lshl_add_u64 v[70:71], v[70:71], 0, v[62:63]
	v_lshl_add_u64 v[68:69], v[68:69], 0, v[62:63]
	s_cselect_b64 s[4:5], -1, 0
	global_load_dwordx4 v[100:103], v[70:71], off
	global_load_dwordx4 v[104:107], v[70:71], off offset:1024
	global_load_dwordx4 v[108:111], v[68:69], off
	global_load_dwordx4 v[112:115], v[68:69], off offset:1024
	s_and_b64 vcc, s[4:5], exec
	global_store_dwordx2 v[64:65], v[116:117], off sc1
	global_store_dwordx2 v[64:65], v[118:119], off offset:32 sc1
	s_cselect_b32 s0, s0, s25
	s_waitcnt lgkmcnt(0)
	s_barrier
	v_lshlrev_b32_e32 v52, 16, v74
	v_and_b32_e32 v53, 0xffff0000, v74
	v_lshlrev_b32_e32 v54, 16, v75
	v_and_b32_e32 v55, 0xffff0000, v75


; #define LAS __attribute__((address_space(3)))
; __device__ __forceinline__ void scan_step(LAS unsigned char* L, bf16* S, int c, const ScanOps& o, f32x4 (&acc)[2], int w, int fr, int fq) {
;     ...
; #pragma unroll
;     for (int q = 0; q < 2; ++q) { const int tw = 2 * w + q, p0 = 16 * (tw >> 2);
;         const LAS unsigned char* sp = L + (c & 1) * ARR + (p0 + fr) * LD + fq * 16;
;         const bf16x8 s0 = *(const LAS bf16x8*)sp, s1 = *(const LAS bf16x8*)(sp + 64);
;         f32x4 a = (f32x4){bflo(o.qi[q].x), bfhi(o.qi[q].x), bflo(o.qi[q].y), bfhi(o.qi[q].y)};
;         a = __builtin_amdgcn_mfma_f32_16x16x32_bf16(o.pf[q][0], s0, a, 0, 0, 0);
;         a = __builtin_amdgcn_mfma_f32_16x16x32_bf16(o.pf[q][1], s1, a, 0, 0, 0);
;         acc[q] = a; }
	s_lshl_b32 s0, s0, 13
	ds_read_b128 v[70:73], v83
	ds_read_b128 v[74:77], v83 offset:64
	s_add_u32 s12, s17, s0
	v_lshl_add_u64 v[68:69], v[60:61], 0, s[0:1]
	s_addc_u32 s0, s18, 0
	s_add_u32 s4, s12, s19
	s_waitcnt lgkmcnt(1)
	v_mfma_f32_16x16x32_bf16 v[48:51], v[8:11], v[70:73], v[48:51]
	s_addc_u32 s5, s0, 0
	s_add_u32 s26, s12, s20
	s_addc_u32 s27, s0, 0
	v_mfma_f32_16x16x32_bf16 v[20:23], v[20:23], v[70:73], v[52:55]
	s_add_i32 s0, s24, 0x5000
	s_cmp_lt_u32 s25, 59
	s_mov_b32 s15, s1
	v_lshl_add_u64 v[52:53], s[26:27], 0, v[56:57]
	s_waitcnt lgkmcnt(0)
	v_mfma_f32_16x16x32_bf16 v[48:51], v[0:3], v[74:77], v[48:51]
	s_cselect_b32 s14, s0, s24
	v_lshl_add_u64 v[72:73], v[52:53], 0, v[62:63]
	v_lshl_add_u64 v[8:9], s[4:5], 0, v[56:57]
	v_mfma_f32_16x16x32_bf16 v[52:55], v[4:7], v[74:77], v[20:23]
	s_lshl_b64 s[4:5], s[14:15], 1
	s_add_u32 s0, s17, s4


; #define LAS __attribute__((address_space(3)))
; #define LBAR() asm volatile("s_waitcnt lgkmcnt(0)\n\ts_barrier" ::: "memory")
; __device__ __forceinline__ void scan_step(LAS unsigned char* L, bf16* S, int c, const ScanOps& o, f32x4 (&acc)[2], int w, int fr, int fq) {
; #pragma unroll
;     for (int q = 0; q < 2; ++q) { const int tw = 2 * w + q, p0 = 16 * (tw >> 2), q0 = 16 * (tw & 3);
;         st4_g(S + (size_t)c * 4096 + (p0 + fr) * 64 + q0 + 4 * fq, acc[q]);
;         st4_lds(L + (c & 1) * ARR + (p0 + fr) * LD + (q0 + 4 * fq) * 2, acc[q]); }
;     LBAR();
; #pragma unroll
;     for (int q = 0; q < 2; ++q) { const int tw = 2 * w + q, p0 = 16 * (tw >> 2);
;         const LAS unsigned char* sp = L + (c & 1) * ARR + (p0 + fr) * LD + fq * 16;
;         const bf16x8 s0 = *(const LAS bf16x8*)sp, s1 = *(const LAS bf16x8*)(sp + 64);
;         f32x4 a = (f32x4){bflo(o.qi[q].x), bfhi(o.qi[q].x), bflo(o.qi[q].y), bfhi(o.qi[q].y)};
;         a = __builtin_amdgcn_mfma_f32_16x16x32_bf16(o.pf[q][0], s0, a, 0, 0, 0);
;         a = __builtin_amdgcn_mfma_f32_16x16x32_bf16(o.pf[q][1], s1, a, 0, 0, 0);
;         acc[q] = a; }
; }
; __device__ __forceinline__ void rwkv_state_scan(Frame& F, int bh) {
;     LAS unsigned char* L = F.lds;
;     const int lane = F.lane, w = F.wave, fr = lane & 15, fq = lane >> 4;
;     const bf16* PT = (const bf16*)(F.ws + WS_PT) + (size_t)bh * NCH * 4096; const bf16* QC = (const bf16*)(F.ws + WS_QC) + (size_t)bh * NCH * 4096;
;     bf16* S = (bf16*)(F.ws + WS_S) + (size_t)bh * NCH * 4096;
;     f32x4 acc[2]; acc[0] = (f32x4){0.f, 0.f, 0.f, 0.f}; acc[1] = acc[0];
;     ScanOps o0, o1, o2, o3;
;     scan_load(PT, QC, 0, o0, w, fr, fq); scan_load(PT, QC, 1, o1, w, fr, fq); scan_load(PT, QC, 2, o2, w, fr, fq); scan_load(PT, QC, 3, o3, w, fr, fq);
; #pragma unroll 1
;     for (int c = 0; c < NCH; c += 4) {
;         const int n0 = (c + 4 < NCH) ? c + 4 : c, n1 = (c + 5 < NCH) ? c + 5 : c, n2 = (c + 6 < NCH) ? c + 6 : c, n3 = (c + 7 < NCH) ? c + 7 : c;
;         scan_step(L, S, c, o0, acc, w, fr, fq);     scan_load(PT, QC, n0, o0, w, fr, fq);
;         scan_step(L, S, c + 1, o1, acc, w, fr, fq); scan_load(PT, QC, n1, o1, w, fr, fq);
;         scan_step(L, S, c + 2, o2, acc, w, fr, fq); scan_load(PT, QC, n2, o2, w, fr, fq);
;         scan_step(L, S, c + 3, o3, acc, w, fr, fq); scan_load(PT, QC, n3, o3, w, fr, fq);
	v_lshl_add_u64 v[78:79], v[68:69], 0, s[6:7]
	v_lshl_add_u64 v[70:71], v[8:9], 0, v[62:63]
	s_addc_u32 s12, s18, s5
	v_lshl_add_u64 v[116:117], v[68:69], 0, s[8:9]
	global_load_dwordx2 v[68:69], v[78:79], off
	global_load_dwordx4 v[8:11], v[70:71], off
	global_load_dwordx4 v[0:3], v[70:71], off offset:1024
	global_load_dwordx4 v[20:23], v[72:73], off
	global_load_dwordx4 v[4:7], v[72:73], off offset:1024
	global_load_dwordx2 v[74:75], v[116:117], off
	v_lshl_add_u64 v[70:71], v[60:61], 0, s[4:5]
	s_add_u32 s4, s0, s19
	v_cvt_pk_bf16_f32 v48, v48, v49
	v_cvt_pk_bf16_f32 v49, v50, v51
	v_cvt_pk_bf16_f32 v50, v52, v53
	v_cvt_pk_bf16_f32 v51, v54, v55
	s_addc_u32 s5, s12, 0
	global_store_dwordx2 v[120:121], v[48:49], off sc1
	ds_write_b64 v128, v[48:49] offset:9216
	global_store_dwordx2 v[120:121], v[50:51], off offset:32 sc1
	ds_write_b64 v82, v[50:51] offset:9216
	v_lshl_add_u64 v[48:49], s[4:5], 0, v[56:57]
	s_waitcnt lgkmcnt(0)
	s_barrier
	v_lshl_add_u64 v[78:79], v[48:49], 0, v[62:63]
	ds_read_b128 v[48:51], v83 offset:9216
	ds_read_b128 v[52:55], v83 offset:9280
	s_add_u32 s14, s0, s20
	s_addc_u32 s15, s12, 0
	s_add_i32 s0, s24, 0x6000
	s_cmp_lt_u32 s25, 58
	s_waitcnt vmcnt(26)
	v_lshlrev_b32_e32 v84, 16, v140
	v_and_b32_e32 v85, 0xffff0000, v140
	v_lshlrev_b32_e32 v86, 16, v141
	v_and_b32_e32 v87, 0xffff0000, v141
	v_lshlrev_b32_e32 v88, 16, v146
	v_and_b32_e32 v89, 0xffff0000, v146
	v_lshlrev_b32_e32 v90, 16, v147
	v_and_b32_e32 v91, 0xffff0000, v147
	s_waitcnt lgkmcnt(1)
	v_mfma_f32_16x16x32_bf16 v[40:43], v[40:43], v[48:51], v[84:87]
	s_mov_b32 s13, s1
	s_cselect_b32 s12, s0, s24
	s_lshl_b64 s[4:5], s[12:13], 1
	v_mfma_f32_16x16x32_bf16 v[48:51], v[32:35], v[48:51], v[88:91]
	v_lshl_add_u64 v[84:85], v[60:61], 0, s[4:5]
	v_lshl_add_u64 v[72:73], v[70:71], 0, s[6:7]
	v_lshl_add_u64 v[76:77], v[70:71], 0, s[8:9]
	v_lshl_add_u64 v[88:89], v[84:85], 0, s[6:7]
	v_lshl_add_u64 v[90:91], v[84:85], 0, s[8:9]
	s_waitcnt lgkmcnt(0)
	v_mfma_f32_16x16x32_bf16 v[84:87], v[12:15], v[52:55], v[40:43]
	global_load_dwordx2 v[140:141], v[72:73], off
	v_lshl_add_u64 v[72:73], s[14:15], 0, v[56:57]
	v_lshl_add_u64 v[72:73], v[72:73], 0, v[62:63]
	v_mfma_f32_16x16x32_bf16 v[48:51], v[16:19], v[52:55], v[48:51]
	global_load_dwordx4 v[40:43], v[78:79], off
	global_load_dwordx4 v[32:35], v[72:73], off
	s_nop 1
	v_cvt_pk_bf16_f32 v52, v84, v85
	v_cvt_pk_bf16_f32 v53, v86, v87
	global_load_dwordx4 v[12:15], v[78:79], off offset:1024
	global_load_dwordx4 v[16:19], v[72:73], off offset:1024
	s_nop 0
	global_load_dwordx2 v[146:147], v[76:77], off
	v_cvt_pk_bf16_f32 v48, v48, v49
	v_cvt_pk_bf16_f32 v49, v50, v51
	global_store_dwordx2 v[122:123], v[52:53], off sc1
	ds_write_b64 v128, v[52:53]
	global_store_dwordx2 v[122:123], v[48:49], off offset:32 sc1
	ds_write_b64 v82, v[48:49]
	s_waitcnt lgkmcnt(0)
	s_barrier
	ds_read_b128 v[48:51], v83
	ds_read_b128 v[52:55], v83 offset:64
	s_add_u32 s0, s17, s4
	s_addc_u32 s13, s18, s5
	s_add_u32 s4, s0, s19
	s_addc_u32 s5, s13, 0
	s_waitcnt vmcnt(26)
	v_lshlrev_b32_e32 v92, 16, v142
	v_and_b32_e32 v93, 0xffff0000, v142
	v_lshlrev_b32_e32 v94, 16, v143
	v_and_b32_e32 v95, 0xffff0000, v143
	v_lshlrev_b32_e32 v96, 16, v144
	v_and_b32_e32 v97, 0xffff0000, v144
	v_lshlrev_b32_e32 v98, 16, v145
	v_and_b32_e32 v99, 0xffff0000, v145
	s_waitcnt lgkmcnt(1)
	v_mfma_f32_16x16x32_bf16 v[28:31], v[28:31], v[48:51], v[92:95]
	s_add_u32 s12, s0, s20
	v_lshl_add_u64 v[72:73], s[4:5], 0, v[56:57]
	s_addc_u32 s13, s13, 0
	v_mfma_f32_16x16x32_bf16 v[48:51], v[44:47], v[48:51], v[96:99]
	v_lshl_add_u64 v[92:93], v[72:73], 0, v[62:63]
	v_lshl_add_u64 v[44:45], s[12:13], 0, v[56:57]
	v_lshl_add_u64 v[94:95], v[44:45], 0, v[62:63]
	s_waitcnt lgkmcnt(0)
	v_mfma_f32_16x16x32_bf16 v[84:87], v[24:27], v[52:55], v[28:31]
	global_load_dwordx2 v[142:143], v[88:89], off
	s_nop 1
	global_load_dwordx4 v[28:31], v[92:93], off
	global_load_dwordx4 v[44:47], v[94:95], off
	s_waitcnt vmcnt(25)
	v_lshlrev_b32_e32 v88, 16, v126
	v_and_b32_e32 v89, 0xffff0000, v126
	v_mfma_f32_16x16x32_bf16 v[48:51], v[36:39], v[52:55], v[48:51]
	global_load_dwordx4 v[24:27], v[92:93], off offset:1024
	global_load_dwordx4 v[36:39], v[94:95], off offset:1024
	global_load_dwordx2 v[144:145], v[90:91], off
	v_add_co_u32_e64 v52, s[4:5], s21, v64
	v_cvt_pk_bf16_f32 v54, v84, v85
	s_nop 0
	v_addc_co_u32_e64 v53, s[4:5], 0, v65, s[4:5]
	v_cvt_pk_bf16_f32 v55, v86, v87
	v_cvt_pk_bf16_f32 v48, v48, v49
	v_cvt_pk_bf16_f32 v49, v50, v51
	global_store_dwordx2 v[52:53], v[54:55], off sc1
	ds_write_b64 v128, v[54:55] offset:9216
	global_store_dwordx2 v[52:53], v[48:49], off offset:32 sc1
	ds_write_b64 v82, v[48:49] offset:9216
	s_waitcnt lgkmcnt(0)
	s_barrier
	ds_read_b128 v[48:51], v83 offset:9216
	ds_read_b128 v[84:87], v83 offset:9280
	v_lshlrev_b32_e32 v52, 16, v124
	v_and_b32_e32 v53, 0xffff0000, v124
	v_lshlrev_b32_e32 v54, 16, v125
	v_and_b32_e32 v55, 0xffff0000, v125
	v_lshlrev_b32_e32 v90, 16, v127
	v_and_b32_e32 v91, 0xffff0000, v127
	s_add_i32 s0, s24, 0x7000
	s_waitcnt vmcnt(29) lgkmcnt(1)
	v_mfma_f32_16x16x32_bf16 v[52:55], v[100:103], v[48:51], v[52:55]
	s_cmp_lt_u32 s25, 57
	s_cselect_b32 s0, s0, s24
	s_lshl_b64 s[4:5], s[0:1], 1
	s_waitcnt vmcnt(27)
	v_mfma_f32_16x16x32_bf16 v[48:51], v[108:111], v[48:51], v[88:91]
	s_add_u32 s14, s17, s4
	s_addc_u32 s12, s18, s5
	s_add_u32 s4, s2, s4
	s_waitcnt lgkmcnt(0)
	v_mfma_f32_16x16x32_bf16 v[52:55], v[104:107], v[84:87], v[52:55]
	s_mov_b32 s26, s25
	v_lshl_add_u64 v[64:65], v[64:65], 0, s[10:11]
	s_addc_u32 s5, s3, s5
	s_waitcnt vmcnt(26)
	v_mfma_f32_16x16x32_bf16 v[48:51], v[112:115], v[84:87], v[48:51]
	s_addk_i32 s24, 0x4000
	s_cbranch_vccnz .LBB0_1531
	s_waitcnt vmcnt(0)
	s_waitcnt lgkmcnt(0)
	s_barrier

; template<int THRL> __device__ __forceinline__ void attn_unit(int b,int h,int qb,const bf16*Q,const bf16*__restrict__ K,const bf16*__restrict__ V,bf16*O,char*shm,const int wid){
;     ...
;     asm volatile("s_waitcnt lgkmcnt(0)":::"memory");
;     #pragma unroll
;     for(int i=0;i<4;++i){const int row=i*8+(lane>>3),ch=lane&7; const u32x4 v=*(const u32x4*)(stg+row*64+ch*8); ATTN_STORE16(Ow+(long)row*PO+ch*8,v);} }
;   asm volatile("s_waitcnt lgkmcnt(0)\n\ts_barrier":::"memory");
.Lq_skip2:
	s_waitcnt lgkmcnt(1)
	global_store_dwordx4 v[14:15], v[2:5], off sc1
	s_mov_b64 s[6:7], 0
	s_nop 0
	v_lshlrev_b64 v[2:3], 11, v[16:17]
	v_lshl_add_u64 v[2:3], v[12:13], 0, v[2:3]
	s_waitcnt lgkmcnt(0)
	global_store_dwordx4 v[2:3], v[6:9], off sc1
	s_nop 1
	v_add_u32_e32 v6, 16, v10
	v_lshl_add_u32 v0, v6, 7, v18
	ds_read_b128 v[2:5], v0 offset:51200
	v_ashrrev_i32_e32 v7, 31, v6
	v_add_u32_e32 v10, 24, v10
	v_lshlrev_b64 v[6:7], 11, v[6:7]
	v_lshl_add_u32 v0, v10, 7, v18
	v_lshl_add_u64 v[14:15], v[12:13], 0, v[6:7]
	ds_read_b128 v[6:9], v0 offset:51200
	v_ashrrev_i32_e32 v11, 31, v10
	s_waitcnt lgkmcnt(1)
	global_store_dwordx4 v[14:15], v[2:5], off sc1
	s_nop 1
	v_lshlrev_b64 v[2:3], 11, v[10:11]
	v_lshl_add_u64 v[2:3], v[12:13], 0, v[2:3]
	s_waitcnt lgkmcnt(0)
	global_store_dwordx4 v[2:3], v[6:9], off sc1
	s_waitcnt lgkmcnt(0)
	s_barrier

; #define LAS __attribute__((address_space(3)))
; #define LBAR() asm volatile("s_waitcnt lgkmcnt(0)\n\ts_barrier" ::: "memory")
; __device__ __forceinline__ void rwkv_chunk_out_all(Frame& F) {
;     ...
;         for (int q = 0; q < 2; ++q) { const int tw = 2 * w + q, p0 = 16 * (tw >> 2), q0 = 16 * (tw & 3);
;             f32x4 a = (f32x4){bflo(cur.y0[q].x), bfhi(cur.y0[q].x), bflo(cur.y0[q].y), bfhi(cur.y0[q].y)};
; #pragma unroll
;             for (int k = 0; k < 2; ++k) a = __builtin_amdgcn_mfma_f32_16x16x32_bf16(cur.sf[q][k], cur.rf[q][k], a, 0, 0, 0);
; #pragma unroll
;             for (int v = 0; v < 4; ++v) *(LAS float*)(L + L_YL + ((p0 + fr) * 65 + q0 + 4 * fq + v) * 4) = a[v];
;         }
;         LBAR();
;         {
;             const float gw = (PRM + 4608)[gc], gb = (PRM + 5120)[gc];
;             bf16* YM = (bf16*)(F.ws + WS_YMIX);
;             float yv[8], sm[8], sv[8];
; #pragma unroll
;             for (int tt = 0; tt < 8; ++tt) { yv[tt] = *(const LAS float*)(L + L_YL + ((8 * w + tt) * 65 + ch) * 4); sm[tt] = yv[tt]; }
;             wave_sum8(sm);
; #pragma unroll
;             for (int tt = 0; tt < 8; ++tt) { yv[tt] -= sm[tt] * (1.f / 64.f); sv[tt] = yv[tt] * yv[tt]; }
;             wave_sum8(sv);
.Lp7_body:
	v_lshlrev_b32_e32 v92, 16, v76
	v_and_b32_e32 v93, 0xffff0000, v76
	v_lshlrev_b32_e32 v94, 16, v77
	v_and_b32_e32 v95, 0xffff0000, v77
	s_lshr_b32 s7, s11, 26
	s_add_i32 s7, s10, s7
	v_mfma_f32_16x16x32_bf16 v[52:55], v[52:55], v[36:39], v[92:95]
	s_ashr_i32 s7, s7, 6
	s_lshr_b32 s11, s11, 23
	s_add_i32 s10, s10, s11
	v_mfma_f32_16x16x32_bf16 v[48:51], v[48:51], v[32:35], v[52:55]
	s_lshr_b32 s11, s7, 29
	s_add_i32 s11, s7, s11
	s_and_b32 s11, s11, 0x3fffff8
	s_nop 0
	v_lshlrev_b32_e32 v52, 16, v74
	v_and_b32_e32 v53, 0xffff0000, v74
	v_lshlrev_b32_e32 v54, 16, v75
	v_and_b32_e32 v55, 0xffff0000, v75
	s_sub_i32 s11, s7, s11
	ds_write2_b32 v79, v48, v49 offset1:1
	ds_write2_b32 v79, v50, v51 offset0:2 offset1:3
	v_mfma_f32_16x16x32_bf16 v[36:39], v[44:47], v[36:39], v[52:55]
	v_lshl_add_u32 v44, s11, 6, v208
	v_ashrrev_i32_e32 v45, 31, v44
	s_lshl_b32 s10, s10, 3
	v_mfma_f32_16x16x32_bf16 v[32:35], v[40:43], v[32:35], v[36:39]
	s_nop 7
	ds_write2_b32 v80, v32, v33 offset1:1
	ds_write2_b32 v80, v34, v35 offset0:2 offset1:3
	v_lshlrev_b64 v[32:33], 2, v[44:45]
	s_waitcnt lgkmcnt(0)
	s_barrier
	v_lshl_add_u64 v[34:35], s[0:1], 0, v[32:33]
	v_lshl_add_u64 v[32:33], s[2:3], 0, v[32:33]
	s_waitcnt vmcnt(12)
	v_mov_b32_e32 v36, v100
	v_mov_b32_e32 v37, v101
	v_add_u32_e32 v32, 0, v78
	ds_read_b32 v34, v32
	ds_read_b32 v38, v81
	ds_read_b32 v39, v82
	ds_read_b32 v40, v84
	ds_read_b32 v41, v83
	ds_read_b32 v42, v85
	ds_read_b32 v43, v86
	ds_read_b32 v46, v87
	s_waitcnt lgkmcnt(4)
	v_mov_b32_e32 v32, v40
	v_mov_b32_e32 v33, v34
	s_nop 1
	v_permlane32_swap_b32_e32 v33, v32
	v_add_f32_e32 v32, v33, v32
	s_waitcnt lgkmcnt(2)
	v_mov_b32_e32 v33, v42
	v_mov_b32_e32 v35, v38
	s_nop 1
	v_permlane32_swap_b32_e32 v35, v33
	v_add_f32_e32 v33, v35, v33
	v_mov_b32_e32 v35, v39
	s_waitcnt lgkmcnt(1)
	v_mov_b32_e32 v47, v43
	s_nop 1
	v_permlane32_swap_b32_e32 v35, v47
	v_add_f32_e32 v35, v35, v47
	s_nop 1
	v_permlane16_swap_b32_e32 v32, v35
	v_add_f32_e32 v32, v32, v35
	v_mov_b32_e32 v47, v41
	s_waitcnt lgkmcnt(0)
	v_mov_b32_e32 v48, v46
	v_add_f32_dpp v32, v32, v32 quad_perm:[1,0,3,2] row_mask:0xf bank_mask:0xf bound_ctrl:1
	s_nop 0
	v_permlane32_swap_b32_e32 v47, v48
	v_add_f32_dpp v32, v32, v32 quad_perm:[2,3,0,1] row_mask:0xf bank_mask:0xf bound_ctrl:1
	v_add_f32_e32 v47, v47, v48
	s_nop 1
	v_permlane16_swap_b32_e32 v33, v47
	v_add_f32_dpp v32, v32, v32 row_half_mirror row_mask:0xf bank_mask:0xf bound_ctrl:1
	v_add_f32_e32 v33, v33, v47
	s_and_b32 s10, s10, 0xfffff000
	v_add_f32_dpp v32, v32, v32 row_mirror row_mask:0xf bank_mask:0xf bound_ctrl:1
	v_add_f32_dpp v33, v33, v33 quad_perm:[1,0,3,2] row_mask:0xf bank_mask:0xf bound_ctrl:1
	v_readlane_b32 s11, v32, 0
	v_readlane_b32 s14, v32, 16
	v_readlane_b32 s15, v32, 32
	v_readlane_b32 s16, v32, 48
	v_fmac_f32_e32 v34, s11, v89
	v_fmac_f32_e32 v39, s14, v89
	v_fmac_f32_e32 v40, s15, v89
	v_fmac_f32_e32 v43, s16, v89
	v_mul_f32_e32 v32, v34, v34
	v_mul_f32_e32 v35, v39, v39
	v_mul_f32_e32 v48, v40, v40
	v_mul_f32_e32 v50, v43, v43
	s_nop 0
	v_permlane32_swap_b32_e32 v32, v48
	v_permlane32_swap_b32_e32 v35, v50
	v_add_f32_e32 v32, v32, v48
	v_add_f32_e32 v35, v35, v50
	s_nop 1
	v_permlane16_swap_b32_e32 v32, v35
	v_add_f32_dpp v33, v33, v33 quad_perm:[2,3,0,1] row_mask:0xf bank_mask:0xf bound_ctrl:1
	v_add_f32_e32 v32, v32, v35
	s_lshl_b32 s7, s7, 12
	v_add_f32_dpp v33, v33, v33 row_half_mirror row_mask:0xf bank_mask:0xf bound_ctrl:1
	v_add_f32_dpp v32, v32, v32 quad_perm:[1,0,3,2] row_mask:0xf bank_mask:0xf bound_ctrl:1
	s_sub_i32 s7, s10, s7
	v_add_f32_dpp v33, v33, v33 row_mirror row_mask:0xf bank_mask:0xf bound_ctrl:1
	v_add_f32_dpp v32, v32, v32 quad_perm:[2,3,0,1] row_mask:0xf bank_mask:0xf bound_ctrl:1
	v_readlane_b32 s17, v33, 0
	v_readlane_b32 s18, v33, 16
	v_readlane_b32 s19, v33, 32
	v_readlane_b32 s20, v33, 48
	v_add_f32_dpp v32, v32, v32 row_half_mirror row_mask:0xf bank_mask:0xf bound_ctrl:1
	v_fmac_f32_e32 v38, s17, v89
	v_fmac_f32_e32 v41, s18, v89
	v_fmac_f32_e32 v42, s19, v89
	v_fmac_f32_e32 v46, s20, v89
	v_add_f32_dpp v32, v32, v32 row_mirror row_mask:0xf bank_mask:0xf bound_ctrl:1
	v_mul_f32_e32 v33, v38, v38
	v_mul_f32_e32 v47, v41, v41
	v_mul_f32_e32 v49, v42, v42
	v_mul_f32_e32 v51, v46, v46
	v_readlane_b32 s11, v32, 0
	v_permlane32_swap_b32_e32 v33, v49
	v_permlane32_swap_b32_e32 v47, v51
	v_readlane_b32 s16, v32, 16
	v_readlane_b32 s17, v32, 32
	v_readlane_b32 s18, v32, 48
	v_fma_f32 v32, s11, v90, v88
	v_add_f32_e32 v33, v33, v49
	v_add_f32_e32 v47, v47, v51
	v_rsq_f32_e32 v35, v32
	s_nop 0
	v_permlane16_swap_b32_e32 v33, v47
	v_add_f32_e32 v33, v33, v47
	v_mul_f32_e32 v34, v34, v35
	v_fma_f32 v34, v36, v34, v37
	v_add_f32_dpp v33, v33, v33 quad_perm:[1,0,3,2] row_mask:0xf bank_mask:0xf bound_ctrl:1
; __device__ __forceinline__ unsigned f2bf(float f) { return pk2(f, 0.f) & 0xffffu; }
; #define LBAR() asm volatile("s_waitcnt lgkmcnt(0)\n\ts_barrier" ::: "memory")
; __device__ __forceinline__ void rwkv_chunk_out_all(Frame& F) {
;     ...
; #pragma unroll
;             for (int tt = 0; tt < 8; ++tt) { const int t = 8 * w + tt;
;                 const float yn = yv[tt] * __builtin_amdgcn_rsqf(sv[tt] * (1.f / 64.f) + GN_EPS) * gw + gb;
;                 const float o = (yn + ((tt & 1) ? bfhi(vbq[tt >> 1]) : bflo(vbq[tt >> 1]))) * ((tt & 1) ? bfhi(ggq[tt >> 1]) : bflo(ggq[tt >> 1]));
;                 YM[(size_t)(row0 + t) * D + gc] = (bf16)f2bf(o); }
;         }
;         LBAR();
;         cur = nxt;
	v_lshlrev_b32_e32 v35, 16, v28
	v_add_f32_e32 v34, v34, v35
	v_add_f32_dpp v33, v33, v33 quad_perm:[2,3,0,1] row_mask:0xf bank_mask:0xf bound_ctrl:1
	v_lshlrev_b32_e32 v35, 16, v24
	v_mul_f32_e32 v34, v34, v35
	v_add_f32_dpp v33, v33, v33 row_half_mirror row_mask:0xf bank_mask:0xf bound_ctrl:1
	s_add_i32 s10, s12, s7
	s_add_i32 s14, s10, -7
	v_add_f32_dpp v33, v33, v33 row_mirror row_mask:0xf bank_mask:0xf bound_ctrl:1
	s_ashr_i32 s15, s14, 31
	v_readlane_b32 s19, v33, 0
	v_readlane_b32 s20, v33, 16
	v_readlane_b32 s21, v33, 32
	v_readlane_b32 s22, v33, 48
	v_lshl_add_u64 v[32:33], v[44:45], 1, s[4:5]
	v_cvt_pk_bf16_f32 v44, v34, s0
	v_fma_f32 v34, s19, v90, v88
	v_rsq_f32_e32 v45, v34
	s_lshl_b64 s[14:15], s[14:15], 11
	v_lshl_add_u64 v[34:35], v[32:33], 0, s[14:15]
	global_store_short v[34:35], v44, off sc1
	v_mul_f32_e32 v34, v38, v45
	v_fma_f32 v34, v36, v34, v37
	v_and_b32_e32 v28, 0xffff0000, v28
	v_add_f32_e32 v28, v34, v28
	v_and_b32_e32 v24, 0xffff0000, v24
	v_mul_f32_e32 v24, v28, v24
	v_fma_f32 v28, s16, v90, v88
	s_add_i32 s14, s10, -6
	v_rsq_f32_e32 v28, v28
	s_ashr_i32 s15, s14, 31
	s_lshl_b64 s[14:15], s[14:15], 11
	v_cvt_pk_bf16_f32 v24, v24, s0
	v_lshl_add_u64 v[34:35], v[32:33], 0, s[14:15]
	global_store_short v[34:35], v24, off sc1
	v_mul_f32_e32 v24, v39, v28
	v_fma_f32 v24, v36, v24, v37
	v_lshlrev_b32_e32 v28, 16, v29
	v_add_f32_e32 v24, v24, v28
	v_lshlrev_b32_e32 v28, 16, v25
	v_mul_f32_e32 v24, v24, v28
	v_fma_f32 v28, s20, v90, v88
	s_add_i32 s14, s10, -5
	v_rsq_f32_e32 v28, v28
	s_ashr_i32 s15, s14, 31
	s_lshl_b64 s[14:15], s[14:15], 11
	v_cvt_pk_bf16_f32 v24, v24, s0
	v_lshl_add_u64 v[34:35], v[32:33], 0, s[14:15]
	global_store_short v[34:35], v24, off sc1
	v_mul_f32_e32 v24, v41, v28
	v_fma_f32 v24, v36, v24, v37
	v_and_b32_e32 v28, 0xffff0000, v29
	v_add_f32_e32 v24, v24, v28
	v_and_b32_e32 v25, 0xffff0000, v25
	v_mul_f32_e32 v24, v24, v25
	v_cvt_pk_bf16_f32 v28, v24, s0
	v_fma_f32 v24, s17, v90, v88
	s_add_i32 s14, s10, -4
	v_rsq_f32_e32 v29, v24
	s_ashr_i32 s15, s14, 31
	s_lshl_b64 s[14:15], s[14:15], 11
	v_lshl_add_u64 v[24:25], v[32:33], 0, s[14:15]
	global_store_short v[24:25], v28, off sc1
	v_mul_f32_e32 v24, v40, v29
	v_fma_f32 v24, v36, v24, v37
	v_lshlrev_b32_e32 v25, 16, v30
	v_add_f32_e32 v24, v24, v25
	v_lshlrev_b32_e32 v25, 16, v26
	v_mul_f32_e32 v24, v24, v25
	v_cvt_pk_bf16_f32 v28, v24, s0
	v_fma_f32 v24, s21, v90, v88
	s_add_i32 s14, s10, -3
	v_rsq_f32_e32 v29, v24
	s_ashr_i32 s15, s14, 31
	s_lshl_b64 s[14:15], s[14:15], 11
	v_lshl_add_u64 v[24:25], v[32:33], 0, s[14:15]
	global_store_short v[24:25], v28, off sc1
	v_mul_f32_e32 v24, v42, v29
	v_fma_f32 v24, v36, v24, v37
	v_and_b32_e32 v25, 0xffff0000, v30
	v_add_f32_e32 v24, v24, v25
	v_and_b32_e32 v25, 0xffff0000, v26
	v_mul_f32_e32 v24, v24, v25
	v_cvt_pk_bf16_f32 v26, v24, s0
	v_fma_f32 v24, s18, v90, v88
	s_add_i32 s14, s10, -2
	v_rsq_f32_e32 v28, v24
	s_ashr_i32 s15, s14, 31
	s_lshl_b64 s[14:15], s[14:15], 11
	v_lshl_add_u64 v[24:25], v[32:33], 0, s[14:15]
	global_store_short v[24:25], v26, off sc1
	v_mul_f32_e32 v24, v43, v28
	v_fma_f32 v24, v36, v24, v37
	v_lshlrev_b32_e32 v25, 16, v31
	v_add_f32_e32 v24, v24, v25
	v_lshlrev_b32_e32 v25, 16, v27
	v_mul_f32_e32 v24, v24, v25
	v_cvt_pk_bf16_f32 v26, v24, s0
	v_fma_f32 v24, s22, v90, v88
	s_add_i32 s14, s10, -1
	v_rsq_f32_e32 v28, v24
	s_ashr_i32 s15, s14, 31
	s_lshl_b64 s[14:15], s[14:15], 11
	v_lshl_add_u64 v[24:25], v[32:33], 0, s[14:15]
	global_store_short v[24:25], v26, off sc1
	v_mul_f32_e32 v24, v46, v28
	v_fmac_f32_e32 v37, v36, v24
	v_and_b32_e32 v24, 0xffff0000, v31
	v_add_f32_e32 v24, v37, v24
	v_and_b32_e32 v25, 0xffff0000, v27
	s_ashr_i32 s11, s10, 31
	v_mul_f32_e32 v24, v24, v25
	s_lshl_b64 s[10:11], s[10:11], 11
	v_cvt_pk_bf16_f32 v26, v24, s0
	v_lshl_add_u64 v[24:25], v[32:33], 0, s[10:11]
	global_store_short v[24:25], v26, off sc1
	s_waitcnt lgkmcnt(0)
	s_barrier
	s_waitcnt vmcnt(8)
	v_mov_b64_e32 v[34:35], v[14:15]
	v_mov_b64_e32 v[38:39], v[10:11]
	v_mov_b64_e32 v[42:43], v[22:23]
	v_mov_b64_e32 v[46:47], v[18:19]
	v_mov_b64_e32 v[50:51], v[6:7]
	v_mov_b64_e32 v[54:55], v[2:3]
	s_add_i32 s12, s12, s13
	s_andn2_b64 vcc, exec, s[8:9]
	v_mov_b64_e32 v[32:33], v[12:13]
	v_mov_b64_e32 v[36:37], v[8:9]
	v_mov_b64_e32 v[40:41], v[20:21]
	v_mov_b64_e32 v[44:45], v[16:17]
	v_mov_b64_e32 v[48:49], v[4:5]
	v_mov_b64_e32 v[52:53], v[0:1]
	v_mov_b64_e32 v[74:75], v[72:73]
	v_mov_b64_e32 v[76:77], v[70:71]
	v_mov_b64_e32 v[28:29], v[104:105]
	v_mov_b64_e32 v[30:31], v[106:107]
	v_mov_b64_e32 v[24:25], v[108:109]
	v_mov_b64_e32 v[26:27], v[110:111]
	v_mov_b32_e32 v100, v112
	v_mov_b32_e32 v101, v113
	s_mov_b32 s10, s6
	s_cbranch_vccz .LBB0_1679

; #define GAS __attribute__((address_space(1)))
; __device__ __forceinline__ unsigned pk2(float lo, float hi) { f32x2_k v = {lo, hi}; bf16x2_k b = __builtin_convertvector(v, bf16x2_k); return __builtin_bit_cast(unsigned, b); }
; __device__ __forceinline__ void diff_post_rows(Frame& F) {
;     ...
;     for (; m < M; m += 2 * NGW) {
; #pragma unroll
;         for (int r = 0; r < 2; ++r)
; #pragma unroll
;             for (int hd = 0; hd < 4; ++hd) { const int mr = m + (2 + r) * NGW; n1[r][hd] = 0u; n2[r][hd] = 0u;
;                 if (mr < M) { n1[r][hd] = *(const GAS unsigned*)(O + (size_t)mr * 1024 + (hd * 4 + vh) * 64 + d); n2[r][hd] = *(const GAS unsigned*)(O + (size_t)mr * 1024 + (hd * 4 + 2 + vh) * 64 + d); } }
;         float o0[8], o1[8], ss[8];
; #pragma unroll
;         for (int r = 0; r < 2; ++r)
; #pragma unroll
;             for (int hd = 0; hd < 4; ++hd) { const unsigned w1 = c1[r][hd], w2 = c2[r][hd]; const int k = r * 4 + hd;
;                 o0[k] = bflo(w1) - lam * bflo(w2); o1[k] = bfhi(w1) - lam * bfhi(w2); ss[k] = o0[k] * o0[k] + o1[k] * o1[k]; }
;         wave_sum8(ss);
; #pragma unroll
;         for (int r = 0; r < 2; ++r) { const int mr = m + r * NGW;
;             if (mr < M) {
; #pragma unroll
;                 for (int hd = 0; hd < 4; ++hd) { const int k = r * 4 + hd; const float rs = __builtin_amdgcn_rsqf(ss[k] * (1.f / 128.f) + SUBLN_EPS);
;                     *(GAS unsigned*)(YM + (size_t)mr * D + 512 + hd * 128 + e0) = pk2(o0[k] * rs * sw0, o1[k] * rs * sw1); } } }
; #pragma unroll
;         for (int r = 0; r < 2; ++r)
; #pragma unroll
;             for (int hd = 0; hd < 4; ++hd) { c1[r][hd] = n1[r][hd]; c2[r][hd] = n2[r][hd]; }
.LBB0_1712:
	s_waitcnt vmcnt(1)
	v_lshlrev_b32_e32 v84, 16, v27
	v_and_b32_e32 v85, 0xffff0000, v27
	v_lshlrev_b32_e32 v26, 16, v44
	s_waitcnt vmcnt(0)
	v_lshlrev_b32_e32 v46, 16, v63
	v_and_b32_e32 v27, 0xffff0000, v44
	v_and_b32_e32 v47, 0xffff0000, v63
	v_pk_fma_f32 v[46:47], v[18:19], v[46:47], v[26:27] neg_lo:[1,0,0] neg_hi:[1,0,0]
	v_lshlrev_b32_e32 v44, 16, v66
	v_mul_f32_e32 v26, v47, v47
	v_pk_fma_f32 v[94:95], v[46:47], v[46:47], v[26:27] op_sel_hi:[1,1,0]
	v_lshlrev_b32_e32 v26, 16, v45
	v_and_b32_e32 v27, 0xffff0000, v45
	v_and_b32_e32 v45, 0xffff0000, v66
	v_pk_fma_f32 v[26:27], v[18:19], v[44:45], v[26:27] neg_lo:[1,0,0] neg_hi:[1,0,0]
	v_lshlrev_b32_e32 v80, 16, v48
	v_mul_f32_e32 v44, v27, v27
	v_lshlrev_b32_e32 v82, 16, v49
	v_and_b32_e32 v81, 0xffff0000, v48
	v_and_b32_e32 v83, 0xffff0000, v49
	v_pk_fma_f32 v[96:97], v[26:27], v[26:27], v[44:45] op_sel_hi:[1,1,0]
	v_lshlrev_b32_e32 v44, 16, v65
	v_lshlrev_b32_e32 v48, 16, v67
	v_and_b32_e32 v45, 0xffff0000, v65
	v_and_b32_e32 v49, 0xffff0000, v67
	v_pk_fma_f32 v[44:45], v[18:19], v[48:49], v[44:45] neg_lo:[1,0,0] neg_hi:[1,0,0]
	v_lshlrev_b32_e32 v98, 16, v68
	v_mul_f32_e32 v48, v45, v45
	v_pk_fma_f32 v[66:67], v[44:45], v[44:45], v[48:49] op_sel_hi:[1,1,0]
	v_lshlrev_b32_e32 v48, 16, v62
	v_and_b32_e32 v49, 0xffff0000, v62
	v_and_b32_e32 v99, 0xffff0000, v68
	v_pk_fma_f32 v[48:49], v[18:19], v[98:99], v[48:49] neg_lo:[1,0,0] neg_hi:[1,0,0]
	v_lshlrev_b32_e32 v92, 16, v58
	v_and_b32_e32 v93, 0xffff0000, v58
	v_mul_f32_e32 v58, v49, v49
	v_pk_fma_f32 v[80:81], v[18:19], v[82:83], v[80:81] neg_lo:[1,0,0] neg_hi:[1,0,0]
	v_pk_fma_f32 v[62:63], v[48:49], v[48:49], v[58:59] op_sel_hi:[1,1,0]
	v_mul_f32_e32 v58, v81, v81
	v_pk_fma_f32 v[82:83], v[80:81], v[80:81], v[58:59] op_sel_hi:[1,1,0]
	v_lshlrev_b32_e32 v86, 16, v52
	v_and_b32_e32 v87, 0xffff0000, v52
	v_permlane32_swap_b32_e32 v82, v94
	v_lshlrev_b32_e32 v88, 16, v55
	v_and_b32_e32 v89, 0xffff0000, v55
	v_add_f32_e32 v55, v82, v94
	v_pk_fma_f32 v[82:83], v[18:19], v[86:87], v[84:85] neg_lo:[1,0,0] neg_hi:[1,0,0]
	v_lshlrev_b32_e32 v90, 16, v57
	v_mul_f32_e32 v58, v83, v83
	v_pk_fma_f32 v[84:85], v[82:83], v[82:83], v[58:59] op_sel_hi:[1,1,0]
	v_and_b32_e32 v91, 0xffff0000, v57
	s_nop 0
	v_permlane32_swap_b32_e32 v84, v96
	v_add_f32_e32 v57, v84, v96
	v_pk_fma_f32 v[84:85], v[18:19], v[90:91], v[88:89] neg_lo:[1,0,0] neg_hi:[1,0,0]
	v_lshlrev_b32_e32 v52, 16, v53
	v_mul_f32_e32 v58, v85, v85
	v_pk_fma_f32 v[86:87], v[84:85], v[84:85], v[58:59] op_sel_hi:[1,1,0]
	v_and_b32_e32 v53, 0xffff0000, v53
	s_nop 0
	v_permlane32_swap_b32_e32 v86, v66
	v_add_f32_e32 v58, v86, v66
	s_nop 1
	v_permlane16_swap_b32_e32 v55, v58
	v_add_f32_e32 v55, v55, v58
	v_lshl_add_u64 v[98:99], s[8:9], 0, v[24:25]
	v_pk_fma_f32 v[52:53], v[18:19], v[92:93], v[52:53] neg_lo:[1,0,0] neg_hi:[1,0,0]
	v_add_f32_dpp v55, v55, v55 quad_perm:[1,0,3,2] row_mask:0xf bank_mask:0xf bound_ctrl:1
	s_nop 1
	v_add_f32_dpp v55, v55, v55 quad_perm:[2,3,0,1] row_mask:0xf bank_mask:0xf bound_ctrl:1
	s_nop 1
	v_add_f32_dpp v55, v55, v55 row_half_mirror row_mask:0xf bank_mask:0xf bound_ctrl:1
	s_nop 1
	v_add_f32_dpp v55, v55, v55 row_mirror row_mask:0xf bank_mask:0xf bound_ctrl:1
	s_nop 0
	v_readlane_b32 s4, v55, 0
	v_readlane_b32 s11, v55, 32
	v_readlane_b32 s10, v55, 48
	v_fma_f32 v58, s4, v51, v50
	v_rsq_f32_e32 v58, v58
	v_readlane_b32 s4, v55, 16
	v_pk_mul_f32 v[66:67], v[80:81], v[58:59] op_sel_hi:[1,0]
	s_nop 0
	v_fma_f32 v58, s4, v51, v50
	v_rsq_f32_e32 v58, v58
	v_pk_mul_f32 v[66:67], v[20:21], v[66:67]
	v_pk_mul_f32 v[80:81], v[84:85], v[58:59] op_sel_hi:[1,0]
	v_cvt_pk_bf16_f32 v55, v66, v67
	v_add_co_u32_e32 v66, vcc, s15, v98
	v_pk_mul_f32 v[80:81], v[20:21], v[80:81]
	s_nop 0
	v_addc_co_u32_e32 v67, vcc, 0, v99, vcc
	v_mul_f32_e32 v58, v53, v53
	global_store_dword v[66:67], v55, off offset:1024 sc1
	v_cvt_pk_bf16_f32 v55, v80, v81
	v_pk_fma_f32 v[80:81], v[52:53], v[52:53], v[58:59] op_sel_hi:[1,1,0]
	global_store_dword v[66:67], v55, off offset:1536 sc1
	s_nop 0
	v_permlane32_swap_b32_e32 v80, v62
	v_add_f32_e32 v55, v80, v62
	s_nop 1
	v_permlane16_swap_b32_e32 v57, v55
	v_add_f32_e32 v55, v57, v55
	s_nop 1
	v_add_f32_dpp v55, v55, v55 quad_perm:[1,0,3,2] row_mask:0xf bank_mask:0xf bound_ctrl:1
	s_nop 1
	v_add_f32_dpp v55, v55, v55 quad_perm:[2,3,0,1] row_mask:0xf bank_mask:0xf bound_ctrl:1
	s_nop 1
	v_add_f32_dpp v55, v55, v55 row_half_mirror row_mask:0xf bank_mask:0xf bound_ctrl:1
	s_nop 1
	v_add_f32_dpp v55, v55, v55 row_mirror row_mask:0xf bank_mask:0xf bound_ctrl:1
	s_nop 0
	v_readlane_b32 s4, v55, 0
	v_readlane_b32 s18, v55, 32
	v_readlane_b32 s17, v55, 48
	v_fma_f32 v57, s4, v51, v50
	v_rsq_f32_e32 v58, v57
	v_readlane_b32 s4, v55, 16
	v_pk_mul_f32 v[62:63], v[82:83], v[58:59] op_sel_hi:[1,0]
	s_nop 0
	v_fma_f32 v55, s4, v51, v50
	v_rsq_f32_e32 v58, v55
	v_pk_mul_f32 v[62:63], v[20:21], v[62:63]
	s_add_i32 s4, s13, s16
	v_cvt_pk_bf16_f32 v55, v62, v63
	v_pk_mul_f32 v[52:53], v[52:53], v[58:59] op_sel_hi:[1,0]
	s_cmpk_gt_i32 s4, 0x3fff
	v_pk_mul_f32 v[52:53], v[20:21], v[52:53]
	global_store_dword v[66:67], v55, off offset:1280 sc1
	v_cvt_pk_bf16_f32 v52, v52, v53
	global_store_dword v[66:67], v52, off offset:1792 sc1
	s_cbranch_scc1 .LBB0_1697
	v_fma_f32 v52, s11, v51, v50
	v_rsq_f32_e32 v52, v52
	s_ashr_i32 s5, s4, 31
	s_lshl_b64 s[4:5], s[4:5], 11
	s_add_u32 s4, s86, s4
	v_pk_mul_f32 v[46:47], v[46:47], v[52:53] op_sel_hi:[1,0]
	s_addc_u32 s5, s87, s5
	v_pk_mul_f32 v[46:47], v[20:21], v[46:47]
	v_lshl_add_u64 v[62:63], v[0:1], 1, s[4:5]
	v_cvt_pk_bf16_f32 v53, v46, v47
	v_fma_f32 v47, s18, v51, v50
	v_add_co_u32_e32 v46, vcc, s15, v62
	v_rsq_f32_e32 v52, v47
	s_nop 0
	v_addc_co_u32_e32 v47, vcc, 0, v63, vcc
	global_store_dword v[46:47], v53, off offset:1024 sc1
	v_fma_f32 v46, s10, v51, v50
	v_rsq_f32_e32 v46, v46
	v_pk_mul_f32 v[26:27], v[26:27], v[52:53] op_sel_hi:[1,0]
	v_lshl_add_u64 v[66:67], v[62:63], 0, s[6:7]
	v_pk_mul_f32 v[26:27], v[20:21], v[26:27]
	s_nop 0
	v_cvt_pk_bf16_f32 v26, v26, v27
	global_store_dword v[66:67], v26, off offset:256 sc1
	v_pk_mul_f32 v[26:27], v[44:45], v[46:47] op_sel_hi:[1,0]
	v_fma_f32 v44, s17, v51, v50
	v_rsq_f32_e32 v44, v44
	v_pk_mul_f32 v[26:27], v[20:21], v[26:27]
	s_nop 0
	v_cvt_pk_bf16_f32 v26, v26, v27
	global_store_dword v[66:67], v26, off offset:512 sc1
	v_pk_mul_f32 v[26:27], v[48:49], v[44:45] op_sel_hi:[1,0]
	s_nop 0
	v_pk_mul_f32 v[26:27], v[20:21], v[26:27]
	s_nop 0
	v_cvt_pk_bf16_f32 v26, v26, v27
	global_store_dword v[66:67], v26, off offset:768 sc1
	s_branch .LBB0_1697

; __device__ __forceinline__ u32x4 pack_bf8(f32x4 a, f32x4 b) { u32x4 w; w.x = cvt_pk_bf16(a[0], a[1]); w.y = cvt_pk_bf16(a[2], a[3]); w.z = cvt_pk_bf16(b[0], b[1]); w.w = cvt_pk_bf16(b[2], b[3]); return w; }
;     __device__ __forceinline__ void fused(f32x4 (&acc)[2][2][4][2], const Unit& u, int wr, int wc, int fr, int fq, PG8_LAS unsigned char* lds, int wid, int lane) const {
;     ...
; #pragma unroll
;         for (int ai = 0; ai < 2; ++ai)
; #pragma unroll
;             for (int m = 0; m < 4; ++m) { const int r = ai * HALF + wr * 64 + m * 16 + fr; const float rs = S[r]; const size_t off = (size_t)(u.pm * BM + r) * ldc + col0;
; #pragma unroll
;                 for (int bj = 0; bj < 2; ++bj) { const f32x4 x0 = acc[ai][bj][m][0], x1 = acc[ai][bj][m][1];
;                     __builtin_nontemporal_store(pack_bf8(x0, x1), (u32x4*)(out + off + bj * HALF));
;                     *(u32x4*)(xn + off + bj * HALF) = pack_bf8(x0 * gv[bj][0] * rs, x1 * gv[bj][1] * rs); }
;                 asm volatile("" ::: "memory"); }
.LBB0_1849:
	s_or_b64 exec, exec, s[0:1]
	s_mov_b32 s2, 0x19000
	v_add_co_u32_e32 v80, vcc, s2, v182
	s_waitcnt lgkmcnt(0)
	s_barrier
	s_mov_b64 s[0:1], 0x19000
	v_addc_co_u32_e32 v81, vcc, 0, v183, vcc
	global_load_dwordx4 v[140:143], v[80:81], off
	v_lshl_add_u64 v[80:81], v[182:183], 0, s[0:1]
	global_load_dwordx4 v[136:139], v[80:81], off offset:16
	s_waitcnt lgkmcnt(0)
	global_load_dwordx4 v[132:135], v[80:81], off offset:512
	s_nop 0
	global_load_dwordx4 v[80:83], v[80:81], off offset:528
	v_add_u32_e32 v164, 16, v150
	v_ashrrev_i32_e32 v151, 31, v150
	ds_read_b32 v166, v158 offset:8192
	v_add_u32_e32 v152, 48, v150
	v_add_u32_e32 v156, 32, v150
	v_ashrrev_i32_e32 v165, 31, v164
	v_lshlrev_b64 v[150:151], 10, v[150:151]
	s_add_u32 s0, s86, 0xc000000
	v_lshl_add_u64 v[150:151], v[150:151], 0, v[178:179]
	v_lshlrev_b64 v[164:165], 10, v[164:165]
	s_addc_u32 s1, s87, 0
	v_lshlrev_b64 v[150:151], 1, v[150:151]
	v_lshl_add_u64 v[164:165], v[164:165], 0, v[178:179]
	v_cvt_pk_bf16_f32 v160, v120, v121
	v_cvt_pk_bf16_f32 v161, v122, v123
	v_cvt_pk_bf16_f32 v162, v124, v125
	v_cvt_pk_bf16_f32 v163, v126, v127
	v_lshl_add_u64 v[168:169], s[0:1], 0, v[150:151]
	v_lshlrev_b64 v[164:165], 1, v[164:165]
	v_lshl_add_u64 v[150:151], s[80:81], 0, v[150:151]
	global_store_dwordx4 v[168:169], v[160:163], off nt
	v_ashrrev_i32_e32 v157, 31, v156
	v_ashrrev_i32_e32 v153, 31, v152
	v_lshl_add_u64 v[160:161], s[0:1], 0, v[164:165]
	v_lshl_add_u64 v[162:163], s[80:81], 0, v[164:165]
	s_waitcnt vmcnt(3)
	v_pk_mul_f32 v[126:127], v[126:127], v[138:139]
	v_pk_mul_f32 v[122:123], v[122:123], v[142:143]
	v_pk_mul_f32 v[120:121], v[120:121], v[140:141]
	v_pk_mul_f32 v[124:125], v[124:125], v[136:137]
	s_waitcnt vmcnt(2)
	v_pk_mul_f32 v[164:165], v[118:119], v[134:135]
	v_pk_mul_f32 v[170:171], v[116:117], v[132:133]
	s_waitcnt vmcnt(1)
	v_pk_mul_f32 v[172:173], v[110:111], v[82:83]
	v_pk_mul_f32 v[174:175], v[108:109], v[80:81]
	s_waitcnt lgkmcnt(0)
	v_pk_mul_f32 v[122:123], v[122:123], v[166:167] op_sel_hi:[1,0]
	v_pk_mul_f32 v[120:121], v[120:121], v[166:167] op_sel_hi:[1,0]
	v_pk_mul_f32 v[126:127], v[126:127], v[166:167] op_sel_hi:[1,0]
	v_pk_mul_f32 v[124:125], v[124:125], v[166:167] op_sel_hi:[1,0]
	v_pk_mul_f32 v[164:165], v[164:165], v[166:167] op_sel_hi:[1,0]
	v_pk_mul_f32 v[170:171], v[170:171], v[166:167] op_sel_hi:[1,0]
	v_pk_mul_f32 v[172:173], v[172:173], v[166:167] op_sel_hi:[1,0]
	v_pk_mul_f32 v[166:167], v[174:175], v[166:167] op_sel_hi:[1,0]
	v_cvt_pk_bf16_f32 v120, v120, v121
	v_cvt_pk_bf16_f32 v121, v122, v123
	v_cvt_pk_bf16_f32 v122, v124, v125
	v_cvt_pk_bf16_f32 v123, v126, v127
	global_store_dwordx4 v[150:151], v[120:123], off sc1
	v_cvt_pk_bf16_f32 v116, v116, v117
	v_cvt_pk_bf16_f32 v117, v118, v119
	v_cvt_pk_bf16_f32 v118, v108, v109
	v_cvt_pk_bf16_f32 v119, v110, v111
	global_store_dwordx4 v[168:169], v[116:119], off offset:256 nt
	v_cvt_pk_bf16_f32 v108, v170, v171
	v_cvt_pk_bf16_f32 v109, v164, v165
	v_cvt_pk_bf16_f32 v110, v166, v167
	v_cvt_pk_bf16_f32 v111, v172, v173
	global_store_dwordx4 v[150:151], v[108:111], off offset:256 sc1
	ds_read_b32 v116, v158 offset:8256
	v_pk_mul_f32 v[176:177], v[114:115], v[142:143]
	v_pk_mul_f32 v[180:181], v[112:113], v[140:141]
	v_cvt_pk_bf16_f32 v108, v112, v113
	v_cvt_pk_bf16_f32 v109, v114, v115
	v_cvt_pk_bf16_f32 v110, v128, v129
	v_cvt_pk_bf16_f32 v111, v130, v131
	v_pk_mul_f32 v[182:183], v[130:131], v[138:139]
	v_pk_mul_f32 v[184:185], v[128:129], v[136:137]
	global_store_dwordx4 v[160:161], v[108:111], off nt
	v_pk_mul_f32 v[186:187], v[102:103], v[134:135]
	v_pk_mul_f32 v[188:189], v[100:101], v[132:133]
	s_waitcnt lgkmcnt(0)
	v_pk_mul_f32 v[110:111], v[176:177], v[116:117] op_sel_hi:[1,0]
	v_pk_mul_f32 v[108:109], v[180:181], v[116:117] op_sel_hi:[1,0]
	v_pk_mul_f32 v[112:113], v[182:183], v[116:117] op_sel_hi:[1,0]
	v_pk_mul_f32 v[114:115], v[184:185], v[116:117] op_sel_hi:[1,0]
	v_cvt_pk_bf16_f32 v108, v108, v109
	v_cvt_pk_bf16_f32 v109, v110, v111
	s_nop 0
	v_cvt_pk_bf16_f32 v110, v114, v115
	v_cvt_pk_bf16_f32 v111, v112, v113
	global_store_dwordx4 v[162:163], v[108:111], off sc1
	v_cvt_pk_bf16_f32 v100, v100, v101
	v_cvt_pk_bf16_f32 v101, v102, v103
	v_cvt_pk_bf16_f32 v102, v104, v105
	v_cvt_pk_bf16_f32 v103, v106, v107
	global_store_dwordx4 v[160:161], v[100:103], off offset:256 nt
	v_pk_mul_f32 v[106:107], v[106:107], v[82:83]
	v_pk_mul_f32 v[104:105], v[104:105], v[80:81]
	v_pk_mul_f32 v[102:103], v[186:187], v[116:117] op_sel_hi:[1,0]
	v_pk_mul_f32 v[100:101], v[188:189], v[116:117] op_sel_hi:[1,0]
	v_pk_mul_f32 v[106:107], v[106:107], v[116:117] op_sel_hi:[1,0]
	v_pk_mul_f32 v[104:105], v[104:105], v[116:117] op_sel_hi:[1,0]
	v_cvt_pk_bf16_f32 v100, v100, v101
	v_cvt_pk_bf16_f32 v101, v102, v103
	s_nop 0
	v_cvt_pk_bf16_f32 v102, v104, v105
	v_cvt_pk_bf16_f32 v103, v106, v107
	global_store_dwordx4 v[162:163], v[100:103], off offset:256 sc1
	ds_read_b32 v104, v158 offset:8320
	s_nop 0
	v_lshlrev_b64 v[100:101], 10, v[156:157]
	v_lshl_add_u64 v[106:107], v[100:101], 0, v[178:179]
	v_cvt_pk_bf16_f32 v100, v92, v93
	v_cvt_pk_bf16_f32 v101, v94, v95
	v_cvt_pk_bf16_f32 v102, v96, v97
	v_lshlrev_b64 v[106:107], 1, v[106:107]
	v_pk_mul_f32 v[94:95], v[94:95], v[142:143]
	v_pk_mul_f32 v[92:93], v[92:93], v[140:141]
	v_pk_mul_f32 v[96:97], v[96:97], v[136:137]
	v_lshl_add_u64 v[108:109], s[0:1], 0, v[106:107]
	s_waitcnt lgkmcnt(0)
; __device__ __forceinline__ u32x4 pack_bf8(f32x4 a, f32x4 b) { u32x4 w; w.x = cvt_pk_bf16(a[0], a[1]); w.y = cvt_pk_bf16(a[2], a[3]); w.z = cvt_pk_bf16(b[0], b[1]); w.w = cvt_pk_bf16(b[2], b[3]); return w; }
;     __device__ __forceinline__ void fused(f32x4 (&acc)[2][2][4][2], const Unit& u, int wr, int wc, int fr, int fq, PG8_LAS unsigned char* lds, int wid, int lane) const {
;     ...
; #pragma unroll
;         for (int ai = 0; ai < 2; ++ai)
; #pragma unroll
;             for (int m = 0; m < 4; ++m) { const int r = ai * HALF + wr * 64 + m * 16 + fr; const float rs = S[r]; const size_t off = (size_t)(u.pm * BM + r) * ldc + col0;
; #pragma unroll
;                 for (int bj = 0; bj < 2; ++bj) { const f32x4 x0 = acc[ai][bj][m][0], x1 = acc[ai][bj][m][1];
;                     __builtin_nontemporal_store(pack_bf8(x0, x1), (u32x4*)(out + off + bj * HALF));
;                     *(u32x4*)(xn + off + bj * HALF) = pack_bf8(x0 * gv[bj][0] * rs, x1 * gv[bj][1] * rs); }
;                 asm volatile("" ::: "memory"); }
	v_pk_mul_f32 v[94:95], v[94:95], v[104:105] op_sel_hi:[1,0]
	v_pk_mul_f32 v[92:93], v[92:93], v[104:105] op_sel_hi:[1,0]
	v_pk_mul_f32 v[96:97], v[96:97], v[104:105] op_sel_hi:[1,0]
	v_cvt_pk_bf16_f32 v103, v98, v99
	global_store_dwordx4 v[108:109], v[100:103], off nt
	v_pk_mul_f32 v[98:99], v[98:99], v[138:139]
	v_cvt_pk_bf16_f32 v92, v92, v93
	v_cvt_pk_bf16_f32 v93, v94, v95
	v_cvt_pk_bf16_f32 v94, v96, v97
	v_lshl_add_u64 v[96:97], s[80:81], 0, v[106:107]
	v_pk_mul_f32 v[98:99], v[98:99], v[104:105] op_sel_hi:[1,0]
	s_nop 0
	v_cvt_pk_bf16_f32 v95, v98, v99
	global_store_dwordx4 v[96:97], v[92:95], off sc1
	s_nop 1
	v_cvt_pk_bf16_f32 v92, v84, v85
	v_cvt_pk_bf16_f32 v93, v86, v87
	v_pk_mul_f32 v[86:87], v[86:87], v[134:135]
	v_pk_mul_f32 v[84:85], v[84:85], v[132:133]
	v_cvt_pk_bf16_f32 v94, v88, v89
	v_cvt_pk_bf16_f32 v95, v90, v91
	v_pk_mul_f32 v[86:87], v[86:87], v[104:105] op_sel_hi:[1,0]
	v_pk_mul_f32 v[84:85], v[84:85], v[104:105] op_sel_hi:[1,0]
	v_pk_mul_f32 v[90:91], v[90:91], v[82:83]
	v_pk_mul_f32 v[88:89], v[88:89], v[80:81]
	global_store_dwordx4 v[108:109], v[92:95], off offset:256 nt
	v_pk_mul_f32 v[90:91], v[90:91], v[104:105] op_sel_hi:[1,0]
	v_pk_mul_f32 v[88:89], v[88:89], v[104:105] op_sel_hi:[1,0]
	v_cvt_pk_bf16_f32 v84, v84, v85
	v_cvt_pk_bf16_f32 v85, v86, v87
	s_nop 0
	v_cvt_pk_bf16_f32 v86, v88, v89
	v_cvt_pk_bf16_f32 v87, v90, v91
	global_store_dwordx4 v[96:97], v[84:87], off offset:256 sc1
	ds_read_b32 v88, v158 offset:8384
	s_nop 0
	v_lshlrev_b64 v[84:85], 10, v[152:153]
	v_lshl_add_u64 v[90:91], v[84:85], 0, v[178:179]
	v_lshlrev_b64 v[90:91], 1, v[90:91]
	v_cvt_pk_bf16_f32 v84, v76, v77
	v_cvt_pk_bf16_f32 v85, v78, v79
	v_cvt_pk_bf16_f32 v86, v72, v73
	v_cvt_pk_bf16_f32 v87, v74, v75
	v_lshl_add_u64 v[92:93], s[0:1], 0, v[90:91]
	v_pk_mul_f32 v[76:77], v[76:77], v[140:141]
	v_pk_mul_f32 v[74:75], v[74:75], v[138:139]
	v_pk_mul_f32 v[72:73], v[72:73], v[136:137]
	global_store_dwordx4 v[92:93], v[84:87], off nt
	v_pk_mul_f32 v[78:79], v[78:79], v[142:143]
	s_waitcnt lgkmcnt(0)
	v_pk_mul_f32 v[76:77], v[76:77], v[88:89] op_sel_hi:[1,0]
	v_pk_mul_f32 v[84:85], v[74:75], v[88:89] op_sel_hi:[1,0]
	v_pk_mul_f32 v[74:75], v[72:73], v[88:89] op_sel_hi:[1,0]
	v_pk_mul_f32 v[78:79], v[78:79], v[88:89] op_sel_hi:[1,0]
	v_cvt_pk_bf16_f32 v72, v76, v77
	v_lshl_add_u64 v[76:77], s[80:81], 0, v[90:91]
	v_cvt_pk_bf16_f32 v73, v78, v79
	v_cvt_pk_bf16_f32 v74, v74, v75
	v_cvt_pk_bf16_f32 v75, v84, v85
	global_store_dwordx4 v[76:77], v[72:75], off sc1
	s_nop 1
	v_cvt_pk_bf16_f32 v72, v68, v69
	v_cvt_pk_bf16_f32 v73, v70, v71
	v_cvt_pk_bf16_f32 v74, v64, v65
	v_cvt_pk_bf16_f32 v75, v66, v67
	v_pk_mul_f32 v[66:67], v[66:67], v[82:83]
	v_pk_mul_f32 v[64:65], v[64:65], v[80:81]
	global_store_dwordx4 v[92:93], v[72:75], off offset:256 nt
	v_pk_mul_f32 v[70:71], v[70:71], v[134:135]
	v_pk_mul_f32 v[68:69], v[68:69], v[132:133]
	v_pk_mul_f32 v[72:73], v[66:67], v[88:89] op_sel_hi:[1,0]
	v_pk_mul_f32 v[66:67], v[64:65], v[88:89] op_sel_hi:[1,0]
	v_pk_mul_f32 v[70:71], v[70:71], v[88:89] op_sel_hi:[1,0]
	v_pk_mul_f32 v[68:69], v[68:69], v[88:89] op_sel_hi:[1,0]
	s_nop 0
	v_cvt_pk_bf16_f32 v64, v68, v69
	v_cvt_pk_bf16_f32 v65, v70, v71
	v_cvt_pk_bf16_f32 v66, v66, v67
	v_cvt_pk_bf16_f32 v67, v72, v73
	global_store_dwordx4 v[76:77], v[64:67], off offset:256 sc1
	ds_read_b32 v68, v158 offset:8704
	v_lshl_add_u64 v[70:71], v[154:155], 0, v[178:179]
	v_lshlrev_b64 v[70:71], 1, v[70:71]
	v_cvt_pk_bf16_f32 v64, v60, v61
	v_cvt_pk_bf16_f32 v65, v62, v63
	v_cvt_pk_bf16_f32 v66, v56, v57
	v_cvt_pk_bf16_f32 v67, v58, v59
	v_lshl_add_u64 v[72:73], s[0:1], 0, v[70:71]
	v_pk_mul_f32 v[60:61], v[60:61], v[140:141]
	v_pk_mul_f32 v[58:59], v[58:59], v[138:139]
	v_pk_mul_f32 v[56:57], v[56:57], v[136:137]
	global_store_dwordx4 v[72:73], v[64:67], off nt
	v_pk_mul_f32 v[62:63], v[62:63], v[142:143]
	s_waitcnt lgkmcnt(0)
	v_pk_mul_f32 v[60:61], v[60:61], v[68:69] op_sel_hi:[1,0]
	v_pk_mul_f32 v[64:65], v[58:59], v[68:69] op_sel_hi:[1,0]
	v_pk_mul_f32 v[58:59], v[56:57], v[68:69] op_sel_hi:[1,0]
	v_pk_mul_f32 v[62:63], v[62:63], v[68:69] op_sel_hi:[1,0]
	v_cvt_pk_bf16_f32 v56, v60, v61
	v_lshl_add_u64 v[60:61], s[80:81], 0, v[70:71]
	v_cvt_pk_bf16_f32 v57, v62, v63
	v_cvt_pk_bf16_f32 v58, v58, v59
	v_cvt_pk_bf16_f32 v59, v64, v65
	global_store_dwordx4 v[60:61], v[56:59], off sc1
	s_nop 1
	v_cvt_pk_bf16_f32 v56, v52, v53
	v_cvt_pk_bf16_f32 v57, v54, v55
	v_cvt_pk_bf16_f32 v58, v48, v49
	v_cvt_pk_bf16_f32 v59, v50, v51
	v_pk_mul_f32 v[50:51], v[50:51], v[82:83]
	v_pk_mul_f32 v[48:49], v[48:49], v[80:81]
	global_store_dwordx4 v[72:73], v[56:59], off offset:256 nt
	v_pk_mul_f32 v[54:55], v[54:55], v[134:135]
	v_pk_mul_f32 v[52:53], v[52:53], v[132:133]
	v_pk_mul_f32 v[56:57], v[50:51], v[68:69] op_sel_hi:[1,0]
	v_pk_mul_f32 v[50:51], v[48:49], v[68:69] op_sel_hi:[1,0]
	v_pk_mul_f32 v[54:55], v[54:55], v[68:69] op_sel_hi:[1,0]
	v_pk_mul_f32 v[52:53], v[52:53], v[68:69] op_sel_hi:[1,0]
	s_nop 0
	v_cvt_pk_bf16_f32 v48, v52, v53
	v_cvt_pk_bf16_f32 v49, v54, v55
	v_cvt_pk_bf16_f32 v50, v50, v51
	v_cvt_pk_bf16_f32 v51, v56, v57
	global_store_dwordx4 v[60:61], v[48:51], off offset:256 sc1
	ds_read_b32 v52, v158 offset:8768
	v_lshl_add_u64 v[54:55], v[148:149], 0, v[178:179]
	v_lshlrev_b64 v[54:55], 1, v[54:55]
	v_cvt_pk_bf16_f32 v48, v44, v45
	v_cvt_pk_bf16_f32 v49, v46, v47
	v_cvt_pk_bf16_f32 v50, v40, v41
	v_cvt_pk_bf16_f32 v51, v42, v43
	v_lshl_add_u64 v[56:57], s[0:1], 0, v[54:55]
	v_pk_mul_f32 v[44:45], v[44:45], v[140:141]
	v_pk_mul_f32 v[42:43], v[42:43], v[138:139]
	v_pk_mul_f32 v[40:41], v[40:41], v[136:137]
	global_store_dwordx4 v[56:57], v[48:51], off nt
	v_pk_mul_f32 v[46:47], v[46:47], v[142:143]
	s_waitcnt lgkmcnt(0)
; __device__ __forceinline__ u32x4 pack_bf8(f32x4 a, f32x4 b) { u32x4 w; w.x = cvt_pk_bf16(a[0], a[1]); w.y = cvt_pk_bf16(a[2], a[3]); w.z = cvt_pk_bf16(b[0], b[1]); w.w = cvt_pk_bf16(b[2], b[3]); return w; }
;     __device__ __forceinline__ void fused(f32x4 (&acc)[2][2][4][2], const Unit& u, int wr, int wc, int fr, int fq, PG8_LAS unsigned char* lds, int wid, int lane) const {
;     ...
; #pragma unroll
;         for (int ai = 0; ai < 2; ++ai)
; #pragma unroll
;             for (int m = 0; m < 4; ++m) { const int r = ai * HALF + wr * 64 + m * 16 + fr; const float rs = S[r]; const size_t off = (size_t)(u.pm * BM + r) * ldc + col0;
; #pragma unroll
;                 for (int bj = 0; bj < 2; ++bj) { const f32x4 x0 = acc[ai][bj][m][0], x1 = acc[ai][bj][m][1];
;                     __builtin_nontemporal_store(pack_bf8(x0, x1), (u32x4*)(out + off + bj * HALF));
;                     *(u32x4*)(xn + off + bj * HALF) = pack_bf8(x0 * gv[bj][0] * rs, x1 * gv[bj][1] * rs); }
;                 asm volatile("" ::: "memory"); }
	v_pk_mul_f32 v[44:45], v[44:45], v[52:53] op_sel_hi:[1,0]
	v_pk_mul_f32 v[48:49], v[42:43], v[52:53] op_sel_hi:[1,0]
	v_pk_mul_f32 v[42:43], v[40:41], v[52:53] op_sel_hi:[1,0]
	v_pk_mul_f32 v[46:47], v[46:47], v[52:53] op_sel_hi:[1,0]
	v_cvt_pk_bf16_f32 v40, v44, v45
	v_lshl_add_u64 v[44:45], s[80:81], 0, v[54:55]
	v_cvt_pk_bf16_f32 v41, v46, v47
	v_cvt_pk_bf16_f32 v42, v42, v43
	v_cvt_pk_bf16_f32 v43, v48, v49
	global_store_dwordx4 v[44:45], v[40:43], off sc1
	s_nop 1
	v_cvt_pk_bf16_f32 v40, v36, v37
	v_cvt_pk_bf16_f32 v41, v38, v39
	v_cvt_pk_bf16_f32 v42, v32, v33
	v_cvt_pk_bf16_f32 v43, v34, v35
	v_pk_mul_f32 v[34:35], v[34:35], v[82:83]
	v_pk_mul_f32 v[32:33], v[32:33], v[80:81]
	global_store_dwordx4 v[56:57], v[40:43], off offset:256 nt
	v_pk_mul_f32 v[38:39], v[38:39], v[134:135]
	v_pk_mul_f32 v[36:37], v[36:37], v[132:133]
	v_pk_mul_f32 v[40:41], v[34:35], v[52:53] op_sel_hi:[1,0]
	v_pk_mul_f32 v[34:35], v[32:33], v[52:53] op_sel_hi:[1,0]
	v_pk_mul_f32 v[38:39], v[38:39], v[52:53] op_sel_hi:[1,0]
	v_pk_mul_f32 v[36:37], v[36:37], v[52:53] op_sel_hi:[1,0]
	s_nop 0
	v_cvt_pk_bf16_f32 v32, v36, v37
	v_cvt_pk_bf16_f32 v33, v38, v39
	v_cvt_pk_bf16_f32 v34, v34, v35
	v_cvt_pk_bf16_f32 v35, v40, v41
	global_store_dwordx4 v[44:45], v[32:35], off offset:256 sc1
	ds_read_b32 v36, v158 offset:8832
	v_lshl_add_u64 v[38:39], v[146:147], 0, v[178:179]
	v_lshlrev_b64 v[38:39], 1, v[38:39]
	v_cvt_pk_bf16_f32 v32, v28, v29
	v_cvt_pk_bf16_f32 v33, v30, v31
	v_cvt_pk_bf16_f32 v34, v24, v25
	v_cvt_pk_bf16_f32 v35, v26, v27
	v_lshl_add_u64 v[40:41], s[0:1], 0, v[38:39]
	v_pk_mul_f32 v[28:29], v[28:29], v[140:141]
	v_pk_mul_f32 v[26:27], v[26:27], v[138:139]
	v_pk_mul_f32 v[24:25], v[24:25], v[136:137]
	global_store_dwordx4 v[40:41], v[32:35], off nt
	v_pk_mul_f32 v[30:31], v[30:31], v[142:143]
	s_waitcnt lgkmcnt(0)
	v_pk_mul_f32 v[28:29], v[28:29], v[36:37] op_sel_hi:[1,0]
	v_pk_mul_f32 v[32:33], v[26:27], v[36:37] op_sel_hi:[1,0]
	v_pk_mul_f32 v[26:27], v[24:25], v[36:37] op_sel_hi:[1,0]
	v_pk_mul_f32 v[30:31], v[30:31], v[36:37] op_sel_hi:[1,0]
	v_cvt_pk_bf16_f32 v24, v28, v29
	v_lshl_add_u64 v[28:29], s[80:81], 0, v[38:39]
	v_cvt_pk_bf16_f32 v25, v30, v31
	v_cvt_pk_bf16_f32 v26, v26, v27
	v_cvt_pk_bf16_f32 v27, v32, v33
	global_store_dwordx4 v[28:29], v[24:27], off sc1
	s_nop 1
	v_cvt_pk_bf16_f32 v24, v20, v21
	v_cvt_pk_bf16_f32 v25, v22, v23
	v_cvt_pk_bf16_f32 v26, v16, v17
	v_cvt_pk_bf16_f32 v27, v18, v19
	v_pk_mul_f32 v[18:19], v[18:19], v[82:83]
	v_pk_mul_f32 v[16:17], v[16:17], v[80:81]
	global_store_dwordx4 v[40:41], v[24:27], off offset:256 nt
	v_pk_mul_f32 v[22:23], v[22:23], v[134:135]
	v_pk_mul_f32 v[20:21], v[20:21], v[132:133]
	v_pk_mul_f32 v[24:25], v[18:19], v[36:37] op_sel_hi:[1,0]
	v_pk_mul_f32 v[18:19], v[16:17], v[36:37] op_sel_hi:[1,0]
	v_pk_mul_f32 v[22:23], v[22:23], v[36:37] op_sel_hi:[1,0]
	v_pk_mul_f32 v[20:21], v[20:21], v[36:37] op_sel_hi:[1,0]
	s_nop 0
	v_cvt_pk_bf16_f32 v16, v20, v21
	v_cvt_pk_bf16_f32 v17, v22, v23
	v_cvt_pk_bf16_f32 v18, v18, v19
	v_cvt_pk_bf16_f32 v19, v24, v25
	global_store_dwordx4 v[28:29], v[16:19], off offset:256 sc1
	ds_read_b32 v20, v158 offset:8896
	v_lshl_add_u64 v[22:23], v[144:145], 0, v[178:179]
	v_lshlrev_b64 v[22:23], 1, v[22:23]
	v_cvt_pk_bf16_f32 v16, v12, v13
	v_cvt_pk_bf16_f32 v17, v14, v15
	v_cvt_pk_bf16_f32 v18, v8, v9
	v_cvt_pk_bf16_f32 v19, v10, v11
	v_lshl_add_u64 v[24:25], s[0:1], 0, v[22:23]
	v_pk_mul_f32 v[12:13], v[12:13], v[140:141]
	v_pk_mul_f32 v[10:11], v[10:11], v[138:139]
	v_pk_mul_f32 v[8:9], v[8:9], v[136:137]
	global_store_dwordx4 v[24:25], v[16:19], off nt
	v_pk_mul_f32 v[14:15], v[14:15], v[142:143]
	s_waitcnt lgkmcnt(0)
	v_pk_mul_f32 v[12:13], v[12:13], v[20:21] op_sel_hi:[1,0]
	v_pk_mul_f32 v[16:17], v[10:11], v[20:21] op_sel_hi:[1,0]
	v_pk_mul_f32 v[10:11], v[8:9], v[20:21] op_sel_hi:[1,0]
	v_pk_mul_f32 v[14:15], v[14:15], v[20:21] op_sel_hi:[1,0]
	v_cvt_pk_bf16_f32 v8, v12, v13
	v_lshl_add_u64 v[12:13], s[80:81], 0, v[22:23]
	v_cvt_pk_bf16_f32 v9, v14, v15
	v_cvt_pk_bf16_f32 v10, v10, v11
	v_cvt_pk_bf16_f32 v11, v16, v17
	global_store_dwordx4 v[12:13], v[8:11], off sc1
	s_nop 1
	v_cvt_pk_bf16_f32 v8, v4, v5
	v_cvt_pk_bf16_f32 v9, v6, v7
	v_cvt_pk_bf16_f32 v10, v0, v1
	v_cvt_pk_bf16_f32 v11, v2, v3
	v_pk_mul_f32 v[2:3], v[2:3], v[82:83]
	v_pk_mul_f32 v[0:1], v[0:1], v[80:81]
	global_store_dwordx4 v[24:25], v[8:11], off offset:256 nt
	v_pk_mul_f32 v[6:7], v[6:7], v[134:135]
	v_pk_mul_f32 v[4:5], v[4:5], v[132:133]
	v_pk_mul_f32 v[8:9], v[2:3], v[20:21] op_sel_hi:[1,0]
	v_pk_mul_f32 v[2:3], v[0:1], v[20:21] op_sel_hi:[1,0]
	v_pk_mul_f32 v[6:7], v[6:7], v[20:21] op_sel_hi:[1,0]
	v_pk_mul_f32 v[4:5], v[4:5], v[20:21] op_sel_hi:[1,0]
	s_nop 0
	v_cvt_pk_bf16_f32 v0, v4, v5
	v_cvt_pk_bf16_f32 v1, v6, v7
	v_cvt_pk_bf16_f32 v2, v2, v3
	v_cvt_pk_bf16_f32 v3, v8, v9
	global_store_dwordx4 v[12:13], v[0:3], off offset:256 sc1

; __device__ __forceinline__ unsigned cvt_pk_bf16(float lo, float hi) { unsigned r; asm volatile("v_cvt_pk_bf16_f32 %0, %1, %2" : "=v"(r) : "v"(lo), "v"(hi)); return r; }
; __device__ __forceinline__ f32x2p silu_mul2(f32x2p g, f32x2p u) {
;     const f32x2p t = g * (-1.4426950408889634f); f32x2p e; e.x = __builtin_amdgcn_exp2f(t.x); e.y = __builtin_amdgcn_exp2f(t.y);
;     const f32x2p d = e + 1.0f; f32x2p r; r.x = __builtin_amdgcn_rcpf(d.x); r.y = __builtin_amdgcn_rcpf(d.y);
;     return (g * u) * r;
; }
;     __device__ __forceinline__ void operator()(const f32x4 (&acc)[2][2][4][2], const Unit& u, int wr, int wc, int fr, int fq) const {
;     ...
;             for (int m = 0; m < 4; ++m) { bf16_t* rowp = O + (size_t)(row0 + ai * HALF + m * 16) * ldc + col0;
;                 const f32x4 g0 = acc[ai][0][m][0], g1 = acc[ai][0][m][1], u0 = acc[ai][1][m][0], u1 = acc[ai][1][m][1];
;                 const f32x2p a = silu_mul2((f32x2p){g0[0], g0[1]}, (f32x2p){u0[0], u0[1]}), b = silu_mul2((f32x2p){g0[2], g0[3]}, (f32x2p){u0[2], u0[3]});
;                 const f32x2p c = silu_mul2((f32x2p){g1[0], g1[1]}, (f32x2p){u1[0], u1[1]}), d = silu_mul2((f32x2p){g1[2], g1[3]}, (f32x2p){u1[2], u1[3]});
;                 u32x4 w; w.x = cvt_pk_bf16(a.x, a.y); w.y = cvt_pk_bf16(b.x, b.y); w.z = cvt_pk_bf16(c.x, c.y); w.w = cvt_pk_bf16(d.x, d.y);
;                 *(u32x4*)rowp = w; }
.LBB0_1915:
	v_pk_mul_f32 v[158:159], v[124:125], s[8:9] op_sel_hi:[1,0]
	v_pk_mul_f32 v[160:161], v[126:127], s[8:9] op_sel_hi:[1,0]
	v_pk_mul_f32 v[122:123], v[126:127], v[122:123]
	v_pk_mul_f32 v[120:121], v[124:125], v[120:121]
	v_pk_mul_f32 v[124:125], v[116:117], s[8:9] op_sel_hi:[1,0]
	v_pk_mul_f32 v[126:127], v[118:119], s[8:9] op_sel_hi:[1,0]
	v_exp_f32_e32 v158, v158
	v_exp_f32_e32 v159, v159
	v_exp_f32_e32 v160, v160
	v_exp_f32_e32 v161, v161
	v_exp_f32_e32 v124, v124
	v_exp_f32_e32 v125, v125
	v_exp_f32_e32 v126, v126
	v_exp_f32_e32 v127, v127
	v_pk_add_f32 v[158:159], v[158:159], 1.0 op_sel_hi:[1,0]
	v_pk_add_f32 v[160:161], v[160:161], 1.0 op_sel_hi:[1,0]
	v_pk_add_f32 v[124:125], v[124:125], 1.0 op_sel_hi:[1,0]
	v_pk_add_f32 v[126:127], v[126:127], 1.0 op_sel_hi:[1,0]
	v_readlane_b32 s22, v254, 15
	v_rcp_f32_e32 v158, v158
	v_rcp_f32_e32 v159, v159
	v_rcp_f32_e32 v160, v160
	v_rcp_f32_e32 v161, v161
	v_rcp_f32_e32 v124, v124
	v_rcp_f32_e32 v125, v125
	v_rcp_f32_e32 v126, v126
	v_rcp_f32_e32 v127, v127
	v_lshl_add_u32 v146, s41, 7, v150
	v_readlane_b32 s23, v254, 16
	v_lshl_add_u32 v154, s20, 8, v148
	v_ashrrev_i32_e32 v147, 31, v146
	v_mov_b64_e32 v[144:145], s[22:23]
	v_mad_i64_i32 v[156:157], s[22:23], v154, s40, v[144:145]
	v_lshlrev_b64 v[146:147], 1, v[146:147]
	v_pk_mul_f32 v[114:115], v[118:119], v[114:115]
	v_pk_mul_f32 v[112:113], v[116:117], v[112:113]
	v_lshl_add_u64 v[156:157], v[156:157], 0, v[146:147]
	v_pk_mul_f32 v[120:121], v[158:159], v[120:121]
	v_pk_mul_f32 v[122:123], v[160:161], v[122:123]
	v_pk_mul_f32 v[116:117], v[124:125], v[112:113]
	v_pk_mul_f32 v[118:119], v[126:127], v[114:115]
	v_cvt_pk_bf16_f32 v112, v120, v121
	v_cvt_pk_bf16_f32 v113, v122, v123
	v_cvt_pk_bf16_f32 v114, v116, v117
	v_pk_mul_f32 v[116:117], v[110:111], s[8:9] op_sel_hi:[1,0]
	v_cvt_pk_bf16_f32 v115, v118, v119
	global_store_dwordx4 v[156:157], v[112:115], off sc1
	v_pk_mul_f32 v[106:107], v[110:111], v[106:107]
	v_pk_mul_f32 v[104:105], v[108:109], v[104:105]
	v_pk_mul_f32 v[114:115], v[108:109], s[8:9] op_sel_hi:[1,0]
	v_pk_mul_f32 v[108:109], v[100:101], s[8:9] op_sel_hi:[1,0]
	v_pk_mul_f32 v[110:111], v[102:103], s[8:9] op_sel_hi:[1,0]
	v_exp_f32_e32 v114, v114
	v_exp_f32_e32 v115, v115
	v_exp_f32_e32 v116, v116
	v_exp_f32_e32 v117, v117
	v_exp_f32_e32 v108, v108
	v_exp_f32_e32 v109, v109
	v_exp_f32_e32 v110, v110
	v_exp_f32_e32 v111, v111
	v_pk_add_f32 v[114:115], v[114:115], 1.0 op_sel_hi:[1,0]
	v_pk_add_f32 v[116:117], v[116:117], 1.0 op_sel_hi:[1,0]
	v_pk_add_f32 v[108:109], v[108:109], 1.0 op_sel_hi:[1,0]
	v_pk_add_f32 v[110:111], v[110:111], 1.0 op_sel_hi:[1,0]
	v_rcp_f32_e32 v114, v114
	v_rcp_f32_e32 v115, v115
	v_rcp_f32_e32 v116, v116
	v_rcp_f32_e32 v117, v117
	v_rcp_f32_e32 v108, v108
	v_rcp_f32_e32 v109, v109
	v_rcp_f32_e32 v110, v110
	v_rcp_f32_e32 v111, v111
	v_or_b32_e32 v112, 16, v154
	v_mad_i64_i32 v[112:113], s[22:23], v112, s40, v[144:145]
	v_pk_mul_f32 v[98:99], v[102:103], v[98:99]
	v_pk_mul_f32 v[96:97], v[100:101], v[96:97]
	v_lshl_add_u64 v[112:113], v[112:113], 0, v[146:147]
	v_pk_mul_f32 v[104:105], v[114:115], v[104:105]
	v_pk_mul_f32 v[106:107], v[116:117], v[106:107]
	v_pk_mul_f32 v[100:101], v[108:109], v[96:97]
	v_pk_mul_f32 v[102:103], v[110:111], v[98:99]
	v_cvt_pk_bf16_f32 v96, v104, v105
	v_cvt_pk_bf16_f32 v97, v106, v107
	v_cvt_pk_bf16_f32 v98, v100, v101
	v_pk_mul_f32 v[100:101], v[94:95], s[8:9] op_sel_hi:[1,0]
	v_cvt_pk_bf16_f32 v99, v102, v103
	global_store_dwordx4 v[112:113], v[96:99], off sc1
	v_pk_mul_f32 v[90:91], v[94:95], v[90:91]
	v_pk_mul_f32 v[88:89], v[92:93], v[88:89]
	v_pk_mul_f32 v[98:99], v[92:93], s[8:9] op_sel_hi:[1,0]
	v_pk_mul_f32 v[92:93], v[84:85], s[8:9] op_sel_hi:[1,0]
	v_pk_mul_f32 v[94:95], v[86:87], s[8:9] op_sel_hi:[1,0]
	v_exp_f32_e32 v98, v98
	v_exp_f32_e32 v99, v99
	v_exp_f32_e32 v100, v100
	v_exp_f32_e32 v101, v101
	v_exp_f32_e32 v92, v92
	v_exp_f32_e32 v93, v93
	v_exp_f32_e32 v94, v94
	v_exp_f32_e32 v95, v95
	v_pk_add_f32 v[98:99], v[98:99], 1.0 op_sel_hi:[1,0]
	v_pk_add_f32 v[100:101], v[100:101], 1.0 op_sel_hi:[1,0]
	v_pk_add_f32 v[92:93], v[92:93], 1.0 op_sel_hi:[1,0]
	v_pk_add_f32 v[94:95], v[94:95], 1.0 op_sel_hi:[1,0]
	v_rcp_f32_e32 v98, v98
	v_rcp_f32_e32 v99, v99
	v_rcp_f32_e32 v100, v100
	v_rcp_f32_e32 v101, v101
	v_rcp_f32_e32 v92, v92
	v_rcp_f32_e32 v93, v93
	v_rcp_f32_e32 v94, v94
	v_rcp_f32_e32 v95, v95
	v_or_b32_e32 v96, 32, v154
	v_mad_i64_i32 v[96:97], s[22:23], v96, s40, v[144:145]
	v_pk_mul_f32 v[82:83], v[86:87], v[82:83]
	v_pk_mul_f32 v[80:81], v[84:85], v[80:81]
	v_lshl_add_u64 v[96:97], v[96:97], 0, v[146:147]
	v_pk_mul_f32 v[88:89], v[98:99], v[88:89]
	v_pk_mul_f32 v[90:91], v[100:101], v[90:91]
	v_pk_mul_f32 v[84:85], v[92:93], v[80:81]
	v_pk_mul_f32 v[86:87], v[94:95], v[82:83]
	v_cvt_pk_bf16_f32 v80, v88, v89
	v_cvt_pk_bf16_f32 v81, v90, v91
	v_cvt_pk_bf16_f32 v82, v84, v85
	v_pk_mul_f32 v[84:85], v[78:79], s[8:9] op_sel_hi:[1,0]
	v_cvt_pk_bf16_f32 v83, v86, v87
	global_store_dwordx4 v[96:97], v[80:83], off sc1
	v_pk_mul_f32 v[74:75], v[78:79], v[74:75]
	v_pk_mul_f32 v[72:73], v[76:77], v[72:73]
	v_pk_mul_f32 v[82:83], v[76:77], s[8:9] op_sel_hi:[1,0]
	v_pk_mul_f32 v[76:77], v[68:69], s[8:9] op_sel_hi:[1,0]
	v_pk_mul_f32 v[78:79], v[70:71], s[8:9] op_sel_hi:[1,0]
	v_exp_f32_e32 v82, v82
	v_exp_f32_e32 v83, v83
	v_exp_f32_e32 v84, v84
	v_exp_f32_e32 v85, v85
	v_exp_f32_e32 v76, v76
	v_exp_f32_e32 v77, v77
	v_exp_f32_e32 v78, v78
	v_exp_f32_e32 v79, v79
	v_pk_add_f32 v[82:83], v[82:83], 1.0 op_sel_hi:[1,0]
	v_pk_add_f32 v[84:85], v[84:85], 1.0 op_sel_hi:[1,0]
	v_pk_add_f32 v[76:77], v[76:77], 1.0 op_sel_hi:[1,0]
; __device__ __forceinline__ unsigned cvt_pk_bf16(float lo, float hi) { unsigned r; asm volatile("v_cvt_pk_bf16_f32 %0, %1, %2" : "=v"(r) : "v"(lo), "v"(hi)); return r; }
; __device__ __forceinline__ f32x2p silu_mul2(f32x2p g, f32x2p u) {
;     const f32x2p t = g * (-1.4426950408889634f); f32x2p e; e.x = __builtin_amdgcn_exp2f(t.x); e.y = __builtin_amdgcn_exp2f(t.y);
;     const f32x2p d = e + 1.0f; f32x2p r; r.x = __builtin_amdgcn_rcpf(d.x); r.y = __builtin_amdgcn_rcpf(d.y);
;     return (g * u) * r;
; }
;     __device__ __forceinline__ void operator()(const f32x4 (&acc)[2][2][4][2], const Unit& u, int wr, int wc, int fr, int fq) const {
;     ...
;             for (int m = 0; m < 4; ++m) { bf16_t* rowp = O + (size_t)(row0 + ai * HALF + m * 16) * ldc + col0;
;                 const f32x4 g0 = acc[ai][0][m][0], g1 = acc[ai][0][m][1], u0 = acc[ai][1][m][0], u1 = acc[ai][1][m][1];
;                 const f32x2p a = silu_mul2((f32x2p){g0[0], g0[1]}, (f32x2p){u0[0], u0[1]}), b = silu_mul2((f32x2p){g0[2], g0[3]}, (f32x2p){u0[2], u0[3]});
;                 const f32x2p c = silu_mul2((f32x2p){g1[0], g1[1]}, (f32x2p){u1[0], u1[1]}), d = silu_mul2((f32x2p){g1[2], g1[3]}, (f32x2p){u1[2], u1[3]});
;                 u32x4 w; w.x = cvt_pk_bf16(a.x, a.y); w.y = cvt_pk_bf16(b.x, b.y); w.z = cvt_pk_bf16(c.x, c.y); w.w = cvt_pk_bf16(d.x, d.y);
;                 *(u32x4*)rowp = w; }
	v_pk_add_f32 v[78:79], v[78:79], 1.0 op_sel_hi:[1,0]
	v_rcp_f32_e32 v82, v82
	v_rcp_f32_e32 v83, v83
	v_rcp_f32_e32 v84, v84
	v_rcp_f32_e32 v85, v85
	v_rcp_f32_e32 v76, v76
	v_rcp_f32_e32 v77, v77
	v_rcp_f32_e32 v78, v78
	v_rcp_f32_e32 v79, v79
	v_or_b32_e32 v80, 48, v154
	v_mad_i64_i32 v[80:81], s[22:23], v80, s40, v[144:145]
	v_pk_mul_f32 v[66:67], v[70:71], v[66:67]
	v_pk_mul_f32 v[64:65], v[68:69], v[64:65]
	v_lshl_add_u64 v[80:81], v[80:81], 0, v[146:147]
	v_pk_mul_f32 v[72:73], v[82:83], v[72:73]
	v_pk_mul_f32 v[74:75], v[84:85], v[74:75]
	v_pk_mul_f32 v[68:69], v[76:77], v[64:65]
	v_pk_mul_f32 v[70:71], v[78:79], v[66:67]
	v_cvt_pk_bf16_f32 v64, v72, v73
	v_cvt_pk_bf16_f32 v65, v74, v75
	v_cvt_pk_bf16_f32 v66, v68, v69
	v_pk_mul_f32 v[68:69], v[62:63], s[8:9] op_sel_hi:[1,0]
	v_cvt_pk_bf16_f32 v67, v70, v71
	global_store_dwordx4 v[80:81], v[64:67], off sc1
	v_pk_mul_f32 v[58:59], v[62:63], v[58:59]
	v_pk_mul_f32 v[56:57], v[60:61], v[56:57]
	v_pk_mul_f32 v[66:67], v[60:61], s[8:9] op_sel_hi:[1,0]
	v_pk_mul_f32 v[60:61], v[52:53], s[8:9] op_sel_hi:[1,0]
	v_pk_mul_f32 v[62:63], v[54:55], s[8:9] op_sel_hi:[1,0]
	v_exp_f32_e32 v66, v66
	v_exp_f32_e32 v67, v67
	v_exp_f32_e32 v68, v68
	v_exp_f32_e32 v69, v69
	v_exp_f32_e32 v60, v60
	v_exp_f32_e32 v61, v61
	v_exp_f32_e32 v62, v62
	v_exp_f32_e32 v63, v63
	v_pk_add_f32 v[66:67], v[66:67], 1.0 op_sel_hi:[1,0]
	v_pk_add_f32 v[68:69], v[68:69], 1.0 op_sel_hi:[1,0]
	v_pk_add_f32 v[60:61], v[60:61], 1.0 op_sel_hi:[1,0]
	v_pk_add_f32 v[62:63], v[62:63], 1.0 op_sel_hi:[1,0]
	v_rcp_f32_e32 v66, v66
	v_rcp_f32_e32 v67, v67
	v_rcp_f32_e32 v68, v68
	v_rcp_f32_e32 v69, v69
	v_rcp_f32_e32 v60, v60
	v_rcp_f32_e32 v61, v61
	v_rcp_f32_e32 v62, v62
	v_rcp_f32_e32 v63, v63
	v_add_u32_e32 v64, 0x80, v154
	v_mad_i64_i32 v[64:65], s[22:23], v64, s40, v[144:145]
	v_pk_mul_f32 v[50:51], v[54:55], v[50:51]
	v_pk_mul_f32 v[48:49], v[52:53], v[48:49]
	v_lshl_add_u64 v[64:65], v[64:65], 0, v[146:147]
	v_pk_mul_f32 v[56:57], v[66:67], v[56:57]
	v_pk_mul_f32 v[58:59], v[68:69], v[58:59]
	v_pk_mul_f32 v[52:53], v[60:61], v[48:49]
	v_pk_mul_f32 v[54:55], v[62:63], v[50:51]
	v_cvt_pk_bf16_f32 v48, v56, v57
	v_cvt_pk_bf16_f32 v49, v58, v59
	v_cvt_pk_bf16_f32 v50, v52, v53
	v_pk_mul_f32 v[52:53], v[46:47], s[8:9] op_sel_hi:[1,0]
	v_cvt_pk_bf16_f32 v51, v54, v55
	global_store_dwordx4 v[64:65], v[48:51], off sc1
	v_pk_mul_f32 v[42:43], v[46:47], v[42:43]
	v_pk_mul_f32 v[40:41], v[44:45], v[40:41]
	v_pk_mul_f32 v[50:51], v[44:45], s[8:9] op_sel_hi:[1,0]
	v_pk_mul_f32 v[44:45], v[36:37], s[8:9] op_sel_hi:[1,0]
	v_pk_mul_f32 v[46:47], v[38:39], s[8:9] op_sel_hi:[1,0]
	v_exp_f32_e32 v50, v50
	v_exp_f32_e32 v51, v51
	v_exp_f32_e32 v52, v52
	v_exp_f32_e32 v53, v53
	v_exp_f32_e32 v44, v44
	v_exp_f32_e32 v45, v45
	v_exp_f32_e32 v46, v46
	v_exp_f32_e32 v47, v47
	v_pk_add_f32 v[50:51], v[50:51], 1.0 op_sel_hi:[1,0]
	v_pk_add_f32 v[52:53], v[52:53], 1.0 op_sel_hi:[1,0]
	v_pk_add_f32 v[44:45], v[44:45], 1.0 op_sel_hi:[1,0]
	v_pk_add_f32 v[46:47], v[46:47], 1.0 op_sel_hi:[1,0]
	v_rcp_f32_e32 v50, v50
	v_rcp_f32_e32 v51, v51
	v_rcp_f32_e32 v52, v52
	v_rcp_f32_e32 v53, v53
	v_rcp_f32_e32 v44, v44
	v_rcp_f32_e32 v45, v45
	v_rcp_f32_e32 v46, v46
	v_rcp_f32_e32 v47, v47
	v_add_u32_e32 v48, 0x90, v154
	v_mad_i64_i32 v[48:49], s[22:23], v48, s40, v[144:145]
	v_pk_mul_f32 v[34:35], v[38:39], v[34:35]
	v_pk_mul_f32 v[32:33], v[36:37], v[32:33]
	v_lshl_add_u64 v[48:49], v[48:49], 0, v[146:147]
	v_pk_mul_f32 v[40:41], v[50:51], v[40:41]
	v_pk_mul_f32 v[42:43], v[52:53], v[42:43]
	v_pk_mul_f32 v[36:37], v[44:45], v[32:33]
	v_pk_mul_f32 v[38:39], v[46:47], v[34:35]
	v_cvt_pk_bf16_f32 v32, v40, v41
	v_cvt_pk_bf16_f32 v33, v42, v43
	v_cvt_pk_bf16_f32 v34, v36, v37
	v_pk_mul_f32 v[36:37], v[30:31], s[8:9] op_sel_hi:[1,0]
	v_cvt_pk_bf16_f32 v35, v38, v39
	global_store_dwordx4 v[48:49], v[32:35], off sc1
	v_pk_mul_f32 v[26:27], v[30:31], v[26:27]
	v_pk_mul_f32 v[24:25], v[28:29], v[24:25]
	v_pk_mul_f32 v[34:35], v[28:29], s[8:9] op_sel_hi:[1,0]
	v_pk_mul_f32 v[28:29], v[20:21], s[8:9] op_sel_hi:[1,0]
	v_pk_mul_f32 v[30:31], v[22:23], s[8:9] op_sel_hi:[1,0]
	v_exp_f32_e32 v34, v34
	v_exp_f32_e32 v35, v35
	v_exp_f32_e32 v36, v36
	v_exp_f32_e32 v37, v37
	v_exp_f32_e32 v28, v28
	v_exp_f32_e32 v29, v29
	v_exp_f32_e32 v30, v30
	v_exp_f32_e32 v31, v31
	v_pk_add_f32 v[34:35], v[34:35], 1.0 op_sel_hi:[1,0]
	v_pk_add_f32 v[36:37], v[36:37], 1.0 op_sel_hi:[1,0]
	v_pk_add_f32 v[28:29], v[28:29], 1.0 op_sel_hi:[1,0]
	v_pk_add_f32 v[30:31], v[30:31], 1.0 op_sel_hi:[1,0]
	v_rcp_f32_e32 v34, v34
	v_rcp_f32_e32 v35, v35
	v_rcp_f32_e32 v36, v36
	v_rcp_f32_e32 v37, v37
	v_rcp_f32_e32 v28, v28
	v_rcp_f32_e32 v29, v29
	v_rcp_f32_e32 v30, v30
	v_rcp_f32_e32 v31, v31
	v_add_u32_e32 v32, 0xa0, v154
	v_mad_i64_i32 v[32:33], s[22:23], v32, s40, v[144:145]
	v_pk_mul_f32 v[18:19], v[22:23], v[18:19]
	v_pk_mul_f32 v[16:17], v[20:21], v[16:17]
	v_lshl_add_u64 v[32:33], v[32:33], 0, v[146:147]
	v_pk_mul_f32 v[24:25], v[34:35], v[24:25]
	v_pk_mul_f32 v[26:27], v[36:37], v[26:27]
	v_pk_mul_f32 v[20:21], v[28:29], v[16:17]
	v_pk_mul_f32 v[22:23], v[30:31], v[18:19]
	v_cvt_pk_bf16_f32 v16, v24, v25
	v_cvt_pk_bf16_f32 v17, v26, v27
	v_cvt_pk_bf16_f32 v18, v20, v21
	v_pk_mul_f32 v[20:21], v[14:15], s[8:9] op_sel_hi:[1,0]
	v_cvt_pk_bf16_f32 v19, v22, v23
	global_store_dwordx4 v[32:33], v[16:19], off sc1
	v_pk_mul_f32 v[10:11], v[14:15], v[10:11]
	v_pk_mul_f32 v[8:9], v[12:13], v[8:9]
	v_pk_mul_f32 v[18:19], v[12:13], s[8:9] op_sel_hi:[1,0]
	v_pk_mul_f32 v[12:13], v[4:5], s[8:9] op_sel_hi:[1,0]
	v_pk_mul_f32 v[14:15], v[6:7], s[8:9] op_sel_hi:[1,0]
	v_exp_f32_e32 v18, v18
	v_exp_f32_e32 v19, v19
	v_exp_f32_e32 v20, v20
	v_exp_f32_e32 v21, v21
	v_exp_f32_e32 v12, v12
	v_exp_f32_e32 v13, v13
	v_exp_f32_e32 v14, v14
	v_exp_f32_e32 v15, v15
	v_pk_add_f32 v[18:19], v[18:19], 1.0 op_sel_hi:[1,0]
	v_pk_add_f32 v[20:21], v[20:21], 1.0 op_sel_hi:[1,0]
	v_pk_add_f32 v[12:13], v[12:13], 1.0 op_sel_hi:[1,0]
	v_pk_add_f32 v[14:15], v[14:15], 1.0 op_sel_hi:[1,0]
	v_rcp_f32_e32 v18, v18
	v_rcp_f32_e32 v19, v19
	v_rcp_f32_e32 v20, v20
	v_rcp_f32_e32 v21, v21
	v_rcp_f32_e32 v12, v12
	v_rcp_f32_e32 v13, v13
	v_rcp_f32_e32 v14, v14
	v_rcp_f32_e32 v15, v15
	v_add_u32_e32 v16, 0xb0, v154
	v_mad_i64_i32 v[16:17], s[22:23], v16, s40, v[144:145]
	v_lshl_add_u64 v[16:17], v[16:17], 0, v[146:147]
	v_pk_mul_f32 v[2:3], v[6:7], v[2:3]
	v_pk_mul_f32 v[0:1], v[4:5], v[0:1]
	s_andn2_b64 vcc, exec, s[4:5]
	s_mov_b64 s[4:5], -1
	v_pk_mul_f32 v[8:9], v[18:19], v[8:9]
	v_pk_mul_f32 v[10:11], v[20:21], v[10:11]
	v_pk_mul_f32 v[4:5], v[12:13], v[0:1]
	v_pk_mul_f32 v[6:7], v[14:15], v[2:3]
	v_cvt_pk_bf16_f32 v0, v8, v9
	v_cvt_pk_bf16_f32 v1, v10, v11
	v_cvt_pk_bf16_f32 v2, v4, v5
	s_nop 0
	v_cvt_pk_bf16_f32 v3, v6, v7
	global_store_dwordx4 v[16:17], v[0:3], off sc1
	s_cbranch_vccnz .LBB0_1908
	s_andn2_b64 vcc, exec, s[0:1]
	s_cbranch_vccnz .LBB0_1907
	s_barrier
	s_branch .LBB0_1907

; #define GAS __attribute__((address_space(1)))
; #define LAS __attribute__((address_space(3)))
; __device__ __forceinline__ unsigned pk2(float lo, float hi) { f32x2_k v = {lo, hi}; bf16x2_k b = __builtin_convertvector(v, bf16x2_k); return __builtin_bit_cast(unsigned, b); }
; __device__ __forceinline__ void p0_finish(const P0Job& j, const f32x4 (&v)[16], LAS float* scr, int lane) {
;     ...
;     const int c = lane & 7;
; #pragma unroll
;     for (int hb = 0; hb < 2; ++hb) { const int drow0 = p0_drow(j.kind, n0 + 32 * hb);
;         if (n0 + 32 * hb < j.N && k0 + 8 * c < j.K) {
; #pragma unroll
;             for (int jj = 0; jj < 4; ++jj) { const int n = (lane >> 3) + 8 * jj; const LAS float* sp = scr + (8 * c) * 65 + 32 * hb + n;
;                 v4u o; o.x = pk2(sp[0 * 65], sp[1 * 65]); o.y = pk2(sp[2 * 65], sp[3 * 65]); o.z = pk2(sp[4 * 65], sp[5 * 65]); o.w = pk2(sp[6 * 65], sp[7 * 65]);
;                 GAS v4u* dp = (GAS v4u*)(j.WT + (size_t)(drow0 + n) * j.ldk + k0 + 8 * c); if (j.late) __builtin_nontemporal_store(o, dp); else *dp = o; } } }
.LBB0_2106:
	s_ashr_i32 s53, s52, 31
	v_or_b32_e32 v64, s52, v132
	s_cmp_lt_i32 s54, s77
	s_cselect_b64 s[56:57], -1, 0
	v_cmp_gt_i32_e64 s[8:9], s76, v64
	s_and_b64 s[66:67], s[56:57], s[8:9]
	v_add_u32_e32 v64, 0x400, v134
	v_lshlrev_b32_e32 v130, 1, v132
	s_and_saveexec_b64 s[56:57], s[66:67]
	s_cbranch_execz .LBB0_2108
	v_add_u32_e32 v95, s64, v133
	ds_read2_b32 v[100:101], v134 offset0:65 offset1:73
	ds_read2_b32 v[102:103], v134 offset1:8
	ds_read2_b32 v[104:105], v134 offset0:130 offset1:138
	ds_read2_b32 v[106:107], v134 offset0:195 offset1:203
	ds_read2_b32 v[108:109], v64 offset0:4 offset1:12
	ds_read2_b32 v[110:111], v64 offset0:69 offset1:77
	ds_read2_b32 v[112:113], v64 offset0:134 offset1:142
	ds_read2_b32 v[114:115], v64 offset0:199 offset1:207
	v_mad_u64_u32 v[116:117], s[66:67], v95, s76, 0
	s_waitcnt lgkmcnt(6)
	v_cvt_pk_bf16_f32 v96, v102, v100
	v_ashrrev_i32_e32 v102, 31, v95
	v_mov_b32_e32 v100, v117
	v_mad_u64_u32 v[118:119], s[66:67], v102, s76, v[100:101]
	v_mov_b32_e32 v117, v118
	v_lshl_add_u64 v[116:117], v[116:117], 1, s[50:51]
	s_lshl_b64 s[66:67], s[52:53], 1
	v_lshl_add_u64 v[116:117], v[116:117], 0, s[66:67]
	s_waitcnt lgkmcnt(4)
	v_cvt_pk_bf16_f32 v97, v104, v106
	s_waitcnt lgkmcnt(2)
	v_cvt_pk_bf16_f32 v98, v108, v110
	s_waitcnt lgkmcnt(0)
	v_cvt_pk_bf16_f32 v99, v112, v114
	v_lshl_add_u64 v[116:117], v[116:117], 0, v[130:131]
	v_add_u32_e32 v95, s64, v135
	global_store_dwordx4 v[116:117], v[96:99], off sc1
	s_nop 1
	v_cvt_pk_bf16_f32 v96, v103, v101
	v_mad_u64_u32 v[100:101], s[80:81], v95, s76, 0
	v_ashrrev_i32_e32 v103, 31, v95
	v_mov_b32_e32 v102, v101
	v_mad_u64_u32 v[102:103], s[80:81], v103, s76, v[102:103]
	v_mov_b32_e32 v101, v102
	v_lshl_add_u64 v[100:101], v[100:101], 1, s[50:51]
	v_lshl_add_u64 v[100:101], v[100:101], 0, s[66:67]
	v_cvt_pk_bf16_f32 v97, v105, v107
	v_cvt_pk_bf16_f32 v98, v109, v111
	v_cvt_pk_bf16_f32 v99, v113, v115
	v_lshl_add_u64 v[100:101], v[100:101], 0, v[130:131]
	v_add_u32_e32 v95, s64, v136
	ds_read2_b32 v[102:103], v134 offset0:81 offset1:89
	ds_read2_b32 v[104:105], v134 offset0:16 offset1:24
	ds_read2_b32 v[106:107], v134 offset0:146 offset1:154
	ds_read2_b32 v[108:109], v134 offset0:211 offset1:219
	ds_read2_b32 v[110:111], v64 offset0:20 offset1:28
	ds_read2_b32 v[112:113], v64 offset0:85 offset1:93
	ds_read2_b32 v[114:115], v64 offset0:150 offset1:158
	ds_read2_b32 v[116:117], v64 offset0:215 offset1:223
	global_store_dwordx4 v[100:101], v[96:99], off sc1
	v_mad_u64_u32 v[100:101], s[80:81], v95, s76, 0
	s_waitcnt lgkmcnt(6)
	v_cvt_pk_bf16_f32 v96, v104, v102
	v_ashrrev_i32_e32 v104, 31, v95
	v_mov_b32_e32 v102, v101
	v_mad_u64_u32 v[118:119], s[80:81], v104, s76, v[102:103]
	v_mov_b32_e32 v101, v118
	v_lshl_add_u64 v[100:101], v[100:101], 1, s[50:51]
	v_lshl_add_u64 v[100:101], v[100:101], 0, s[66:67]
	s_waitcnt lgkmcnt(4)
	v_cvt_pk_bf16_f32 v97, v106, v108
	s_waitcnt lgkmcnt(2)
	v_cvt_pk_bf16_f32 v98, v110, v112
	s_waitcnt lgkmcnt(0)
	v_cvt_pk_bf16_f32 v99, v114, v116
	v_lshl_add_u64 v[100:101], v[100:101], 0, v[130:131]
	v_add_u32_e32 v95, s64, v137
	global_store_dwordx4 v[100:101], v[96:99], off sc1
	v_mad_u64_u32 v[100:101], s[64:65], v95, s76, 0
	s_nop 0
	v_cvt_pk_bf16_f32 v96, v105, v103
	v_ashrrev_i32_e32 v103, 31, v95
	v_mov_b32_e32 v102, v101
	v_mad_u64_u32 v[102:103], s[64:65], v103, s76, v[102:103]
	v_mov_b32_e32 v101, v102
	v_lshl_add_u64 v[100:101], v[100:101], 1, s[50:51]
	v_lshl_add_u64 v[100:101], v[100:101], 0, s[66:67]
	v_cvt_pk_bf16_f32 v97, v107, v109
	v_cvt_pk_bf16_f32 v98, v111, v113
	v_cvt_pk_bf16_f32 v99, v115, v117
	v_lshl_add_u64 v[100:101], v[100:101], 0, v[130:131]
	global_store_dwordx4 v[100:101], v[96:99], off sc1

; #define GAS __attribute__((address_space(1)))
; #define LAS __attribute__((address_space(3)))
; __device__ __forceinline__ unsigned pk2(float lo, float hi) { f32x2_k v = {lo, hi}; bf16x2_k b = __builtin_convertvector(v, bf16x2_k); return __builtin_bit_cast(unsigned, b); }
; __device__ __forceinline__ void p0_finish(const P0Job& j, const f32x4 (&v)[16], LAS float* scr, int lane) {
;     ...
;     const int c = lane & 7;
; #pragma unroll
;     for (int hb = 0; hb < 2; ++hb) { const int drow0 = p0_drow(j.kind, n0 + 32 * hb);
;         if (n0 + 32 * hb < j.N && k0 + 8 * c < j.K) {
; #pragma unroll
;             for (int jj = 0; jj < 4; ++jj) { const int n = (lane >> 3) + 8 * jj; const LAS float* sp = scr + (8 * c) * 65 + 32 * hb + n;
;                 v4u o; o.x = pk2(sp[0 * 65], sp[1 * 65]); o.y = pk2(sp[2 * 65], sp[3 * 65]); o.z = pk2(sp[4 * 65], sp[5 * 65]); o.w = pk2(sp[6 * 65], sp[7 * 65]);
;                 GAS v4u* dp = (GAS v4u*)(j.WT + (size_t)(drow0 + n) * j.ldk + k0 + 8 * c); if (j.late) __builtin_nontemporal_store(o, dp); else *dp = o; } } }
.LBB0_2117:
	s_cmp_lt_i32 s55, s77
	s_cselect_b64 s[54:55], -1, 0
	s_and_b64 s[54:55], s[54:55], s[8:9]
	s_and_saveexec_b64 s[8:9], s[54:55]
	s_cbranch_execz .LBB0_2119
	v_add_u32_e32 v95, s64, v133
	ds_read2_b32 v[100:101], v134 offset0:97 offset1:105
	ds_read2_b32 v[102:103], v134 offset0:32 offset1:40
	ds_read2_b32 v[104:105], v134 offset0:162 offset1:170
	ds_read2_b32 v[106:107], v134 offset0:227 offset1:235
	ds_read2_b32 v[108:109], v64 offset0:36 offset1:44
	ds_read2_b32 v[110:111], v64 offset0:101 offset1:109
	ds_read2_b32 v[112:113], v64 offset0:166 offset1:174
	ds_read2_b32 v[114:115], v64 offset0:231 offset1:239
	v_mad_u64_u32 v[116:117], s[54:55], v95, s76, 0
	s_waitcnt lgkmcnt(6)
	v_cvt_pk_bf16_f32 v96, v102, v100
	v_ashrrev_i32_e32 v102, 31, v95
	v_mov_b32_e32 v100, v117
	v_mad_u64_u32 v[118:119], s[54:55], v102, s76, v[100:101]
	v_mov_b32_e32 v117, v118
	v_lshl_add_u64 v[116:117], v[116:117], 1, s[50:51]
	s_lshl_b64 s[52:53], s[52:53], 1
	v_lshl_add_u64 v[116:117], v[116:117], 0, s[52:53]
	s_waitcnt lgkmcnt(4)
	v_cvt_pk_bf16_f32 v97, v104, v106
	s_waitcnt lgkmcnt(2)
	v_cvt_pk_bf16_f32 v98, v108, v110
	s_waitcnt lgkmcnt(0)
	v_cvt_pk_bf16_f32 v99, v112, v114
	v_lshl_add_u64 v[116:117], v[116:117], 0, v[130:131]
	v_add_u32_e32 v95, s64, v135
	global_store_dwordx4 v[116:117], v[96:99], off sc1
	s_nop 1
	v_cvt_pk_bf16_f32 v96, v103, v101
	v_mad_u64_u32 v[100:101], s[54:55], v95, s76, 0
	v_ashrrev_i32_e32 v103, 31, v95
	v_mov_b32_e32 v102, v101
	v_mad_u64_u32 v[102:103], s[54:55], v103, s76, v[102:103]
	v_mov_b32_e32 v101, v102
	v_lshl_add_u64 v[100:101], v[100:101], 1, s[50:51]
	v_lshl_add_u64 v[100:101], v[100:101], 0, s[52:53]
	v_cvt_pk_bf16_f32 v97, v105, v107
	v_cvt_pk_bf16_f32 v98, v109, v111
	v_cvt_pk_bf16_f32 v99, v113, v115
	v_lshl_add_u64 v[100:101], v[100:101], 0, v[130:131]
	v_add_u32_e32 v95, s64, v136
	ds_read2_b32 v[102:103], v134 offset0:113 offset1:121
	ds_read2_b32 v[104:105], v134 offset0:48 offset1:56
	ds_read2_b32 v[106:107], v134 offset0:178 offset1:186
	ds_read2_b32 v[108:109], v134 offset0:243 offset1:251
	ds_read2_b32 v[110:111], v64 offset0:52 offset1:60
	ds_read2_b32 v[112:113], v64 offset0:117 offset1:125
	ds_read2_b32 v[114:115], v64 offset0:182 offset1:190
	ds_read2_b32 v[116:117], v64 offset0:247 offset1:255
	global_store_dwordx4 v[100:101], v[96:99], off sc1
	v_mad_u64_u32 v[100:101], s[54:55], v95, s76, 0
	s_waitcnt lgkmcnt(6)
	v_cvt_pk_bf16_f32 v96, v104, v102
	v_ashrrev_i32_e32 v104, 31, v95
	v_mov_b32_e32 v102, v101
	v_mad_u64_u32 v[118:119], s[54:55], v104, s76, v[102:103]
	v_mov_b32_e32 v101, v118
	v_lshl_add_u64 v[100:101], v[100:101], 1, s[50:51]
	v_lshl_add_u64 v[100:101], v[100:101], 0, s[52:53]
	s_waitcnt lgkmcnt(4)
	v_cvt_pk_bf16_f32 v97, v106, v108
	s_waitcnt lgkmcnt(2)
	v_cvt_pk_bf16_f32 v98, v110, v112
	s_waitcnt lgkmcnt(0)
	v_cvt_pk_bf16_f32 v99, v114, v116
	v_lshl_add_u64 v[100:101], v[100:101], 0, v[130:131]
	v_add_u32_e32 v95, s64, v137
	global_store_dwordx4 v[100:101], v[96:99], off sc1
	v_mad_u64_u32 v[100:101], s[54:55], v95, s76, 0
	s_nop 0
	v_cvt_pk_bf16_f32 v96, v105, v103
	v_ashrrev_i32_e32 v103, 31, v95
	v_mov_b32_e32 v102, v101
	v_mad_u64_u32 v[102:103], s[54:55], v103, s76, v[102:103]
	v_mov_b32_e32 v101, v102
	v_lshl_add_u64 v[100:101], v[100:101], 1, s[50:51]
	v_lshl_add_u64 v[100:101], v[100:101], 0, s[52:53]
	v_cvt_pk_bf16_f32 v97, v107, v109
	v_cvt_pk_bf16_f32 v98, v111, v113
	v_cvt_pk_bf16_f32 v99, v115, v117
	v_lshl_add_u64 v[100:101], v[100:101], 0, v[130:131]
	global_store_dwordx4 v[100:101], v[96:99], off sc1

; #define GAS __attribute__((address_space(1)))
; #define LAS __attribute__((address_space(3)))
; __device__ __forceinline__ unsigned pk2(float lo, float hi) { f32x2_k v = {lo, hi}; bf16x2_k b = __builtin_convertvector(v, bf16x2_k); return __builtin_bit_cast(unsigned, b); }
; __device__ __forceinline__ void p0_finish(const P0Job& j, const f32x4 (&v)[16], LAS float* scr, int lane) {
;     ...
;     const int c = lane & 7;
; #pragma unroll
;     for (int hb = 0; hb < 2; ++hb) { const int drow0 = p0_drow(j.kind, n0 + 32 * hb);
;         if (n0 + 32 * hb < j.N && k0 + 8 * c < j.K) {
; #pragma unroll
;             for (int jj = 0; jj < 4; ++jj) { const int n = (lane >> 3) + 8 * jj; const LAS float* sp = scr + (8 * c) * 65 + 32 * hb + n;
;                 v4u o; o.x = pk2(sp[0 * 65], sp[1 * 65]); o.y = pk2(sp[2 * 65], sp[3 * 65]); o.z = pk2(sp[4 * 65], sp[5 * 65]); o.w = pk2(sp[6 * 65], sp[7 * 65]);
;                 GAS v4u* dp = (GAS v4u*)(j.WT + (size_t)(drow0 + n) * j.ldk + k0 + 8 * c); if (j.late) __builtin_nontemporal_store(o, dp); else *dp = o; } } }
.LBB0_2135:
	s_lshl_b32 s50, s52, 6
	s_ashr_i32 s51, s50, 31
	v_or_b32_e32 v65, s50, v132
	s_cmp_lt_i32 s54, s73
	s_cselect_b64 s[52:53], -1, 0
	v_cmp_gt_i32_e64 s[8:9], s75, v65
	s_and_b64 s[58:59], s[52:53], s[8:9]
	s_and_saveexec_b64 s[52:53], s[58:59]
	s_cbranch_execz .LBB0_2137
	ds_read2_b32 v[70:71], v134 offset0:65 offset1:73
	ds_read2_b32 v[72:73], v134 offset1:8
	ds_read2_b32 v[74:75], v134 offset0:130 offset1:138
	ds_read2_b32 v[76:77], v134 offset0:195 offset1:203
	ds_read2_b32 v[78:79], v64 offset0:4 offset1:12
	ds_read2_b32 v[80:81], v64 offset0:69 offset1:77
	ds_read2_b32 v[82:83], v64 offset0:134 offset1:142
	ds_read2_b32 v[84:85], v64 offset0:199 offset1:207
	v_add_u32_e32 v65, s57, v133
	v_mad_i64_i32 v[86:87], s[58:59], v65, s75, 0
	v_lshl_add_u64 v[86:87], v[86:87], 1, s[48:49]
	s_lshl_b64 s[58:59], s[50:51], 1
	v_lshl_add_u64 v[86:87], v[86:87], 0, s[58:59]
	s_waitcnt lgkmcnt(0)
	v_cvt_pk_bf16_f32 v66, v72, v70
	v_cvt_pk_bf16_f32 v67, v74, v76
	v_cvt_pk_bf16_f32 v68, v78, v80
	v_cvt_pk_bf16_f32 v69, v82, v84
	v_lshl_add_u64 v[86:87], v[86:87], 0, v[130:131]
	v_add_u32_e32 v65, s57, v135
	global_store_dwordx4 v[86:87], v[66:69], off sc1
	s_nop 1
	v_cvt_pk_bf16_f32 v66, v73, v71
	v_mad_i64_i32 v[70:71], s[60:61], v65, s75, 0
	v_lshl_add_u64 v[70:71], v[70:71], 1, s[48:49]
	v_cvt_pk_bf16_f32 v67, v75, v77
	v_cvt_pk_bf16_f32 v68, v79, v81
	v_cvt_pk_bf16_f32 v69, v83, v85
	v_lshl_add_u64 v[70:71], v[70:71], 0, s[58:59]
	ds_read2_b32 v[72:73], v134 offset0:81 offset1:89
	ds_read2_b32 v[74:75], v134 offset0:16 offset1:24
	ds_read2_b32 v[76:77], v134 offset0:146 offset1:154
	ds_read2_b32 v[78:79], v134 offset0:211 offset1:219
	ds_read2_b32 v[80:81], v64 offset0:20 offset1:28
	ds_read2_b32 v[82:83], v64 offset0:85 offset1:93
	ds_read2_b32 v[84:85], v64 offset0:150 offset1:158
	ds_read2_b32 v[86:87], v64 offset0:215 offset1:223
	v_lshl_add_u64 v[70:71], v[70:71], 0, v[130:131]
	v_add_u32_e32 v65, s57, v136
	global_store_dwordx4 v[70:71], v[66:69], off sc1
	v_mad_i64_i32 v[70:71], s[60:61], v65, s75, 0
	v_lshl_add_u64 v[70:71], v[70:71], 1, s[48:49]
	v_lshl_add_u64 v[70:71], v[70:71], 0, s[58:59]
	s_waitcnt lgkmcnt(6)
	v_cvt_pk_bf16_f32 v66, v74, v72
	s_waitcnt lgkmcnt(4)
	v_cvt_pk_bf16_f32 v67, v76, v78
	s_waitcnt lgkmcnt(2)
	v_cvt_pk_bf16_f32 v68, v80, v82
	s_waitcnt lgkmcnt(0)
	v_cvt_pk_bf16_f32 v69, v84, v86
	v_lshl_add_u64 v[70:71], v[70:71], 0, v[130:131]
	v_add_u32_e32 v65, s57, v137
	global_store_dwordx4 v[70:71], v[66:69], off sc1
	v_mad_i64_i32 v[70:71], s[60:61], v65, s75, 0
	v_lshl_add_u64 v[70:71], v[70:71], 1, s[48:49]
	v_lshl_add_u64 v[70:71], v[70:71], 0, s[58:59]
	v_cvt_pk_bf16_f32 v66, v75, v73
	v_cvt_pk_bf16_f32 v67, v77, v79
	v_cvt_pk_bf16_f32 v68, v81, v83
	v_cvt_pk_bf16_f32 v69, v85, v87
	v_lshl_add_u64 v[70:71], v[70:71], 0, v[130:131]
	global_store_dwordx4 v[70:71], v[66:69], off sc1

; #define GAS __attribute__((address_space(1)))
; #define LAS __attribute__((address_space(3)))
; __device__ __forceinline__ unsigned pk2(float lo, float hi) { f32x2_k v = {lo, hi}; bf16x2_k b = __builtin_convertvector(v, bf16x2_k); return __builtin_bit_cast(unsigned, b); }
; __device__ __forceinline__ void p0_finish(const P0Job& j, const f32x4 (&v)[16], LAS float* scr, int lane) {
;     ...
;     const int c = lane & 7;
; #pragma unroll
;     for (int hb = 0; hb < 2; ++hb) { const int drow0 = p0_drow(j.kind, n0 + 32 * hb);
;         if (n0 + 32 * hb < j.N && k0 + 8 * c < j.K) {
; #pragma unroll
;             for (int jj = 0; jj < 4; ++jj) { const int n = (lane >> 3) + 8 * jj; const LAS float* sp = scr + (8 * c) * 65 + 32 * hb + n;
;                 v4u o; o.x = pk2(sp[0 * 65], sp[1 * 65]); o.y = pk2(sp[2 * 65], sp[3 * 65]); o.z = pk2(sp[4 * 65], sp[5 * 65]); o.w = pk2(sp[6 * 65], sp[7 * 65]);
;                 GAS v4u* dp = (GAS v4u*)(j.WT + (size_t)(drow0 + n) * j.ldk + k0 + 8 * c); if (j.late) __builtin_nontemporal_store(o, dp); else *dp = o; } } }
.LBB0_2148:
	s_cmp_lt_i32 s58, s73
	s_cselect_b64 s[52:53], -1, 0
	s_and_b64 s[52:53], s[52:53], s[8:9]
	s_and_saveexec_b64 s[8:9], s[52:53]
	s_cbranch_execz .LBB0_1923
	ds_read2_b32 v[70:71], v134 offset0:97 offset1:105
	ds_read2_b32 v[72:73], v134 offset0:32 offset1:40
	ds_read2_b32 v[74:75], v134 offset0:162 offset1:170
	ds_read2_b32 v[76:77], v134 offset0:227 offset1:235
	ds_read2_b32 v[78:79], v64 offset0:36 offset1:44
	ds_read2_b32 v[80:81], v64 offset0:101 offset1:109
	ds_read2_b32 v[82:83], v64 offset0:166 offset1:174
	ds_read2_b32 v[84:85], v64 offset0:231 offset1:239
	v_add_u32_e32 v65, s57, v133
	v_mad_i64_i32 v[86:87], s[52:53], v65, s75, 0
	v_lshl_add_u64 v[86:87], v[86:87], 1, s[48:49]
	s_lshl_b64 s[50:51], s[50:51], 1
	v_lshl_add_u64 v[86:87], v[86:87], 0, s[50:51]
	s_waitcnt lgkmcnt(0)
	v_cvt_pk_bf16_f32 v66, v72, v70
	v_cvt_pk_bf16_f32 v67, v74, v76
	v_cvt_pk_bf16_f32 v68, v78, v80
	v_cvt_pk_bf16_f32 v69, v82, v84
	v_lshl_add_u64 v[86:87], v[86:87], 0, v[130:131]
	v_add_u32_e32 v65, s57, v135
	global_store_dwordx4 v[86:87], v[66:69], off sc1
	s_nop 1
	v_cvt_pk_bf16_f32 v66, v73, v71
	v_mad_i64_i32 v[70:71], s[52:53], v65, s75, 0
	v_lshl_add_u64 v[70:71], v[70:71], 1, s[48:49]
	v_lshl_add_u64 v[70:71], v[70:71], 0, s[50:51]
	v_cvt_pk_bf16_f32 v67, v75, v77
	v_cvt_pk_bf16_f32 v68, v79, v81
	v_cvt_pk_bf16_f32 v69, v83, v85
	v_lshl_add_u64 v[70:71], v[70:71], 0, v[130:131]
	ds_read2_b32 v[72:73], v134 offset0:113 offset1:121
	ds_read2_b32 v[74:75], v134 offset0:48 offset1:56
	ds_read2_b32 v[76:77], v134 offset0:178 offset1:186
	ds_read2_b32 v[78:79], v134 offset0:243 offset1:251
	ds_read2_b32 v[80:81], v64 offset0:52 offset1:60
	ds_read2_b32 v[82:83], v64 offset0:117 offset1:125
	ds_read2_b32 v[84:85], v64 offset0:182 offset1:190
	ds_read2_b32 v[86:87], v64 offset0:247 offset1:255
	global_store_dwordx4 v[70:71], v[66:69], off sc1
	s_waitcnt lgkmcnt(6)
	v_cvt_pk_bf16_f32 v64, v74, v72
	s_waitcnt lgkmcnt(4)
	v_cvt_pk_bf16_f32 v65, v76, v78
	v_add_u32_e32 v68, s57, v136
	v_mad_i64_i32 v[68:69], s[52:53], v68, s75, 0
	v_lshl_add_u64 v[68:69], v[68:69], 1, s[48:49]
	v_lshl_add_u64 v[68:69], v[68:69], 0, s[50:51]
	s_waitcnt lgkmcnt(2)
	v_cvt_pk_bf16_f32 v66, v80, v82
	s_waitcnt lgkmcnt(0)
	v_cvt_pk_bf16_f32 v67, v84, v86
	v_lshl_add_u64 v[68:69], v[68:69], 0, v[130:131]
	global_store_dwordx4 v[68:69], v[64:67], off sc1
	v_add_u32_e32 v68, s57, v137
	v_mad_i64_i32 v[68:69], s[52:53], v68, s75, 0
	v_lshl_add_u64 v[68:69], v[68:69], 1, s[48:49]
	v_lshl_add_u64 v[68:69], v[68:69], 0, s[50:51]
	v_cvt_pk_bf16_f32 v64, v75, v73
	v_cvt_pk_bf16_f32 v65, v77, v79
	v_cvt_pk_bf16_f32 v66, v81, v83
	v_cvt_pk_bf16_f32 v67, v85, v87
	v_lshl_add_u64 v[68:69], v[68:69], 0, v[130:131]
	global_store_dwordx4 v[68:69], v[64:67], off sc1
	s_branch .LBB0_1923

; #define GAS __attribute__((address_space(1)))
; #define LAS __attribute__((address_space(3)))
; __device__ __forceinline__ unsigned pk2(float lo, float hi) { f32x2_k v = {lo, hi}; bf16x2_k b = __builtin_convertvector(v, bf16x2_k); return __builtin_bit_cast(unsigned, b); }
; __device__ __forceinline__ void p0_finish(const P0Job& j, const f32x4 (&v)[16], LAS float* scr, int lane) {
;     ...
;     const int c = lane & 7;
; #pragma unroll
;     for (int hb = 0; hb < 2; ++hb) { const int drow0 = p0_drow(j.kind, n0 + 32 * hb);
;         if (n0 + 32 * hb < j.N && k0 + 8 * c < j.K) {
; #pragma unroll
;             for (int jj = 0; jj < 4; ++jj) { const int n = (lane >> 3) + 8 * jj; const LAS float* sp = scr + (8 * c) * 65 + 32 * hb + n;
;                 v4u o; o.x = pk2(sp[0 * 65], sp[1 * 65]); o.y = pk2(sp[2 * 65], sp[3 * 65]); o.z = pk2(sp[4 * 65], sp[5 * 65]); o.w = pk2(sp[6 * 65], sp[7 * 65]);
;                 GAS v4u* dp = (GAS v4u*)(j.WT + (size_t)(drow0 + n) * j.ldk + k0 + 8 * c); if (j.late) __builtin_nontemporal_store(o, dp); else *dp = o; } } }
.LBB0_2341:
	s_ashr_i32 s53, s52, 31
	v_or_b32_e32 v64, s52, v132
	s_cmp_lt_i32 s54, s74
	s_cselect_b64 s[56:57], -1, 0
	v_cmp_gt_i32_e64 s[6:7], s73, v64
	s_and_b64 s[66:67], s[56:57], s[6:7]
	v_add_u32_e32 v64, 0x400, v134
	v_lshlrev_b32_e32 v130, 1, v132
	s_and_saveexec_b64 s[56:57], s[66:67]
	s_cbranch_execz .LBB0_2343
	v_add_u32_e32 v95, s64, v133
	ds_read2_b32 v[100:101], v134 offset0:65 offset1:73
	ds_read2_b32 v[102:103], v134 offset1:8
	ds_read2_b32 v[104:105], v134 offset0:130 offset1:138
	ds_read2_b32 v[106:107], v134 offset0:195 offset1:203
	ds_read2_b32 v[108:109], v64 offset0:4 offset1:12
	ds_read2_b32 v[110:111], v64 offset0:69 offset1:77
	ds_read2_b32 v[112:113], v64 offset0:134 offset1:142
	ds_read2_b32 v[114:115], v64 offset0:199 offset1:207
	v_mad_u64_u32 v[116:117], s[66:67], v95, s73, 0
	s_waitcnt lgkmcnt(6)
	v_cvt_pk_bf16_f32 v96, v102, v100
	v_ashrrev_i32_e32 v102, 31, v95
	v_mov_b32_e32 v100, v117
	v_mad_u64_u32 v[118:119], s[66:67], v102, s73, v[100:101]
	v_mov_b32_e32 v117, v118
	v_lshl_add_u64 v[116:117], v[116:117], 1, s[50:51]
	s_lshl_b64 s[66:67], s[52:53], 1
	v_lshl_add_u64 v[116:117], v[116:117], 0, s[66:67]
	s_waitcnt lgkmcnt(4)
	v_cvt_pk_bf16_f32 v97, v104, v106
	s_waitcnt lgkmcnt(2)
	v_cvt_pk_bf16_f32 v98, v108, v110
	s_waitcnt lgkmcnt(0)
	v_cvt_pk_bf16_f32 v99, v112, v114
	v_lshl_add_u64 v[116:117], v[116:117], 0, v[130:131]
	v_add_u32_e32 v95, s64, v135
	global_store_dwordx4 v[116:117], v[96:99], off sc1
	s_nop 1
	v_cvt_pk_bf16_f32 v96, v103, v101
	v_mad_u64_u32 v[100:101], s[76:77], v95, s73, 0
	v_ashrrev_i32_e32 v103, 31, v95
	v_mov_b32_e32 v102, v101
	v_mad_u64_u32 v[102:103], s[76:77], v103, s73, v[102:103]
	v_mov_b32_e32 v101, v102
	v_lshl_add_u64 v[100:101], v[100:101], 1, s[50:51]
	v_lshl_add_u64 v[100:101], v[100:101], 0, s[66:67]
	v_cvt_pk_bf16_f32 v97, v105, v107
	v_cvt_pk_bf16_f32 v98, v109, v111
	v_cvt_pk_bf16_f32 v99, v113, v115
	v_lshl_add_u64 v[100:101], v[100:101], 0, v[130:131]
	v_add_u32_e32 v95, s64, v136
	ds_read2_b32 v[102:103], v134 offset0:81 offset1:89
	ds_read2_b32 v[104:105], v134 offset0:16 offset1:24
	ds_read2_b32 v[106:107], v134 offset0:146 offset1:154
	ds_read2_b32 v[108:109], v134 offset0:211 offset1:219
	ds_read2_b32 v[110:111], v64 offset0:20 offset1:28
	ds_read2_b32 v[112:113], v64 offset0:85 offset1:93
	ds_read2_b32 v[114:115], v64 offset0:150 offset1:158
	ds_read2_b32 v[116:117], v64 offset0:215 offset1:223
	global_store_dwordx4 v[100:101], v[96:99], off sc1
	v_mad_u64_u32 v[100:101], s[76:77], v95, s73, 0
	s_waitcnt lgkmcnt(6)
	v_cvt_pk_bf16_f32 v96, v104, v102
	v_ashrrev_i32_e32 v104, 31, v95
	v_mov_b32_e32 v102, v101
	v_mad_u64_u32 v[118:119], s[76:77], v104, s73, v[102:103]
	v_mov_b32_e32 v101, v118
	v_lshl_add_u64 v[100:101], v[100:101], 1, s[50:51]
	v_lshl_add_u64 v[100:101], v[100:101], 0, s[66:67]
	s_waitcnt lgkmcnt(4)
	v_cvt_pk_bf16_f32 v97, v106, v108
	s_waitcnt lgkmcnt(2)
	v_cvt_pk_bf16_f32 v98, v110, v112
	s_waitcnt lgkmcnt(0)
	v_cvt_pk_bf16_f32 v99, v114, v116
	v_lshl_add_u64 v[100:101], v[100:101], 0, v[130:131]
	v_add_u32_e32 v95, s64, v137
	global_store_dwordx4 v[100:101], v[96:99], off sc1
	v_mad_u64_u32 v[100:101], s[64:65], v95, s73, 0
	s_nop 0
	v_cvt_pk_bf16_f32 v96, v105, v103
	v_ashrrev_i32_e32 v103, 31, v95
	v_mov_b32_e32 v102, v101
	v_mad_u64_u32 v[102:103], s[64:65], v103, s73, v[102:103]
	v_mov_b32_e32 v101, v102
	v_lshl_add_u64 v[100:101], v[100:101], 1, s[50:51]
	v_lshl_add_u64 v[100:101], v[100:101], 0, s[66:67]
	v_readlane_b32 s77, v254, 10
	v_cvt_pk_bf16_f32 v97, v107, v109
	v_cvt_pk_bf16_f32 v98, v111, v113
	v_cvt_pk_bf16_f32 v99, v115, v117
	v_lshl_add_u64 v[100:101], v[100:101], 0, v[130:131]
	global_store_dwordx4 v[100:101], v[96:99], off sc1

; #define GAS __attribute__((address_space(1)))
; #define LAS __attribute__((address_space(3)))
; __device__ __forceinline__ unsigned pk2(float lo, float hi) { f32x2_k v = {lo, hi}; bf16x2_k b = __builtin_convertvector(v, bf16x2_k); return __builtin_bit_cast(unsigned, b); }
; __device__ __forceinline__ void p0_finish(const P0Job& j, const f32x4 (&v)[16], LAS float* scr, int lane) {
;     ...
;     const int c = lane & 7;
; #pragma unroll
;     for (int hb = 0; hb < 2; ++hb) { const int drow0 = p0_drow(j.kind, n0 + 32 * hb);
;         if (n0 + 32 * hb < j.N && k0 + 8 * c < j.K) {
; #pragma unroll
;             for (int jj = 0; jj < 4; ++jj) { const int n = (lane >> 3) + 8 * jj; const LAS float* sp = scr + (8 * c) * 65 + 32 * hb + n;
;                 v4u o; o.x = pk2(sp[0 * 65], sp[1 * 65]); o.y = pk2(sp[2 * 65], sp[3 * 65]); o.z = pk2(sp[4 * 65], sp[5 * 65]); o.w = pk2(sp[6 * 65], sp[7 * 65]);
;                 GAS v4u* dp = (GAS v4u*)(j.WT + (size_t)(drow0 + n) * j.ldk + k0 + 8 * c); if (j.late) __builtin_nontemporal_store(o, dp); else *dp = o; } } }
.LBB0_2352:
	s_cmp_lt_i32 s55, s74
	s_cselect_b64 s[54:55], -1, 0
	s_and_b64 s[54:55], s[54:55], s[6:7]
	s_and_saveexec_b64 s[6:7], s[54:55]
	s_cbranch_execz .LBB0_2354
	v_add_u32_e32 v95, s64, v133
	ds_read2_b32 v[100:101], v134 offset0:97 offset1:105
	ds_read2_b32 v[102:103], v134 offset0:32 offset1:40
	ds_read2_b32 v[104:105], v134 offset0:162 offset1:170
	ds_read2_b32 v[106:107], v134 offset0:227 offset1:235
	ds_read2_b32 v[108:109], v64 offset0:36 offset1:44
	ds_read2_b32 v[110:111], v64 offset0:101 offset1:109
	ds_read2_b32 v[112:113], v64 offset0:166 offset1:174
	ds_read2_b32 v[114:115], v64 offset0:231 offset1:239
	v_mad_u64_u32 v[116:117], s[54:55], v95, s73, 0
	s_waitcnt lgkmcnt(6)
	v_cvt_pk_bf16_f32 v96, v102, v100
	v_ashrrev_i32_e32 v102, 31, v95
	v_mov_b32_e32 v100, v117
	v_mad_u64_u32 v[118:119], s[54:55], v102, s73, v[100:101]
	v_mov_b32_e32 v117, v118
	v_lshl_add_u64 v[116:117], v[116:117], 1, s[50:51]
	s_lshl_b64 s[52:53], s[52:53], 1
	v_lshl_add_u64 v[116:117], v[116:117], 0, s[52:53]
	s_waitcnt lgkmcnt(4)
	v_cvt_pk_bf16_f32 v97, v104, v106
	s_waitcnt lgkmcnt(2)
	v_cvt_pk_bf16_f32 v98, v108, v110
	s_waitcnt lgkmcnt(0)
	v_cvt_pk_bf16_f32 v99, v112, v114
	v_lshl_add_u64 v[116:117], v[116:117], 0, v[130:131]
	v_add_u32_e32 v95, s64, v135
	global_store_dwordx4 v[116:117], v[96:99], off sc1
	s_nop 1
	v_cvt_pk_bf16_f32 v96, v103, v101
	v_mad_u64_u32 v[100:101], s[54:55], v95, s73, 0
	v_ashrrev_i32_e32 v103, 31, v95
	v_mov_b32_e32 v102, v101
	v_mad_u64_u32 v[102:103], s[54:55], v103, s73, v[102:103]
	v_mov_b32_e32 v101, v102
	v_lshl_add_u64 v[100:101], v[100:101], 1, s[50:51]
	v_lshl_add_u64 v[100:101], v[100:101], 0, s[52:53]
	v_cvt_pk_bf16_f32 v97, v105, v107
	v_cvt_pk_bf16_f32 v98, v109, v111
	v_cvt_pk_bf16_f32 v99, v113, v115
	v_lshl_add_u64 v[100:101], v[100:101], 0, v[130:131]
	v_add_u32_e32 v95, s64, v136
	ds_read2_b32 v[102:103], v134 offset0:113 offset1:121
	ds_read2_b32 v[104:105], v134 offset0:48 offset1:56
	ds_read2_b32 v[106:107], v134 offset0:178 offset1:186
	ds_read2_b32 v[108:109], v134 offset0:243 offset1:251
	ds_read2_b32 v[110:111], v64 offset0:52 offset1:60
	ds_read2_b32 v[112:113], v64 offset0:117 offset1:125
	ds_read2_b32 v[114:115], v64 offset0:182 offset1:190
	ds_read2_b32 v[116:117], v64 offset0:247 offset1:255
	global_store_dwordx4 v[100:101], v[96:99], off sc1
	v_mad_u64_u32 v[100:101], s[54:55], v95, s73, 0
	s_waitcnt lgkmcnt(6)
	v_cvt_pk_bf16_f32 v96, v104, v102
	v_ashrrev_i32_e32 v104, 31, v95
	v_mov_b32_e32 v102, v101
	v_mad_u64_u32 v[118:119], s[54:55], v104, s73, v[102:103]
	v_mov_b32_e32 v101, v118
	v_lshl_add_u64 v[100:101], v[100:101], 1, s[50:51]
	v_lshl_add_u64 v[100:101], v[100:101], 0, s[52:53]
	s_waitcnt lgkmcnt(4)
	v_cvt_pk_bf16_f32 v97, v106, v108
	s_waitcnt lgkmcnt(2)
	v_cvt_pk_bf16_f32 v98, v110, v112
	s_waitcnt lgkmcnt(0)
	v_cvt_pk_bf16_f32 v99, v114, v116
	v_lshl_add_u64 v[100:101], v[100:101], 0, v[130:131]
	v_add_u32_e32 v95, s64, v137
	global_store_dwordx4 v[100:101], v[96:99], off sc1
	v_mad_u64_u32 v[100:101], s[54:55], v95, s73, 0
	s_nop 0
	v_cvt_pk_bf16_f32 v96, v105, v103
	v_ashrrev_i32_e32 v103, 31, v95
	v_mov_b32_e32 v102, v101
	v_mad_u64_u32 v[102:103], s[54:55], v103, s73, v[102:103]
	v_mov_b32_e32 v101, v102
	v_lshl_add_u64 v[100:101], v[100:101], 1, s[50:51]
	v_lshl_add_u64 v[100:101], v[100:101], 0, s[52:53]
	v_cvt_pk_bf16_f32 v97, v107, v109
	v_cvt_pk_bf16_f32 v98, v111, v113
	v_cvt_pk_bf16_f32 v99, v115, v117
	v_lshl_add_u64 v[100:101], v[100:101], 0, v[130:131]
	global_store_dwordx4 v[100:101], v[96:99], off sc1

; #define GAS __attribute__((address_space(1)))
; #define LAS __attribute__((address_space(3)))
; __device__ __forceinline__ unsigned pk2(float lo, float hi) { f32x2_k v = {lo, hi}; bf16x2_k b = __builtin_convertvector(v, bf16x2_k); return __builtin_bit_cast(unsigned, b); }
; __device__ __forceinline__ void p0_finish(const P0Job& j, const f32x4 (&v)[16], LAS float* scr, int lane) {
;     ...
;     const int c = lane & 7;
; #pragma unroll
;     for (int hb = 0; hb < 2; ++hb) { const int drow0 = p0_drow(j.kind, n0 + 32 * hb);
;         if (n0 + 32 * hb < j.N && k0 + 8 * c < j.K) {
; #pragma unroll
;             for (int jj = 0; jj < 4; ++jj) { const int n = (lane >> 3) + 8 * jj; const LAS float* sp = scr + (8 * c) * 65 + 32 * hb + n;
;                 v4u o; o.x = pk2(sp[0 * 65], sp[1 * 65]); o.y = pk2(sp[2 * 65], sp[3 * 65]); o.z = pk2(sp[4 * 65], sp[5 * 65]); o.w = pk2(sp[6 * 65], sp[7 * 65]);
;                 GAS v4u* dp = (GAS v4u*)(j.WT + (size_t)(drow0 + n) * j.ldk + k0 + 8 * c); if (j.late) __builtin_nontemporal_store(o, dp); else *dp = o; } } }
.LBB0_2370:
	s_lshl_b32 s50, s52, 6
	s_ashr_i32 s51, s50, 31
	v_or_b32_e32 v65, s50, v132
	s_cmp_lt_i32 s54, s71
	s_cselect_b64 s[52:53], -1, 0
	v_cmp_gt_i32_e64 s[6:7], s70, v65
	s_and_b64 s[58:59], s[52:53], s[6:7]
	s_and_saveexec_b64 s[52:53], s[58:59]
	s_cbranch_execz .LBB0_2372
	ds_read2_b32 v[70:71], v134 offset0:65 offset1:73
	ds_read2_b32 v[72:73], v134 offset1:8
	ds_read2_b32 v[74:75], v134 offset0:130 offset1:138
	ds_read2_b32 v[76:77], v134 offset0:195 offset1:203
	ds_read2_b32 v[78:79], v64 offset0:4 offset1:12
	ds_read2_b32 v[80:81], v64 offset0:69 offset1:77
	ds_read2_b32 v[82:83], v64 offset0:134 offset1:142
	ds_read2_b32 v[84:85], v64 offset0:199 offset1:207
	v_add_u32_e32 v65, s57, v133
	v_mad_i64_i32 v[86:87], s[58:59], v65, s70, 0
	v_lshl_add_u64 v[86:87], v[86:87], 1, s[48:49]
	s_lshl_b64 s[58:59], s[50:51], 1
	v_lshl_add_u64 v[86:87], v[86:87], 0, s[58:59]
	s_waitcnt lgkmcnt(6)
	v_cvt_pk_bf16_f32 v66, v72, v70
	s_waitcnt lgkmcnt(4)
	v_cvt_pk_bf16_f32 v67, v74, v76
	s_waitcnt lgkmcnt(2)
	v_cvt_pk_bf16_f32 v68, v78, v80
	s_waitcnt lgkmcnt(0)
	v_cvt_pk_bf16_f32 v69, v82, v84
	v_lshl_add_u64 v[86:87], v[86:87], 0, v[130:131]
	v_add_u32_e32 v65, s57, v135
	global_store_dwordx4 v[86:87], v[66:69], off sc1
	s_nop 1
	v_cvt_pk_bf16_f32 v66, v73, v71
	v_mad_i64_i32 v[70:71], s[60:61], v65, s70, 0
	v_lshl_add_u64 v[70:71], v[70:71], 1, s[48:49]
	v_cvt_pk_bf16_f32 v67, v75, v77
	v_cvt_pk_bf16_f32 v68, v79, v81
	v_cvt_pk_bf16_f32 v69, v83, v85
	v_lshl_add_u64 v[70:71], v[70:71], 0, s[58:59]
	ds_read2_b32 v[72:73], v134 offset0:81 offset1:89
	ds_read2_b32 v[74:75], v134 offset0:16 offset1:24
	ds_read2_b32 v[76:77], v134 offset0:146 offset1:154
	ds_read2_b32 v[78:79], v134 offset0:211 offset1:219
	ds_read2_b32 v[80:81], v64 offset0:20 offset1:28
	ds_read2_b32 v[82:83], v64 offset0:85 offset1:93
	ds_read2_b32 v[84:85], v64 offset0:150 offset1:158
	ds_read2_b32 v[86:87], v64 offset0:215 offset1:223
	v_lshl_add_u64 v[70:71], v[70:71], 0, v[130:131]
	v_add_u32_e32 v65, s57, v136
	global_store_dwordx4 v[70:71], v[66:69], off sc1
	v_mad_i64_i32 v[70:71], s[60:61], v65, s70, 0
	v_lshl_add_u64 v[70:71], v[70:71], 1, s[48:49]
	v_lshl_add_u64 v[70:71], v[70:71], 0, s[58:59]
	s_waitcnt lgkmcnt(6)
	v_cvt_pk_bf16_f32 v66, v74, v72
	s_waitcnt lgkmcnt(4)
	v_cvt_pk_bf16_f32 v67, v76, v78
	s_waitcnt lgkmcnt(2)
	v_cvt_pk_bf16_f32 v68, v80, v82
	s_waitcnt lgkmcnt(0)
	v_cvt_pk_bf16_f32 v69, v84, v86
	v_lshl_add_u64 v[70:71], v[70:71], 0, v[130:131]
	v_add_u32_e32 v65, s57, v137
	global_store_dwordx4 v[70:71], v[66:69], off sc1
	v_mad_i64_i32 v[70:71], s[60:61], v65, s70, 0
	v_lshl_add_u64 v[70:71], v[70:71], 1, s[48:49]
	v_lshl_add_u64 v[70:71], v[70:71], 0, s[58:59]
	v_cvt_pk_bf16_f32 v66, v75, v73
	v_cvt_pk_bf16_f32 v67, v77, v79
	v_cvt_pk_bf16_f32 v68, v81, v83
	v_cvt_pk_bf16_f32 v69, v85, v87
	v_lshl_add_u64 v[70:71], v[70:71], 0, v[130:131]
	global_store_dwordx4 v[70:71], v[66:69], off sc1

; #define GAS __attribute__((address_space(1)))
; #define LAS __attribute__((address_space(3)))
; __device__ __forceinline__ unsigned pk2(float lo, float hi) { f32x2_k v = {lo, hi}; bf16x2_k b = __builtin_convertvector(v, bf16x2_k); return __builtin_bit_cast(unsigned, b); }
; __device__ __forceinline__ void p0_finish(const P0Job& j, const f32x4 (&v)[16], LAS float* scr, int lane) {
;     ...
;     const int c = lane & 7;
; #pragma unroll
;     for (int hb = 0; hb < 2; ++hb) { const int drow0 = p0_drow(j.kind, n0 + 32 * hb);
;         if (n0 + 32 * hb < j.N && k0 + 8 * c < j.K) {
; #pragma unroll
;             for (int jj = 0; jj < 4; ++jj) { const int n = (lane >> 3) + 8 * jj; const LAS float* sp = scr + (8 * c) * 65 + 32 * hb + n;
;                 v4u o; o.x = pk2(sp[0 * 65], sp[1 * 65]); o.y = pk2(sp[2 * 65], sp[3 * 65]); o.z = pk2(sp[4 * 65], sp[5 * 65]); o.w = pk2(sp[6 * 65], sp[7 * 65]);
;                 GAS v4u* dp = (GAS v4u*)(j.WT + (size_t)(drow0 + n) * j.ldk + k0 + 8 * c); if (j.late) __builtin_nontemporal_store(o, dp); else *dp = o; } } }
.LBB0_2383:
	s_cmp_lt_i32 s58, s71
	s_cselect_b64 s[52:53], -1, 0
	s_and_b64 s[52:53], s[52:53], s[6:7]
	s_and_saveexec_b64 s[6:7], s[52:53]
	s_cbranch_execz .LBB0_2155
	ds_read2_b32 v[70:71], v134 offset0:97 offset1:105
	ds_read2_b32 v[72:73], v134 offset0:32 offset1:40
	ds_read2_b32 v[74:75], v134 offset0:162 offset1:170
	ds_read2_b32 v[76:77], v134 offset0:227 offset1:235
	ds_read2_b32 v[78:79], v64 offset0:36 offset1:44
	ds_read2_b32 v[80:81], v64 offset0:101 offset1:109
	ds_read2_b32 v[82:83], v64 offset0:166 offset1:174
	ds_read2_b32 v[84:85], v64 offset0:231 offset1:239
	v_add_u32_e32 v65, s57, v133
	v_mad_i64_i32 v[86:87], s[52:53], v65, s70, 0
	v_lshl_add_u64 v[86:87], v[86:87], 1, s[48:49]
	s_lshl_b64 s[50:51], s[50:51], 1
	v_lshl_add_u64 v[86:87], v[86:87], 0, s[50:51]
	s_waitcnt lgkmcnt(6)
	v_cvt_pk_bf16_f32 v66, v72, v70
	s_waitcnt lgkmcnt(4)
	v_cvt_pk_bf16_f32 v67, v74, v76
	s_waitcnt lgkmcnt(2)
	v_cvt_pk_bf16_f32 v68, v78, v80
	s_waitcnt lgkmcnt(0)
	v_cvt_pk_bf16_f32 v69, v82, v84
	v_lshl_add_u64 v[86:87], v[86:87], 0, v[130:131]
	v_add_u32_e32 v65, s57, v135
	global_store_dwordx4 v[86:87], v[66:69], off sc1
	s_nop 1
	v_cvt_pk_bf16_f32 v66, v73, v71
	v_mad_i64_i32 v[70:71], s[52:53], v65, s70, 0
	v_lshl_add_u64 v[70:71], v[70:71], 1, s[48:49]
	v_lshl_add_u64 v[70:71], v[70:71], 0, s[50:51]
	v_cvt_pk_bf16_f32 v67, v75, v77
	v_cvt_pk_bf16_f32 v68, v79, v81
	v_cvt_pk_bf16_f32 v69, v83, v85
	v_lshl_add_u64 v[70:71], v[70:71], 0, v[130:131]
	ds_read2_b32 v[72:73], v134 offset0:113 offset1:121
	ds_read2_b32 v[74:75], v134 offset0:48 offset1:56
	ds_read2_b32 v[76:77], v134 offset0:178 offset1:186
	ds_read2_b32 v[78:79], v134 offset0:243 offset1:251
	ds_read2_b32 v[80:81], v64 offset0:52 offset1:60
	ds_read2_b32 v[82:83], v64 offset0:117 offset1:125
	ds_read2_b32 v[84:85], v64 offset0:182 offset1:190
	ds_read2_b32 v[86:87], v64 offset0:247 offset1:255
	global_store_dwordx4 v[70:71], v[66:69], off sc1
	s_waitcnt lgkmcnt(6)
	v_cvt_pk_bf16_f32 v64, v74, v72
	s_waitcnt lgkmcnt(4)
	v_cvt_pk_bf16_f32 v65, v76, v78
	v_add_u32_e32 v68, s57, v136
	v_mad_i64_i32 v[68:69], s[52:53], v68, s70, 0
	v_lshl_add_u64 v[68:69], v[68:69], 1, s[48:49]
	v_lshl_add_u64 v[68:69], v[68:69], 0, s[50:51]
	s_waitcnt lgkmcnt(2)
	v_cvt_pk_bf16_f32 v66, v80, v82
	s_waitcnt lgkmcnt(0)
	v_cvt_pk_bf16_f32 v67, v84, v86
	v_lshl_add_u64 v[68:69], v[68:69], 0, v[130:131]
	global_store_dwordx4 v[68:69], v[64:67], off sc1
	v_add_u32_e32 v68, s57, v137
	v_mad_i64_i32 v[68:69], s[52:53], v68, s70, 0
	v_lshl_add_u64 v[68:69], v[68:69], 1, s[48:49]
	v_lshl_add_u64 v[68:69], v[68:69], 0, s[50:51]
	v_cvt_pk_bf16_f32 v64, v75, v73
	v_cvt_pk_bf16_f32 v65, v77, v79
	v_cvt_pk_bf16_f32 v66, v81, v83
	v_cvt_pk_bf16_f32 v67, v85, v87
	v_lshl_add_u64 v[68:69], v[68:69], 0, v[130:131]
	global_store_dwordx4 v[68:69], v[64:67], off sc1
	s_branch .LBB0_2155
